# all global stores write-through (sc1) and the per-XCD L2 writeback in the hierarchical grid barrier dropped
# speedup vs baseline: 1.0071x; 1.0060x over previous
.LBB0_86:
	s_waitcnt vmcnt(2)
	v_lshl_add_u64 v[14:15], s[8:9], 0, v[4:5]
	global_load_dwordx4 v[10:13], v[14:15], off
	v_add_co_u32_e32 v14, vcc, 0x3000000, v14
	s_waitcnt vmcnt(2)
	v_lshl_add_u64 v[18:19], s[12:13], 0, v[4:5]
	v_and_b32_e32 v0, 0x3fc, v6
	v_addc_co_u32_e32 v15, vcc, 0, v15, vcc
	v_lshlrev_b32_e32 v0, 2, v0
	global_load_dwordx4 v[14:17], v[14:15], off
	s_nop 0
	global_load_dwordx4 v[18:21], v[18:19], off offset:-8
	s_nop 0
	global_load_dwordx4 v[22:25], v0, s[40:41]
	v_lshl_add_u64 v[2:3], v[2:3], 0, s[94:95]
	v_lshl_add_u64 v[4:5], v[4:5], 0, s[4:5]
	v_lshl_add_u64 v[6:7], v[6:7], 0, s[6:7]
	s_waitcnt vmcnt(2)
	v_pk_add_f32 v[10:11], v[10:11], v[14:15]
	v_pk_add_f32 v[12:13], v[12:13], v[16:17]
	s_waitcnt vmcnt(0)
	v_pk_fma_f32 v[10:11], v[18:19], v[22:23], v[10:11]
	v_pk_fma_f32 v[12:13], v[20:21], v[24:25], v[12:13]
	v_mul_f32_e32 v0, 0x3d372713, v10
	v_mul_f32_e32 v0, v10, v0
	v_fma_f32 v0, v10, v0, v10
	v_mul_f32_e32 v0, 0x3f4c422a, v0
	v_add_f32_e32 v0, v0, v0
	v_mul_f32_e32 v0, 0x3fb8aa3b, v0
	v_exp_f32_e32 v14, v0
	v_mul_f32_e32 v0, 0x3d372713, v11
	v_mul_f32_e32 v0, v11, v0
	v_fma_f32 v0, v11, v0, v11
	v_mul_f32_e32 v0, 0x3f4c422a, v0
	v_add_f32_e32 v0, v0, v0
	v_mul_f32_e32 v0, 0x3fb8aa3b, v0
	v_exp_f32_e32 v15, v0
	v_pk_mul_f32 v[10:11], v[10:11], 0.5 op_sel_hi:[1,0]
	v_pk_add_f32 v[14:15], v[14:15], 1.0 op_sel_hi:[1,0]
	s_nop 0
	v_div_scale_f32 v0, s[20:21], v15, v15, 2.0
	v_rcp_f32_e32 v18, v0
	s_nop 0
	v_fma_f32 v19, -v0, v18, 1.0
	v_fmac_f32_e32 v18, v19, v18
	v_div_scale_f32 v19, vcc, 2.0, v15, 2.0
	v_mul_f32_e32 v22, v19, v18
	v_fma_f32 v23, -v0, v22, v19
	v_fmac_f32_e32 v22, v23, v18
	v_fma_f32 v0, -v0, v22, v19
	v_div_fmas_f32 v0, v0, v18, v22
	v_div_fixup_f32 v15, v0, v15, 2.0
	v_div_scale_f32 v0, s[20:21], v14, v14, 2.0
	v_rcp_f32_e32 v18, v0
	s_nop 0
	v_fma_f32 v19, -v0, v18, 1.0
	v_fmac_f32_e32 v18, v19, v18
	v_div_scale_f32 v19, vcc, 2.0, v14, 2.0
	v_mul_f32_e32 v22, v19, v18
	v_fma_f32 v23, -v0, v22, v19
	v_fmac_f32_e32 v22, v23, v18
	v_fma_f32 v0, -v0, v22, v19
	v_div_fmas_f32 v0, v0, v18, v22
	v_div_fixup_f32 v14, v0, v14, 2.0
	v_mul_f32_e32 v0, 0x3d372713, v12
	v_mul_f32_e32 v0, v12, v0
	v_fma_f32 v0, v12, v0, v12
	v_mul_f32_e32 v0, 0x3f4c422a, v0
	v_pk_add_f32 v[14:15], v[14:15], 1.0 op_sel_hi:[1,0] neg_lo:[1,0] neg_hi:[1,0]
	v_add_f32_e32 v0, v0, v0
	v_pk_add_f32 v[14:15], v[14:15], 1.0 op_sel_hi:[1,0]
	v_mul_f32_e32 v0, 0x3fb8aa3b, v0
	v_pk_mul_f32 v[10:11], v[10:11], v[14:15]
	v_exp_f32_e32 v14, v0
	v_mul_f32_e32 v0, 0x3d372713, v13
	v_mul_f32_e32 v0, v13, v0
	v_fma_f32 v0, v13, v0, v13
	v_mul_f32_e32 v0, 0x3f4c422a, v0
	v_add_f32_e32 v0, v0, v0
	v_mul_f32_e32 v0, 0x3fb8aa3b, v0
	v_exp_f32_e32 v15, v0
	v_pk_mul_f32 v[12:13], v[12:13], 0.5 op_sel_hi:[1,0]
	v_cvt_pk_bf16_f32 v10, v10, v11
	v_pk_add_f32 v[14:15], v[14:15], 1.0 op_sel_hi:[1,0]
	s_nop 0
	v_div_scale_f32 v0, s[20:21], v15, v15, 2.0
	v_rcp_f32_e32 v16, v0
	s_nop 0
	v_fma_f32 v17, -v0, v16, 1.0
	v_fmac_f32_e32 v16, v17, v16
	v_div_scale_f32 v17, vcc, 2.0, v15, 2.0
	v_mul_f32_e32 v18, v17, v16
	v_fma_f32 v19, -v0, v18, v17
	v_fmac_f32_e32 v18, v19, v16
	v_fma_f32 v0, -v0, v18, v17
	v_div_fmas_f32 v0, v0, v16, v18
	v_div_fixup_f32 v15, v0, v15, 2.0
	v_div_scale_f32 v0, s[20:21], v14, v14, 2.0
	v_rcp_f32_e32 v16, v0
	s_mov_b64 s[20:21], 0x2fffff
	v_fma_f32 v17, -v0, v16, 1.0
	v_fmac_f32_e32 v16, v17, v16
	v_div_scale_f32 v17, vcc, 2.0, v14, 2.0
	v_mul_f32_e32 v18, v17, v16
	v_fma_f32 v19, -v0, v18, v17
	v_fmac_f32_e32 v18, v19, v16
	v_fma_f32 v0, -v0, v18, v17
	v_div_fmas_f32 v0, v0, v16, v18
	v_div_fixup_f32 v14, v0, v14, 2.0
	v_pk_add_f32 v[14:15], v[14:15], 1.0 op_sel_hi:[1,0] neg_lo:[1,0] neg_hi:[1,0]
	v_cmp_lt_u64_e32 vcc, s[20:21], v[2:3]
	v_pk_add_f32 v[14:15], v[14:15], 1.0 op_sel_hi:[1,0]
	s_or_b64 s[42:43], vcc, s[42:43]
	v_pk_mul_f32 v[12:13], v[12:13], v[14:15]
	s_nop 0
	v_cvt_pk_bf16_f32 v11, v12, v13
	global_store_dwordx2 v[8:9], v[10:11], off offset:-4 sc1
	v_lshl_add_u64 v[8:9], v[8:9], 0, s[10:11]
	s_andn2_b64 exec, exec, s[42:43]
	s_cbranch_execnz .LBB0_86

.LS5P_loopd1:
	s_add_u32 s20, s28, 2
	s_cmp_lt_u32 s20, s52
	s_cselect_b64 s[58:59], s[50:51], 0
	v_lshl_add_u64 v[248:249], v[248:249], 0, s[58:59]
	global_load_dwordx4 v[110:113], v[248:249], off offset:16
	global_load_dwordx4 v[106:109], v[248:249], off
	ds_read_b128 v[216:219], v208
	ds_read_b128 v[220:223], v208 offset:4352
	ds_read_b128 v[224:227], v208 offset:64
	ds_read_b128 v[228:231], v208 offset:4416
	v_fmac_f32_e32 v49, v152, v182
	v_fmac_f32_e32 v65, v152, v178
	v_fma_f32 v49, -v153, v178, v49
	v_fmac_f32_e32 v65, v153, v182
	v_mfma_f32_32x32x16_bf16 v[2:17], v[212:215], v[70:73], 0
	v_fmac_f32_e32 v48, v152, v49
	v_fmac_f32_e32 v64, v152, v65
	v_cvt_pk_bf16_f32 v184, v49, v65
	v_fma_f32 v48, -v153, v65, v48
	v_fmac_f32_e32 v64, v153, v49
	ds_write_b32 v207, v184 offset:4080
	v_fmac_f32_e32 v47, v152, v48
	v_fmac_f32_e32 v63, v152, v64
	v_cvt_pk_bf16_f32 v185, v48, v64
	v_fma_f32 v47, -v153, v64, v47
	v_fmac_f32_e32 v63, v153, v48
	ds_write_b32 v207, v185 offset:3808
	v_mfma_f32_32x32x16_bf16 v[18:33], v[212:215], v[78:81], 0
	v_fmac_f32_e32 v46, v152, v47
	v_fmac_f32_e32 v62, v152, v63
	v_cvt_pk_bf16_f32 v184, v47, v63
	v_fma_f32 v46, -v153, v63, v46
	v_fmac_f32_e32 v62, v153, v47
	ds_write_b32 v207, v184 offset:3536
	v_fmac_f32_e32 v45, v152, v46
	v_fmac_f32_e32 v61, v152, v62
	v_cvt_pk_bf16_f32 v185, v46, v62
	v_fma_f32 v45, -v153, v62, v45
	v_fmac_f32_e32 v61, v153, v46
	ds_write_b32 v207, v185 offset:3264
	s_waitcnt lgkmcnt(6)
	v_mfma_f32_16x16x32_bf16 v[232:235], v[82:85], v[216:219], 0
	v_fmac_f32_e32 v44, v152, v45
	v_fmac_f32_e32 v60, v152, v61
	v_cvt_pk_bf16_f32 v184, v45, v61
	v_fma_f32 v44, -v153, v61, v44
	v_fmac_f32_e32 v60, v153, v45
	ds_write_b32 v207, v184 offset:2992
	v_mfma_f32_16x16x32_bf16 v[236:239], v[82:85], v[220:223], 0
	v_fmac_f32_e32 v43, v152, v44
	v_fmac_f32_e32 v59, v152, v60
	v_cvt_pk_bf16_f32 v185, v44, v60
	v_fma_f32 v43, -v153, v60, v43
	v_fmac_f32_e32 v59, v153, v44
	ds_write_b32 v207, v185 offset:2720
	s_waitcnt lgkmcnt(6)
	v_mfma_f32_16x16x32_bf16 v[232:235], v[86:89], v[224:227], v[232:235]
	v_fmac_f32_e32 v42, v152, v43
	v_fmac_f32_e32 v58, v152, v59
	v_cvt_pk_bf16_f32 v184, v43, v59
	v_fma_f32 v42, -v153, v59, v42
	v_fmac_f32_e32 v58, v153, v43
	ds_write_b32 v207, v184 offset:2448
	v_mfma_f32_16x16x32_bf16 v[236:239], v[86:89], v[228:231], v[236:239]
	v_fmac_f32_e32 v41, v152, v42
	v_fmac_f32_e32 v57, v152, v58
	v_cvt_pk_bf16_f32 v185, v42, v58
	v_fma_f32 v41, -v153, v58, v41
	v_fmac_f32_e32 v57, v153, v42
	ds_write_b32 v207, v185 offset:2176
	ds_read_b128 v[216:219], v208 offset:128
	ds_read_b128 v[220:223], v208 offset:4480
	ds_read_b128 v[224:227], v208 offset:192
	ds_read_b128 v[228:231], v208 offset:4544
	v_fmac_f32_e32 v40, v152, v41
	v_fmac_f32_e32 v56, v152, v57
	v_cvt_pk_bf16_f32 v184, v41, v57
	v_fma_f32 v40, -v153, v57, v40
	v_fmac_f32_e32 v56, v153, v41
	ds_write_b32 v207, v184 offset:1904
	v_fmac_f32_e32 v39, v152, v40
	v_fmac_f32_e32 v55, v152, v56
	v_cvt_pk_bf16_f32 v185, v40, v56
	v_fma_f32 v39, -v153, v56, v39
	v_fmac_f32_e32 v55, v153, v40
	ds_write_b32 v207, v185 offset:1632
	v_fmac_f32_e32 v38, v152, v39
	v_fmac_f32_e32 v54, v152, v55
	v_cvt_pk_bf16_f32 v184, v39, v55
	v_fma_f32 v38, -v153, v55, v38
	v_fmac_f32_e32 v54, v153, v39
	ds_write_b32 v207, v184 offset:1360
	s_waitcnt lgkmcnt(5)
	v_mfma_f32_16x16x32_bf16 v[232:235], v[90:93], v[216:219], v[232:235]
	v_fmac_f32_e32 v37, v152, v38
	v_fmac_f32_e32 v53, v152, v54
	v_cvt_pk_bf16_f32 v185, v38, v54
	v_fma_f32 v37, -v153, v54, v37
	v_fmac_f32_e32 v53, v153, v38
	ds_write_b32 v207, v185 offset:1088
	v_mfma_f32_16x16x32_bf16 v[236:239], v[90:93], v[220:223], v[236:239]
	v_fmac_f32_e32 v36, v152, v37
	v_fmac_f32_e32 v52, v152, v53
	v_cvt_pk_bf16_f32 v184, v37, v53
	v_fma_f32 v36, -v153, v53, v36
	v_fmac_f32_e32 v52, v153, v37
	ds_write_b32 v207, v184 offset:816
	s_waitcnt lgkmcnt(5)
	v_mfma_f32_16x16x32_bf16 v[232:235], v[94:97], v[224:227], v[232:235]
	v_fmac_f32_e32 v35, v152, v36
	v_fmac_f32_e32 v51, v152, v52
	v_cvt_pk_bf16_f32 v185, v36, v52
	v_fma_f32 v35, -v153, v52, v35
	v_fmac_f32_e32 v51, v153, v36
	ds_write_b32 v207, v185 offset:544
	v_mfma_f32_16x16x32_bf16 v[236:239], v[94:97], v[228:231], v[236:239]
	v_fma_f32 v182, v152, v35, v34
	v_fma_f32 v178, v152, v51, v50
	v_cvt_pk_bf16_f32 v184, v35, v51
	v_fma_f32 v182, -v153, v51, v182
	v_fmac_f32_e32 v178, v153, v35
	ds_write_b32 v207, v184 offset:272
	v_cvt_pk_bf16_f32 v185, v182, v178
	ds_write_b32 v207, v185 offset:0
	s_cmp_eq_u32 s28, 0
	s_cbranch_scc1 .LS5P_nstd1e
	global_store_dwordx4 v[240:241], v[232:235], off sc1
	global_store_dwordx4 v[244:245], v[236:239], off sc1
	v_lshl_add_u64 v[240:241], v[240:241], 0, s[50:51]
	v_lshl_add_u64 v[244:245], v[244:245], 0, s[50:51]
.LS5P_nstd1e:
	s_waitcnt vmcnt(6)
	v_cvt_pk_bf16_f32 v212, v102, v103
	v_cvt_pk_bf16_f32 v213, v104, v105
	v_cvt_pk_bf16_f32 v214, v98, v99
	v_cvt_pk_bf16_f32 v215, v100, v101
	v_fmac_f32_e32 v17, v154, v180
	v_fmac_f32_e32 v33, v154, v176
	v_fma_f32 v17, -v155, v176, v17
	v_fmac_f32_e32 v33, v155, v180
	v_mfma_f32_32x32x16_bf16 v[34:49], v[212:215], v[66:69], 0
	v_fmac_f32_e32 v16, v154, v17
	v_fmac_f32_e32 v32, v154, v33
	v_cvt_pk_bf16_f32 v184, v17, v33
	v_fma_f32 v16, -v155, v33, v16
	v_fmac_f32_e32 v32, v155, v17
	ds_write_b32 v207, v184 offset:4208
	v_fmac_f32_e32 v15, v154, v16
	v_fmac_f32_e32 v31, v154, v32
	v_cvt_pk_bf16_f32 v185, v16, v32
	v_fma_f32 v15, -v155, v32, v15
	v_fmac_f32_e32 v31, v155, v16
	ds_write_b32 v207, v185 offset:3936
	v_mfma_f32_32x32x16_bf16 v[50:65], v[212:215], v[74:77], 0
	v_fmac_f32_e32 v14, v154, v15
	v_fmac_f32_e32 v30, v154, v31
	v_cvt_pk_bf16_f32 v184, v15, v31
	v_fma_f32 v14, -v155, v31, v14
	v_fmac_f32_e32 v30, v155, v15
	ds_write_b32 v207, v184 offset:3664
	v_fmac_f32_e32 v13, v154, v14
	v_fmac_f32_e32 v29, v154, v30
	v_cvt_pk_bf16_f32 v185, v14, v30
	v_fma_f32 v13, -v155, v30, v13
	v_fmac_f32_e32 v29, v155, v14
	ds_write_b32 v207, v185 offset:3392
	v_fmac_f32_e32 v12, v154, v13
	v_fmac_f32_e32 v28, v154, v29
	v_cvt_pk_bf16_f32 v184, v13, v29
	v_fma_f32 v12, -v155, v29, v12
	v_fmac_f32_e32 v28, v155, v13
	ds_write_b32 v207, v184 offset:3120
	v_fmac_f32_e32 v11, v154, v12
	v_fmac_f32_e32 v27, v154, v28
	v_cvt_pk_bf16_f32 v185, v12, v28
	v_fma_f32 v11, -v155, v28, v11
	v_fmac_f32_e32 v27, v155, v12
	ds_write_b32 v207, v185 offset:2848
	v_fmac_f32_e32 v10, v154, v11
	v_fmac_f32_e32 v26, v154, v27
	v_cvt_pk_bf16_f32 v184, v11, v27
	v_fma_f32 v10, -v155, v27, v10
	v_fmac_f32_e32 v26, v155, v11
	ds_write_b32 v207, v184 offset:2576
	v_fmac_f32_e32 v9, v154, v10
	v_fmac_f32_e32 v25, v154, v26
	v_cvt_pk_bf16_f32 v185, v10, v26
	v_fma_f32 v9, -v155, v26, v9
	v_fmac_f32_e32 v25, v155, v10
	ds_write_b32 v207, v185 offset:2304
	v_fmac_f32_e32 v8, v154, v9
	v_fmac_f32_e32 v24, v154, v25
	v_cvt_pk_bf16_f32 v184, v9, v25
	v_fma_f32 v8, -v155, v25, v8
	v_fmac_f32_e32 v24, v155, v9
	ds_write_b32 v207, v184 offset:2032
	v_fmac_f32_e32 v7, v154, v8
	v_fmac_f32_e32 v23, v154, v24
	v_cvt_pk_bf16_f32 v185, v8, v24
	v_fma_f32 v7, -v155, v24, v7
	v_fmac_f32_e32 v23, v155, v8
	ds_write_b32 v207, v185 offset:1760
	v_fmac_f32_e32 v6, v154, v7
	v_fmac_f32_e32 v22, v154, v23
	v_cvt_pk_bf16_f32 v184, v7, v23
	v_fma_f32 v6, -v155, v23, v6
	v_fmac_f32_e32 v22, v155, v7
	ds_write_b32 v207, v184 offset:1488
	v_fmac_f32_e32 v5, v154, v6
	v_fmac_f32_e32 v21, v154, v22
	v_cvt_pk_bf16_f32 v185, v6, v22
	v_fma_f32 v5, -v155, v22, v5
	v_fmac_f32_e32 v21, v155, v6
	ds_write_b32 v207, v185 offset:1216
	v_fmac_f32_e32 v4, v154, v5
	v_fmac_f32_e32 v20, v154, v21
	v_cvt_pk_bf16_f32 v184, v5, v21
	v_fma_f32 v4, -v155, v21, v4
	v_fmac_f32_e32 v20, v155, v5
	ds_write_b32 v207, v184 offset:944
	v_fmac_f32_e32 v3, v154, v4
	v_fmac_f32_e32 v19, v154, v20
	v_cvt_pk_bf16_f32 v185, v4, v20
	v_fma_f32 v3, -v155, v20, v3
	v_fmac_f32_e32 v19, v155, v4
	ds_write_b32 v207, v185 offset:672
	v_fma_f32 v180, v154, v3, v2
	v_fma_f32 v176, v154, v19, v18
	v_cvt_pk_bf16_f32 v184, v3, v19
	v_fma_f32 v180, -v155, v19, v180
	v_fmac_f32_e32 v176, v155, v3
	ds_write_b32 v207, v184 offset:400
	v_cvt_pk_bf16_f32 v185, v180, v176
	ds_write_b32 v207, v185 offset:128
	s_add_u32 s28, s28, 1
	s_add_u32 s20, s28, 2
	s_cmp_lt_u32 s20, s52
	s_cselect_b64 s[58:59], s[50:51], 0
	v_lshl_add_u64 v[248:249], v[248:249], 0, s[58:59]
	global_load_dwordx4 v[98:101], v[248:249], off offset:16
	global_load_dwordx4 v[102:105], v[248:249], off
	ds_read_b128 v[216:219], v208
	ds_read_b128 v[220:223], v208 offset:4352
	ds_read_b128 v[224:227], v208 offset:64
	ds_read_b128 v[228:231], v208 offset:4416
	v_fmac_f32_e32 v49, v152, v182
	v_fmac_f32_e32 v65, v152, v178
	v_fma_f32 v49, -v153, v178, v49
	v_fmac_f32_e32 v65, v153, v182
	v_mfma_f32_32x32x16_bf16 v[2:17], v[212:215], v[70:73], 0
	v_fmac_f32_e32 v48, v152, v49
	v_fmac_f32_e32 v64, v152, v65
	v_cvt_pk_bf16_f32 v184, v49, v65
	v_fma_f32 v48, -v153, v65, v48
	v_fmac_f32_e32 v64, v153, v49
	ds_write_b32 v207, v184 offset:4080
	v_fmac_f32_e32 v47, v152, v48
	v_fmac_f32_e32 v63, v152, v64
	v_cvt_pk_bf16_f32 v185, v48, v64
	v_fma_f32 v47, -v153, v64, v47
	v_fmac_f32_e32 v63, v153, v48
	ds_write_b32 v207, v185 offset:3808
	v_mfma_f32_32x32x16_bf16 v[18:33], v[212:215], v[78:81], 0
	v_fmac_f32_e32 v46, v152, v47
	v_fmac_f32_e32 v62, v152, v63
	v_cvt_pk_bf16_f32 v184, v47, v63
	v_fma_f32 v46, -v153, v63, v46
	v_fmac_f32_e32 v62, v153, v47
	ds_write_b32 v207, v184 offset:3536
	v_fmac_f32_e32 v45, v152, v46
	v_fmac_f32_e32 v61, v152, v62
	v_cvt_pk_bf16_f32 v185, v46, v62
	v_fma_f32 v45, -v153, v62, v45
	v_fmac_f32_e32 v61, v153, v46
	ds_write_b32 v207, v185 offset:3264
	s_waitcnt lgkmcnt(6)
	v_mfma_f32_16x16x32_bf16 v[232:235], v[82:85], v[216:219], 0
	v_fmac_f32_e32 v44, v152, v45
	v_fmac_f32_e32 v60, v152, v61
	v_cvt_pk_bf16_f32 v184, v45, v61
	v_fma_f32 v44, -v153, v61, v44
	v_fmac_f32_e32 v60, v153, v45
	ds_write_b32 v207, v184 offset:2992
	v_mfma_f32_16x16x32_bf16 v[236:239], v[82:85], v[220:223], 0
	v_fmac_f32_e32 v43, v152, v44
	v_fmac_f32_e32 v59, v152, v60
	v_cvt_pk_bf16_f32 v185, v44, v60
	v_fma_f32 v43, -v153, v60, v43
	v_fmac_f32_e32 v59, v153, v44
	ds_write_b32 v207, v185 offset:2720
	s_waitcnt lgkmcnt(6)
	v_mfma_f32_16x16x32_bf16 v[232:235], v[86:89], v[224:227], v[232:235]
	v_fmac_f32_e32 v42, v152, v43
	v_fmac_f32_e32 v58, v152, v59
	v_cvt_pk_bf16_f32 v184, v43, v59
	v_fma_f32 v42, -v153, v59, v42
	v_fmac_f32_e32 v58, v153, v43
	ds_write_b32 v207, v184 offset:2448
	v_mfma_f32_16x16x32_bf16 v[236:239], v[86:89], v[228:231], v[236:239]
	v_fmac_f32_e32 v41, v152, v42
	v_fmac_f32_e32 v57, v152, v58
	v_cvt_pk_bf16_f32 v185, v42, v58
	v_fma_f32 v41, -v153, v58, v41
	v_fmac_f32_e32 v57, v153, v42
	ds_write_b32 v207, v185 offset:2176
	ds_read_b128 v[216:219], v208 offset:128
	ds_read_b128 v[220:223], v208 offset:4480
	ds_read_b128 v[224:227], v208 offset:192
	ds_read_b128 v[228:231], v208 offset:4544
	v_fmac_f32_e32 v40, v152, v41
	v_fmac_f32_e32 v56, v152, v57
	v_cvt_pk_bf16_f32 v184, v41, v57
	v_fma_f32 v40, -v153, v57, v40
	v_fmac_f32_e32 v56, v153, v41
	ds_write_b32 v207, v184 offset:1904
	v_fmac_f32_e32 v39, v152, v40
	v_fmac_f32_e32 v55, v152, v56
	v_cvt_pk_bf16_f32 v185, v40, v56
	v_fma_f32 v39, -v153, v56, v39
	v_fmac_f32_e32 v55, v153, v40
	ds_write_b32 v207, v185 offset:1632
	v_fmac_f32_e32 v38, v152, v39
	v_fmac_f32_e32 v54, v152, v55
	v_cvt_pk_bf16_f32 v184, v39, v55
	v_fma_f32 v38, -v153, v55, v38
	v_fmac_f32_e32 v54, v153, v39
	ds_write_b32 v207, v184 offset:1360
	s_waitcnt lgkmcnt(5)
	v_mfma_f32_16x16x32_bf16 v[232:235], v[90:93], v[216:219], v[232:235]
	v_fmac_f32_e32 v37, v152, v38
	v_fmac_f32_e32 v53, v152, v54
	v_cvt_pk_bf16_f32 v185, v38, v54
	v_fma_f32 v37, -v153, v54, v37
	v_fmac_f32_e32 v53, v153, v38
	ds_write_b32 v207, v185 offset:1088
	v_mfma_f32_16x16x32_bf16 v[236:239], v[90:93], v[220:223], v[236:239]
	v_fmac_f32_e32 v36, v152, v37
	v_fmac_f32_e32 v52, v152, v53
	v_cvt_pk_bf16_f32 v184, v37, v53
	v_fma_f32 v36, -v153, v53, v36
	v_fmac_f32_e32 v52, v153, v37
	ds_write_b32 v207, v184 offset:816
	s_waitcnt lgkmcnt(5)
	v_mfma_f32_16x16x32_bf16 v[232:235], v[94:97], v[224:227], v[232:235]
	v_fmac_f32_e32 v35, v152, v36
	v_fmac_f32_e32 v51, v152, v52
	v_cvt_pk_bf16_f32 v185, v36, v52
	v_fma_f32 v35, -v153, v52, v35
	v_fmac_f32_e32 v51, v153, v36
	ds_write_b32 v207, v185 offset:544
	v_mfma_f32_16x16x32_bf16 v[236:239], v[94:97], v[228:231], v[236:239]
	v_fma_f32 v182, v152, v35, v34
	v_fma_f32 v178, v152, v51, v50
	v_cvt_pk_bf16_f32 v184, v35, v51
	v_fma_f32 v182, -v153, v51, v182
	v_fmac_f32_e32 v178, v153, v35
	ds_write_b32 v207, v184 offset:272
	v_cvt_pk_bf16_f32 v185, v182, v178
	ds_write_b32 v207, v185 offset:0
	global_store_dwordx4 v[240:241], v[232:235], off sc1
	global_store_dwordx4 v[244:245], v[236:239], off sc1
	v_lshl_add_u64 v[240:241], v[240:241], 0, s[50:51]
	v_lshl_add_u64 v[244:245], v[244:245], 0, s[50:51]
	s_cmp_eq_u32 s28, 1
	s_cbranch_scc0 .LS5P_wd1o
	s_waitcnt vmcnt(4)

.LS5P_loopd0:
	s_add_u32 s20, s28, 2
	s_cmp_lt_u32 s20, s52
	s_cselect_b64 s[58:59], s[50:51], 0
	v_lshl_add_u64 v[248:249], v[248:249], 0, s[58:59]
	global_load_dwordx4 v[110:113], v[248:249], off offset:16
	global_load_dwordx4 v[106:109], v[248:249], off
	ds_read_b128 v[216:219], v208
	ds_read_b128 v[220:223], v208 offset:4352
	ds_read_b128 v[224:227], v208 offset:64
	ds_read_b128 v[228:231], v208 offset:4416
	v_fmac_f32_e32 v34, v152, v182
	v_fmac_f32_e32 v50, v152, v178
	v_fma_f32 v34, -v153, v178, v34
	v_fmac_f32_e32 v50, v153, v182
	v_mfma_f32_32x32x16_bf16 v[2:17], v[212:215], v[70:73], 0
	v_fmac_f32_e32 v35, v152, v34
	v_fmac_f32_e32 v51, v152, v50
	v_cvt_pk_bf16_f32 v184, v34, v50
	v_fma_f32 v35, -v153, v50, v35
	v_fmac_f32_e32 v51, v153, v34
	ds_write_b32 v207, v184 offset:0
	v_fmac_f32_e32 v36, v152, v35
	v_fmac_f32_e32 v52, v152, v51
	v_cvt_pk_bf16_f32 v185, v35, v51
	v_fma_f32 v36, -v153, v51, v36
	v_fmac_f32_e32 v52, v153, v35
	ds_write_b32 v207, v185 offset:272
	v_mfma_f32_32x32x16_bf16 v[18:33], v[212:215], v[78:81], 0
	v_fmac_f32_e32 v37, v152, v36
	v_fmac_f32_e32 v53, v152, v52
	v_cvt_pk_bf16_f32 v184, v36, v52
	v_fma_f32 v37, -v153, v52, v37
	v_fmac_f32_e32 v53, v153, v36
	ds_write_b32 v207, v184 offset:544
	v_fmac_f32_e32 v38, v152, v37
	v_fmac_f32_e32 v54, v152, v53
	v_cvt_pk_bf16_f32 v185, v37, v53
	v_fma_f32 v38, -v153, v53, v38
	v_fmac_f32_e32 v54, v153, v37
	ds_write_b32 v207, v185 offset:816
	s_waitcnt lgkmcnt(6)
	v_mfma_f32_16x16x32_bf16 v[232:235], v[82:85], v[216:219], 0
	v_fmac_f32_e32 v39, v152, v38
	v_fmac_f32_e32 v55, v152, v54
	v_cvt_pk_bf16_f32 v184, v38, v54
	v_fma_f32 v39, -v153, v54, v39
	v_fmac_f32_e32 v55, v153, v38
	ds_write_b32 v207, v184 offset:1088
	v_mfma_f32_16x16x32_bf16 v[236:239], v[82:85], v[220:223], 0
	v_fmac_f32_e32 v40, v152, v39
	v_fmac_f32_e32 v56, v152, v55
	v_cvt_pk_bf16_f32 v185, v39, v55
	v_fma_f32 v40, -v153, v55, v40
	v_fmac_f32_e32 v56, v153, v39
	ds_write_b32 v207, v185 offset:1360
	s_waitcnt lgkmcnt(6)
	v_mfma_f32_16x16x32_bf16 v[232:235], v[86:89], v[224:227], v[232:235]
	v_fmac_f32_e32 v41, v152, v40
	v_fmac_f32_e32 v57, v152, v56
	v_cvt_pk_bf16_f32 v184, v40, v56
	v_fma_f32 v41, -v153, v56, v41
	v_fmac_f32_e32 v57, v153, v40
	ds_write_b32 v207, v184 offset:1632
	v_mfma_f32_16x16x32_bf16 v[236:239], v[86:89], v[228:231], v[236:239]
	v_fmac_f32_e32 v42, v152, v41
	v_fmac_f32_e32 v58, v152, v57
	v_cvt_pk_bf16_f32 v185, v41, v57
	v_fma_f32 v42, -v153, v57, v42
	v_fmac_f32_e32 v58, v153, v41
	ds_write_b32 v207, v185 offset:1904
	ds_read_b128 v[216:219], v208 offset:128
	ds_read_b128 v[220:223], v208 offset:4480
	ds_read_b128 v[224:227], v208 offset:192
	ds_read_b128 v[228:231], v208 offset:4544
	v_fmac_f32_e32 v43, v152, v42
	v_fmac_f32_e32 v59, v152, v58
	v_cvt_pk_bf16_f32 v184, v42, v58
	v_fma_f32 v43, -v153, v58, v43
	v_fmac_f32_e32 v59, v153, v42
	ds_write_b32 v207, v184 offset:2176
	v_fmac_f32_e32 v44, v152, v43
	v_fmac_f32_e32 v60, v152, v59
	v_cvt_pk_bf16_f32 v185, v43, v59
	v_fma_f32 v44, -v153, v59, v44
	v_fmac_f32_e32 v60, v153, v43
	ds_write_b32 v207, v185 offset:2448
	v_fmac_f32_e32 v45, v152, v44
	v_fmac_f32_e32 v61, v152, v60
	v_cvt_pk_bf16_f32 v184, v44, v60
	v_fma_f32 v45, -v153, v60, v45
	v_fmac_f32_e32 v61, v153, v44
	ds_write_b32 v207, v184 offset:2720
	s_waitcnt lgkmcnt(5)
	v_mfma_f32_16x16x32_bf16 v[232:235], v[90:93], v[216:219], v[232:235]
	v_fmac_f32_e32 v46, v152, v45
	v_fmac_f32_e32 v62, v152, v61
	v_cvt_pk_bf16_f32 v185, v45, v61
	v_fma_f32 v46, -v153, v61, v46
	v_fmac_f32_e32 v62, v153, v45
	ds_write_b32 v207, v185 offset:2992
	v_mfma_f32_16x16x32_bf16 v[236:239], v[90:93], v[220:223], v[236:239]
	v_fmac_f32_e32 v47, v152, v46
	v_fmac_f32_e32 v63, v152, v62
	v_cvt_pk_bf16_f32 v184, v46, v62
	v_fma_f32 v47, -v153, v62, v47
	v_fmac_f32_e32 v63, v153, v46
	ds_write_b32 v207, v184 offset:3264
	s_waitcnt lgkmcnt(5)
	v_mfma_f32_16x16x32_bf16 v[232:235], v[94:97], v[224:227], v[232:235]
	v_fmac_f32_e32 v48, v152, v47
	v_fmac_f32_e32 v64, v152, v63
	v_cvt_pk_bf16_f32 v185, v47, v63
	v_fma_f32 v48, -v153, v63, v48
	v_fmac_f32_e32 v64, v153, v47
	ds_write_b32 v207, v185 offset:3536
	v_mfma_f32_16x16x32_bf16 v[236:239], v[94:97], v[228:231], v[236:239]
	v_fma_f32 v182, v152, v48, v49
	v_fma_f32 v178, v152, v64, v65
	v_cvt_pk_bf16_f32 v184, v48, v64
	v_fma_f32 v182, -v153, v64, v182
	v_fmac_f32_e32 v178, v153, v48
	ds_write_b32 v207, v184 offset:3808
	v_cvt_pk_bf16_f32 v185, v182, v178
	ds_write_b32 v207, v185 offset:4080
	s_cmp_eq_u32 s28, 0
	s_cbranch_scc1 .LS5P_nstd0e
	global_store_dwordx4 v[240:241], v[232:235], off sc1
	global_store_dwordx4 v[244:245], v[236:239], off sc1
	v_lshl_add_u64 v[240:241], v[240:241], 0, s[50:51]
	v_lshl_add_u64 v[244:245], v[244:245], 0, s[50:51]
.LS5P_nstd0e:
	s_waitcnt vmcnt(6)
	v_cvt_pk_bf16_f32 v212, v102, v103
	v_cvt_pk_bf16_f32 v213, v104, v105
	v_cvt_pk_bf16_f32 v214, v98, v99
	v_cvt_pk_bf16_f32 v215, v100, v101
	v_fmac_f32_e32 v2, v154, v180
	v_fmac_f32_e32 v18, v154, v176
	v_fma_f32 v2, -v155, v176, v2
	v_fmac_f32_e32 v18, v155, v180
	v_mfma_f32_32x32x16_bf16 v[34:49], v[212:215], v[66:69], 0
	v_fmac_f32_e32 v3, v154, v2
	v_fmac_f32_e32 v19, v154, v18
	v_cvt_pk_bf16_f32 v184, v2, v18
	v_fma_f32 v3, -v155, v18, v3
	v_fmac_f32_e32 v19, v155, v2
	ds_write_b32 v207, v184 offset:128
	v_fmac_f32_e32 v4, v154, v3
	v_fmac_f32_e32 v20, v154, v19
	v_cvt_pk_bf16_f32 v185, v3, v19
	v_fma_f32 v4, -v155, v19, v4
	v_fmac_f32_e32 v20, v155, v3
	ds_write_b32 v207, v185 offset:400
	v_mfma_f32_32x32x16_bf16 v[50:65], v[212:215], v[74:77], 0
	v_fmac_f32_e32 v5, v154, v4
	v_fmac_f32_e32 v21, v154, v20
	v_cvt_pk_bf16_f32 v184, v4, v20
	v_fma_f32 v5, -v155, v20, v5
	v_fmac_f32_e32 v21, v155, v4
	ds_write_b32 v207, v184 offset:672
	v_fmac_f32_e32 v6, v154, v5
	v_fmac_f32_e32 v22, v154, v21
	v_cvt_pk_bf16_f32 v185, v5, v21
	v_fma_f32 v6, -v155, v21, v6
	v_fmac_f32_e32 v22, v155, v5
	ds_write_b32 v207, v185 offset:944
	v_fmac_f32_e32 v7, v154, v6
	v_fmac_f32_e32 v23, v154, v22
	v_cvt_pk_bf16_f32 v184, v6, v22
	v_fma_f32 v7, -v155, v22, v7
	v_fmac_f32_e32 v23, v155, v6
	ds_write_b32 v207, v184 offset:1216
	v_fmac_f32_e32 v8, v154, v7
	v_fmac_f32_e32 v24, v154, v23
	v_cvt_pk_bf16_f32 v185, v7, v23
	v_fma_f32 v8, -v155, v23, v8
	v_fmac_f32_e32 v24, v155, v7
	ds_write_b32 v207, v185 offset:1488
	v_fmac_f32_e32 v9, v154, v8
	v_fmac_f32_e32 v25, v154, v24
	v_cvt_pk_bf16_f32 v184, v8, v24
	v_fma_f32 v9, -v155, v24, v9
	v_fmac_f32_e32 v25, v155, v8
	ds_write_b32 v207, v184 offset:1760
	v_fmac_f32_e32 v10, v154, v9
	v_fmac_f32_e32 v26, v154, v25
	v_cvt_pk_bf16_f32 v185, v9, v25
	v_fma_f32 v10, -v155, v25, v10
	v_fmac_f32_e32 v26, v155, v9
	ds_write_b32 v207, v185 offset:2032
	v_fmac_f32_e32 v11, v154, v10
	v_fmac_f32_e32 v27, v154, v26
	v_cvt_pk_bf16_f32 v184, v10, v26
	v_fma_f32 v11, -v155, v26, v11
	v_fmac_f32_e32 v27, v155, v10
	ds_write_b32 v207, v184 offset:2304
	v_fmac_f32_e32 v12, v154, v11
	v_fmac_f32_e32 v28, v154, v27
	v_cvt_pk_bf16_f32 v185, v11, v27
	v_fma_f32 v12, -v155, v27, v12
	v_fmac_f32_e32 v28, v155, v11
	ds_write_b32 v207, v185 offset:2576
	v_fmac_f32_e32 v13, v154, v12
	v_fmac_f32_e32 v29, v154, v28
	v_cvt_pk_bf16_f32 v184, v12, v28
	v_fma_f32 v13, -v155, v28, v13
	v_fmac_f32_e32 v29, v155, v12
	ds_write_b32 v207, v184 offset:2848
	v_fmac_f32_e32 v14, v154, v13
	v_fmac_f32_e32 v30, v154, v29
	v_cvt_pk_bf16_f32 v185, v13, v29
	v_fma_f32 v14, -v155, v29, v14
	v_fmac_f32_e32 v30, v155, v13
	ds_write_b32 v207, v185 offset:3120
	v_fmac_f32_e32 v15, v154, v14
	v_fmac_f32_e32 v31, v154, v30
	v_cvt_pk_bf16_f32 v184, v14, v30
	v_fma_f32 v15, -v155, v30, v15
	v_fmac_f32_e32 v31, v155, v14
	ds_write_b32 v207, v184 offset:3392
	v_fmac_f32_e32 v16, v154, v15
	v_fmac_f32_e32 v32, v154, v31
	v_cvt_pk_bf16_f32 v185, v15, v31
	v_fma_f32 v16, -v155, v31, v16
	v_fmac_f32_e32 v32, v155, v15
	ds_write_b32 v207, v185 offset:3664
	v_fma_f32 v180, v154, v16, v17
	v_fma_f32 v176, v154, v32, v33
	v_cvt_pk_bf16_f32 v184, v16, v32
	v_fma_f32 v180, -v155, v32, v180
	v_fmac_f32_e32 v176, v155, v16
	ds_write_b32 v207, v184 offset:3936
	v_cvt_pk_bf16_f32 v185, v180, v176
	ds_write_b32 v207, v185 offset:4208
	s_add_u32 s28, s28, 1
	s_add_u32 s20, s28, 2
	s_cmp_lt_u32 s20, s52
	s_cselect_b64 s[58:59], s[50:51], 0
	v_lshl_add_u64 v[248:249], v[248:249], 0, s[58:59]
	global_load_dwordx4 v[98:101], v[248:249], off offset:16
	global_load_dwordx4 v[102:105], v[248:249], off
	ds_read_b128 v[216:219], v208
	ds_read_b128 v[220:223], v208 offset:4352
	ds_read_b128 v[224:227], v208 offset:64
	ds_read_b128 v[228:231], v208 offset:4416
	v_fmac_f32_e32 v34, v152, v182
	v_fmac_f32_e32 v50, v152, v178
	v_fma_f32 v34, -v153, v178, v34
	v_fmac_f32_e32 v50, v153, v182
	v_mfma_f32_32x32x16_bf16 v[2:17], v[212:215], v[70:73], 0
	v_fmac_f32_e32 v35, v152, v34
	v_fmac_f32_e32 v51, v152, v50
	v_cvt_pk_bf16_f32 v184, v34, v50
	v_fma_f32 v35, -v153, v50, v35
	v_fmac_f32_e32 v51, v153, v34
	ds_write_b32 v207, v184 offset:0
	v_fmac_f32_e32 v36, v152, v35
	v_fmac_f32_e32 v52, v152, v51
	v_cvt_pk_bf16_f32 v185, v35, v51
	v_fma_f32 v36, -v153, v51, v36
	v_fmac_f32_e32 v52, v153, v35
	ds_write_b32 v207, v185 offset:272
	v_mfma_f32_32x32x16_bf16 v[18:33], v[212:215], v[78:81], 0
	v_fmac_f32_e32 v37, v152, v36
	v_fmac_f32_e32 v53, v152, v52
	v_cvt_pk_bf16_f32 v184, v36, v52
	v_fma_f32 v37, -v153, v52, v37
	v_fmac_f32_e32 v53, v153, v36
	ds_write_b32 v207, v184 offset:544
	v_fmac_f32_e32 v38, v152, v37
	v_fmac_f32_e32 v54, v152, v53
	v_cvt_pk_bf16_f32 v185, v37, v53
	v_fma_f32 v38, -v153, v53, v38
	v_fmac_f32_e32 v54, v153, v37
	ds_write_b32 v207, v185 offset:816
	s_waitcnt lgkmcnt(6)
	v_mfma_f32_16x16x32_bf16 v[232:235], v[82:85], v[216:219], 0
	v_fmac_f32_e32 v39, v152, v38
	v_fmac_f32_e32 v55, v152, v54
	v_cvt_pk_bf16_f32 v184, v38, v54
	v_fma_f32 v39, -v153, v54, v39
	v_fmac_f32_e32 v55, v153, v38
	ds_write_b32 v207, v184 offset:1088
	v_mfma_f32_16x16x32_bf16 v[236:239], v[82:85], v[220:223], 0
	v_fmac_f32_e32 v40, v152, v39
	v_fmac_f32_e32 v56, v152, v55
	v_cvt_pk_bf16_f32 v185, v39, v55
	v_fma_f32 v40, -v153, v55, v40
	v_fmac_f32_e32 v56, v153, v39
	ds_write_b32 v207, v185 offset:1360
	s_waitcnt lgkmcnt(6)
	v_mfma_f32_16x16x32_bf16 v[232:235], v[86:89], v[224:227], v[232:235]
	v_fmac_f32_e32 v41, v152, v40
	v_fmac_f32_e32 v57, v152, v56
	v_cvt_pk_bf16_f32 v184, v40, v56
	v_fma_f32 v41, -v153, v56, v41
	v_fmac_f32_e32 v57, v153, v40
	ds_write_b32 v207, v184 offset:1632
	v_mfma_f32_16x16x32_bf16 v[236:239], v[86:89], v[228:231], v[236:239]
	v_fmac_f32_e32 v42, v152, v41
	v_fmac_f32_e32 v58, v152, v57
	v_cvt_pk_bf16_f32 v185, v41, v57
	v_fma_f32 v42, -v153, v57, v42
	v_fmac_f32_e32 v58, v153, v41
	ds_write_b32 v207, v185 offset:1904
	ds_read_b128 v[216:219], v208 offset:128
	ds_read_b128 v[220:223], v208 offset:4480
	ds_read_b128 v[224:227], v208 offset:192
	ds_read_b128 v[228:231], v208 offset:4544
	v_fmac_f32_e32 v43, v152, v42
	v_fmac_f32_e32 v59, v152, v58
	v_cvt_pk_bf16_f32 v184, v42, v58
	v_fma_f32 v43, -v153, v58, v43
	v_fmac_f32_e32 v59, v153, v42
	ds_write_b32 v207, v184 offset:2176
	v_fmac_f32_e32 v44, v152, v43
	v_fmac_f32_e32 v60, v152, v59
	v_cvt_pk_bf16_f32 v185, v43, v59
	v_fma_f32 v44, -v153, v59, v44
	v_fmac_f32_e32 v60, v153, v43
	ds_write_b32 v207, v185 offset:2448
	v_fmac_f32_e32 v45, v152, v44
	v_fmac_f32_e32 v61, v152, v60
	v_cvt_pk_bf16_f32 v184, v44, v60
	v_fma_f32 v45, -v153, v60, v45
	v_fmac_f32_e32 v61, v153, v44
	ds_write_b32 v207, v184 offset:2720
	s_waitcnt lgkmcnt(5)
	v_mfma_f32_16x16x32_bf16 v[232:235], v[90:93], v[216:219], v[232:235]
	v_fmac_f32_e32 v46, v152, v45
	v_fmac_f32_e32 v62, v152, v61
	v_cvt_pk_bf16_f32 v185, v45, v61
	v_fma_f32 v46, -v153, v61, v46
	v_fmac_f32_e32 v62, v153, v45
	ds_write_b32 v207, v185 offset:2992
	v_mfma_f32_16x16x32_bf16 v[236:239], v[90:93], v[220:223], v[236:239]
	v_fmac_f32_e32 v47, v152, v46
	v_fmac_f32_e32 v63, v152, v62
	v_cvt_pk_bf16_f32 v184, v46, v62
	v_fma_f32 v47, -v153, v62, v47
	v_fmac_f32_e32 v63, v153, v46
	ds_write_b32 v207, v184 offset:3264
	s_waitcnt lgkmcnt(5)
	v_mfma_f32_16x16x32_bf16 v[232:235], v[94:97], v[224:227], v[232:235]
	v_fmac_f32_e32 v48, v152, v47
	v_fmac_f32_e32 v64, v152, v63
	v_cvt_pk_bf16_f32 v185, v47, v63
	v_fma_f32 v48, -v153, v63, v48
	v_fmac_f32_e32 v64, v153, v47
	ds_write_b32 v207, v185 offset:3536
	v_mfma_f32_16x16x32_bf16 v[236:239], v[94:97], v[228:231], v[236:239]
	v_fma_f32 v182, v152, v48, v49
	v_fma_f32 v178, v152, v64, v65
	v_cvt_pk_bf16_f32 v184, v48, v64
	v_fma_f32 v182, -v153, v64, v182
	v_fmac_f32_e32 v178, v153, v48
	ds_write_b32 v207, v184 offset:3808
	v_cvt_pk_bf16_f32 v185, v182, v178
	ds_write_b32 v207, v185 offset:4080
	global_store_dwordx4 v[240:241], v[232:235], off sc1
	global_store_dwordx4 v[244:245], v[236:239], off sc1
	v_lshl_add_u64 v[240:241], v[240:241], 0, s[50:51]
	v_lshl_add_u64 v[244:245], v[244:245], 0, s[50:51]
	s_cmp_eq_u32 s28, 1
	s_cbranch_scc0 .LS5P_wd0o
	s_waitcnt vmcnt(4)

.LS5P_epi:
	ds_read_b128 v[216:219], v208
	ds_read_b128 v[220:223], v208 offset:4352
	ds_read_b128 v[224:227], v208 offset:64
	ds_read_b128 v[228:231], v208 offset:4416
	ds_read_b128 v[2:5], v208 offset:128
	ds_read_b128 v[6:9], v208 offset:4480
	ds_read_b128 v[10:13], v208 offset:192
	ds_read_b128 v[14:17], v208 offset:4544
	s_waitcnt lgkmcnt(6)
	v_mfma_f32_16x16x32_bf16 v[232:235], v[82:85], v[216:219], 0
	v_mfma_f32_16x16x32_bf16 v[236:239], v[82:85], v[220:223], 0
	s_waitcnt lgkmcnt(4)
	v_mfma_f32_16x16x32_bf16 v[232:235], v[86:89], v[224:227], v[232:235]
	v_mfma_f32_16x16x32_bf16 v[236:239], v[86:89], v[228:231], v[236:239]
	s_waitcnt lgkmcnt(2)
	v_mfma_f32_16x16x32_bf16 v[232:235], v[90:93], v[2:5], v[232:235]
	v_mfma_f32_16x16x32_bf16 v[236:239], v[90:93], v[6:9], v[236:239]
	s_waitcnt lgkmcnt(0)
	v_mfma_f32_16x16x32_bf16 v[232:235], v[94:97], v[10:13], v[232:235]
	v_mfma_f32_16x16x32_bf16 v[236:239], v[94:97], v[14:17], v[236:239]
	s_nop 7
	global_store_dwordx4 v[240:241], v[232:235], off sc1
	global_store_dwordx4 v[244:245], v[236:239], off sc1
	s_branch .LS5Q_done

.LS5Q_wr1d1e:
	s_waitcnt vmcnt(4)
	v_cvt_pk_bf16_f32 v212, v102, v103
	v_cvt_pk_bf16_f32 v213, v104, v105
	v_cvt_pk_bf16_f32 v214, v98, v99
	v_cvt_pk_bf16_f32 v215, v100, v101
	s_add_u32 s20, s28, 3
	s_cmp_lt_u32 s20, s52
	s_cselect_b64 s[58:59], s[50:51], 0
	v_lshl_add_u64 v[248:249], v[248:249], 0, s[58:59]
	global_load_dwordx4 v[98:101], v[248:249], off offset:16
	global_load_dwordx4 v[102:105], v[248:249], off
	ds_read_b128 v[216:219], v173 offset:60416
	ds_read_b128 v[220:223], v173 offset:60480
	ds_read_b128 v[224:227], v173 offset:60544
	ds_read_b128 v[228:231], v173 offset:60608
	v_fmac_f32_e32 v49, v154, v180
	v_fmac_f32_e32 v65, v154, v176
	v_fma_f32 v49, -v155, v176, v49
	v_fmac_f32_e32 v65, v155, v180
	v_mfma_f32_32x32x16_bf16 v[2:17], v[212:215], v[70:73], 0
	v_fmac_f32_e32 v48, v154, v49
	v_fmac_f32_e32 v64, v154, v65
	v_cvt_pk_bf16_f32 v184, v49, v65
	v_fma_f32 v48, -v155, v65, v48
	v_fmac_f32_e32 v64, v155, v49
	ds_write_b32 v172, v184 offset:4080
	v_fmac_f32_e32 v47, v154, v48
	v_fmac_f32_e32 v63, v154, v64
	v_cvt_pk_bf16_f32 v185, v48, v64
	v_fma_f32 v47, -v155, v64, v47
	v_fmac_f32_e32 v63, v155, v48
	ds_write_b32 v172, v185 offset:3808
	v_mfma_f32_32x32x16_bf16 v[18:33], v[212:215], v[78:81], 0
	v_fmac_f32_e32 v46, v154, v47
	v_fmac_f32_e32 v62, v154, v63
	v_cvt_pk_bf16_f32 v184, v47, v63
	v_fma_f32 v46, -v155, v63, v46
	v_fmac_f32_e32 v62, v155, v47
	ds_write_b32 v172, v184 offset:3536
	v_fmac_f32_e32 v45, v154, v46
	v_fmac_f32_e32 v61, v154, v62
	v_cvt_pk_bf16_f32 v185, v46, v62
	v_fma_f32 v45, -v155, v62, v45
	v_fmac_f32_e32 v61, v155, v46
	ds_write_b32 v172, v185 offset:3264
	s_waitcnt lgkmcnt(4)
	v_mfma_f32_16x16x32_bf16 v[232:235], v[82:85], v[216:219], 0
	v_fmac_f32_e32 v44, v154, v45
	v_fmac_f32_e32 v60, v154, v61
	v_cvt_pk_bf16_f32 v184, v45, v61
	v_fma_f32 v44, -v155, v61, v44
	v_fmac_f32_e32 v60, v155, v45
	ds_write_b32 v172, v184 offset:2992
	v_mfma_f32_16x16x32_bf16 v[232:235], v[86:89], v[220:223], v[232:235]
	v_fmac_f32_e32 v43, v154, v44
	v_fmac_f32_e32 v59, v154, v60
	v_cvt_pk_bf16_f32 v185, v44, v60
	v_fma_f32 v43, -v155, v60, v43
	v_fmac_f32_e32 v59, v155, v44
	ds_write_b32 v172, v185 offset:2720
	v_mfma_f32_16x16x32_bf16 v[232:235], v[90:93], v[224:227], v[232:235]
	v_fmac_f32_e32 v42, v154, v43
	v_fmac_f32_e32 v58, v154, v59
	v_cvt_pk_bf16_f32 v184, v43, v59
	v_fma_f32 v42, -v155, v59, v42
	v_fmac_f32_e32 v58, v155, v43
	ds_write_b32 v172, v184 offset:2448
	v_mfma_f32_16x16x32_bf16 v[232:235], v[94:97], v[228:231], v[232:235]
	v_fmac_f32_e32 v41, v154, v42
	v_fmac_f32_e32 v57, v154, v58
	v_cvt_pk_bf16_f32 v185, v42, v58
	v_fma_f32 v41, -v155, v58, v41
	v_fmac_f32_e32 v57, v155, v42
	ds_write_b32 v172, v185 offset:2176
	v_fmac_f32_e32 v40, v154, v41
	v_fmac_f32_e32 v56, v154, v57
	v_cvt_pk_bf16_f32 v184, v41, v57
	v_fma_f32 v40, -v155, v57, v40
	v_fmac_f32_e32 v56, v155, v41
	ds_write_b32 v172, v184 offset:1904
	v_fmac_f32_e32 v39, v154, v40
	v_fmac_f32_e32 v55, v154, v56
	v_cvt_pk_bf16_f32 v185, v40, v56
	v_fma_f32 v39, -v155, v56, v39
	v_fmac_f32_e32 v55, v155, v40
	ds_write_b32 v172, v185 offset:1632
	s_cmp_eq_u32 s28, 0
	s_cbranch_scc1 .LS5Q_nstr1d1e
	global_store_dwordx4 v[240:241], v[232:235], off sc1
	v_lshl_add_u64 v[240:241], v[240:241], 0, s[50:51]

.LS5Q_wr1d1o:
	s_waitcnt vmcnt(4)
	v_cvt_pk_bf16_f32 v212, v106, v107
	v_cvt_pk_bf16_f32 v213, v108, v109
	v_cvt_pk_bf16_f32 v214, v110, v111
	v_cvt_pk_bf16_f32 v215, v112, v113
	s_add_u32 s20, s28, 3
	s_cmp_lt_u32 s20, s52
	s_cselect_b64 s[58:59], s[50:51], 0
	v_lshl_add_u64 v[248:249], v[248:249], 0, s[58:59]
	global_load_dwordx4 v[110:113], v[248:249], off offset:16
	global_load_dwordx4 v[106:109], v[248:249], off
	ds_read_b128 v[216:219], v173 offset:0
	ds_read_b128 v[220:223], v173 offset:64
	ds_read_b128 v[224:227], v173 offset:128
	ds_read_b128 v[228:231], v173 offset:192
	v_fmac_f32_e32 v17, v154, v180
	v_fmac_f32_e32 v33, v154, v176
	v_fma_f32 v17, -v155, v176, v17
	v_fmac_f32_e32 v33, v155, v180
	v_mfma_f32_32x32x16_bf16 v[34:49], v[212:215], v[70:73], 0
	v_fmac_f32_e32 v16, v154, v17
	v_fmac_f32_e32 v32, v154, v33
	v_cvt_pk_bf16_f32 v184, v17, v33
	v_fma_f32 v16, -v155, v33, v16
	v_fmac_f32_e32 v32, v155, v17
	ds_write_b32 v172, v184 offset:64496
	v_fmac_f32_e32 v15, v154, v16
	v_fmac_f32_e32 v31, v154, v32
	v_cvt_pk_bf16_f32 v185, v16, v32
	v_fma_f32 v15, -v155, v32, v15
	v_fmac_f32_e32 v31, v155, v16
	ds_write_b32 v172, v185 offset:64224
	v_mfma_f32_32x32x16_bf16 v[50:65], v[212:215], v[78:81], 0
	v_fmac_f32_e32 v14, v154, v15
	v_fmac_f32_e32 v30, v154, v31
	v_cvt_pk_bf16_f32 v184, v15, v31
	v_fma_f32 v14, -v155, v31, v14
	v_fmac_f32_e32 v30, v155, v15
	ds_write_b32 v172, v184 offset:63952
	v_fmac_f32_e32 v13, v154, v14
	v_fmac_f32_e32 v29, v154, v30
	v_cvt_pk_bf16_f32 v185, v14, v30
	v_fma_f32 v13, -v155, v30, v13
	v_fmac_f32_e32 v29, v155, v14
	ds_write_b32 v172, v185 offset:63680
	s_waitcnt lgkmcnt(4)
	v_mfma_f32_16x16x32_bf16 v[232:235], v[82:85], v[216:219], 0
	v_fmac_f32_e32 v12, v154, v13
	v_fmac_f32_e32 v28, v154, v29
	v_cvt_pk_bf16_f32 v184, v13, v29
	v_fma_f32 v12, -v155, v29, v12
	v_fmac_f32_e32 v28, v155, v13
	ds_write_b32 v172, v184 offset:63408
	v_mfma_f32_16x16x32_bf16 v[232:235], v[86:89], v[220:223], v[232:235]
	v_fmac_f32_e32 v11, v154, v12
	v_fmac_f32_e32 v27, v154, v28
	v_cvt_pk_bf16_f32 v185, v12, v28
	v_fma_f32 v11, -v155, v28, v11
	v_fmac_f32_e32 v27, v155, v12
	ds_write_b32 v172, v185 offset:63136
	v_mfma_f32_16x16x32_bf16 v[232:235], v[90:93], v[224:227], v[232:235]
	v_fmac_f32_e32 v10, v154, v11
	v_fmac_f32_e32 v26, v154, v27
	v_cvt_pk_bf16_f32 v184, v11, v27
	v_fma_f32 v10, -v155, v27, v10
	v_fmac_f32_e32 v26, v155, v11
	ds_write_b32 v172, v184 offset:62864
	v_mfma_f32_16x16x32_bf16 v[232:235], v[94:97], v[228:231], v[232:235]
	v_fmac_f32_e32 v9, v154, v10
	v_fmac_f32_e32 v25, v154, v26
	v_cvt_pk_bf16_f32 v185, v10, v26
	v_fma_f32 v9, -v155, v26, v9
	v_fmac_f32_e32 v25, v155, v10
	ds_write_b32 v172, v185 offset:62592
	v_fmac_f32_e32 v8, v154, v9
	v_fmac_f32_e32 v24, v154, v25
	v_cvt_pk_bf16_f32 v184, v9, v25
	v_fma_f32 v8, -v155, v25, v8
	v_fmac_f32_e32 v24, v155, v9
	ds_write_b32 v172, v184 offset:62320
	v_fmac_f32_e32 v7, v154, v8
	v_fmac_f32_e32 v23, v154, v24
	v_cvt_pk_bf16_f32 v185, v8, v24
	v_fma_f32 v7, -v155, v24, v7
	v_fmac_f32_e32 v23, v155, v8
	ds_write_b32 v172, v185 offset:62048
	global_store_dwordx4 v[240:241], v[232:235], off sc1
	v_lshl_add_u64 v[240:241], v[240:241], 0, s[50:51]
	v_fmac_f32_e32 v6, v154, v7
	v_fmac_f32_e32 v22, v154, v23
	v_cvt_pk_bf16_f32 v184, v7, v23
	v_fma_f32 v6, -v155, v23, v6
	v_fmac_f32_e32 v22, v155, v7
	ds_write_b32 v172, v184 offset:61776
	v_fmac_f32_e32 v5, v154, v6
	v_fmac_f32_e32 v21, v154, v22
	v_cvt_pk_bf16_f32 v185, v6, v22
	v_fma_f32 v5, -v155, v22, v5
	v_fmac_f32_e32 v21, v155, v6
	ds_write_b32 v172, v185 offset:61504
	v_fmac_f32_e32 v4, v154, v5
	v_fmac_f32_e32 v20, v154, v21
	v_cvt_pk_bf16_f32 v184, v5, v21
	v_fma_f32 v4, -v155, v21, v4
	v_fmac_f32_e32 v20, v155, v5
	ds_write_b32 v172, v184 offset:61232
	v_fmac_f32_e32 v3, v154, v4
	v_fmac_f32_e32 v19, v154, v20
	v_cvt_pk_bf16_f32 v185, v4, v20
	v_fma_f32 v3, -v155, v20, v3
	v_fmac_f32_e32 v19, v155, v4
	ds_write_b32 v172, v185 offset:60960
	v_fma_f32 v180, v154, v3, v2
	v_fma_f32 v176, v154, v19, v18
	v_cvt_pk_bf16_f32 v184, v3, v19
	v_fma_f32 v180, -v155, v19, v180
	v_fmac_f32_e32 v176, v155, v3
	ds_write_b32 v172, v184 offset:60688
	v_cvt_pk_bf16_f32 v185, v180, v176
	ds_write_b32 v172, v185 offset:60416
	s_waitcnt lgkmcnt(0)
	s_barrier
	s_add_u32 s28, s28, 1
	s_cmp_lt_u32 s28, s52
	s_cbranch_scc1 .LS5Q_loopr1d1
	s_branch .LS5Q_epi

.LS5Q_wr1d0e:
	s_waitcnt vmcnt(4)
	v_cvt_pk_bf16_f32 v212, v102, v103
	v_cvt_pk_bf16_f32 v213, v104, v105
	v_cvt_pk_bf16_f32 v214, v98, v99
	v_cvt_pk_bf16_f32 v215, v100, v101
	s_add_u32 s20, s28, 3
	s_cmp_lt_u32 s20, s52
	s_cselect_b64 s[58:59], s[50:51], 0
	v_lshl_add_u64 v[248:249], v[248:249], 0, s[58:59]
	global_load_dwordx4 v[98:101], v[248:249], off offset:16
	global_load_dwordx4 v[102:105], v[248:249], off
	ds_read_b128 v[216:219], v173 offset:60416
	ds_read_b128 v[220:223], v173 offset:60480
	ds_read_b128 v[224:227], v173 offset:60544
	ds_read_b128 v[228:231], v173 offset:60608
	v_fmac_f32_e32 v34, v154, v180
	v_fmac_f32_e32 v50, v154, v176
	v_fma_f32 v34, -v155, v176, v34
	v_fmac_f32_e32 v50, v155, v180
	v_mfma_f32_32x32x16_bf16 v[2:17], v[212:215], v[70:73], 0
	v_fmac_f32_e32 v35, v154, v34
	v_fmac_f32_e32 v51, v154, v50
	v_cvt_pk_bf16_f32 v184, v34, v50
	v_fma_f32 v35, -v155, v50, v35
	v_fmac_f32_e32 v51, v155, v34
	ds_write_b32 v172, v184 offset:0
	v_fmac_f32_e32 v36, v154, v35
	v_fmac_f32_e32 v52, v154, v51
	v_cvt_pk_bf16_f32 v185, v35, v51
	v_fma_f32 v36, -v155, v51, v36
	v_fmac_f32_e32 v52, v155, v35
	ds_write_b32 v172, v185 offset:272
	v_mfma_f32_32x32x16_bf16 v[18:33], v[212:215], v[78:81], 0
	v_fmac_f32_e32 v37, v154, v36
	v_fmac_f32_e32 v53, v154, v52
	v_cvt_pk_bf16_f32 v184, v36, v52
	v_fma_f32 v37, -v155, v52, v37
	v_fmac_f32_e32 v53, v155, v36
	ds_write_b32 v172, v184 offset:544
	v_fmac_f32_e32 v38, v154, v37
	v_fmac_f32_e32 v54, v154, v53
	v_cvt_pk_bf16_f32 v185, v37, v53
	v_fma_f32 v38, -v155, v53, v38
	v_fmac_f32_e32 v54, v155, v37
	ds_write_b32 v172, v185 offset:816
	s_waitcnt lgkmcnt(4)
	v_mfma_f32_16x16x32_bf16 v[232:235], v[82:85], v[216:219], 0
	v_fmac_f32_e32 v39, v154, v38
	v_fmac_f32_e32 v55, v154, v54
	v_cvt_pk_bf16_f32 v184, v38, v54
	v_fma_f32 v39, -v155, v54, v39
	v_fmac_f32_e32 v55, v155, v38
	ds_write_b32 v172, v184 offset:1088
	v_mfma_f32_16x16x32_bf16 v[232:235], v[86:89], v[220:223], v[232:235]
	v_fmac_f32_e32 v40, v154, v39
	v_fmac_f32_e32 v56, v154, v55
	v_cvt_pk_bf16_f32 v185, v39, v55
	v_fma_f32 v40, -v155, v55, v40
	v_fmac_f32_e32 v56, v155, v39
	ds_write_b32 v172, v185 offset:1360
	v_mfma_f32_16x16x32_bf16 v[232:235], v[90:93], v[224:227], v[232:235]
	v_fmac_f32_e32 v41, v154, v40
	v_fmac_f32_e32 v57, v154, v56
	v_cvt_pk_bf16_f32 v184, v40, v56
	v_fma_f32 v41, -v155, v56, v41
	v_fmac_f32_e32 v57, v155, v40
	ds_write_b32 v172, v184 offset:1632
	v_mfma_f32_16x16x32_bf16 v[232:235], v[94:97], v[228:231], v[232:235]
	v_fmac_f32_e32 v42, v154, v41
	v_fmac_f32_e32 v58, v154, v57
	v_cvt_pk_bf16_f32 v185, v41, v57
	v_fma_f32 v42, -v155, v57, v42
	v_fmac_f32_e32 v58, v155, v41
	ds_write_b32 v172, v185 offset:1904
	v_fmac_f32_e32 v43, v154, v42
	v_fmac_f32_e32 v59, v154, v58
	v_cvt_pk_bf16_f32 v184, v42, v58
	v_fma_f32 v43, -v155, v58, v43
	v_fmac_f32_e32 v59, v155, v42
	ds_write_b32 v172, v184 offset:2176
	v_fmac_f32_e32 v44, v154, v43
	v_fmac_f32_e32 v60, v154, v59
	v_cvt_pk_bf16_f32 v185, v43, v59
	v_fma_f32 v44, -v155, v59, v44
	v_fmac_f32_e32 v60, v155, v43
	ds_write_b32 v172, v185 offset:2448
	s_cmp_eq_u32 s28, 0
	s_cbranch_scc1 .LS5Q_nstr1d0e
	global_store_dwordx4 v[240:241], v[232:235], off sc1
	v_lshl_add_u64 v[240:241], v[240:241], 0, s[50:51]

.LS5Q_wr1d0o:
	s_waitcnt vmcnt(4)
	v_cvt_pk_bf16_f32 v212, v106, v107
	v_cvt_pk_bf16_f32 v213, v108, v109
	v_cvt_pk_bf16_f32 v214, v110, v111
	v_cvt_pk_bf16_f32 v215, v112, v113
	s_add_u32 s20, s28, 3
	s_cmp_lt_u32 s20, s52
	s_cselect_b64 s[58:59], s[50:51], 0
	v_lshl_add_u64 v[248:249], v[248:249], 0, s[58:59]
	global_load_dwordx4 v[110:113], v[248:249], off offset:16
	global_load_dwordx4 v[106:109], v[248:249], off
	ds_read_b128 v[216:219], v173 offset:0
	ds_read_b128 v[220:223], v173 offset:64
	ds_read_b128 v[224:227], v173 offset:128
	ds_read_b128 v[228:231], v173 offset:192
	v_fmac_f32_e32 v2, v154, v180
	v_fmac_f32_e32 v18, v154, v176
	v_fma_f32 v2, -v155, v176, v2
	v_fmac_f32_e32 v18, v155, v180
	v_mfma_f32_32x32x16_bf16 v[34:49], v[212:215], v[70:73], 0
	v_fmac_f32_e32 v3, v154, v2
	v_fmac_f32_e32 v19, v154, v18
	v_cvt_pk_bf16_f32 v184, v2, v18
	v_fma_f32 v3, -v155, v18, v3
	v_fmac_f32_e32 v19, v155, v2
	ds_write_b32 v172, v184 offset:60416
	v_fmac_f32_e32 v4, v154, v3
	v_fmac_f32_e32 v20, v154, v19
	v_cvt_pk_bf16_f32 v185, v3, v19
	v_fma_f32 v4, -v155, v19, v4
	v_fmac_f32_e32 v20, v155, v3
	ds_write_b32 v172, v185 offset:60688
	v_mfma_f32_32x32x16_bf16 v[50:65], v[212:215], v[78:81], 0
	v_fmac_f32_e32 v5, v154, v4
	v_fmac_f32_e32 v21, v154, v20
	v_cvt_pk_bf16_f32 v184, v4, v20
	v_fma_f32 v5, -v155, v20, v5
	v_fmac_f32_e32 v21, v155, v4
	ds_write_b32 v172, v184 offset:60960
	v_fmac_f32_e32 v6, v154, v5
	v_fmac_f32_e32 v22, v154, v21
	v_cvt_pk_bf16_f32 v185, v5, v21
	v_fma_f32 v6, -v155, v21, v6
	v_fmac_f32_e32 v22, v155, v5
	ds_write_b32 v172, v185 offset:61232
	s_waitcnt lgkmcnt(4)
	v_mfma_f32_16x16x32_bf16 v[232:235], v[82:85], v[216:219], 0
	v_fmac_f32_e32 v7, v154, v6
	v_fmac_f32_e32 v23, v154, v22
	v_cvt_pk_bf16_f32 v184, v6, v22
	v_fma_f32 v7, -v155, v22, v7
	v_fmac_f32_e32 v23, v155, v6
	ds_write_b32 v172, v184 offset:61504
	v_mfma_f32_16x16x32_bf16 v[232:235], v[86:89], v[220:223], v[232:235]
	v_fmac_f32_e32 v8, v154, v7
	v_fmac_f32_e32 v24, v154, v23
	v_cvt_pk_bf16_f32 v185, v7, v23
	v_fma_f32 v8, -v155, v23, v8
	v_fmac_f32_e32 v24, v155, v7
	ds_write_b32 v172, v185 offset:61776
	v_mfma_f32_16x16x32_bf16 v[232:235], v[90:93], v[224:227], v[232:235]
	v_fmac_f32_e32 v9, v154, v8
	v_fmac_f32_e32 v25, v154, v24
	v_cvt_pk_bf16_f32 v184, v8, v24
	v_fma_f32 v9, -v155, v24, v9
	v_fmac_f32_e32 v25, v155, v8
	ds_write_b32 v172, v184 offset:62048
	v_mfma_f32_16x16x32_bf16 v[232:235], v[94:97], v[228:231], v[232:235]
	v_fmac_f32_e32 v10, v154, v9
	v_fmac_f32_e32 v26, v154, v25
	v_cvt_pk_bf16_f32 v185, v9, v25
	v_fma_f32 v10, -v155, v25, v10
	v_fmac_f32_e32 v26, v155, v9
	ds_write_b32 v172, v185 offset:62320
	v_fmac_f32_e32 v11, v154, v10
	v_fmac_f32_e32 v27, v154, v26
	v_cvt_pk_bf16_f32 v184, v10, v26
	v_fma_f32 v11, -v155, v26, v11
	v_fmac_f32_e32 v27, v155, v10
	ds_write_b32 v172, v184 offset:62592
	v_fmac_f32_e32 v12, v154, v11
	v_fmac_f32_e32 v28, v154, v27
	v_cvt_pk_bf16_f32 v185, v11, v27
	v_fma_f32 v12, -v155, v27, v12
	v_fmac_f32_e32 v28, v155, v11
	ds_write_b32 v172, v185 offset:62864
	global_store_dwordx4 v[240:241], v[232:235], off sc1
	v_lshl_add_u64 v[240:241], v[240:241], 0, s[50:51]
	v_fmac_f32_e32 v13, v154, v12
	v_fmac_f32_e32 v29, v154, v28
	v_cvt_pk_bf16_f32 v184, v12, v28
	v_fma_f32 v13, -v155, v28, v13
	v_fmac_f32_e32 v29, v155, v12
	ds_write_b32 v172, v184 offset:63136
	v_fmac_f32_e32 v14, v154, v13
	v_fmac_f32_e32 v30, v154, v29
	v_cvt_pk_bf16_f32 v185, v13, v29
	v_fma_f32 v14, -v155, v29, v14
	v_fmac_f32_e32 v30, v155, v13
	ds_write_b32 v172, v185 offset:63408
	v_fmac_f32_e32 v15, v154, v14
	v_fmac_f32_e32 v31, v154, v30
	v_cvt_pk_bf16_f32 v184, v14, v30
	v_fma_f32 v15, -v155, v30, v15
	v_fmac_f32_e32 v31, v155, v14
	ds_write_b32 v172, v184 offset:63680
	v_fmac_f32_e32 v16, v154, v15
	v_fmac_f32_e32 v32, v154, v31
	v_cvt_pk_bf16_f32 v185, v15, v31
	v_fma_f32 v16, -v155, v31, v16
	v_fmac_f32_e32 v32, v155, v15
	ds_write_b32 v172, v185 offset:63952
	v_fma_f32 v180, v154, v16, v17
	v_fma_f32 v176, v154, v32, v33
	v_cvt_pk_bf16_f32 v184, v16, v32
	v_fma_f32 v180, -v155, v32, v180
	v_fmac_f32_e32 v176, v155, v16
	ds_write_b32 v172, v184 offset:64224
	v_cvt_pk_bf16_f32 v185, v180, v176
	ds_write_b32 v172, v185 offset:64496
	s_waitcnt lgkmcnt(0)
	s_barrier
	s_add_u32 s28, s28, 1
	s_cmp_lt_u32 s28, s52
	s_cbranch_scc1 .LS5Q_loopr1d0
	s_branch .LS5Q_epi

.LS5Q_wr0d1e:
	s_waitcnt vmcnt(4)
	v_cvt_pk_bf16_f32 v212, v102, v103
	v_cvt_pk_bf16_f32 v213, v104, v105
	v_cvt_pk_bf16_f32 v214, v98, v99
	v_cvt_pk_bf16_f32 v215, v100, v101
	s_add_u32 s20, s28, 3
	s_cmp_lt_u32 s20, s52
	s_cselect_b64 s[58:59], s[50:51], 0
	v_lshl_add_u64 v[248:249], v[248:249], 0, s[58:59]
	global_load_dwordx4 v[98:101], v[248:249], off offset:16
	global_load_dwordx4 v[102:105], v[248:249], off
	ds_read_b128 v[216:219], v173 offset:60416
	ds_read_b128 v[220:223], v173 offset:60480
	ds_read_b128 v[224:227], v173 offset:60544
	ds_read_b128 v[228:231], v173 offset:60608
	v_fmac_f32_e32 v49, v152, v182
	v_fmac_f32_e32 v65, v152, v178
	v_fma_f32 v49, -v153, v178, v49
	v_fmac_f32_e32 v65, v153, v182
	v_mfma_f32_32x32x16_bf16 v[2:17], v[212:215], v[66:69], 0
	v_fmac_f32_e32 v48, v152, v49
	v_fmac_f32_e32 v64, v152, v65
	v_cvt_pk_bf16_f32 v184, v49, v65
	v_fma_f32 v48, -v153, v65, v48
	v_fmac_f32_e32 v64, v153, v49
	ds_write_b32 v172, v184 offset:4080
	v_fmac_f32_e32 v47, v152, v48
	v_fmac_f32_e32 v63, v152, v64
	v_cvt_pk_bf16_f32 v185, v48, v64
	v_fma_f32 v47, -v153, v64, v47
	v_fmac_f32_e32 v63, v153, v48
	ds_write_b32 v172, v185 offset:3808
	v_mfma_f32_32x32x16_bf16 v[18:33], v[212:215], v[74:77], 0
	v_fmac_f32_e32 v46, v152, v47
	v_fmac_f32_e32 v62, v152, v63
	v_cvt_pk_bf16_f32 v184, v47, v63
	v_fma_f32 v46, -v153, v63, v46
	v_fmac_f32_e32 v62, v153, v47
	ds_write_b32 v172, v184 offset:3536
	v_fmac_f32_e32 v45, v152, v46
	v_fmac_f32_e32 v61, v152, v62
	v_cvt_pk_bf16_f32 v185, v46, v62
	v_fma_f32 v45, -v153, v62, v45
	v_fmac_f32_e32 v61, v153, v46
	ds_write_b32 v172, v185 offset:3264
	s_waitcnt lgkmcnt(4)
	v_mfma_f32_16x16x32_bf16 v[232:235], v[82:85], v[216:219], 0
	v_fmac_f32_e32 v44, v152, v45
	v_fmac_f32_e32 v60, v152, v61
	v_cvt_pk_bf16_f32 v184, v45, v61
	v_fma_f32 v44, -v153, v61, v44
	v_fmac_f32_e32 v60, v153, v45
	ds_write_b32 v172, v184 offset:2992
	v_mfma_f32_16x16x32_bf16 v[232:235], v[86:89], v[220:223], v[232:235]
	v_fmac_f32_e32 v43, v152, v44
	v_fmac_f32_e32 v59, v152, v60
	v_cvt_pk_bf16_f32 v185, v44, v60
	v_fma_f32 v43, -v153, v60, v43
	v_fmac_f32_e32 v59, v153, v44
	ds_write_b32 v172, v185 offset:2720
	v_mfma_f32_16x16x32_bf16 v[232:235], v[90:93], v[224:227], v[232:235]
	v_fmac_f32_e32 v42, v152, v43
	v_fmac_f32_e32 v58, v152, v59
	v_cvt_pk_bf16_f32 v184, v43, v59
	v_fma_f32 v42, -v153, v59, v42
	v_fmac_f32_e32 v58, v153, v43
	ds_write_b32 v172, v184 offset:2448
	v_mfma_f32_16x16x32_bf16 v[232:235], v[94:97], v[228:231], v[232:235]
	v_fmac_f32_e32 v41, v152, v42
	v_fmac_f32_e32 v57, v152, v58
	v_cvt_pk_bf16_f32 v185, v42, v58
	v_fma_f32 v41, -v153, v58, v41
	v_fmac_f32_e32 v57, v153, v42
	ds_write_b32 v172, v185 offset:2176
	v_fmac_f32_e32 v40, v152, v41
	v_fmac_f32_e32 v56, v152, v57
	v_cvt_pk_bf16_f32 v184, v41, v57
	v_fma_f32 v40, -v153, v57, v40
	v_fmac_f32_e32 v56, v153, v41
	ds_write_b32 v172, v184 offset:1904
	v_fmac_f32_e32 v39, v152, v40
	v_fmac_f32_e32 v55, v152, v56
	v_cvt_pk_bf16_f32 v185, v40, v56
	v_fma_f32 v39, -v153, v56, v39
	v_fmac_f32_e32 v55, v153, v40
	ds_write_b32 v172, v185 offset:1632
	s_cmp_eq_u32 s28, 0
	s_cbranch_scc1 .LS5Q_nstr0d1e
	global_store_dwordx4 v[240:241], v[232:235], off sc1
	v_lshl_add_u64 v[240:241], v[240:241], 0, s[50:51]

.LS5Q_wr0d1o:
	s_waitcnt vmcnt(4)
	v_cvt_pk_bf16_f32 v212, v106, v107
	v_cvt_pk_bf16_f32 v213, v108, v109
	v_cvt_pk_bf16_f32 v214, v110, v111
	v_cvt_pk_bf16_f32 v215, v112, v113
	s_add_u32 s20, s28, 3
	s_cmp_lt_u32 s20, s52
	s_cselect_b64 s[58:59], s[50:51], 0
	v_lshl_add_u64 v[248:249], v[248:249], 0, s[58:59]
	global_load_dwordx4 v[110:113], v[248:249], off offset:16
	global_load_dwordx4 v[106:109], v[248:249], off
	ds_read_b128 v[216:219], v173 offset:0
	ds_read_b128 v[220:223], v173 offset:64
	ds_read_b128 v[224:227], v173 offset:128
	ds_read_b128 v[228:231], v173 offset:192
	v_fmac_f32_e32 v17, v152, v182
	v_fmac_f32_e32 v33, v152, v178
	v_fma_f32 v17, -v153, v178, v17
	v_fmac_f32_e32 v33, v153, v182
	v_mfma_f32_32x32x16_bf16 v[34:49], v[212:215], v[66:69], 0
	v_fmac_f32_e32 v16, v152, v17
	v_fmac_f32_e32 v32, v152, v33
	v_cvt_pk_bf16_f32 v184, v17, v33
	v_fma_f32 v16, -v153, v33, v16
	v_fmac_f32_e32 v32, v153, v17
	ds_write_b32 v172, v184 offset:64496
	v_fmac_f32_e32 v15, v152, v16
	v_fmac_f32_e32 v31, v152, v32
	v_cvt_pk_bf16_f32 v185, v16, v32
	v_fma_f32 v15, -v153, v32, v15
	v_fmac_f32_e32 v31, v153, v16
	ds_write_b32 v172, v185 offset:64224
	v_mfma_f32_32x32x16_bf16 v[50:65], v[212:215], v[74:77], 0
	v_fmac_f32_e32 v14, v152, v15
	v_fmac_f32_e32 v30, v152, v31
	v_cvt_pk_bf16_f32 v184, v15, v31
	v_fma_f32 v14, -v153, v31, v14
	v_fmac_f32_e32 v30, v153, v15
	ds_write_b32 v172, v184 offset:63952
	v_fmac_f32_e32 v13, v152, v14
	v_fmac_f32_e32 v29, v152, v30
	v_cvt_pk_bf16_f32 v185, v14, v30
	v_fma_f32 v13, -v153, v30, v13
	v_fmac_f32_e32 v29, v153, v14
	ds_write_b32 v172, v185 offset:63680
	s_waitcnt lgkmcnt(4)
	v_mfma_f32_16x16x32_bf16 v[232:235], v[82:85], v[216:219], 0
	v_fmac_f32_e32 v12, v152, v13
	v_fmac_f32_e32 v28, v152, v29
	v_cvt_pk_bf16_f32 v184, v13, v29
	v_fma_f32 v12, -v153, v29, v12
	v_fmac_f32_e32 v28, v153, v13
	ds_write_b32 v172, v184 offset:63408
	v_mfma_f32_16x16x32_bf16 v[232:235], v[86:89], v[220:223], v[232:235]
	v_fmac_f32_e32 v11, v152, v12
	v_fmac_f32_e32 v27, v152, v28
	v_cvt_pk_bf16_f32 v185, v12, v28
	v_fma_f32 v11, -v153, v28, v11
	v_fmac_f32_e32 v27, v153, v12
	ds_write_b32 v172, v185 offset:63136
	v_mfma_f32_16x16x32_bf16 v[232:235], v[90:93], v[224:227], v[232:235]
	v_fmac_f32_e32 v10, v152, v11
	v_fmac_f32_e32 v26, v152, v27
	v_cvt_pk_bf16_f32 v184, v11, v27
	v_fma_f32 v10, -v153, v27, v10
	v_fmac_f32_e32 v26, v153, v11
	ds_write_b32 v172, v184 offset:62864
	v_mfma_f32_16x16x32_bf16 v[232:235], v[94:97], v[228:231], v[232:235]
	v_fmac_f32_e32 v9, v152, v10
	v_fmac_f32_e32 v25, v152, v26
	v_cvt_pk_bf16_f32 v185, v10, v26
	v_fma_f32 v9, -v153, v26, v9
	v_fmac_f32_e32 v25, v153, v10
	ds_write_b32 v172, v185 offset:62592
	v_fmac_f32_e32 v8, v152, v9
	v_fmac_f32_e32 v24, v152, v25
	v_cvt_pk_bf16_f32 v184, v9, v25
	v_fma_f32 v8, -v153, v25, v8
	v_fmac_f32_e32 v24, v153, v9
	ds_write_b32 v172, v184 offset:62320
	v_fmac_f32_e32 v7, v152, v8
	v_fmac_f32_e32 v23, v152, v24
	v_cvt_pk_bf16_f32 v185, v8, v24
	v_fma_f32 v7, -v153, v24, v7
	v_fmac_f32_e32 v23, v153, v8
	ds_write_b32 v172, v185 offset:62048
	global_store_dwordx4 v[240:241], v[232:235], off sc1
	v_lshl_add_u64 v[240:241], v[240:241], 0, s[50:51]
	v_fmac_f32_e32 v6, v152, v7
	v_fmac_f32_e32 v22, v152, v23
	v_cvt_pk_bf16_f32 v184, v7, v23
	v_fma_f32 v6, -v153, v23, v6
	v_fmac_f32_e32 v22, v153, v7
	ds_write_b32 v172, v184 offset:61776
	v_fmac_f32_e32 v5, v152, v6
	v_fmac_f32_e32 v21, v152, v22
	v_cvt_pk_bf16_f32 v185, v6, v22
	v_fma_f32 v5, -v153, v22, v5
	v_fmac_f32_e32 v21, v153, v6
	ds_write_b32 v172, v185 offset:61504
	v_fmac_f32_e32 v4, v152, v5
	v_fmac_f32_e32 v20, v152, v21
	v_cvt_pk_bf16_f32 v184, v5, v21
	v_fma_f32 v4, -v153, v21, v4
	v_fmac_f32_e32 v20, v153, v5
	ds_write_b32 v172, v184 offset:61232
	v_fmac_f32_e32 v3, v152, v4
	v_fmac_f32_e32 v19, v152, v20
	v_cvt_pk_bf16_f32 v185, v4, v20
	v_fma_f32 v3, -v153, v20, v3
	v_fmac_f32_e32 v19, v153, v4
	ds_write_b32 v172, v185 offset:60960
	v_fma_f32 v182, v152, v3, v2
	v_fma_f32 v178, v152, v19, v18
	v_cvt_pk_bf16_f32 v184, v3, v19
	v_fma_f32 v182, -v153, v19, v182
	v_fmac_f32_e32 v178, v153, v3
	ds_write_b32 v172, v184 offset:60688
	v_cvt_pk_bf16_f32 v185, v182, v178
	ds_write_b32 v172, v185 offset:60416
	s_waitcnt lgkmcnt(0)
	s_barrier
	s_add_u32 s28, s28, 1
	s_cmp_lt_u32 s28, s52
	s_cbranch_scc1 .LS5Q_loopr0d1
	s_branch .LS5Q_epi

.LS5Q_wr0d0e:
	s_waitcnt vmcnt(4)
	v_cvt_pk_bf16_f32 v212, v102, v103
	v_cvt_pk_bf16_f32 v213, v104, v105
	v_cvt_pk_bf16_f32 v214, v98, v99
	v_cvt_pk_bf16_f32 v215, v100, v101
	s_add_u32 s20, s28, 3
	s_cmp_lt_u32 s20, s52
	s_cselect_b64 s[58:59], s[50:51], 0
	v_lshl_add_u64 v[248:249], v[248:249], 0, s[58:59]
	global_load_dwordx4 v[98:101], v[248:249], off offset:16
	global_load_dwordx4 v[102:105], v[248:249], off
	ds_read_b128 v[216:219], v173 offset:60416
	ds_read_b128 v[220:223], v173 offset:60480
	ds_read_b128 v[224:227], v173 offset:60544
	ds_read_b128 v[228:231], v173 offset:60608
	v_fmac_f32_e32 v34, v152, v182
	v_fmac_f32_e32 v50, v152, v178
	v_fma_f32 v34, -v153, v178, v34
	v_fmac_f32_e32 v50, v153, v182
	v_mfma_f32_32x32x16_bf16 v[2:17], v[212:215], v[66:69], 0
	v_fmac_f32_e32 v35, v152, v34
	v_fmac_f32_e32 v51, v152, v50
	v_cvt_pk_bf16_f32 v184, v34, v50
	v_fma_f32 v35, -v153, v50, v35
	v_fmac_f32_e32 v51, v153, v34
	ds_write_b32 v172, v184 offset:0
	v_fmac_f32_e32 v36, v152, v35
	v_fmac_f32_e32 v52, v152, v51
	v_cvt_pk_bf16_f32 v185, v35, v51
	v_fma_f32 v36, -v153, v51, v36
	v_fmac_f32_e32 v52, v153, v35
	ds_write_b32 v172, v185 offset:272
	v_mfma_f32_32x32x16_bf16 v[18:33], v[212:215], v[74:77], 0
	v_fmac_f32_e32 v37, v152, v36
	v_fmac_f32_e32 v53, v152, v52
	v_cvt_pk_bf16_f32 v184, v36, v52
	v_fma_f32 v37, -v153, v52, v37
	v_fmac_f32_e32 v53, v153, v36
	ds_write_b32 v172, v184 offset:544
	v_fmac_f32_e32 v38, v152, v37
	v_fmac_f32_e32 v54, v152, v53
	v_cvt_pk_bf16_f32 v185, v37, v53
	v_fma_f32 v38, -v153, v53, v38
	v_fmac_f32_e32 v54, v153, v37
	ds_write_b32 v172, v185 offset:816
	s_waitcnt lgkmcnt(4)
	v_mfma_f32_16x16x32_bf16 v[232:235], v[82:85], v[216:219], 0
	v_fmac_f32_e32 v39, v152, v38
	v_fmac_f32_e32 v55, v152, v54
	v_cvt_pk_bf16_f32 v184, v38, v54
	v_fma_f32 v39, -v153, v54, v39
	v_fmac_f32_e32 v55, v153, v38
	ds_write_b32 v172, v184 offset:1088
	v_mfma_f32_16x16x32_bf16 v[232:235], v[86:89], v[220:223], v[232:235]
	v_fmac_f32_e32 v40, v152, v39
	v_fmac_f32_e32 v56, v152, v55
	v_cvt_pk_bf16_f32 v185, v39, v55
	v_fma_f32 v40, -v153, v55, v40
	v_fmac_f32_e32 v56, v153, v39
	ds_write_b32 v172, v185 offset:1360
	v_mfma_f32_16x16x32_bf16 v[232:235], v[90:93], v[224:227], v[232:235]
	v_fmac_f32_e32 v41, v152, v40
	v_fmac_f32_e32 v57, v152, v56
	v_cvt_pk_bf16_f32 v184, v40, v56
	v_fma_f32 v41, -v153, v56, v41
	v_fmac_f32_e32 v57, v153, v40
	ds_write_b32 v172, v184 offset:1632
	v_mfma_f32_16x16x32_bf16 v[232:235], v[94:97], v[228:231], v[232:235]
	v_fmac_f32_e32 v42, v152, v41
	v_fmac_f32_e32 v58, v152, v57
	v_cvt_pk_bf16_f32 v185, v41, v57
	v_fma_f32 v42, -v153, v57, v42
	v_fmac_f32_e32 v58, v153, v41
	ds_write_b32 v172, v185 offset:1904
	v_fmac_f32_e32 v43, v152, v42
	v_fmac_f32_e32 v59, v152, v58
	v_cvt_pk_bf16_f32 v184, v42, v58
	v_fma_f32 v43, -v153, v58, v43
	v_fmac_f32_e32 v59, v153, v42
	ds_write_b32 v172, v184 offset:2176
	v_fmac_f32_e32 v44, v152, v43
	v_fmac_f32_e32 v60, v152, v59
	v_cvt_pk_bf16_f32 v185, v43, v59
	v_fma_f32 v44, -v153, v59, v44
	v_fmac_f32_e32 v60, v153, v43
	ds_write_b32 v172, v185 offset:2448
	s_cmp_eq_u32 s28, 0
	s_cbranch_scc1 .LS5Q_nstr0d0e
	global_store_dwordx4 v[240:241], v[232:235], off sc1
	v_lshl_add_u64 v[240:241], v[240:241], 0, s[50:51]

.LS5Q_wr0d0o:
	s_waitcnt vmcnt(4)
	v_cvt_pk_bf16_f32 v212, v106, v107
	v_cvt_pk_bf16_f32 v213, v108, v109
	v_cvt_pk_bf16_f32 v214, v110, v111
	v_cvt_pk_bf16_f32 v215, v112, v113
	s_add_u32 s20, s28, 3
	s_cmp_lt_u32 s20, s52
	s_cselect_b64 s[58:59], s[50:51], 0
	v_lshl_add_u64 v[248:249], v[248:249], 0, s[58:59]
	global_load_dwordx4 v[110:113], v[248:249], off offset:16
	global_load_dwordx4 v[106:109], v[248:249], off
	ds_read_b128 v[216:219], v173 offset:0
	ds_read_b128 v[220:223], v173 offset:64
	ds_read_b128 v[224:227], v173 offset:128
	ds_read_b128 v[228:231], v173 offset:192
	v_fmac_f32_e32 v2, v152, v182
	v_fmac_f32_e32 v18, v152, v178
	v_fma_f32 v2, -v153, v178, v2
	v_fmac_f32_e32 v18, v153, v182
	v_mfma_f32_32x32x16_bf16 v[34:49], v[212:215], v[66:69], 0
	v_fmac_f32_e32 v3, v152, v2
	v_fmac_f32_e32 v19, v152, v18
	v_cvt_pk_bf16_f32 v184, v2, v18
	v_fma_f32 v3, -v153, v18, v3
	v_fmac_f32_e32 v19, v153, v2
	ds_write_b32 v172, v184 offset:60416
	v_fmac_f32_e32 v4, v152, v3
	v_fmac_f32_e32 v20, v152, v19
	v_cvt_pk_bf16_f32 v185, v3, v19
	v_fma_f32 v4, -v153, v19, v4
	v_fmac_f32_e32 v20, v153, v3
	ds_write_b32 v172, v185 offset:60688
	v_mfma_f32_32x32x16_bf16 v[50:65], v[212:215], v[74:77], 0
	v_fmac_f32_e32 v5, v152, v4
	v_fmac_f32_e32 v21, v152, v20
	v_cvt_pk_bf16_f32 v184, v4, v20
	v_fma_f32 v5, -v153, v20, v5
	v_fmac_f32_e32 v21, v153, v4
	ds_write_b32 v172, v184 offset:60960
	v_fmac_f32_e32 v6, v152, v5
	v_fmac_f32_e32 v22, v152, v21
	v_cvt_pk_bf16_f32 v185, v5, v21
	v_fma_f32 v6, -v153, v21, v6
	v_fmac_f32_e32 v22, v153, v5
	ds_write_b32 v172, v185 offset:61232
	s_waitcnt lgkmcnt(4)
	v_mfma_f32_16x16x32_bf16 v[232:235], v[82:85], v[216:219], 0
	v_fmac_f32_e32 v7, v152, v6
	v_fmac_f32_e32 v23, v152, v22
	v_cvt_pk_bf16_f32 v184, v6, v22
	v_fma_f32 v7, -v153, v22, v7
	v_fmac_f32_e32 v23, v153, v6
	ds_write_b32 v172, v184 offset:61504
	v_mfma_f32_16x16x32_bf16 v[232:235], v[86:89], v[220:223], v[232:235]
	v_fmac_f32_e32 v8, v152, v7
	v_fmac_f32_e32 v24, v152, v23
	v_cvt_pk_bf16_f32 v185, v7, v23
	v_fma_f32 v8, -v153, v23, v8
	v_fmac_f32_e32 v24, v153, v7
	ds_write_b32 v172, v185 offset:61776
	v_mfma_f32_16x16x32_bf16 v[232:235], v[90:93], v[224:227], v[232:235]
	v_fmac_f32_e32 v9, v152, v8
	v_fmac_f32_e32 v25, v152, v24
	v_cvt_pk_bf16_f32 v184, v8, v24
	v_fma_f32 v9, -v153, v24, v9
	v_fmac_f32_e32 v25, v153, v8
	ds_write_b32 v172, v184 offset:62048
	v_mfma_f32_16x16x32_bf16 v[232:235], v[94:97], v[228:231], v[232:235]
	v_fmac_f32_e32 v10, v152, v9
	v_fmac_f32_e32 v26, v152, v25
	v_cvt_pk_bf16_f32 v185, v9, v25
	v_fma_f32 v10, -v153, v25, v10
	v_fmac_f32_e32 v26, v153, v9
	ds_write_b32 v172, v185 offset:62320
	v_fmac_f32_e32 v11, v152, v10
	v_fmac_f32_e32 v27, v152, v26
	v_cvt_pk_bf16_f32 v184, v10, v26
	v_fma_f32 v11, -v153, v26, v11
	v_fmac_f32_e32 v27, v153, v10
	ds_write_b32 v172, v184 offset:62592
	v_fmac_f32_e32 v12, v152, v11
	v_fmac_f32_e32 v28, v152, v27
	v_cvt_pk_bf16_f32 v185, v11, v27
	v_fma_f32 v12, -v153, v27, v12
	v_fmac_f32_e32 v28, v153, v11
	ds_write_b32 v172, v185 offset:62864
	global_store_dwordx4 v[240:241], v[232:235], off sc1
	v_lshl_add_u64 v[240:241], v[240:241], 0, s[50:51]
	v_fmac_f32_e32 v13, v152, v12
	v_fmac_f32_e32 v29, v152, v28
	v_cvt_pk_bf16_f32 v184, v12, v28
	v_fma_f32 v13, -v153, v28, v13
	v_fmac_f32_e32 v29, v153, v12
	ds_write_b32 v172, v184 offset:63136
	v_fmac_f32_e32 v14, v152, v13
	v_fmac_f32_e32 v30, v152, v29
	v_cvt_pk_bf16_f32 v185, v13, v29
	v_fma_f32 v14, -v153, v29, v14
	v_fmac_f32_e32 v30, v153, v13
	ds_write_b32 v172, v185 offset:63408
	v_fmac_f32_e32 v15, v152, v14
	v_fmac_f32_e32 v31, v152, v30
	v_cvt_pk_bf16_f32 v184, v14, v30
	v_fma_f32 v15, -v153, v30, v15
	v_fmac_f32_e32 v31, v153, v14
	ds_write_b32 v172, v184 offset:63680
	v_fmac_f32_e32 v16, v152, v15
	v_fmac_f32_e32 v32, v152, v31
	v_cvt_pk_bf16_f32 v185, v15, v31
	v_fma_f32 v16, -v153, v31, v16
	v_fmac_f32_e32 v32, v153, v15
	ds_write_b32 v172, v185 offset:63952
	v_fma_f32 v182, v152, v16, v17
	v_fma_f32 v178, v152, v32, v33
	v_cvt_pk_bf16_f32 v184, v16, v32
	v_fma_f32 v182, -v153, v32, v182
	v_fmac_f32_e32 v178, v153, v16
	ds_write_b32 v172, v184 offset:64224
	v_cvt_pk_bf16_f32 v185, v182, v178
	ds_write_b32 v172, v185 offset:64496
	s_waitcnt lgkmcnt(0)
	s_barrier
	s_add_u32 s28, s28, 1
	s_cmp_lt_u32 s28, s52
	s_cbranch_scc1 .LS5Q_loopr0d0
	s_branch .LS5Q_epi
.LS5Q_epi:
	ds_read_b128 v[216:219], v173 offset:60416
	ds_read_b128 v[220:223], v173 offset:60480
	ds_read_b128 v[224:227], v173 offset:60544
	ds_read_b128 v[228:231], v173 offset:60608
	s_waitcnt lgkmcnt(0)
	v_mfma_f32_16x16x32_bf16 v[232:235], v[82:85], v[216:219], 0
	v_mfma_f32_16x16x32_bf16 v[232:235], v[86:89], v[220:223], v[232:235]
	v_mfma_f32_16x16x32_bf16 v[232:235], v[90:93], v[224:227], v[232:235]
	v_mfma_f32_16x16x32_bf16 v[232:235], v[94:97], v[228:231], v[232:235]
	s_nop 7
	global_store_dwordx4 v[240:241], v[232:235], off sc1
.LS5Q_done:
.LBB0_106:
	s_or_b64 exec, exec, s[2:3]
	s_and_saveexec_b64 s[2:3], s[44:45]
	s_cbranch_execz .LBB0_91
	v_readlane_b32 s4, v251, 12
	v_readlane_b32 s5, v251, 13
	s_nop 1
	v_lshl_add_u64 v[2:3], v[150:151], 2, s[4:5]
	v_add_co_u32_e32 v4, vcc, 0x4000, v2
	global_store_dword v[2:3], v182, off sc1
	s_nop 0
	v_addc_co_u32_e32 v5, vcc, 0, v3, vcc
	global_store_dword v[4:5], v178, off sc1
	global_store_dword v[2:3], v180, off offset:128 sc1
	global_store_dword v[4:5], v176, off offset:128 sc1
	s_branch .LBB0_91

.LBB0_114:
	v_ashrrev_i32_e32 v5, 31, v4
	v_lshlrev_b64 v[6:7], 11, v[4:5]
	v_lshl_or_b32 v8, v0, 2, v6
	v_mov_b32_e32 v9, v7
	v_lshl_add_u64 v[22:23], s[6:7], 0, v[8:9]
	s_waitcnt vmcnt(27)
	v_lshl_add_u64 v[10:11], s[38:39], 0, v[8:9]
	global_load_dword v5, v[22:23], off
	global_load_dword v17, v[10:11], off
	v_lshl_add_u64 v[10:11], s[4:5], 0, v[8:9]
	global_load_dword v18, v[10:11], off
	global_load_dword v20, v[22:23], off offset:256
	v_or_b32_e32 v10, 0x100, v8
	v_mov_b32_e32 v11, v7
	v_lshl_add_u64 v[12:13], s[38:39], 0, v[10:11]
	v_lshl_add_u64 v[10:11], s[4:5], 0, v[10:11]
	global_load_dword v31, v[12:13], off
	global_load_dword v33, v[10:11], off
	v_or_b32_e32 v10, 0x200, v8
	v_mov_b32_e32 v11, v7
	v_lshl_add_u64 v[12:13], s[38:39], 0, v[10:11]
	v_lshl_add_u64 v[10:11], s[4:5], 0, v[10:11]
	global_load_dword v75, v[12:13], off
	global_load_dword v78, v[10:11], off
	v_or_b32_e32 v10, 0x300, v8
	v_mov_b32_e32 v11, v7
	v_lshl_add_u64 v[12:13], s[38:39], 0, v[10:11]
	v_lshl_add_u64 v[10:11], s[4:5], 0, v[10:11]
	v_lshl_add_u64 v[26:27], s[46:47], 0, v[8:9]
	global_load_dword v79, v[12:13], off
	global_load_dword v80, v[10:11], off
	v_or_b32_e32 v10, 0x400, v8
	v_mov_b32_e32 v11, v7
	v_add_co_u32_e32 v24, vcc, s8, v26
	v_lshl_add_u64 v[12:13], s[38:39], 0, v[10:11]
	v_lshl_add_u64 v[10:11], s[4:5], 0, v[10:11]
	v_addc_co_u32_e32 v25, vcc, 0, v27, vcc
	global_load_dword v81, v[12:13], off
	global_load_dword v82, v[10:11], off
	global_load_dword v16, v[26:27], off
	global_load_dword v30, v[24:25], off
	global_load_dword v32, v[26:27], off offset:256
	global_load_dword v74, v[24:25], off offset:256
	s_waitcnt vmcnt(40)
	v_lshl_add_u64 v[34:35], s[10:11], 0, v[8:9]
	global_load_dword v77, v[34:35], off
	global_load_dword v76, v[34:35], off offset:256
	v_mov_b32_e32 v11, v7
	v_or_b32_e32 v10, 0x500, v8
	v_lshl_add_u64 v[12:13], s[38:39], 0, v[10:11]
	v_lshl_add_u64 v[10:11], s[4:5], 0, v[10:11]
	global_load_dword v83, v[12:13], off
	global_load_dword v84, v[10:11], off
	v_mov_b32_e32 v29, v7
	v_mov_b32_e32 v43, v7
	v_or_b32_e32 v28, 0x600, v8
	v_or_b32_e32 v42, 0x700, v8
	v_lshl_add_u64 v[14:15], s[16:17], 0, v[8:9]
	v_lshl_add_u64 v[8:9], s[38:39], 0, v[28:29]
	v_lshl_add_u64 v[44:45], s[38:39], 0, v[42:43]
	v_lshl_add_u64 v[42:43], s[4:5], 0, v[42:43]
	global_load_dword v21, v[14:15], off
	global_load_dword v13, v[14:15], off offset:256
	global_load_dword v41, v[22:23], off offset:512
	global_load_dword v37, v[34:35], off offset:512
	global_load_dword v38, v[26:27], off offset:512
	global_load_dword v19, v[14:15], off offset:512
	global_load_dword v39, v[22:23], off offset:768
	global_load_dword v36, v[34:35], off offset:768
	global_load_dword v40, v[26:27], off offset:768
	global_load_dword v73, v[14:15], off offset:768
	global_load_dword v11, v[22:23], off offset:1024
	v_lshl_add_u64 v[28:29], s[4:5], 0, v[28:29]
	global_load_dword v85, v[8:9], off
	global_load_dword v86, v[28:29], off
	s_nop 0
	global_load_dword v45, v[44:45], off
	s_nop 0
	global_load_dword v43, v[42:43], off
	s_nop 0
	global_load_dword v44, v[24:25], off offset:512
	global_load_dword v42, v[24:25], off offset:768
	s_mov_b32 s2, 0x3a27c5ac
	v_lshl_add_u64 v[6:7], v[2:3], 0, v[6:7]
	v_add_u32_e32 v72, s82, v72
	v_add_u32_e32 v4, s83, v4
	s_waitcnt vmcnt(36)
	v_mul_f32_e32 v5, v46, v5
	s_waitcnt vmcnt(34)
	v_add_f32_e32 v8, v17, v18
	v_mul_f32_e32 v12, v5, v8
	s_waitcnt vmcnt(33)
	v_mul_f32_e32 v9, v47, v20
	s_waitcnt vmcnt(31)
	v_add_f32_e32 v10, v31, v33
	v_mov_b32_dpp v12, v12 quad_perm:[1,0,3,2] row_mask:0xf bank_mask:0xf bound_ctrl:1
	v_fmac_f32_e32 v12, v5, v8
	s_waitcnt vmcnt(29)
	v_add_f32_e32 v87, v75, v78
	v_add_f32_dpp v5, v12, v12 quad_perm:[2,3,0,1] row_mask:0xf bank_mask:0xf bound_ctrl:1
	v_mul_f32_e32 v12, v9, v10
	s_waitcnt vmcnt(27)
	v_add_f32_e32 v88, v79, v80
	v_mov_b32_dpp v12, v12 quad_perm:[1,0,3,2] row_mask:0xf bank_mask:0xf bound_ctrl:1
	v_fmac_f32_e32 v12, v9, v10
	v_add_f32_dpp v5, v5, v5 row_half_mirror row_mask:0xf bank_mask:0xf bound_ctrl:1
	s_waitcnt vmcnt(25)
	v_add_f32_e32 v29, v81, v82
	v_add_f32_dpp v9, v12, v12 quad_perm:[2,3,0,1] row_mask:0xf bank_mask:0xf bound_ctrl:1
	v_add_f32_dpp v5, v5, v5 row_mirror row_mask:0xf bank_mask:0xf bound_ctrl:1
	ds_bpermute_b32 v8, v70, v5
	v_add_f32_dpp v9, v9, v9 row_half_mirror row_mask:0xf bank_mask:0xf bound_ctrl:1
	s_waitcnt lgkmcnt(0)
	v_add_f32_e32 v17, v5, v8
	v_add_f32_dpp v10, v9, v9 row_mirror row_mask:0xf bank_mask:0xf bound_ctrl:1
	ds_bpermute_b32 v12, v70, v10
	ds_bpermute_b32 v31, v71, v17
	global_load_dword v9, v[34:35], off offset:1024
	s_waitcnt vmcnt(11)
	v_mul_f32_e32 v39, v49, v39
	s_waitcnt lgkmcnt(1)
	v_add_f32_e32 v33, v10, v12
	ds_bpermute_b32 v75, v71, v33
	global_load_dword v10, v[26:27], off offset:1024
	global_load_dword v12, v[24:25], off offset:1024
	global_load_dword v5, v[14:15], off offset:1024
	global_load_dword v80, v[22:23], off offset:1280
	global_load_dword v8, v[34:35], off offset:1280
	s_waitcnt lgkmcnt(1)
	v_pk_add_f32 v[16:17], v[16:17], v[30:31]
	global_load_dword v28, v[26:27], off offset:1280
	s_waitcnt lgkmcnt(0)
	v_pk_add_f32 v[30:31], v[32:33], v[74:75]
	v_mov_b32_e32 v33, v17
	v_mov_b32_e32 v32, v31
	v_mov_b32_e32 v31, v16
	v_pk_fma_f32 v[32:33], v[76:77], v[32:33], v[30:31]
	s_waitcnt vmcnt(11)
	v_add_f32_e32 v77, v85, v86
	v_mul_f32_e32 v11, v50, v11
	v_mov_b32_dpp v17, v33 quad_perm:[1,0,3,2] row_mask:0xf bank_mask:0xf bound_ctrl:1
	v_mov_b32_dpp v16, v32 quad_perm:[1,0,3,2] row_mask:0xf bank_mask:0xf bound_ctrl:1
	v_pk_add_f32 v[16:17], v[32:33], v[16:17]
	s_nop 1
	v_mov_b32_dpp v31, v17 quad_perm:[2,3,0,1] row_mask:0xf bank_mask:0xf bound_ctrl:1
	v_mov_b32_dpp v30, v16 quad_perm:[2,3,0,1] row_mask:0xf bank_mask:0xf bound_ctrl:1
	v_pk_add_f32 v[16:17], v[16:17], v[30:31]
	s_nop 1
	v_mov_b32_dpp v31, v17 row_half_mirror row_mask:0xf bank_mask:0xf bound_ctrl:1
	v_mov_b32_dpp v30, v16 row_half_mirror row_mask:0xf bank_mask:0xf bound_ctrl:1
	v_pk_add_f32 v[16:17], v[16:17], v[30:31]
	s_nop 1
	v_mov_b32_dpp v31, v17 row_mirror row_mask:0xf bank_mask:0xf bound_ctrl:1
	v_mov_b32_dpp v30, v16 row_mirror row_mask:0xf bank_mask:0xf bound_ctrl:1
	v_pk_add_f32 v[16:17], v[16:17], v[30:31]
	ds_bpermute_b32 v75, v70, v17
	ds_bpermute_b32 v74, v70, v16
	v_add_f32_e32 v31, v83, v84
	s_waitcnt lgkmcnt(0)
	v_pk_add_f32 v[78:79], v[16:17], v[74:75]
	ds_bpermute_b32 v83, v71, v79
	ds_bpermute_b32 v82, v71, v78
	global_load_dword v30, v[24:25], off offset:1280
	global_load_dword v74, v[14:15], off offset:1280
	global_load_dword v76, v[22:23], off offset:1536
	global_load_dword v17, v[34:35], off offset:1536
	global_load_dword v18, v[26:27], off offset:1536
	global_load_dword v20, v[24:25], off offset:1536
	global_load_dword v75, v[14:15], off offset:1536
	s_waitcnt lgkmcnt(0)
	v_pk_add_f32 v[78:79], v[78:79], v[82:83]
	s_nop 0
	v_pk_fma_f32 v[32:33], v[78:79], s[12:13], v[32:33] op_sel_hi:[1,0,1] neg_lo:[1,0,0] neg_hi:[1,0,0]
	s_nop 0
	v_pk_mul_f32 v[78:79], v[32:33], v[32:33]
	s_nop 1
	v_mov_b32_dpp v79, v79 quad_perm:[1,0,3,2] row_mask:0xf bank_mask:0xf bound_ctrl:1
	v_mov_b32_dpp v78, v78 quad_perm:[1,0,3,2] row_mask:0xf bank_mask:0xf bound_ctrl:1
	v_pk_fma_f32 v[78:79], v[32:33], v[32:33], v[78:79]
	s_nop 1
	v_mov_b32_dpp v83, v79 quad_perm:[2,3,0,1] row_mask:0xf bank_mask:0xf bound_ctrl:1
	v_mov_b32_dpp v82, v78 quad_perm:[2,3,0,1] row_mask:0xf bank_mask:0xf bound_ctrl:1
	v_pk_add_f32 v[78:79], v[78:79], v[82:83]
	s_nop 1
	v_mov_b32_dpp v83, v79 row_half_mirror row_mask:0xf bank_mask:0xf bound_ctrl:1
	v_mov_b32_dpp v82, v78 row_half_mirror row_mask:0xf bank_mask:0xf bound_ctrl:1
	v_pk_add_f32 v[78:79], v[78:79], v[82:83]
	s_nop 1
	v_mov_b32_dpp v83, v79 row_mirror row_mask:0xf bank_mask:0xf bound_ctrl:1
	v_mov_b32_dpp v82, v78 row_mirror row_mask:0xf bank_mask:0xf bound_ctrl:1
	v_pk_add_f32 v[78:79], v[78:79], v[82:83]
	ds_bpermute_b32 v83, v70, v79
	ds_bpermute_b32 v82, v70, v78
	s_waitcnt lgkmcnt(0)
	v_pk_add_f32 v[82:83], v[78:79], v[82:83]
	global_load_dword v79, v[22:23], off offset:1792
	global_load_dword v16, v[34:35], off offset:1792
	s_waitcnt vmcnt(18)
	v_add_f32_e32 v78, v45, v43
	global_load_dword v26, v[26:27], off offset:1792
	v_mul_f32_e32 v27, v48, v41
	v_mul_f32_e32 v41, v27, v87
	v_mul_f32_e32 v43, v39, v88
	ds_bpermute_b32 v85, v71, v83
	v_mov_b32_dpp v41, v41 quad_perm:[1,0,3,2] row_mask:0xf bank_mask:0xf bound_ctrl:1
	v_mov_b32_dpp v43, v43 quad_perm:[1,0,3,2] row_mask:0xf bank_mask:0xf bound_ctrl:1
	v_fmac_f32_e32 v41, v27, v87
	v_fmac_f32_e32 v43, v39, v88
	ds_bpermute_b32 v84, v71, v82
	v_add_f32_dpp v27, v41, v41 quad_perm:[2,3,0,1] row_mask:0xf bank_mask:0xf bound_ctrl:1
	v_add_f32_dpp v39, v43, v43 quad_perm:[2,3,0,1] row_mask:0xf bank_mask:0xf bound_ctrl:1
	v_mov_b64_e32 v[22:23], s[2:3]
	v_add_f32_dpp v27, v27, v27 row_half_mirror row_mask:0xf bank_mask:0xf bound_ctrl:1
	v_add_f32_dpp v39, v39, v39 row_half_mirror row_mask:0xf bank_mask:0xf bound_ctrl:1
	s_waitcnt lgkmcnt(0)
	v_pk_add_f32 v[34:35], v[82:83], v[84:85]
	v_add_f32_dpp v27, v27, v27 row_mirror row_mask:0xf bank_mask:0xf bound_ctrl:1
	v_add_f32_dpp v43, v39, v39 row_mirror row_mask:0xf bank_mask:0xf bound_ctrl:1
	ds_bpermute_b32 v41, v70, v27
	ds_bpermute_b32 v81, v70, v43
	v_pk_fma_f32 v[34:35], v[34:35], s[12:13], v[22:23] op_sel_hi:[1,0,0]
	global_load_dword v24, v[24:25], off offset:1792
	s_nop 0
	global_load_dword v14, v[14:15], off offset:1792
	v_mul_f32_e32 v82, 0x4b800000, v35
	s_waitcnt lgkmcnt(1)
	v_add_f32_e32 v39, v27, v41
	s_waitcnt lgkmcnt(0)
	v_add_f32_e32 v41, v43, v81
	ds_bpermute_b32 v45, v71, v39
	ds_bpermute_b32 v43, v71, v41
	v_cmp_gt_f32_e32 vcc, s31, v35
	v_cmp_gt_f32_e64 s[40:41], s31, v34
	v_mul_f32_e32 v25, 0x4b800000, v34
	s_waitcnt vmcnt(20) lgkmcnt(1)
	v_pk_add_f32 v[38:39], v[38:39], v[44:45]
	s_waitcnt vmcnt(19) lgkmcnt(0)
	v_pk_add_f32 v[40:41], v[40:41], v[42:43]
	v_mov_b32_e32 v43, v39
	v_mov_b32_e32 v42, v41
	v_mov_b32_e32 v41, v38
	v_pk_fma_f32 v[36:37], v[36:37], v[42:43], v[40:41]
	v_cndmask_b32_e32 v27, v35, v82, vcc
	v_rsq_f32_e32 v27, v27
	v_mov_b32_dpp v39, v37 quad_perm:[1,0,3,2] row_mask:0xf bank_mask:0xf bound_ctrl:1
	v_mov_b32_dpp v38, v36 quad_perm:[1,0,3,2] row_mask:0xf bank_mask:0xf bound_ctrl:1
	v_pk_add_f32 v[38:39], v[36:37], v[38:39]
	v_cndmask_b32_e64 v25, v34, v25, s[40:41]
	v_mul_f32_e32 v15, 0x45800000, v27
	v_mov_b32_dpp v41, v39 quad_perm:[2,3,0,1] row_mask:0xf bank_mask:0xf bound_ctrl:1
	v_mov_b32_dpp v40, v38 quad_perm:[2,3,0,1] row_mask:0xf bank_mask:0xf bound_ctrl:1
	v_pk_add_f32 v[38:39], v[38:39], v[40:41]
	v_rsq_f32_e32 v25, v25
	v_cndmask_b32_e32 v15, v27, v15, vcc
	v_mov_b32_dpp v41, v39 row_half_mirror row_mask:0xf bank_mask:0xf bound_ctrl:1
	v_mov_b32_dpp v40, v38 row_half_mirror row_mask:0xf bank_mask:0xf bound_ctrl:1
	v_pk_add_f32 v[38:39], v[38:39], v[40:41]
	v_mul_f32_e32 v15, v33, v15
	v_fma_f32 v15, v54, v15, v62
	v_mov_b32_dpp v41, v39 row_mirror row_mask:0xf bank_mask:0xf bound_ctrl:1
	v_mov_b32_dpp v40, v38 row_mirror row_mask:0xf bank_mask:0xf bound_ctrl:1
	v_pk_add_f32 v[38:39], v[38:39], v[40:41]
	ds_bpermute_b32 v41, v70, v39
	ds_bpermute_b32 v40, v70, v38
	v_mul_f32_e32 v15, v21, v15
	v_mul_f32_e32 v21, 0x45800000, v25
	v_cndmask_b32_e64 v21, v25, v21, s[40:41]
	v_mul_f32_e32 v21, v32, v21
	s_waitcnt lgkmcnt(0)
	v_pk_add_f32 v[38:39], v[38:39], v[40:41]
	ds_bpermute_b32 v41, v71, v39
	ds_bpermute_b32 v40, v71, v38
	v_fma_f32 v21, v55, v21, v63
	s_waitcnt lgkmcnt(0)
	v_pk_add_f32 v[34:35], v[38:39], v[40:41]
	v_mul_f32_e32 v40, v13, v21
	s_waitcnt vmcnt(14)
	v_mul_f32_e32 v21, v51, v80
	v_mul_f32_e32 v13, v11, v29
	v_mul_f32_e32 v25, v21, v31
	v_pk_fma_f32 v[34:35], v[34:35], s[12:13], v[36:37] op_sel_hi:[1,0,1] neg_lo:[1,0,0] neg_hi:[1,0,0]
	v_mov_b32_dpp v13, v13 quad_perm:[1,0,3,2] row_mask:0xf bank_mask:0xf bound_ctrl:1
	v_mov_b32_dpp v25, v25 quad_perm:[1,0,3,2] row_mask:0xf bank_mask:0xf bound_ctrl:1
	v_fmac_f32_e32 v13, v11, v29
	v_fmac_f32_e32 v25, v21, v31
	v_pk_mul_f32 v[36:37], v[34:35], v[34:35]
	v_add_f32_dpp v11, v13, v13 quad_perm:[2,3,0,1] row_mask:0xf bank_mask:0xf bound_ctrl:1
	v_add_f32_dpp v21, v25, v25 quad_perm:[2,3,0,1] row_mask:0xf bank_mask:0xf bound_ctrl:1
	v_mov_b32_dpp v37, v37 quad_perm:[1,0,3,2] row_mask:0xf bank_mask:0xf bound_ctrl:1
	v_add_f32_dpp v11, v11, v11 row_half_mirror row_mask:0xf bank_mask:0xf bound_ctrl:1
	v_add_f32_dpp v21, v21, v21 row_half_mirror row_mask:0xf bank_mask:0xf bound_ctrl:1
	v_mov_b32_dpp v36, v36 quad_perm:[1,0,3,2] row_mask:0xf bank_mask:0xf bound_ctrl:1
	v_add_f32_dpp v11, v11, v11 row_mirror row_mask:0xf bank_mask:0xf bound_ctrl:1
	v_add_f32_dpp v21, v21, v21 row_mirror row_mask:0xf bank_mask:0xf bound_ctrl:1
	ds_bpermute_b32 v13, v70, v11
	ds_bpermute_b32 v25, v70, v21
	v_pk_fma_f32 v[36:37], v[34:35], v[34:35], v[36:37]
	s_waitcnt lgkmcnt(1)
	v_add_f32_e32 v11, v11, v13
	s_waitcnt lgkmcnt(0)
	v_add_f32_e32 v29, v21, v25
	ds_bpermute_b32 v13, v71, v11
	ds_bpermute_b32 v31, v71, v29
	v_mov_b32_dpp v39, v37 quad_perm:[2,3,0,1] row_mask:0xf bank_mask:0xf bound_ctrl:1
	v_mov_b32_dpp v38, v36 quad_perm:[2,3,0,1] row_mask:0xf bank_mask:0xf bound_ctrl:1
	v_pk_add_f32 v[36:37], v[36:37], v[38:39]
	s_waitcnt lgkmcnt(1)
	v_pk_add_f32 v[10:11], v[10:11], v[12:13]
	s_waitcnt vmcnt(11) lgkmcnt(0)
	v_pk_add_f32 v[12:13], v[28:29], v[30:31]
	v_mov_b32_e32 v29, v11
	v_mov_b32_e32 v28, v13
	v_mov_b32_e32 v13, v10
	v_pk_fma_f32 v[8:9], v[8:9], v[28:29], v[12:13]
	v_mov_b32_dpp v39, v37 row_half_mirror row_mask:0xf bank_mask:0xf bound_ctrl:1
	v_mov_b32_dpp v38, v36 row_half_mirror row_mask:0xf bank_mask:0xf bound_ctrl:1
	v_mov_b32_dpp v11, v9 quad_perm:[1,0,3,2] row_mask:0xf bank_mask:0xf bound_ctrl:1
	v_mov_b32_dpp v10, v8 quad_perm:[1,0,3,2] row_mask:0xf bank_mask:0xf bound_ctrl:1
	v_pk_add_f32 v[10:11], v[8:9], v[10:11]
	v_pk_add_f32 v[36:37], v[36:37], v[38:39]
	s_nop 0
	v_mov_b32_dpp v13, v11 quad_perm:[2,3,0,1] row_mask:0xf bank_mask:0xf bound_ctrl:1
	v_mov_b32_dpp v12, v10 quad_perm:[2,3,0,1] row_mask:0xf bank_mask:0xf bound_ctrl:1
	v_pk_add_f32 v[10:11], v[10:11], v[12:13]
	v_mov_b32_dpp v39, v37 row_mirror row_mask:0xf bank_mask:0xf bound_ctrl:1
	v_mov_b32_dpp v38, v36 row_mirror row_mask:0xf bank_mask:0xf bound_ctrl:1
	v_mov_b32_dpp v13, v11 row_half_mirror row_mask:0xf bank_mask:0xf bound_ctrl:1
	v_mov_b32_dpp v12, v10 row_half_mirror row_mask:0xf bank_mask:0xf bound_ctrl:1
	v_pk_add_f32 v[10:11], v[10:11], v[12:13]
	v_pk_add_f32 v[36:37], v[36:37], v[38:39]
	ds_bpermute_b32 v39, v70, v37
	v_mov_b32_dpp v13, v11 row_mirror row_mask:0xf bank_mask:0xf bound_ctrl:1
	v_mov_b32_dpp v12, v10 row_mirror row_mask:0xf bank_mask:0xf bound_ctrl:1
	v_pk_add_f32 v[10:11], v[10:11], v[12:13]
	ds_bpermute_b32 v13, v70, v11
	ds_bpermute_b32 v12, v70, v10
	ds_bpermute_b32 v38, v70, v36
	s_waitcnt lgkmcnt(1)
	v_pk_add_f32 v[10:11], v[10:11], v[12:13]
	s_waitcnt lgkmcnt(0)
	v_pk_add_f32 v[36:37], v[36:37], v[38:39]
	ds_bpermute_b32 v13, v71, v11
	ds_bpermute_b32 v12, v71, v10
	ds_bpermute_b32 v39, v71, v37
	ds_bpermute_b32 v38, v71, v36
	s_waitcnt lgkmcnt(2)
	v_pk_add_f32 v[10:11], v[10:11], v[12:13]
	s_nop 0
	v_pk_fma_f32 v[8:9], v[10:11], s[12:13], v[8:9] op_sel_hi:[1,0,1] neg_lo:[1,0,0] neg_hi:[1,0,0]
	s_waitcnt lgkmcnt(0)
	v_pk_add_f32 v[32:33], v[36:37], v[38:39]
	v_pk_mul_f32 v[10:11], v[8:9], v[8:9]
	v_pk_fma_f32 v[32:33], v[32:33], s[12:13], v[22:23] op_sel_hi:[1,0,0]
	s_nop 0
	v_mul_f32_e32 v27, 0x4b800000, v33
	v_cmp_gt_f32_e64 s[40:41], s31, v33
	v_mov_b32_dpp v11, v11 quad_perm:[1,0,3,2] row_mask:0xf bank_mask:0xf bound_ctrl:1
	v_mov_b32_dpp v10, v10 quad_perm:[1,0,3,2] row_mask:0xf bank_mask:0xf bound_ctrl:1
	v_cndmask_b32_e64 v21, v33, v27, s[40:41]
	v_pk_fma_f32 v[10:11], v[8:9], v[8:9], v[10:11]
	v_rsq_f32_e32 v21, v21
	v_cmp_gt_f32_e32 vcc, s31, v32
	v_mov_b32_dpp v13, v11 quad_perm:[2,3,0,1] row_mask:0xf bank_mask:0xf bound_ctrl:1
	v_mov_b32_dpp v12, v10 quad_perm:[2,3,0,1] row_mask:0xf bank_mask:0xf bound_ctrl:1
	v_pk_add_f32 v[10:11], v[10:11], v[12:13]
	v_mul_f32_e32 v25, 0x45800000, v21
	v_cndmask_b32_e64 v21, v21, v25, s[40:41]
	v_mov_b32_dpp v13, v11 row_half_mirror row_mask:0xf bank_mask:0xf bound_ctrl:1
	v_mov_b32_dpp v12, v10 row_half_mirror row_mask:0xf bank_mask:0xf bound_ctrl:1
	v_pk_add_f32 v[10:11], v[10:11], v[12:13]
	v_mul_f32_e32 v21, v35, v21
	v_fma_f32 v21, v56, v21, v64
	v_mov_b32_dpp v13, v11 row_mirror row_mask:0xf bank_mask:0xf bound_ctrl:1
	v_mov_b32_dpp v12, v10 row_mirror row_mask:0xf bank_mask:0xf bound_ctrl:1
	v_pk_add_f32 v[10:11], v[10:11], v[12:13]
	ds_bpermute_b32 v13, v70, v11
	ds_bpermute_b32 v12, v70, v10
	v_mul_f32_e32 v28, v19, v21
	v_mul_f32_e32 v19, 0x4b800000, v32
	v_cndmask_b32_e32 v19, v32, v19, vcc
	v_rsq_f32_e32 v19, v19
	s_waitcnt lgkmcnt(0)
	v_pk_add_f32 v[10:11], v[10:11], v[12:13]
	s_waitcnt vmcnt(9)
	v_mul_f32_e32 v12, v52, v76
	v_mul_f32_e32 v13, v12, v77
	v_mul_f32_e32 v21, 0x45800000, v19
	v_cndmask_b32_e32 v19, v19, v21, vcc
	v_mov_b32_dpp v13, v13 quad_perm:[1,0,3,2] row_mask:0xf bank_mask:0xf bound_ctrl:1
	v_fmac_f32_e32 v13, v12, v77
	v_mul_f32_e32 v19, v34, v19
	v_fma_f32 v29, v57, v19, v65
	v_add_f32_dpp v12, v13, v13 quad_perm:[2,3,0,1] row_mask:0xf bank_mask:0xf bound_ctrl:1
	v_mul_f32_e32 v29, v73, v29
	s_nop 0
	v_add_f32_dpp v12, v12, v12 row_half_mirror row_mask:0xf bank_mask:0xf bound_ctrl:1
	s_nop 1
	v_add_f32_dpp v19, v12, v12 row_mirror row_mask:0xf bank_mask:0xf bound_ctrl:1
	s_waitcnt vmcnt(4)
	v_mul_f32_e32 v12, v53, v79
	v_mul_f32_e32 v13, v12, v78
	ds_bpermute_b32 v21, v70, v19
	s_waitcnt lgkmcnt(0)
	v_add_f32_e32 v19, v19, v21
	v_mov_b32_dpp v13, v13 quad_perm:[1,0,3,2] row_mask:0xf bank_mask:0xf bound_ctrl:1
	v_fmac_f32_e32 v13, v12, v78
	ds_bpermute_b32 v21, v71, v19
	s_nop 0
	v_add_f32_dpp v12, v13, v13 quad_perm:[2,3,0,1] row_mask:0xf bank_mask:0xf bound_ctrl:1
	ds_bpermute_b32 v13, v71, v11
	s_nop 0
	v_add_f32_dpp v12, v12, v12 row_half_mirror row_mask:0xf bank_mask:0xf bound_ctrl:1
	s_nop 1
	v_add_f32_dpp v25, v12, v12 row_mirror row_mask:0xf bank_mask:0xf bound_ctrl:1
	ds_bpermute_b32 v27, v70, v25
	ds_bpermute_b32 v12, v71, v10
	s_waitcnt lgkmcnt(1)
	v_add_f32_e32 v27, v25, v27
	ds_bpermute_b32 v25, v71, v27
	s_waitcnt lgkmcnt(1)
	v_pk_add_f32 v[10:11], v[10:11], v[12:13]
	v_pk_add_f32 v[12:13], v[18:19], v[20:21]
	v_pk_fma_f32 v[10:11], v[10:11], s[12:13], v[22:23] op_sel_hi:[1,0,0]
	v_mov_b32_e32 v21, v13
	s_waitcnt vmcnt(1) lgkmcnt(0)
	v_pk_add_f32 v[18:19], v[26:27], v[24:25]
	v_cmp_gt_f32_e32 vcc, s31, v11
	v_mov_b32_e32 v20, v19
	v_mov_b32_e32 v19, v12
	v_pk_fma_f32 v[12:13], v[16:17], v[20:21], v[18:19]
	v_mul_f32_e32 v20, 0x4b800000, v11
	v_cndmask_b32_e32 v11, v11, v20, vcc
	v_mov_b32_dpp v17, v13 quad_perm:[1,0,3,2] row_mask:0xf bank_mask:0xf bound_ctrl:1
	v_mov_b32_dpp v16, v12 quad_perm:[1,0,3,2] row_mask:0xf bank_mask:0xf bound_ctrl:1
	v_pk_add_f32 v[16:17], v[12:13], v[16:17]
	v_rsq_f32_e32 v11, v11
	v_cmp_gt_f32_e64 s[40:41], s31, v10
	v_mov_b32_dpp v19, v17 quad_perm:[2,3,0,1] row_mask:0xf bank_mask:0xf bound_ctrl:1
	v_mov_b32_dpp v18, v16 quad_perm:[2,3,0,1] row_mask:0xf bank_mask:0xf bound_ctrl:1
	v_pk_add_f32 v[16:17], v[16:17], v[18:19]
	v_mul_f32_e32 v20, 0x45800000, v11
	v_cndmask_b32_e32 v11, v11, v20, vcc
	v_mov_b32_dpp v19, v17 row_half_mirror row_mask:0xf bank_mask:0xf bound_ctrl:1
	v_mov_b32_dpp v18, v16 row_half_mirror row_mask:0xf bank_mask:0xf bound_ctrl:1
	v_pk_add_f32 v[16:17], v[16:17], v[18:19]
	v_mul_f32_e32 v9, v9, v11
	v_mul_f32_e32 v11, 0x4b800000, v10
	v_mov_b32_dpp v19, v17 row_mirror row_mask:0xf bank_mask:0xf bound_ctrl:1
	v_mov_b32_dpp v18, v16 row_mirror row_mask:0xf bank_mask:0xf bound_ctrl:1
	v_pk_add_f32 v[16:17], v[16:17], v[18:19]
	ds_bpermute_b32 v19, v70, v17
	ds_bpermute_b32 v18, v70, v16
	v_cndmask_b32_e64 v10, v10, v11, s[40:41]
	v_rsq_f32_e32 v20, v10
	v_fma_f32 v9, v58, v9, v66
	v_mul_f32_e32 v5, v5, v9
	s_waitcnt lgkmcnt(0)
	v_pk_add_f32 v[16:17], v[16:17], v[18:19]
	ds_bpermute_b32 v19, v71, v17
	ds_bpermute_b32 v18, v71, v16
	v_mul_f32_e32 v9, 0x45800000, v20
	v_cndmask_b32_e64 v9, v20, v9, s[40:41]
	v_cvt_pk_bf16_f32 v5, v5, s0
	global_store_short v[6:7], v5, off offset:1536 sc1
	s_waitcnt lgkmcnt(0)
	v_pk_add_f32 v[16:17], v[16:17], v[18:19]
	s_nop 0
	v_pk_fma_f32 v[12:13], v[16:17], s[12:13], v[12:13] op_sel_hi:[1,0,1] neg_lo:[1,0,0] neg_hi:[1,0,0]
	s_nop 0
	v_pk_mul_f32 v[16:17], v[12:13], v[12:13]
	s_nop 1
	v_mov_b32_dpp v17, v17 quad_perm:[1,0,3,2] row_mask:0xf bank_mask:0xf bound_ctrl:1
	v_mov_b32_dpp v16, v16 quad_perm:[1,0,3,2] row_mask:0xf bank_mask:0xf bound_ctrl:1
	v_pk_fma_f32 v[16:17], v[12:13], v[12:13], v[16:17]
	s_nop 1
	v_mov_b32_dpp v19, v17 quad_perm:[2,3,0,1] row_mask:0xf bank_mask:0xf bound_ctrl:1
	v_mov_b32_dpp v18, v16 quad_perm:[2,3,0,1] row_mask:0xf bank_mask:0xf bound_ctrl:1
	v_pk_add_f32 v[16:17], v[16:17], v[18:19]
	s_nop 1
	v_mov_b32_dpp v19, v17 row_half_mirror row_mask:0xf bank_mask:0xf bound_ctrl:1
	v_mov_b32_dpp v18, v16 row_half_mirror row_mask:0xf bank_mask:0xf bound_ctrl:1
	v_pk_add_f32 v[16:17], v[16:17], v[18:19]
	s_nop 1
	v_mov_b32_dpp v19, v17 row_mirror row_mask:0xf bank_mask:0xf bound_ctrl:1
	v_mov_b32_dpp v18, v16 row_mirror row_mask:0xf bank_mask:0xf bound_ctrl:1
	v_pk_add_f32 v[16:17], v[16:17], v[18:19]
	ds_bpermute_b32 v19, v70, v17
	ds_bpermute_b32 v18, v70, v16
	s_waitcnt lgkmcnt(0)
	v_pk_add_f32 v[10:11], v[16:17], v[18:19]
	ds_bpermute_b32 v17, v71, v11
	ds_bpermute_b32 v16, v71, v10
	v_mul_f32_e32 v18, v8, v9
	s_waitcnt lgkmcnt(0)
	v_pk_add_f32 v[8:9], v[10:11], v[16:17]
	s_nop 0
	v_pk_fma_f32 v[8:9], v[8:9], s[12:13], v[22:23] op_sel_hi:[1,0,0]
	s_nop 0
	v_mul_f32_e32 v10, 0x4b800000, v9
	v_cmp_gt_f32_e32 vcc, s31, v9
	v_cmp_gt_f32_e64 s[40:41], s31, v8
	s_nop 0
	v_cndmask_b32_e32 v9, v9, v10, vcc
	v_rsq_f32_e32 v9, v9
	v_fma_f32 v10, v59, v18, v67
	v_mul_f32_e32 v10, v74, v10
	v_cvt_pk_bf16_f32 v5, v10, s0
	v_mul_f32_e32 v11, 0x45800000, v9
	v_cndmask_b32_e32 v9, v9, v11, vcc
	v_mul_f32_e32 v11, 0x4b800000, v8
	v_cndmask_b32_e64 v8, v8, v11, s[40:41]
	v_rsq_f32_e32 v8, v8
	v_mul_f32_e32 v9, v13, v9
	v_fma_f32 v9, v60, v9, v68
	v_mul_f32_e32 v9, v75, v9
	v_mul_f32_e32 v11, 0x45800000, v8
	v_cndmask_b32_e64 v8, v8, v11, s[40:41]
	v_mul_f32_e32 v8, v12, v8
	v_cvt_pk_bf16_f32 v11, v15, s0
	v_fma_f32 v8, v61, v8, v69
	global_store_short v[6:7], v11, off offset:1024 sc1
	v_cvt_pk_bf16_f32 v11, v40, s0
	s_waitcnt vmcnt(2)
	v_mul_f32_e32 v8, v14, v8
	global_store_short v[6:7], v11, off offset:1152 sc1
	v_cvt_pk_bf16_f32 v11, v28, s0
	global_store_short v[6:7], v5, off offset:1664 sc1
	v_cvt_pk_bf16_f32 v5, v9, s0
	v_cmp_lt_i32_e32 vcc, s9, v72
	global_store_short v[6:7], v11, off offset:1280 sc1
	v_cvt_pk_bf16_f32 v11, v29, s0
	global_store_short v[6:7], v5, off offset:1792 sc1
	v_cvt_pk_bf16_f32 v5, v8, s0
	s_or_b64 s[44:45], vcc, s[44:45]
	global_store_short v[6:7], v11, off offset:1408 sc1
	global_store_short v[6:7], v5, off offset:1920 sc1
	s_andn2_b64 exec, exec, s[44:45]
	s_cbranch_execnz .LBB0_114

.LBB0_136:
	ds_bpermute_b32 v35, v157, v34
	v_lshlrev_b32_e32 v38, 1, v0
	v_readlane_b32 s4, v251, 14
	v_lshlrev_b64 v[36:37], 11, v[168:169]
	v_readlane_b32 s5, v251, 15
	s_waitcnt lgkmcnt(0)
	v_add_f32_e32 v0, v34, v35
	v_div_scale_f32 v39, s[2:3], v0, v0, 1.0
	v_rcp_f32_e32 v40, v39
	v_lshl_add_u64 v[34:35], s[4:5], 0, v[36:37]
	v_div_scale_f32 v36, vcc, 1.0, v0, 1.0
	v_fma_f32 v37, -v39, v40, 1.0
	v_fmac_f32_e32 v40, v37, v40
	v_mul_f32_e32 v37, v36, v40
	v_fma_f32 v41, -v39, v37, v36
	v_fmac_f32_e32 v37, v41, v40
	v_fma_f32 v36, -v39, v37, v36
	v_div_fmas_f32 v36, v36, v40, v37
	v_div_fixup_f32 v0, v36, v0, 1.0
	v_mov_b32_e32 v39, v1
	v_pk_mul_f32 v[18:19], v[18:19], v[0:1] op_sel_hi:[1,0]
	v_pk_mul_f32 v[20:21], v[20:21], v[0:1] op_sel_hi:[1,0]
	v_lshl_add_u64 v[34:35], v[34:35], 0, v[38:39]
	v_cvt_pk_bf16_f32 v18, v18, v19
	v_cvt_pk_bf16_f32 v19, v20, v21
	v_lshlrev_b32_e32 v20, 1, v104
	v_mov_b32_e32 v21, v1
	v_pk_mul_f32 v[2:3], v[2:3], v[0:1] op_sel_hi:[1,0]
	v_pk_mul_f32 v[4:5], v[4:5], v[0:1] op_sel_hi:[1,0]
	v_lshl_add_u64 v[20:21], v[34:35], 0, v[20:21]
	v_cvt_pk_bf16_f32 v2, v2, v3
	v_cvt_pk_bf16_f32 v3, v4, v5
	global_store_dwordx2 v[20:21], v[18:19], off sc1
	v_pk_mul_f32 v[18:19], v[22:23], v[0:1] op_sel_hi:[1,0]
	v_pk_mul_f32 v[22:23], v[24:25], v[0:1] op_sel_hi:[1,0]
	global_store_dwordx2 v[20:21], v[2:3], off offset:64 sc1
	v_pk_mul_f32 v[2:3], v[6:7], v[0:1] op_sel_hi:[1,0]
	v_pk_mul_f32 v[4:5], v[8:9], v[0:1] op_sel_hi:[1,0]
	v_cvt_pk_bf16_f32 v18, v18, v19
	v_cvt_pk_bf16_f32 v19, v22, v23
	v_cvt_pk_bf16_f32 v2, v2, v3
	v_cvt_pk_bf16_f32 v3, v4, v5
	global_store_dwordx2 v[20:21], v[18:19], off offset:16 sc1
	v_pk_mul_f32 v[18:19], v[26:27], v[0:1] op_sel_hi:[1,0]
	v_pk_mul_f32 v[22:23], v[28:29], v[0:1] op_sel_hi:[1,0]
	global_store_dwordx2 v[20:21], v[2:3], off offset:80 sc1
	v_pk_mul_f32 v[2:3], v[10:11], v[0:1] op_sel_hi:[1,0]
	v_pk_mul_f32 v[4:5], v[12:13], v[0:1] op_sel_hi:[1,0]
	v_cvt_pk_bf16_f32 v18, v18, v19
	v_cvt_pk_bf16_f32 v19, v22, v23
	v_cvt_pk_bf16_f32 v2, v2, v3
	v_cvt_pk_bf16_f32 v3, v4, v5
	global_store_dwordx2 v[20:21], v[18:19], off offset:32 sc1
	v_pk_mul_f32 v[18:19], v[30:31], v[0:1] op_sel_hi:[1,0]
	v_pk_mul_f32 v[22:23], v[32:33], v[0:1] op_sel_hi:[1,0]
	global_store_dwordx2 v[20:21], v[2:3], off offset:96 sc1
	v_pk_mul_f32 v[2:3], v[14:15], v[0:1] op_sel_hi:[1,0]
	v_pk_mul_f32 v[4:5], v[16:17], v[0:1] op_sel_hi:[1,0]
	v_cvt_pk_bf16_f32 v18, v18, v19
	v_cvt_pk_bf16_f32 v19, v22, v23
	v_cvt_pk_bf16_f32 v2, v2, v3
	v_cvt_pk_bf16_f32 v3, v4, v5
	v_readlane_b32 s6, v251, 16
	v_readlane_b32 s7, v251, 17
	v_readlane_b32 s8, v251, 18
	v_readlane_b32 s9, v251, 19
	v_readlane_b32 s10, v251, 20
	v_readlane_b32 s11, v251, 21
	v_readlane_b32 s12, v251, 22
	v_readlane_b32 s13, v251, 23
	v_readlane_b32 s14, v251, 24
	v_readlane_b32 s15, v251, 25
	v_readlane_b32 s16, v251, 26
	v_readlane_b32 s17, v251, 27
	v_readlane_b32 s18, v251, 28
	v_readlane_b32 s19, v251, 29
	global_store_dwordx2 v[20:21], v[18:19], off offset:48 sc1
	global_store_dwordx2 v[20:21], v[2:3], off offset:112 sc1
	s_mov_b64 s[2:3], 0

.LBB0_147:
	s_waitcnt lgkmcnt(0)
	s_waitcnt lgkmcnt(2)
	ds_read_b128 v[54:57], v219 offset:43008
	ds_read_b128 v[58:61], v219 offset:43024
	ds_read_b128 v[62:65], v219 offset:43040
	ds_read_b128 v[66:69], v219 offset:43056
	s_lshl_b32 s56, s28, 4
	v_or_b32_e32 v163, s56, v99
	s_waitcnt lgkmcnt(2)
	v_pk_add_f32 v[56:57], v[56:57], v[60:61]
	v_pk_add_f32 v[54:55], v[54:55], v[58:59]
	s_waitcnt lgkmcnt(0)
	v_pk_add_f32 v[58:59], v[64:65], v[68:69]
	v_pk_add_f32 v[60:61], v[62:63], v[66:67]
	v_pk_add_f32 v[56:57], v[56:57], v[58:59]
	v_pk_add_f32 v[54:55], v[54:55], v[60:61]
	v_sub_u32_e32 v0, 0xff, v163
	v_pk_mov_b32 v[58:59], v[54:55], v[56:57] op_sel:[1,0]
	v_mov_b32_e32 v55, v57
	v_cndmask_b32_e64 v0, v0, v163, s[54:55]
	v_pk_add_f32 v[54:55], v[58:59], v[54:55]
	s_nop 0
	v_add_f32_e32 v56, v54, v55
	v_add_u32_e32 v54, v0, v91
	v_ashrrev_i32_e32 v55, 31, v54
	v_lshlrev_b64 v[54:55], 11, v[54:55]
	v_lshl_add_u64 v[54:55], v[168:169], 0, v[54:55]
	global_store_dword v[54:55], v56, off sc1
	s_waitcnt lgkmcnt(0)
	s_waitcnt vmcnt(7)
	ds_write_b128 v207, v[2:5] offset:20480
	s_waitcnt vmcnt(6)
	ds_write_b128 v207, v[6:9] offset:24576
	s_waitcnt vmcnt(5)
	ds_write_b128 v207, v[10:13] offset:28672
	s_waitcnt vmcnt(4)
	ds_write_b128 v207, v[14:17] offset:32768
	s_waitcnt vmcnt(3)
	ds_write_b128 v207, v[18:21] offset:36864
	s_and_saveexec_b64 s[2:3], s[48:49]
	s_cbranch_execz .LBB0_149
	s_waitcnt vmcnt(2)
	ds_write_b128 v208, v[30:33] offset:41984

.LBB0_156:
	s_waitcnt lgkmcnt(0)
	s_waitcnt lgkmcnt(2)
	ds_read_b128 v[54:57], v219 offset:43008
	ds_read_b128 v[58:61], v219 offset:43024
	ds_read_b128 v[62:65], v219 offset:43040
	ds_read_b128 v[66:69], v219 offset:43056
	v_xor_b32_e32 v70, 0xffffffef, v163
	s_waitcnt lgkmcnt(5)
	v_or_b32_e32 v0, 16, v163
	s_waitcnt lgkmcnt(2)
	v_pk_add_f32 v[56:57], v[56:57], v[60:61]
	v_pk_add_f32 v[54:55], v[54:55], v[58:59]
	s_waitcnt lgkmcnt(0)
	v_pk_add_f32 v[58:59], v[64:65], v[68:69]
	v_pk_add_f32 v[60:61], v[62:63], v[66:67]
	v_pk_add_f32 v[56:57], v[56:57], v[58:59]
	v_pk_add_f32 v[54:55], v[54:55], v[60:61]
	v_add_u32_e32 v70, 0x100, v70
	v_pk_mov_b32 v[58:59], v[54:55], v[56:57] op_sel:[1,0]
	v_mov_b32_e32 v55, v57
	v_cndmask_b32_e64 v0, v70, v0, s[54:55]
	v_pk_add_f32 v[54:55], v[58:59], v[54:55]
	s_cmp_gt_u32 s28, 13
	v_add_f32_e32 v56, v54, v55
	v_add_u32_e32 v54, v0, v91
	v_ashrrev_i32_e32 v55, 31, v54
	v_lshlrev_b64 v[54:55], 11, v[54:55]
	v_lshl_add_u64 v[54:55], v[168:169], 0, v[54:55]
	global_store_dword v[54:55], v56, off sc1
	s_waitcnt lgkmcnt(0)
	s_cselect_b64 s[2:3], -1, 0
	s_cmp_lt_u32 s28, 14
	s_cbranch_scc0 .LBB0_160
	s_waitcnt vmcnt(7)
	ds_write_b128 v207, v[22:25]
	s_waitcnt vmcnt(6)
	ds_write_b128 v207, v[26:29] offset:4096
	s_waitcnt vmcnt(5)
	ds_write_b128 v207, v[34:37] offset:8192
	s_waitcnt vmcnt(4)
	ds_write_b128 v207, v[38:41] offset:12288
	s_waitcnt vmcnt(3)
	ds_write_b128 v207, v[42:45] offset:16384
	s_and_saveexec_b64 s[20:21], s[48:49]
	s_cbranch_execz .LBB0_159
	s_waitcnt vmcnt(2)
	ds_write_b128 v220, v[46:49] offset:40960

.LBB0_169:
	ds_bpermute_b32 v35, v157, v34
	v_lshlrev_b32_e32 v38, 1, v0
	v_readlane_b32 s4, v251, 14
	v_lshlrev_b64 v[36:37], 11, v[168:169]
	v_readlane_b32 s5, v251, 15
	s_waitcnt lgkmcnt(0)
	v_add_f32_e32 v0, v34, v35
	v_div_scale_f32 v39, s[2:3], v0, v0, 1.0
	v_rcp_f32_e32 v40, v39
	v_lshl_add_u64 v[34:35], s[4:5], 0, v[36:37]
	v_div_scale_f32 v36, vcc, 1.0, v0, 1.0
	v_fma_f32 v37, -v39, v40, 1.0
	v_fmac_f32_e32 v40, v37, v40
	v_mul_f32_e32 v37, v36, v40
	v_fma_f32 v41, -v39, v37, v36
	v_fmac_f32_e32 v37, v41, v40
	v_fma_f32 v36, -v39, v37, v36
	v_div_fmas_f32 v36, v36, v40, v37
	v_div_fixup_f32 v0, v36, v0, 1.0
	v_mov_b32_e32 v39, v1
	v_pk_mul_f32 v[18:19], v[18:19], v[0:1] op_sel_hi:[1,0]
	v_pk_mul_f32 v[20:21], v[20:21], v[0:1] op_sel_hi:[1,0]
	v_lshl_add_u64 v[34:35], v[34:35], 0, v[38:39]
	v_cvt_pk_bf16_f32 v18, v18, v19
	v_cvt_pk_bf16_f32 v19, v20, v21
	v_lshlrev_b32_e32 v20, 1, v104
	v_mov_b32_e32 v21, v1
	v_pk_mul_f32 v[2:3], v[2:3], v[0:1] op_sel_hi:[1,0]
	v_pk_mul_f32 v[4:5], v[4:5], v[0:1] op_sel_hi:[1,0]
	v_lshl_add_u64 v[20:21], v[34:35], 0, v[20:21]
	v_cvt_pk_bf16_f32 v2, v2, v3
	v_cvt_pk_bf16_f32 v3, v4, v5
	global_store_dwordx2 v[20:21], v[18:19], off sc1
	v_pk_mul_f32 v[18:19], v[22:23], v[0:1] op_sel_hi:[1,0]
	v_pk_mul_f32 v[22:23], v[24:25], v[0:1] op_sel_hi:[1,0]
	global_store_dwordx2 v[20:21], v[2:3], off offset:64 sc1
	v_pk_mul_f32 v[2:3], v[6:7], v[0:1] op_sel_hi:[1,0]
	v_pk_mul_f32 v[4:5], v[8:9], v[0:1] op_sel_hi:[1,0]
	v_cvt_pk_bf16_f32 v18, v18, v19
	v_cvt_pk_bf16_f32 v19, v22, v23
	v_cvt_pk_bf16_f32 v2, v2, v3
	v_cvt_pk_bf16_f32 v3, v4, v5
	global_store_dwordx2 v[20:21], v[18:19], off offset:16 sc1
	v_pk_mul_f32 v[18:19], v[26:27], v[0:1] op_sel_hi:[1,0]
	v_pk_mul_f32 v[22:23], v[28:29], v[0:1] op_sel_hi:[1,0]
	global_store_dwordx2 v[20:21], v[2:3], off offset:80 sc1
	v_pk_mul_f32 v[2:3], v[10:11], v[0:1] op_sel_hi:[1,0]
	v_pk_mul_f32 v[4:5], v[12:13], v[0:1] op_sel_hi:[1,0]
	v_cvt_pk_bf16_f32 v18, v18, v19
	v_cvt_pk_bf16_f32 v19, v22, v23
	v_cvt_pk_bf16_f32 v2, v2, v3
	v_cvt_pk_bf16_f32 v3, v4, v5
	global_store_dwordx2 v[20:21], v[18:19], off offset:32 sc1
	v_pk_mul_f32 v[18:19], v[30:31], v[0:1] op_sel_hi:[1,0]
	v_pk_mul_f32 v[22:23], v[32:33], v[0:1] op_sel_hi:[1,0]
	global_store_dwordx2 v[20:21], v[2:3], off offset:96 sc1
	v_pk_mul_f32 v[2:3], v[14:15], v[0:1] op_sel_hi:[1,0]
	v_pk_mul_f32 v[4:5], v[16:17], v[0:1] op_sel_hi:[1,0]
	v_cvt_pk_bf16_f32 v18, v18, v19
	v_cvt_pk_bf16_f32 v19, v22, v23
	v_cvt_pk_bf16_f32 v2, v2, v3
	v_cvt_pk_bf16_f32 v3, v4, v5
	v_readlane_b32 s6, v251, 16
	v_readlane_b32 s7, v251, 17
	v_readlane_b32 s8, v251, 18
	v_readlane_b32 s9, v251, 19
	v_readlane_b32 s10, v251, 20
	v_readlane_b32 s11, v251, 21
	v_readlane_b32 s12, v251, 22
	v_readlane_b32 s13, v251, 23
	v_readlane_b32 s14, v251, 24
	v_readlane_b32 s15, v251, 25
	v_readlane_b32 s16, v251, 26
	v_readlane_b32 s17, v251, 27
	v_readlane_b32 s18, v251, 28
	v_readlane_b32 s19, v251, 29
	global_store_dwordx2 v[20:21], v[18:19], off offset:48 sc1
	global_store_dwordx2 v[20:21], v[2:3], off offset:112 sc1

.LBB0_191:
	s_and_saveexec_b64 s[76:77], s[52:53]
	s_cbranch_execz .LBB0_193
	s_waitcnt lgkmcnt(0)
	s_waitcnt lgkmcnt(2)
	ds_read_b128 v[54:57], v230 offset:43008
	ds_read_b128 v[58:61], v230 offset:43024
	ds_read_b128 v[62:65], v230 offset:43040
	ds_read_b128 v[66:69], v230 offset:43056
	v_lshl_or_b32 v70, s79, 4, v99
	v_sub_u32_e32 v71, 0xfff, v70
	s_waitcnt lgkmcnt(2)
	v_pk_add_f32 v[56:57], v[56:57], v[60:61]
	v_pk_add_f32 v[54:55], v[54:55], v[58:59]
	s_waitcnt lgkmcnt(0)
	v_pk_add_f32 v[58:59], v[64:65], v[68:69]
	v_pk_add_f32 v[60:61], v[62:63], v[66:67]
	v_pk_add_f32 v[56:57], v[56:57], v[58:59]
	v_pk_add_f32 v[54:55], v[54:55], v[60:61]
	v_cndmask_b32_e32 v70, v71, v70, vcc
	v_pk_mov_b32 v[58:59], v[54:55], v[56:57] op_sel:[1,0]
	v_mov_b32_e32 v55, v57
	v_pk_add_f32 v[54:55], v[58:59], v[54:55]
	s_nop 0
	v_add_f32_e32 v56, v54, v55
	v_add_u32_e32 v54, s78, v70
	v_ashrrev_i32_e32 v55, 31, v54
	v_lshlrev_b64 v[54:55], 11, v[54:55]
	v_lshl_add_u64 v[54:55], v[94:95], 0, v[54:55]
	global_store_dword v[54:55], v56, off sc1
	s_waitcnt lgkmcnt(0)

.LBB0_199:
	s_cmp_lg_u32 s79, 0
	s_cselect_b64 s[50:51], -1, 0
	s_and_b64 s[50:51], s[44:45], s[50:51]
	s_and_saveexec_b64 s[76:77], s[50:51]
	s_cbranch_execz .LBB0_201
	s_waitcnt lgkmcnt(7)
	ds_read_b128 v[54:57], v230 offset:59392
	ds_read_b128 v[58:61], v230 offset:59408
	ds_read_b128 v[62:65], v230 offset:59424
	ds_read_b128 v[66:69], v230 offset:59440
	v_lshl_add_u32 v70, s79, 4, v227
	v_sub_u32_e32 v71, 0xfff, v70
	s_waitcnt lgkmcnt(2)
	v_pk_add_f32 v[56:57], v[56:57], v[60:61]
	v_pk_add_f32 v[54:55], v[54:55], v[58:59]
	s_waitcnt lgkmcnt(0)
	v_pk_add_f32 v[58:59], v[64:65], v[68:69]
	v_pk_add_f32 v[60:61], v[62:63], v[66:67]
	v_pk_add_f32 v[56:57], v[56:57], v[58:59]
	v_pk_add_f32 v[54:55], v[54:55], v[60:61]
	v_cndmask_b32_e32 v70, v71, v70, vcc
	v_pk_mov_b32 v[58:59], v[54:55], v[56:57] op_sel:[1,0]
	v_mov_b32_e32 v55, v57
	v_pk_add_f32 v[54:55], v[58:59], v[54:55]
	s_nop 0
	v_add_f32_e32 v56, v54, v55
	v_add_u32_e32 v54, s78, v70
	v_ashrrev_i32_e32 v55, 31, v54
	v_lshlrev_b64 v[54:55], 11, v[54:55]
	v_lshl_add_u64 v[54:55], v[94:95], 0, v[54:55]
	global_store_dword v[54:55], v56, off sc1

.LBB0_208:
	s_and_saveexec_b64 s[76:77], s[52:53]
	s_cbranch_execz .LBB0_210
	s_waitcnt lgkmcnt(0)
	s_waitcnt lgkmcnt(2)
	ds_read_b128 v[54:57], v231 offset:43008
	ds_read_b128 v[58:61], v231 offset:43024
	ds_read_b128 v[62:65], v231 offset:43040
	ds_read_b128 v[66:69], v231 offset:43056
	v_lshl_or_b32 v70, s28, 4, v99
	v_sub_u32_e32 v71, 0xfff, v70
	s_waitcnt lgkmcnt(2)
	v_pk_add_f32 v[56:57], v[56:57], v[60:61]
	v_pk_add_f32 v[54:55], v[54:55], v[58:59]
	s_waitcnt lgkmcnt(0)
	v_pk_add_f32 v[58:59], v[64:65], v[68:69]
	v_pk_add_f32 v[60:61], v[62:63], v[66:67]
	v_pk_add_f32 v[56:57], v[56:57], v[58:59]
	v_pk_add_f32 v[54:55], v[54:55], v[60:61]
	v_cndmask_b32_e32 v70, v71, v70, vcc
	v_pk_mov_b32 v[58:59], v[54:55], v[56:57] op_sel:[1,0]
	v_mov_b32_e32 v55, v57
	v_pk_add_f32 v[54:55], v[58:59], v[54:55]
	s_nop 0
	v_add_f32_e32 v56, v54, v55
	v_add_u32_e32 v54, s78, v70
	v_ashrrev_i32_e32 v55, 31, v54
	v_lshlrev_b64 v[54:55], 11, v[54:55]
	v_lshl_add_u64 v[54:55], v[94:95], 0, v[54:55]
	global_store_dword v[54:55], v56, off sc1
	s_waitcnt lgkmcnt(0)

.LBB0_219:
	s_waitcnt lgkmcnt(2)
	ds_read_b128 v[54:57], v230 offset:43008
	ds_read_b128 v[58:61], v230 offset:43024
	ds_read_b128 v[62:65], v230 offset:43040
	ds_read_b128 v[66:69], v230 offset:43056
	v_lshl_add_u32 v70, s28, 4, v227
	v_sub_u32_e32 v71, 0xfff, v70
	s_waitcnt lgkmcnt(2)
	v_pk_add_f32 v[56:57], v[56:57], v[60:61]
	v_pk_add_f32 v[54:55], v[54:55], v[58:59]
	s_waitcnt lgkmcnt(0)
	v_pk_add_f32 v[58:59], v[64:65], v[68:69]
	v_pk_add_f32 v[60:61], v[62:63], v[66:67]
	v_pk_add_f32 v[56:57], v[56:57], v[58:59]
	v_pk_add_f32 v[54:55], v[54:55], v[60:61]
	v_cndmask_b32_e32 v70, v71, v70, vcc
	v_pk_mov_b32 v[58:59], v[54:55], v[56:57] op_sel:[1,0]
	v_mov_b32_e32 v55, v57
	v_pk_add_f32 v[54:55], v[58:59], v[54:55]
	s_nop 0
	v_add_f32_e32 v56, v54, v55
	v_add_u32_e32 v54, s78, v70
	v_ashrrev_i32_e32 v55, 31, v54
	v_lshlrev_b64 v[54:55], 11, v[54:55]
	v_lshl_add_u64 v[54:55], v[94:95], 0, v[54:55]
	global_store_dword v[54:55], v56, off sc1
	s_branch .LBB0_183
.LBB0_220:
	v_readlane_b32 s4, v255, 8
	v_readlane_b32 s5, v255, 9
	s_and_saveexec_b64 s[20:21], s[4:5]
	s_xor_b64 s[20:21], exec, s[20:21]
	s_cbranch_execz .LBB0_222
	s_waitcnt vmcnt(5)
	ds_read_b128 v[2:5], v230 offset:59392
	s_waitcnt vmcnt(4)
	ds_read_b128 v[6:9], v230 offset:59408
	s_waitcnt vmcnt(3)
	ds_read_b128 v[10:13], v230 offset:59424
	s_waitcnt vmcnt(2)
	ds_read_b128 v[14:17], v230 offset:59440
	v_sub_u32_e32 v0, 0xfff, v232
	v_cndmask_b32_e32 v0, v0, v232, vcc
	s_waitcnt lgkmcnt(2)
	v_pk_add_f32 v[4:5], v[4:5], v[8:9]
	v_pk_add_f32 v[2:3], v[2:3], v[6:7]
	s_waitcnt lgkmcnt(0)
	v_pk_add_f32 v[6:7], v[12:13], v[16:17]
	v_pk_add_f32 v[8:9], v[10:11], v[14:15]
	v_pk_add_f32 v[4:5], v[4:5], v[6:7]
	v_pk_add_f32 v[2:3], v[2:3], v[8:9]
	s_nop 0
	v_pk_mov_b32 v[6:7], v[2:3], v[4:5] op_sel:[1,0]
	v_mov_b32_e32 v3, v5
	v_pk_add_f32 v[2:3], v[6:7], v[2:3]
	v_lshlrev_b32_e32 v4, 2, v90
	v_add_f32_e32 v6, v2, v3
	v_or_b32_e32 v2, s78, v0
	v_ashrrev_i32_e32 v3, 31, v2
	v_lshlrev_b64 v[2:3], 11, v[2:3]
	v_lshl_add_u64 v[2:3], s[2:3], 0, v[2:3]
	v_lshl_add_u64 v[2:3], v[92:93], 2, v[2:3]
	v_mov_b32_e32 v5, v1
	v_lshl_add_u64 v[2:3], v[2:3], 0, v[4:5]
	global_store_dword v[2:3], v6, off sc1

.LBB0_287:
	s_or_b64 exec, exec, s[2:3]
	s_waitcnt lgkmcnt(4)
	v_cvt_pk_bf16_f32 v17, v16, v17
	v_cvt_pk_bf16_f32 v16, v14, v15
	v_cvt_pk_bf16_f32 v14, v6, v7
	v_ashrrev_i32_e32 v6, 31, v0
	v_mul_lo_u32 v7, v5, v0
	v_mul_lo_u32 v6, v4, v6
	v_mad_u64_u32 v[4:5], s[2:3], v4, v0, 0
	v_add3_u32 v5, v5, v6, v7
	v_lshl_add_u64 v[2:3], v[4:5], 1, v[2:3]
	v_lshl_add_u64 v[2:3], v[10:11], 1, v[2:3]
	v_mov_b32_e32 v167, v1
	v_cvt_pk_bf16_f32 v15, v8, v9
	v_lshl_add_u64 v[2:3], v[2:3], 0, v[166:167]
	s_waitcnt lgkmcnt(0)
	v_cvt_pk_bf16_f32 v25, v24, v25
	v_cvt_pk_bf16_f32 v24, v22, v23
	v_cvt_pk_bf16_f32 v23, v20, v21
	v_cvt_pk_bf16_f32 v22, v18, v19
	global_store_dwordx4 v[2:3], v[14:17], off sc1
	global_store_dwordx4 v[2:3], v[22:25], off offset:16 sc1
	s_barrier

.LBB0_293:
	v_lshl_add_u64 v[22:23], v[20:21], 0, s[2:3]
	v_add_co_u32_e32 v30, vcc, s22, v22
	ds_read_b128 v[26:29], v24
	ds_read_b128 v[2:5], v24 offset:16
	v_addc_co_u32_e32 v31, vcc, 0, v23, vcc
	global_load_dwordx4 v[30:33], v[30:31], off
	s_mov_b32 s20, 0x2409000
	s_add_u32 s2, s2, 0x48000
	s_addc_u32 s3, s3, 0
	s_cmp_eq_u32 s2, 0x240000
	s_waitcnt vmcnt(0) lgkmcnt(1)
	v_pk_fma_f32 v[34:35], v[30:31], v[26:27], v[6:7] op_sel_hi:[1,0,1]
	v_pk_fma_f32 v[36:37], v[32:33], v[26:27], v[8:9] op_sel_hi:[1,0,1]
	ds_read_b128 v[6:9], v24 offset:4096
	s_waitcnt lgkmcnt(0)
	v_pk_fma_f32 v[38:39], v[30:31], v[6:7], v[14:15] op_sel_hi:[1,0,1]
	v_pk_fma_f32 v[40:41], v[32:33], v[6:7], v[16:17] op_sel_hi:[1,0,1]
	ds_read_b128 v[14:17], v24 offset:8192
	s_waitcnt lgkmcnt(0)
	v_pk_fma_f32 v[30:31], v[30:31], v[14:15], v[10:11] op_sel_hi:[1,0,1]
	v_add_co_u32_e32 v10, vcc, s20, v22
	v_pk_fma_f32 v[32:33], v[32:33], v[14:15], v[12:13] op_sel_hi:[1,0,1]
	s_nop 0
	v_addc_co_u32_e32 v11, vcc, 0, v23, vcc
	global_load_dwordx4 v[10:13], v[10:11], off
	s_mov_b32 s20, 0x2412000
	s_waitcnt vmcnt(0)
	v_pk_fma_f32 v[34:35], v[10:11], v[26:27], v[34:35] op_sel:[0,1,0]
	v_pk_fma_f32 v[26:27], v[12:13], v[26:27], v[36:37] op_sel:[0,1,0]
	v_pk_fma_f32 v[36:37], v[10:11], v[6:7], v[38:39] op_sel:[0,1,0]
	v_pk_fma_f32 v[30:31], v[10:11], v[14:15], v[30:31] op_sel:[0,1,0]
	v_add_co_u32_e32 v10, vcc, s20, v22
	v_pk_fma_f32 v[6:7], v[12:13], v[6:7], v[40:41] op_sel:[0,1,0]
	s_nop 0
	v_addc_co_u32_e32 v11, vcc, 0, v23, vcc
	v_pk_fma_f32 v[14:15], v[12:13], v[14:15], v[32:33] op_sel:[0,1,0]
	global_load_dwordx4 v[10:13], v[10:11], off
	s_mov_b32 s20, 0x241b000
	s_waitcnt vmcnt(0)
	v_pk_fma_f32 v[32:33], v[10:11], v[28:29], v[34:35] op_sel_hi:[1,0,1]
	v_pk_fma_f32 v[34:35], v[10:11], v[8:9], v[36:37] op_sel_hi:[1,0,1]
	v_pk_fma_f32 v[30:31], v[10:11], v[16:17], v[30:31] op_sel_hi:[1,0,1]
	v_add_co_u32_e32 v10, vcc, s20, v22
	v_pk_fma_f32 v[26:27], v[12:13], v[28:29], v[26:27] op_sel_hi:[1,0,1]
	s_nop 0
	v_addc_co_u32_e32 v11, vcc, 0, v23, vcc
	v_pk_fma_f32 v[6:7], v[12:13], v[8:9], v[6:7] op_sel_hi:[1,0,1]
	v_pk_fma_f32 v[14:15], v[12:13], v[16:17], v[14:15] op_sel_hi:[1,0,1]
	global_load_dwordx4 v[10:13], v[10:11], off
	v_mov_b32_e32 v8, v29
	s_mov_b32 s20, 0x2424000
	s_waitcnt vmcnt(0)
	v_pk_fma_f32 v[28:29], v[10:11], v[8:9], v[32:33] op_sel_hi:[1,0,1]
	v_pk_fma_f32 v[26:27], v[12:13], v[8:9], v[26:27] op_sel_hi:[1,0,1]
	v_mov_b32_e32 v8, v9
	v_pk_fma_f32 v[32:33], v[10:11], v[8:9], v[34:35] op_sel_hi:[1,0,1]
	v_pk_fma_f32 v[34:35], v[12:13], v[8:9], v[6:7] op_sel_hi:[1,0,1]
	v_mov_b32_e32 v6, v17
	v_pk_fma_f32 v[16:17], v[10:11], v[6:7], v[30:31] op_sel_hi:[1,0,1]
	v_pk_fma_f32 v[14:15], v[12:13], v[6:7], v[14:15] op_sel_hi:[1,0,1]
	v_add_co_u32_e32 v6, vcc, s20, v22
	ds_read_b128 v[10:13], v24 offset:4112
	s_nop 0
	v_addc_co_u32_e32 v7, vcc, 0, v23, vcc
	global_load_dwordx4 v[6:9], v[6:7], off
	s_mov_b32 s20, 0x242d000
	s_waitcnt vmcnt(0)
	v_pk_fma_f32 v[30:31], v[6:7], v[2:3], v[28:29] op_sel_hi:[1,0,1]
	v_pk_fma_f32 v[36:37], v[8:9], v[2:3], v[26:27] op_sel_hi:[1,0,1]
	ds_read_b128 v[26:29], v24 offset:8208
	s_waitcnt lgkmcnt(1)
	v_pk_fma_f32 v[32:33], v[6:7], v[10:11], v[32:33] op_sel_hi:[1,0,1]
	v_pk_fma_f32 v[34:35], v[8:9], v[10:11], v[34:35] op_sel_hi:[1,0,1]
	v_add_u32_e32 v24, 32, v24
	s_waitcnt lgkmcnt(0)
	v_pk_fma_f32 v[16:17], v[6:7], v[26:27], v[16:17] op_sel_hi:[1,0,1]
	v_add_co_u32_e32 v6, vcc, s20, v22
	v_pk_fma_f32 v[14:15], v[8:9], v[26:27], v[14:15] op_sel_hi:[1,0,1]
	s_nop 0
	v_addc_co_u32_e32 v7, vcc, 0, v23, vcc
	global_load_dwordx4 v[6:9], v[6:7], off
	s_mov_b32 s20, 0x2436000
	s_waitcnt vmcnt(0)
	v_pk_fma_f32 v[30:31], v[6:7], v[2:3], v[30:31] op_sel:[0,1,0]
	v_pk_fma_f32 v[32:33], v[6:7], v[10:11], v[32:33] op_sel:[0,1,0]
	v_pk_fma_f32 v[16:17], v[6:7], v[26:27], v[16:17] op_sel:[0,1,0]
	v_add_co_u32_e32 v6, vcc, s20, v22
	v_pk_fma_f32 v[2:3], v[8:9], v[2:3], v[36:37] op_sel:[0,1,0]
	s_nop 0
	v_addc_co_u32_e32 v7, vcc, 0, v23, vcc
	v_pk_fma_f32 v[10:11], v[8:9], v[10:11], v[34:35] op_sel:[0,1,0]
	v_pk_fma_f32 v[14:15], v[8:9], v[26:27], v[14:15] op_sel:[0,1,0]
	global_load_dwordx4 v[6:9], v[6:7], off
	s_mov_b32 s20, 0x243f000
	s_waitcnt vmcnt(0)
	v_pk_fma_f32 v[26:27], v[6:7], v[4:5], v[30:31] op_sel_hi:[1,0,1]
	v_pk_fma_f32 v[34:35], v[6:7], v[12:13], v[32:33] op_sel_hi:[1,0,1]
	v_pk_fma_f32 v[36:37], v[6:7], v[28:29], v[16:17] op_sel_hi:[1,0,1]
	v_add_co_u32_e32 v6, vcc, s20, v22
	v_pk_fma_f32 v[2:3], v[8:9], v[4:5], v[2:3] op_sel_hi:[1,0,1]
	s_nop 0
	v_addc_co_u32_e32 v7, vcc, 0, v23, vcc
	global_load_dwordx4 v[30:33], v[6:7], off
	v_mov_b32_e32 v4, v5
	v_pk_fma_f32 v[10:11], v[8:9], v[12:13], v[10:11] op_sel_hi:[1,0,1]
	v_pk_fma_f32 v[38:39], v[8:9], v[28:29], v[14:15] op_sel_hi:[1,0,1]
	s_waitcnt vmcnt(0)
	v_pk_fma_f32 v[8:9], v[32:33], v[4:5], v[2:3] op_sel_hi:[1,0,1]
	v_mov_b32_e32 v2, v13
	v_pk_fma_f32 v[14:15], v[30:31], v[2:3], v[34:35] op_sel_hi:[1,0,1]
	v_pk_fma_f32 v[16:17], v[32:33], v[2:3], v[10:11] op_sel_hi:[1,0,1]
	v_mov_b32_e32 v2, v29
	v_pk_fma_f32 v[6:7], v[30:31], v[4:5], v[26:27] op_sel_hi:[1,0,1]
	v_pk_fma_f32 v[10:11], v[30:31], v[2:3], v[36:37] op_sel_hi:[1,0,1]
	v_pk_fma_f32 v[12:13], v[32:33], v[2:3], v[38:39] op_sel_hi:[1,0,1]
	s_cbranch_scc0 .LBB0_293
	v_readlane_b32 s4, v255, 6
	v_readlane_b32 s5, v255, 7
	ds_write_b128 v235, v[6:9] offset:12288
	ds_write_b128 v235, v[14:17] offset:12544
	ds_write_b128 v235, v[10:13] offset:12800
	s_waitcnt lgkmcnt(0)
	s_barrier
	s_and_saveexec_b64 s[2:3], s[4:5]
	s_cbranch_execz .LBB0_118
	v_add_u32_e32 v6, 1, v0
	s_movk_i32 s20, 0x2400
	v_mad_u64_u32 v[2:3], s[20:21], v6, s20, v[18:19]
	v_or_b32_e32 v2, v2, v106
	v_readlane_b32 s4, v254, 25
	v_ashrrev_i32_e32 v3, 31, v2
	v_readlane_b32 s6, v254, 27
	v_readlane_b32 s7, v254, 28
	ds_read2st64_b32 v[4:5], v236 offset0:51 offset1:54
	v_readlane_b32 s5, v254, 26
	v_lshl_add_u64 v[2:3], v[2:3], 2, s[6:7]
	global_load_dword v0, v[2:3], off
	ds_read2st64_b32 v[2:3], v234 offset0:48 offset1:60
	v_readlane_b32 s8, v254, 29
	v_readlane_b32 s9, v254, 30
	v_readlane_b32 s10, v254, 31
	v_readlane_b32 s11, v254, 32
	v_readlane_b32 s12, v254, 33
	v_readlane_b32 s13, v254, 34
	v_readlane_b32 s14, v254, 35
	v_readlane_b32 s15, v254, 36
	v_readlane_b32 s16, v254, 37
	v_readlane_b32 s17, v254, 38
	v_readlane_b32 s18, v254, 39
	v_readlane_b32 s19, v254, 40
	v_readlane_b32 s4, v253, 33
	v_readlane_b32 s10, v253, 39
	v_readlane_b32 s11, v253, 40
	v_readlane_b32 s5, v253, 34
	v_readlane_b32 s6, v253, 35
	v_readlane_b32 s7, v253, 36
	v_readlane_b32 s8, v253, 37
	v_readlane_b32 s9, v253, 38
	v_readlane_b32 s12, v253, 41
	v_readlane_b32 s13, v253, 42
	v_readlane_b32 s14, v253, 43
	v_readlane_b32 s15, v253, 44
	v_readlane_b32 s16, v253, 45
	v_readlane_b32 s17, v253, 46
	v_readlane_b32 s18, v253, 47
	v_readlane_b32 s19, v253, 48
	s_waitcnt vmcnt(0) lgkmcnt(0)
	v_add_f32_e32 v0, v0, v2
	v_add_f32_e32 v0, v0, v4
	v_add_f32_e32 v0, v0, v5
	ds_read2st64_b32 v[4:5], v236 offset0:57 offset1:63
	s_waitcnt lgkmcnt(0)
	v_add_f32_e32 v0, v0, v4
	v_add_f32_e32 v0, v0, v3
	ds_read2st64_b32 v[2:3], v236 offset0:66 offset1:69
	v_add_f32_e32 v0, v0, v5
	ds_read2st64_b32 v[4:5], v236 offset0:75 offset1:78
	s_waitcnt lgkmcnt(1)
	v_add_f32_e32 v0, v0, v2
	v_add_f32_e32 v0, v0, v3
	ds_read2st64_b32 v[2:3], v234 offset0:72 offset1:84
	s_waitcnt lgkmcnt(0)
	v_add_f32_e32 v0, v0, v2
	v_add_f32_e32 v0, v0, v4
	v_add_f32_e32 v0, v0, v5
	ds_read2st64_b32 v[4:5], v236 offset0:81 offset1:87
	s_waitcnt lgkmcnt(0)
	v_add_f32_e32 v0, v0, v4
	v_add_f32_e32 v0, v0, v3
	ds_read2st64_b32 v[2:3], v236 offset0:90 offset1:93
	v_add_f32_e32 v0, v0, v5
	v_lshlrev_b32_e32 v4, 2, v106
	v_mov_b32_e32 v5, v1
	s_waitcnt lgkmcnt(0)
	v_add_f32_e32 v0, v0, v2
	v_add_f32_e32 v7, v0, v3
	v_and_b32_e32 v0, 12, v185
	v_add_u32_e32 v0, v6, v0
	v_mov_b64_e32 v[2:3], s[10:11]
	v_mad_i64_i32 v[2:3], s[20:21], v0, s30, v[2:3]
	v_lshl_add_u64 v[2:3], v[18:19], 2, v[2:3]
	v_lshl_add_u64 v[2:3], v[2:3], 0, v[4:5]
	global_store_dword v[2:3], v7, off sc1
	s_branch .LBB0_118
.LBB0_296:
	v_ashrrev_i32_e32 v91, 31, v90
	s_waitcnt vmcnt(6)
	v_lshl_add_u64 v[2:3], v[90:91], 2, s[88:89]
	v_or_b32_e32 v2, v2, v159
	v_readlane_b32 s2, v251, 32
	v_lshlrev_b64 v[2:3], 17, v[2:3]
	v_readlane_b32 s3, v251, 33
	v_lshlrev_b32_e32 v4, 14, v157
	v_mov_b32_e32 v5, v1
	v_lshl_add_u64 v[2:3], s[2:3], 0, v[2:3]
	v_lshl_add_u64 v[2:3], v[2:3], 0, v[4:5]
	v_lshlrev_b32_e32 v4, 8, v161
	v_lshl_add_u64 v[2:3], v[2:3], 0, v[4:5]
	v_lshlrev_b32_e32 v4, 2, v108
	v_lshl_add_u64 v[2:3], v[2:3], 0, v[4:5]
	global_store_dwordx4 v[2:3], v[50:53], off sc1
	s_cbranch_execz .LBB0_164
	s_branch .LBB0_170

.LBB0_304:
	s_or_b64 exec, exec, s[2:3]
	global_load_dword v236, v[38:39], off
	global_load_dword v237, v[30:31], off offset:1024
	global_load_dword v238, v[30:31], off offset:1280
	global_load_dword v239, v[30:31], off offset:1536
	global_load_dword v240, v[40:41], off
	global_load_dword v241, v[30:31], off offset:2048
	global_load_dword v242, v[78:79], off
	global_load_dword v243, v[30:31], off offset:2304
	v_lshlrev_b64 v[136:137], 9, v[106:107]
	v_add_f32_e32 v111, v111, v169
	v_fma_f32 v111, v111, 0.5, -v109
	v_readlane_b32 s4, v252, 48
	v_readlane_b32 s12, v252, 56
	v_readlane_b32 s13, v252, 57
	s_mov_b32 s4, 0xf800000
	v_readlane_b32 s10, v252, 54
	v_readlane_b32 s11, v252, 55
	v_readlane_b32 s8, v252, 52
	v_readlane_b32 s9, v252, 53
	v_lshl_add_u64 v[112:113], s[10:11], 0, v[144:145]
	v_add_f32_e32 v101, v101, v103
	v_fma_f32 v101, v101, 0.5, -v99
	v_add_f32_e32 v95, v95, v97
	v_fma_f32 v95, v95, 0.5, -v91
	v_readlane_b32 s5, v252, 49
	v_readlane_b32 s6, v252, 50
	v_readlane_b32 s7, v252, 51
	v_readlane_b32 s14, v252, 58
	v_readlane_b32 s15, v252, 59
	v_readlane_b32 s16, v252, 60
	v_readlane_b32 s17, v252, 61
	v_readlane_b32 s18, v252, 62
	v_readlane_b32 s19, v252, 63
	s_waitcnt vmcnt(7)
	v_mov_b32_e32 v107, v236
	global_load_dword v244, v[78:79], off offset:256
	v_fmac_f32_e32 v109, v111, v107
	v_mov_b32_e32 v111, v1
	v_lshl_add_u64 v[110:111], v[142:143], 0, v[110:111]
	global_store_dword v[110:111], v109, off sc1
	v_add_f32_e32 v109, v165, v171
	v_fma_f32 v109, v109, 0.5, -v168
	s_waitcnt vmcnt(8)
	v_mov_b32_e32 v107, v237
	global_load_dword v245, v[30:31], off offset:2560
	v_fmac_f32_e32 v168, v109, v107
	global_store_dword v[146:147], v168, off offset:1024 sc1
	v_add_f32_e32 v109, v170, v175
	v_fma_f32 v109, v109, 0.5, -v173
	s_waitcnt vmcnt(9)
	v_mov_b32_e32 v107, v238
	global_load_dword v246, v[78:79], off offset:512
	v_fmac_f32_e32 v173, v109, v107
	global_store_dword v[146:147], v173, off offset:1280 sc1
	v_add_f32_e32 v109, v174, v179
	v_fma_f32 v109, v109, 0.5, -v176
	s_waitcnt vmcnt(10)
	v_mov_b32_e32 v107, v239
	global_load_dword v247, v[42:43], off
	v_fmac_f32_e32 v176, v109, v107
	global_store_dword v[146:147], v176, off offset:1536 sc1
	v_add_f32_e32 v109, v178, v183
	v_fma_f32 v109, v109, 0.5, -v177
	s_waitcnt vmcnt(11)
	v_mov_b32_e32 v107, v240
	global_load_dword v248, v[80:81], off offset:-2048
	v_fmac_f32_e32 v177, v109, v107
	v_mov_b32_e32 v109, v1
	v_lshl_add_u64 v[108:109], v[142:143], 0, v[108:109]
	global_store_dword v[108:109], v177, off sc1
	v_add_f32_e32 v108, v182, v184
	v_fma_f32 v108, v108, 0.5, -v180
	s_waitcnt vmcnt(12)
	v_mov_b32_e32 v107, v241
	global_load_dword v249, v[30:31], off offset:3072
	v_fmac_f32_e32 v180, v108, v107
	v_lshl_add_u64 v[108:109], v[136:137], 0, v[16:17]
	v_lshlrev_b64 v[108:109], 2, v[108:109]
	v_lshl_add_u64 v[110:111], s[12:13], 0, v[108:109]
	global_store_dword v[110:111], v180, off offset:-2048 sc1
	v_lshl_add_u64 v[108:109], s[8:9], 0, v[108:109]
	s_waitcnt vmcnt(13)
	v_mov_b32_e32 v107, v242
	global_load_dword v250, v[78:79], off offset:1024
	v_mul_f32_e32 v107, v180, v107
	v_mul_f32_e32 v110, v107, v107
	s_nop 1
	v_mov_b32_dpp v110, v110 quad_perm:[1,0,3,2] row_mask:0xf bank_mask:0xf bound_ctrl:1
	v_fmac_f32_e32 v110, v107, v107
	s_nop 1
	v_add_f32_dpp v110, v110, v110 quad_perm:[2,3,0,1] row_mask:0xf bank_mask:0xf bound_ctrl:1
	s_nop 1
	v_add_f32_dpp v110, v110, v110 row_half_mirror row_mask:0xf bank_mask:0xf bound_ctrl:1
	s_nop 1
	v_add_f32_dpp v110, v110, v110 row_mirror row_mask:0xf bank_mask:0xf bound_ctrl:1
	ds_bpermute_b32 v111, v87, v110
	s_waitcnt lgkmcnt(0)
	v_add_f32_e32 v110, v110, v111
	ds_bpermute_b32 v111, v89, v110
	s_waitcnt lgkmcnt(0)
	v_add_f32_e32 v110, v110, v111
	v_cmp_gt_f32_e32 vcc, s4, v110
	v_mul_f32_e32 v111, 0x4f800000, v110
	s_nop 0
	v_cndmask_b32_e32 v110, v110, v111, vcc
	v_sqrt_f32_e32 v111, v110
	s_nop 0
	v_add_u32_e32 v142, -1, v111
	v_fma_f32 v143, -v142, v111, v110
	v_cmp_ge_f32_e64 s[44:45], 0, v143
	v_add_u32_e32 v143, 1, v111
	s_nop 0
	v_cndmask_b32_e64 v142, v111, v142, s[44:45]
	v_fma_f32 v111, -v143, v111, v110
	v_cmp_lt_f32_e64 s[44:45], 0, v111
	s_nop 1
	v_cndmask_b32_e64 v111, v142, v143, s[44:45]
	v_mul_f32_e32 v142, 0x37800000, v111
	v_cndmask_b32_e32 v111, v111, v142, vcc
	v_cmp_class_f32_e32 vcc, v110, v187
	s_nop 1
	v_cndmask_b32_e32 v110, v111, v110, vcc
	v_max_f32_e32 v110, 0x2b8cbccc, v110
	v_div_scale_f32 v111, s[2:3], v110, v110, v107
	v_rcp_f32_e32 v142, v111
	s_nop 0
	v_fma_f32 v143, -v111, v142, 1.0
	v_fmac_f32_e32 v142, v143, v142
	v_div_scale_f32 v143, vcc, v107, v110, v107
	v_mul_f32_e32 v144, v143, v142
	v_fma_f32 v145, -v111, v144, v143
	v_fmac_f32_e32 v144, v145, v142
	v_fma_f32 v111, -v111, v144, v143
	v_div_fmas_f32 v111, v111, v142, v144
	v_div_fixup_f32 v107, v111, v110, v107
	global_store_dword v[108:109], v107, off offset:-2048 sc1
	v_add_f32_e32 v108, v167, v172
	v_fma_f32 v108, v108, 0.5, -v166
	s_waitcnt vmcnt(14)
	v_mov_b32_e32 v107, v243
	global_load_dword v236, v[30:31], off offset:3328
	v_fmac_f32_e32 v166, v108, v107
	v_lshl_add_u64 v[108:109], v[136:137], 0, v[18:19]
	v_lshlrev_b64 v[108:109], 2, v[108:109]
	v_lshl_add_u64 v[110:111], s[12:13], 0, v[108:109]
	global_store_dword v[110:111], v166, off offset:-2048 sc1
	v_lshl_add_u64 v[108:109], s[8:9], 0, v[108:109]
	s_waitcnt vmcnt(15)
	v_mov_b32_e32 v107, v244
	global_load_dword v237, v[78:79], off offset:1280
	v_mul_f32_e32 v107, v166, v107
	v_mul_f32_e32 v110, v107, v107
	s_nop 1
	v_mov_b32_dpp v110, v110 quad_perm:[1,0,3,2] row_mask:0xf bank_mask:0xf bound_ctrl:1
	v_fmac_f32_e32 v110, v107, v107
	s_nop 1
	v_add_f32_dpp v110, v110, v110 quad_perm:[2,3,0,1] row_mask:0xf bank_mask:0xf bound_ctrl:1
	s_nop 1
	v_add_f32_dpp v110, v110, v110 row_half_mirror row_mask:0xf bank_mask:0xf bound_ctrl:1
	s_nop 1
	v_add_f32_dpp v110, v110, v110 row_mirror row_mask:0xf bank_mask:0xf bound_ctrl:1
	ds_bpermute_b32 v111, v87, v110
	s_waitcnt lgkmcnt(0)
	v_add_f32_e32 v110, v110, v111
	ds_bpermute_b32 v111, v89, v110
	s_waitcnt lgkmcnt(0)
	v_add_f32_e32 v110, v110, v111
	v_cmp_gt_f32_e32 vcc, s4, v110
	v_mul_f32_e32 v111, 0x4f800000, v110
	s_nop 0
	v_cndmask_b32_e32 v110, v110, v111, vcc
	v_sqrt_f32_e32 v111, v110
	s_nop 0
	v_add_u32_e32 v142, -1, v111
	v_fma_f32 v143, -v142, v111, v110
	v_cmp_ge_f32_e64 s[44:45], 0, v143
	v_add_u32_e32 v143, 1, v111
	s_nop 0
	v_cndmask_b32_e64 v142, v111, v142, s[44:45]
	v_fma_f32 v111, -v143, v111, v110
	v_cmp_lt_f32_e64 s[44:45], 0, v111
	s_nop 1
	v_cndmask_b32_e64 v111, v142, v143, s[44:45]
	v_mul_f32_e32 v142, 0x37800000, v111
	v_cndmask_b32_e32 v111, v111, v142, vcc
	v_cmp_class_f32_e32 vcc, v110, v187
	s_nop 1
	v_cndmask_b32_e32 v110, v111, v110, vcc
	v_max_f32_e32 v110, 0x2b8cbccc, v110
	v_div_scale_f32 v111, s[2:3], v110, v110, v107
	v_rcp_f32_e32 v142, v111
	s_nop 0
	v_fma_f32 v143, -v111, v142, 1.0
	v_fmac_f32_e32 v142, v143, v142
	v_div_scale_f32 v143, vcc, v107, v110, v107
	v_mul_f32_e32 v144, v143, v142
	v_fma_f32 v145, -v111, v144, v143
	v_fmac_f32_e32 v144, v145, v142
	v_fma_f32 v111, -v111, v144, v143
	v_div_fmas_f32 v111, v111, v142, v144
	v_div_fixup_f32 v107, v111, v110, v107
	global_store_dword v[108:109], v107, off offset:-2048 sc1
	v_add_f32_e32 v108, v163, v164
	v_fma_f32 v108, v108, 0.5, -v162
	s_waitcnt vmcnt(15)
	v_mov_b32_e32 v107, v245
	global_load_dword v238, v[30:31], off offset:3584
	v_fmac_f32_e32 v162, v108, v107
	v_lshl_add_u64 v[108:109], v[136:137], 0, v[20:21]
	v_lshlrev_b64 v[108:109], 2, v[108:109]
	v_lshl_add_u64 v[110:111], s[12:13], 0, v[108:109]
	global_store_dword v[110:111], v162, off offset:-2048 sc1
	v_lshl_add_u64 v[108:109], s[8:9], 0, v[108:109]
	s_waitcnt vmcnt(15)
	v_mov_b32_e32 v107, v246
	global_load_dword v239, v[78:79], off offset:1536
	v_mul_f32_e32 v107, v162, v107
	v_mul_f32_e32 v110, v107, v107
	s_nop 1
	v_mov_b32_dpp v110, v110 quad_perm:[1,0,3,2] row_mask:0xf bank_mask:0xf bound_ctrl:1
	v_fmac_f32_e32 v110, v107, v107
	s_nop 1
	v_add_f32_dpp v110, v110, v110 quad_perm:[2,3,0,1] row_mask:0xf bank_mask:0xf bound_ctrl:1
	s_nop 1
	v_add_f32_dpp v110, v110, v110 row_half_mirror row_mask:0xf bank_mask:0xf bound_ctrl:1
	s_nop 1
	v_add_f32_dpp v110, v110, v110 row_mirror row_mask:0xf bank_mask:0xf bound_ctrl:1
	ds_bpermute_b32 v111, v87, v110
	s_waitcnt lgkmcnt(0)
	v_add_f32_e32 v110, v110, v111
	ds_bpermute_b32 v111, v89, v110
	s_waitcnt lgkmcnt(0)
	v_add_f32_e32 v110, v110, v111
	v_cmp_gt_f32_e32 vcc, s4, v110
	v_mul_f32_e32 v111, 0x4f800000, v110
	s_nop 0
	v_cndmask_b32_e32 v110, v110, v111, vcc
	v_sqrt_f32_e32 v111, v110
	s_nop 0
	v_add_u32_e32 v142, -1, v111
	v_fma_f32 v143, -v142, v111, v110
	v_cmp_ge_f32_e64 s[44:45], 0, v143
	v_add_u32_e32 v143, 1, v111
	s_nop 0
	v_cndmask_b32_e64 v142, v111, v142, s[44:45]
	v_fma_f32 v111, -v143, v111, v110
	v_cmp_lt_f32_e64 s[44:45], 0, v111
	s_nop 1
	v_cndmask_b32_e64 v111, v142, v143, s[44:45]
	v_mul_f32_e32 v142, 0x37800000, v111
	v_cndmask_b32_e32 v111, v111, v142, vcc
	v_cmp_class_f32_e32 vcc, v110, v187
	s_nop 1
	v_cndmask_b32_e32 v110, v111, v110, vcc
	v_max_f32_e32 v110, 0x2b8cbccc, v110
	v_div_scale_f32 v111, s[2:3], v110, v110, v107
	v_rcp_f32_e32 v142, v111
	s_nop 0
	v_fma_f32 v143, -v111, v142, 1.0
	v_fmac_f32_e32 v142, v143, v142
	v_div_scale_f32 v143, vcc, v107, v110, v107
	v_mul_f32_e32 v144, v143, v142
	v_fma_f32 v145, -v111, v144, v143
	v_fmac_f32_e32 v144, v145, v142
	v_fma_f32 v111, -v111, v144, v143
	v_div_fmas_f32 v111, v111, v142, v144
	v_div_fixup_f32 v107, v111, v110, v107
	global_store_dword v[108:109], v107, off offset:-2048 sc1
	v_add_f32_e32 v108, v160, v161
	v_fma_f32 v108, v108, 0.5, -v159
	s_waitcnt vmcnt(15)
	v_mov_b32_e32 v107, v247
	global_load_dword v240, v[44:45], off
	v_fmac_f32_e32 v159, v108, v107
	v_lshl_add_u64 v[108:109], v[136:137], 0, v[22:23]
	v_lshlrev_b64 v[108:109], 2, v[108:109]
	v_lshl_add_u64 v[110:111], s[12:13], 0, v[108:109]
	global_store_dword v[110:111], v159, off offset:-2048 sc1
	v_lshl_add_u64 v[108:109], s[8:9], 0, v[108:109]
	s_waitcnt vmcnt(15)
	v_mov_b32_e32 v107, v248
	global_load_dword v241, v[82:83], off offset:-2048
	v_mul_f32_e32 v107, v159, v107
	v_mul_f32_e32 v110, v107, v107
	s_nop 1
	v_mov_b32_dpp v110, v110 quad_perm:[1,0,3,2] row_mask:0xf bank_mask:0xf bound_ctrl:1
	v_fmac_f32_e32 v110, v107, v107
	s_nop 1
	v_add_f32_dpp v110, v110, v110 quad_perm:[2,3,0,1] row_mask:0xf bank_mask:0xf bound_ctrl:1
	s_nop 1
	v_add_f32_dpp v110, v110, v110 row_half_mirror row_mask:0xf bank_mask:0xf bound_ctrl:1
	s_nop 1
	v_add_f32_dpp v110, v110, v110 row_mirror row_mask:0xf bank_mask:0xf bound_ctrl:1
	ds_bpermute_b32 v111, v87, v110
	s_waitcnt lgkmcnt(0)
	v_add_f32_e32 v110, v110, v111
	ds_bpermute_b32 v111, v89, v110
	s_waitcnt lgkmcnt(0)
	v_add_f32_e32 v110, v110, v111
	v_cmp_gt_f32_e32 vcc, s4, v110
	v_mul_f32_e32 v111, 0x4f800000, v110
	s_nop 0
	v_cndmask_b32_e32 v110, v110, v111, vcc
	v_sqrt_f32_e32 v111, v110
	s_nop 0
	v_add_u32_e32 v142, -1, v111
	v_fma_f32 v143, -v142, v111, v110
	v_cmp_ge_f32_e64 s[44:45], 0, v143
	v_add_u32_e32 v143, 1, v111
	s_nop 0
	v_cndmask_b32_e64 v142, v111, v142, s[44:45]
	v_fma_f32 v111, -v143, v111, v110
	v_cmp_lt_f32_e64 s[44:45], 0, v111
	s_nop 1
	v_cndmask_b32_e64 v111, v142, v143, s[44:45]
	v_mul_f32_e32 v142, 0x37800000, v111
	v_cndmask_b32_e32 v111, v111, v142, vcc
	v_cmp_class_f32_e32 vcc, v110, v187
	s_nop 1
	v_cndmask_b32_e32 v110, v111, v110, vcc
	v_max_f32_e32 v110, 0x2b8cbccc, v110
	v_div_scale_f32 v111, s[2:3], v110, v110, v107
	v_rcp_f32_e32 v142, v111
	s_nop 0
	v_fma_f32 v143, -v111, v142, 1.0
	v_fmac_f32_e32 v142, v143, v142
	v_div_scale_f32 v143, vcc, v107, v110, v107
	v_mul_f32_e32 v144, v143, v142
	v_fma_f32 v145, -v111, v144, v143
	v_fmac_f32_e32 v144, v145, v142
	v_fma_f32 v111, -v111, v144, v143
	v_div_fmas_f32 v111, v111, v142, v144
	v_div_fixup_f32 v107, v111, v110, v107
	global_store_dword v[108:109], v107, off offset:-2048 sc1
	v_add_f32_e32 v108, v156, v157
	v_fma_f32 v108, v108, 0.5, -v105
	s_waitcnt vmcnt(15)
	v_mov_b32_e32 v107, v249
	global_load_dword v242, v[46:47], off
	v_fmac_f32_e32 v105, v108, v107
	v_lshl_add_u64 v[108:109], v[136:137], 0, v[24:25]
	v_lshlrev_b64 v[108:109], 2, v[108:109]
	v_lshl_add_u64 v[110:111], s[12:13], 0, v[108:109]
	global_store_dword v[110:111], v105, off offset:-2048 sc1
	v_lshl_add_u64 v[108:109], s[8:9], 0, v[108:109]
	s_waitcnt vmcnt(15)
	v_mov_b32_e32 v107, v250
	global_load_dword v243, v[48:49], off
	v_mul_f32_e32 v105, v105, v107
	v_mul_f32_e32 v107, v105, v105
	s_nop 1
	v_mov_b32_dpp v107, v107 quad_perm:[1,0,3,2] row_mask:0xf bank_mask:0xf bound_ctrl:1
	v_fmac_f32_e32 v107, v105, v105
	s_nop 1
	v_add_f32_dpp v107, v107, v107 quad_perm:[2,3,0,1] row_mask:0xf bank_mask:0xf bound_ctrl:1
	s_nop 1
	v_add_f32_dpp v107, v107, v107 row_half_mirror row_mask:0xf bank_mask:0xf bound_ctrl:1
	s_nop 1
	v_add_f32_dpp v107, v107, v107 row_mirror row_mask:0xf bank_mask:0xf bound_ctrl:1
	ds_bpermute_b32 v110, v87, v107
	s_waitcnt lgkmcnt(0)
	v_add_f32_e32 v107, v107, v110
	ds_bpermute_b32 v110, v89, v107
	s_waitcnt lgkmcnt(0)
	v_add_f32_e32 v107, v107, v110
	v_cmp_gt_f32_e32 vcc, s4, v107
	v_mul_f32_e32 v110, 0x4f800000, v107
	s_nop 0
	v_cndmask_b32_e32 v107, v107, v110, vcc
	v_sqrt_f32_e32 v110, v107
	s_nop 0
	v_add_u32_e32 v111, -1, v110
	v_fma_f32 v142, -v111, v110, v107
	v_cmp_ge_f32_e64 s[44:45], 0, v142
	v_add_u32_e32 v142, 1, v110
	s_nop 0
	v_cndmask_b32_e64 v111, v110, v111, s[44:45]
	v_fma_f32 v110, -v142, v110, v107
	v_cmp_lt_f32_e64 s[44:45], 0, v110
	s_nop 1
	v_cndmask_b32_e64 v110, v111, v142, s[44:45]
	v_mul_f32_e32 v111, 0x37800000, v110
	v_cndmask_b32_e32 v110, v110, v111, vcc
	v_cmp_class_f32_e32 vcc, v107, v187
	s_nop 1
	v_cndmask_b32_e32 v107, v110, v107, vcc
	v_max_f32_e32 v107, 0x2b8cbccc, v107
	v_div_scale_f32 v110, s[2:3], v107, v107, v105
	v_rcp_f32_e32 v111, v110
	s_nop 0
	v_fma_f32 v142, -v110, v111, 1.0
	v_fmac_f32_e32 v111, v142, v111
	v_div_scale_f32 v142, vcc, v105, v107, v105
	v_mul_f32_e32 v143, v142, v111
	v_fma_f32 v144, -v110, v143, v142
	v_fmac_f32_e32 v143, v144, v111
	v_fma_f32 v110, -v110, v143, v142
	v_div_fmas_f32 v110, v110, v111, v143
	v_div_fixup_f32 v105, v110, v107, v105
	global_store_dword v[108:109], v105, off offset:-2048 sc1
	v_lshl_add_u64 v[108:109], v[136:137], 0, v[26:27]
	v_lshlrev_b64 v[108:109], 2, v[108:109]
	v_lshl_add_u64 v[110:111], s[12:13], 0, v[108:109]
	v_lshl_add_u64 v[108:109], s[8:9], 0, v[108:109]
	s_waitcnt vmcnt(15)
	v_mov_b32_e32 v105, v236
	global_load_dword v244, v[50:51], off
	v_fmac_f32_e32 v99, v101, v105
	global_store_dword v[110:111], v99, off offset:-2048 sc1
	s_waitcnt vmcnt(15)
	v_mov_b32_e32 v101, v237
	global_load_dword v245, v[52:53], off
	v_mul_f32_e32 v99, v99, v101
	v_mul_f32_e32 v101, v99, v99
	s_nop 1
	v_mov_b32_dpp v101, v101 quad_perm:[1,0,3,2] row_mask:0xf bank_mask:0xf bound_ctrl:1
	v_fmac_f32_e32 v101, v99, v99
	s_nop 1
	v_add_f32_dpp v101, v101, v101 quad_perm:[2,3,0,1] row_mask:0xf bank_mask:0xf bound_ctrl:1
	s_nop 1
	v_add_f32_dpp v101, v101, v101 row_half_mirror row_mask:0xf bank_mask:0xf bound_ctrl:1
	s_nop 1
	v_add_f32_dpp v101, v101, v101 row_mirror row_mask:0xf bank_mask:0xf bound_ctrl:1
	ds_bpermute_b32 v103, v87, v101
	s_waitcnt lgkmcnt(0)
	v_add_f32_e32 v101, v101, v103
	ds_bpermute_b32 v103, v89, v101
	s_waitcnt lgkmcnt(0)
	v_add_f32_e32 v101, v101, v103
	v_cmp_gt_f32_e32 vcc, s4, v101
	v_mul_f32_e32 v103, 0x4f800000, v101
	s_nop 0
	v_cndmask_b32_e32 v101, v101, v103, vcc
	v_sqrt_f32_e32 v103, v101
	s_nop 0
	v_add_u32_e32 v105, -1, v103
	v_fma_f32 v107, -v105, v103, v101
	v_cmp_ge_f32_e64 s[44:45], 0, v107
	v_add_u32_e32 v107, 1, v103
	s_nop 0
	v_cndmask_b32_e64 v105, v103, v105, s[44:45]
	v_fma_f32 v103, -v107, v103, v101
	v_cmp_lt_f32_e64 s[44:45], 0, v103
	s_nop 1
	v_cndmask_b32_e64 v103, v105, v107, s[44:45]
	v_mul_f32_e32 v105, 0x37800000, v103
	v_cndmask_b32_e32 v103, v103, v105, vcc
	v_cmp_class_f32_e32 vcc, v101, v187
	s_nop 1
	v_cndmask_b32_e32 v101, v103, v101, vcc
	v_max_f32_e32 v101, 0x2b8cbccc, v101
	v_div_scale_f32 v103, s[2:3], v101, v101, v99
	v_rcp_f32_e32 v105, v103
	s_nop 0
	v_fma_f32 v107, -v103, v105, 1.0
	v_fmac_f32_e32 v105, v107, v105
	v_div_scale_f32 v107, vcc, v99, v101, v99
	v_mul_f32_e32 v110, v107, v105
	v_fma_f32 v111, -v103, v110, v107
	v_fmac_f32_e32 v110, v111, v105
	v_fma_f32 v103, -v103, v110, v107
	v_div_fmas_f32 v103, v103, v105, v110
	v_div_fixup_f32 v99, v103, v101, v99
	global_store_dword v[108:109], v99, off offset:-2048 sc1
	v_lshl_add_u64 v[108:109], v[136:137], 0, v[28:29]
	v_lshlrev_b64 v[108:109], 2, v[108:109]
	v_lshl_add_u64 v[110:111], s[12:13], 0, v[108:109]
	v_lshl_add_u64 v[108:109], s[8:9], 0, v[108:109]
	s_waitcnt vmcnt(15)
	v_mov_b32_e32 v99, v238
	global_load_dword v246, v[54:55], off
	v_fmac_f32_e32 v91, v95, v99
	global_store_dword v[110:111], v91, off offset:-2048 sc1
	s_waitcnt vmcnt(15)
	v_mov_b32_e32 v95, v239
	global_load_dword v247, v[56:57], off
	v_mul_f32_e32 v91, v91, v95
	v_mul_f32_e32 v95, v91, v91
	s_nop 1
	v_mov_b32_dpp v95, v95 quad_perm:[1,0,3,2] row_mask:0xf bank_mask:0xf bound_ctrl:1
	v_fmac_f32_e32 v95, v91, v91
	s_nop 1
	v_add_f32_dpp v95, v95, v95 quad_perm:[2,3,0,1] row_mask:0xf bank_mask:0xf bound_ctrl:1
	s_nop 1
	v_add_f32_dpp v95, v95, v95 row_half_mirror row_mask:0xf bank_mask:0xf bound_ctrl:1
	s_nop 1
	v_add_f32_dpp v95, v95, v95 row_mirror row_mask:0xf bank_mask:0xf bound_ctrl:1
	ds_bpermute_b32 v97, v87, v95
	s_waitcnt lgkmcnt(0)
	v_add_f32_e32 v95, v95, v97
	ds_bpermute_b32 v97, v89, v95
	s_waitcnt lgkmcnt(0)
	v_add_f32_e32 v95, v95, v97
	v_cmp_gt_f32_e32 vcc, s4, v95
	v_mul_f32_e32 v97, 0x4f800000, v95
	s_nop 0
	v_cndmask_b32_e32 v95, v95, v97, vcc
	v_sqrt_f32_e32 v97, v95
	s_nop 0
	v_add_u32_e32 v99, -1, v97
	v_fma_f32 v101, -v99, v97, v95
	v_cmp_ge_f32_e64 s[44:45], 0, v101
	v_add_u32_e32 v101, 1, v97
	s_nop 0
	v_cndmask_b32_e64 v99, v97, v99, s[44:45]
	v_fma_f32 v97, -v101, v97, v95
	v_cmp_lt_f32_e64 s[44:45], 0, v97
	s_nop 1
	v_cndmask_b32_e64 v97, v99, v101, s[44:45]
	v_mul_f32_e32 v99, 0x37800000, v97
	v_cndmask_b32_e32 v97, v97, v99, vcc
	v_cmp_class_f32_e32 vcc, v95, v187
	s_nop 1
	v_cndmask_b32_e32 v95, v97, v95, vcc
	v_max_f32_e32 v95, 0x2b8cbccc, v95
	v_div_scale_f32 v97, s[2:3], v95, v95, v91
	v_rcp_f32_e32 v99, v97
	s_nop 0
	v_fma_f32 v101, -v97, v99, 1.0
	v_fmac_f32_e32 v99, v101, v99
	v_div_scale_f32 v101, vcc, v91, v95, v91
	v_mul_f32_e32 v103, v101, v99
	v_fma_f32 v105, -v97, v103, v101
	v_fmac_f32_e32 v103, v105, v99
	v_fma_f32 v97, -v97, v103, v101
	v_div_fmas_f32 v97, v97, v99, v103
	v_div_fixup_f32 v91, v97, v95, v91
	global_store_dword v[108:109], v91, off offset:-2048 sc1
	v_add_f32_e32 v95, v231, v230
	v_lshl_add_u64 v[108:109], v[136:137], 0, v[32:33]
	v_fma_f32 v95, v95, 0.5, -v224
	v_lshlrev_b64 v[108:109], 2, v[108:109]
	v_lshl_add_u64 v[110:111], s[12:13], 0, v[108:109]
	v_lshl_add_u64 v[108:109], s[8:9], 0, v[108:109]
	v_mov_b32_e32 v103, v1
	v_mov_b32_e32 v105, v1
	s_waitcnt vmcnt(15)
	v_mov_b32_e32 v91, v240
	global_load_dword v248, v[58:59], off
	v_fmac_f32_e32 v224, v95, v91
	global_store_dword v[110:111], v224, off offset:-2048 sc1
	s_waitcnt vmcnt(15)
	v_mov_b32_e32 v91, v241
	global_load_dword v249, v[60:61], off
	v_mul_f32_e32 v91, v224, v91
	v_mul_f32_e32 v95, v91, v91
	s_nop 1
	v_mov_b32_dpp v95, v95 quad_perm:[1,0,3,2] row_mask:0xf bank_mask:0xf bound_ctrl:1
	v_fmac_f32_e32 v95, v91, v91
	s_nop 1
	v_add_f32_dpp v95, v95, v95 quad_perm:[2,3,0,1] row_mask:0xf bank_mask:0xf bound_ctrl:1
	s_nop 1
	v_add_f32_dpp v95, v95, v95 row_half_mirror row_mask:0xf bank_mask:0xf bound_ctrl:1
	s_nop 1
	v_add_f32_dpp v95, v95, v95 row_mirror row_mask:0xf bank_mask:0xf bound_ctrl:1
	ds_bpermute_b32 v87, v87, v95
	s_waitcnt lgkmcnt(0)
	v_add_f32_e32 v87, v95, v87
	ds_bpermute_b32 v89, v89, v87
	s_waitcnt lgkmcnt(0)
	v_add_f32_e32 v87, v87, v89
	v_cmp_gt_f32_e32 vcc, s4, v87
	v_mul_f32_e32 v89, 0x4f800000, v87
	s_nop 0
	v_cndmask_b32_e32 v87, v87, v89, vcc
	v_sqrt_f32_e32 v89, v87
	s_nop 0
	v_add_u32_e32 v95, -1, v89
	v_fma_f32 v97, -v95, v89, v87
	v_cmp_ge_f32_e64 s[44:45], 0, v97
	v_add_u32_e32 v97, 1, v89
	s_nop 0
	v_cndmask_b32_e64 v95, v89, v95, s[44:45]
	v_fma_f32 v89, -v97, v89, v87
	v_cmp_lt_f32_e64 s[44:45], 0, v89
	s_nop 1
	v_cndmask_b32_e64 v89, v95, v97, s[44:45]
	v_mul_f32_e32 v95, 0x37800000, v89
	v_cndmask_b32_e32 v89, v89, v95, vcc
	v_cmp_class_f32_e32 vcc, v87, v187
	s_nop 1
	v_cndmask_b32_e32 v87, v89, v87, vcc
	v_max_f32_e32 v87, 0x2b8cbccc, v87
	v_div_scale_f32 v89, s[2:3], v87, v87, v91
	v_rcp_f32_e32 v95, v89
	s_nop 0
	v_fma_f32 v97, -v89, v95, 1.0
	v_fmac_f32_e32 v95, v97, v95
	v_div_scale_f32 v97, vcc, v91, v87, v91
	v_mul_f32_e32 v99, v97, v95
	v_fma_f32 v101, -v89, v99, v97
	v_fmac_f32_e32 v99, v101, v95
	v_fma_f32 v89, -v89, v99, v97
	v_div_fmas_f32 v89, v89, v95, v99
	v_div_fixup_f32 v87, v89, v87, v91
	global_store_dword v[108:109], v87, off offset:-2048 sc1
	v_add_f32_e32 v89, v185, v204
	v_fma_f32 v89, v89, 0.5, -v152
	v_mov_b32_e32 v95, v1
	v_lshl_add_u64 v[108:109], v[112:113], 0, v[94:95]
	v_mov_b32_e32 v97, v1
	v_mov_b32_e32 v99, v1
	v_mov_b32_e32 v101, v1
	s_waitcnt vmcnt(15)
	v_mov_b32_e32 v87, v242
	global_load_dword v250, v[62:63], off
	v_fmac_f32_e32 v152, v89, v87
	global_store_dword v[108:109], v152, off offset:-4096 sc1
	v_add_f32_e32 v89, v206, v207
	v_fma_f32 v89, v89, 0.5, -v155
	v_lshl_add_u64 v[108:109], v[112:113], 0, v[96:97]
	s_waitcnt vmcnt(15)
	v_mov_b32_e32 v87, v243
	global_load_dword v236, v[64:65], off
	v_fmac_f32_e32 v155, v89, v87
	global_store_dword v[108:109], v155, off offset:-4096 sc1
	v_add_f32_e32 v89, v209, v211
	v_fma_f32 v89, v89, 0.5, -v205
	v_lshl_add_u64 v[108:109], v[112:113], 0, v[98:99]
	s_waitcnt vmcnt(15)
	v_mov_b32_e32 v87, v244
	global_load_dword v237, v[66:67], off
	v_fmac_f32_e32 v205, v89, v87
	global_store_dword v[108:109], v205, off offset:-4096 sc1
	v_add_f32_e32 v89, v215, v214
	v_fma_f32 v89, v89, 0.5, -v208
	v_lshl_add_u64 v[108:109], v[112:113], 0, v[0:1]
	s_waitcnt vmcnt(15)
	v_mov_b32_e32 v87, v245
	global_load_dword v238, v[68:69], off
	v_fmac_f32_e32 v208, v89, v87
	global_store_dword v[108:109], v208, off offset:-4096 sc1
	v_add_f32_e32 v87, v218, v219
	v_fma_f32 v87, v87, 0.5, -v216
	v_lshl_add_u64 v[108:109], v[112:113], 0, v[100:101]
	s_waitcnt vmcnt(15)
	v_mov_b32_e32 v0, v246
	global_load_dword v239, v[70:71], off
	v_fmac_f32_e32 v216, v87, v0
	global_store_dword v[108:109], v216, off offset:-4096 sc1
	v_add_f32_e32 v87, v223, v227
	v_fma_f32 v87, v87, 0.5, -v217
	v_lshl_add_u64 v[108:109], v[112:113], 0, v[102:103]
	s_waitcnt vmcnt(15)
	v_mov_b32_e32 v0, v247
	global_load_dword v240, v[72:73], off
	v_fmac_f32_e32 v217, v87, v0
	global_store_dword v[108:109], v217, off offset:-4096 sc1
	v_add_f32_e32 v87, v228, v229
	v_fma_f32 v87, v87, 0.5, -v221
	v_lshl_add_u64 v[108:109], v[112:113], 0, v[104:105]
	s_waitcnt vmcnt(15)
	v_mov_b32_e32 v0, v248
	v_fmac_f32_e32 v221, v87, v0
	global_store_dword v[108:109], v221, off offset:-4096 sc1
	v_add_f32_e32 v87, v232, v141
	v_fma_f32 v87, v87, 0.5, -v226
	v_mov_b32_e32 v141, v1
	v_lshl_add_u64 v[108:109], v[112:113], 0, v[140:141]
	s_waitcnt vmcnt(14)
	v_mov_b32_e32 v0, v249
	v_fmac_f32_e32 v226, v87, v0
	global_store_dword v[108:109], v226, off offset:-4096 sc1
	v_add_f32_e32 v87, v234, v235
	v_fma_f32 v87, v87, 0.5, -v233
	s_waitcnt vmcnt(13)
	v_mov_b32_e32 v0, v250
	v_fmac_f32_e32 v233, v87, v0
	v_mul_f32_e32 v0, 0xbfb8aa3b, v233
	v_exp_f32_e32 v0, v0
	s_nop 0
	v_add_f32_e32 v0, 1.0, v0
	v_div_scale_f32 v87, s[2:3], v0, v0, 1.0
	v_rcp_f32_e32 v89, v87
	s_movk_i32 s2, 0x300
	v_mad_i64_i32 v[106:107], s[2:3], v106, s2, v[84:85]
	v_fma_f32 v91, -v87, v89, 1.0
	v_fmac_f32_e32 v89, v91, v89
	v_div_scale_f32 v91, vcc, 1.0, v0, 1.0
	v_mul_f32_e32 v95, v91, v89
	v_fma_f32 v97, -v87, v95, v91
	v_fmac_f32_e32 v95, v97, v89
	v_fma_f32 v87, -v87, v95, v91
	v_div_fmas_f32 v87, v87, v89, v95
	v_div_fixup_f32 v0, v87, v0, 1.0
	v_cvt_pk_bf16_f32 v0, v0, s0
	global_store_short v[106:107], v0, off offset:512 sc1
	v_add_f32_e32 v87, v222, v225
	v_fma_f32 v87, v87, 0.5, -v220
	s_waitcnt vmcnt(12)
	v_mov_b32_e32 v0, v236
	v_fmac_f32_e32 v220, v87, v0
	v_mul_f32_e32 v0, 0xbfb8aa3b, v220
	v_exp_f32_e32 v0, v0
	s_nop 0
	v_add_f32_e32 v0, 1.0, v0
	v_div_scale_f32 v87, s[2:3], v0, v0, 1.0
	v_rcp_f32_e32 v89, v87
	s_nop 0
	v_fma_f32 v91, -v87, v89, 1.0
	v_fmac_f32_e32 v89, v91, v89
	v_div_scale_f32 v91, vcc, 1.0, v0, 1.0
	v_mul_f32_e32 v95, v91, v89
	v_fma_f32 v97, -v87, v95, v91
	v_fmac_f32_e32 v95, v97, v89
	v_fma_f32 v87, -v87, v95, v91
	v_div_fmas_f32 v87, v87, v89, v95
	v_div_fixup_f32 v0, v87, v0, 1.0
	v_cvt_pk_bf16_f32 v0, v0, s0
	global_store_short v[106:107], v0, off offset:640 sc1
	v_add_f32_e32 v87, v212, v213
	v_fma_f32 v87, v87, 0.5, -v210
	s_waitcnt vmcnt(11)
	v_mov_b32_e32 v0, v237
	v_fmac_f32_e32 v210, v87, v0
	v_add_f32_e32 v0, v210, v210
	v_mul_f32_e32 v0, 0x3fb8aa3b, v0
	v_exp_f32_e32 v0, v0
	s_nop 0
	v_add_f32_e32 v0, 1.0, v0
	v_div_scale_f32 v87, s[2:3], v0, v0, 2.0
	v_rcp_f32_e32 v89, v87
	s_nop 0
	v_fma_f32 v91, -v87, v89, 1.0
	v_fmac_f32_e32 v89, v91, v89
	v_div_scale_f32 v91, vcc, 2.0, v0, 2.0
	v_mul_f32_e32 v95, v91, v89
	v_fma_f32 v97, -v87, v95, v91
	v_fmac_f32_e32 v95, v97, v89
	v_fma_f32 v87, -v87, v95, v91
	v_div_fmas_f32 v87, v87, v89, v95
	v_div_fixup_f32 v0, v87, v0, 2.0
	v_sub_f32_e32 v0, 1.0, v0
	v_cvt_pk_bf16_f32 v0, v0, s0
	global_store_short v[106:107], v0, off sc1
	v_add_f32_e32 v87, v154, v153
	v_fma_f32 v87, v87, 0.5, -v151
	s_waitcnt vmcnt(10)
	v_mov_b32_e32 v0, v238
	v_fmac_f32_e32 v151, v87, v0
	v_add_f32_e32 v0, v151, v151
	v_mul_f32_e32 v0, 0x3fb8aa3b, v0
	v_exp_f32_e32 v0, v0
	s_nop 0
	v_add_f32_e32 v0, 1.0, v0
	v_div_scale_f32 v87, s[2:3], v0, v0, 2.0
	v_rcp_f32_e32 v89, v87
	s_nop 0
	v_fma_f32 v91, -v87, v89, 1.0
	v_fmac_f32_e32 v89, v91, v89
	v_div_scale_f32 v91, vcc, 2.0, v0, 2.0
	v_mul_f32_e32 v95, v91, v89
	v_fma_f32 v97, -v87, v95, v91
	v_fmac_f32_e32 v95, v97, v89
	v_fma_f32 v87, -v87, v95, v91
	v_div_fmas_f32 v87, v87, v89, v95
	v_div_fixup_f32 v0, v87, v0, 2.0
	v_sub_f32_e32 v0, 1.0, v0
	v_cvt_pk_bf16_f32 v0, v0, s0
	global_store_short v[106:107], v0, off offset:128 sc1
	v_add_f32_e32 v87, v148, v150
	v_fma_f32 v87, v87, 0.5, -v139
	s_waitcnt vmcnt(9)
	v_mov_b32_e32 v0, v239
	v_fmac_f32_e32 v139, v87, v0
	v_cvt_pk_bf16_f32 v0, v139, s0
	global_store_short v[106:107], v0, off offset:256 sc1
	v_add_f32_e32 v87, v138, v149
	v_fma_f32 v87, v87, 0.5, -v93
	s_waitcnt vmcnt(8)
	v_mov_b32_e32 v0, v240
	v_fmac_f32_e32 v93, v87, v0
	v_cvt_pk_bf16_f32 v0, v93, s0
	global_store_short v[106:107], v0, off offset:384 sc1

.LBB0_306:
	s_movk_i32 s2, 0xbff
	v_cmp_lt_i32_e32 vcc, s2, v158
	s_and_saveexec_b64 s[2:3], vcc
	s_xor_b64 s[2:3], exec, s[2:3]
	s_cbranch_execz .LBB0_308
	v_add_u32_e32 v0, 0xffd00000, v3
	v_lshrrev_b32_e32 v0, 15, v0
	v_lshlrev_b32_e32 v106, 9, v0
	v_mov_b32_e32 v107, v1
	v_lshl_add_u64 v[110:111], s[54:55], 0, v[106:107]
	v_lshl_or_b32 v0, v0, 1, v15
	v_mov_b64_e32 v[106:107], 0x1000
	s_movk_i32 s4, 0x1100
	v_mad_u64_u32 v[108:109], s[20:21], v0, s4, v[106:107]
	v_readlane_b32 s4, v252, 48
	v_add_u32_e32 v87, v134, v3
	v_readlane_b32 s5, v252, 49
	v_lshl_or_b32 v89, v0, 6, v2
	v_lshrrev_b32_e32 v87, 7, v87
	v_mov_b64_e32 v[106:107], s[4:5]
	s_movk_i32 s4, 0x2200
	v_mad_u64_u32 v[106:107], s[20:21], v89, s4, v[106:107]
	v_and_b32_e32 v89, 0xf9, v87
	v_readlane_b32 s6, v252, 50
	v_readlane_b32 s7, v252, 51
	v_readlane_b32 s8, v252, 52
	v_readlane_b32 s9, v252, 53
	v_readlane_b32 s10, v252, 54
	v_readlane_b32 s11, v252, 55
	v_readlane_b32 s12, v252, 56
	v_readlane_b32 s13, v252, 57
	v_readlane_b32 s14, v252, 58
	v_readlane_b32 s15, v252, 59
	v_readlane_b32 s16, v252, 60
	v_readlane_b32 s17, v252, 61
	v_readlane_b32 s18, v252, 62
	v_readlane_b32 s19, v252, 63
	s_mov_b64 s[4:5], 0x2000
	v_or_b32_e32 v112, v110, v89
	v_mov_b32_e32 v113, v111
	v_lshl_add_u64 v[106:107], v[106:107], 0, s[4:5]
	v_lshlrev_b64 v[112:113], 9, v[112:113]
	v_readlane_b32 s4, v253, 49
	v_or_b32_e32 v112, v112, v37
	v_readlane_b32 s8, v253, 53
	v_readlane_b32 s9, v253, 54
	v_and_b32_e32 v0, 4, v35
	v_readlane_b32 s10, v253, 55
	v_lshl_add_u64 v[136:137], s[8:9], 0, v[112:113]
	global_load_dword v91, v[136:137], off
	v_or_b32_e32 v136, v108, v89
	v_mov_b32_e32 v137, v109
	v_readlane_b32 s11, v253, 56
	v_lshlrev_b64 v[136:137], 7, v[136:137]
	s_movk_i32 s20, 0xf1
	v_lshl_add_u64 v[136:137], v[4:5], 0, v[136:137]
	v_lshl_add_u64 v[112:113], s[10:11], 0, v[112:113]
	v_and_or_b32 v93, v87, s20, v0
	s_movk_i32 s20, 0xfb
	v_readlane_b32 s5, v253, 50
	s_movk_i32 s5, 0xf3
	v_or_b32_e32 v89, 4, v89
	s_movk_i32 s4, 0xff
	v_readlane_b32 s6, v253, 51
	v_readlane_b32 s7, v253, 52
	v_readlane_b32 s12, v253, 57
	v_readlane_b32 s13, v253, 58
	v_readlane_b32 s14, v253, 59
	v_readlane_b32 s15, v253, 60
	v_readlane_b32 s16, v253, 61
	v_readlane_b32 s17, v253, 62
	v_readlane_b32 s18, v253, 63
	v_readlane_b32 s19, v254, 0
	s_waitcnt vmcnt(0)
	v_cvt_pk_bf16_f32 v91, v91, s0
	global_store_short v[136:137], v91, off sc1
	global_load_dword v91, v[112:113], off
	v_lshlrev_b32_e32 v112, 1, v93
	v_bitop3_b32 v93, v87, s20, 2 bitop3:0xc8
	v_or_b32_e32 v136, v110, v93
	v_mov_b32_e32 v137, v111
	v_lshlrev_b64 v[136:137], 9, v[136:137]
	v_or_b32_e32 v136, v136, v37
	v_lshl_add_u64 v[138:139], s[8:9], 0, v[136:137]
	v_lshl_add_u64 v[136:137], s[10:11], 0, v[136:137]
	global_load_dword v95, v[138:139], off
	v_or_b32_e32 v138, v108, v93
	global_load_dword v93, v[136:137], off
	v_mov_b32_e32 v113, v1
	v_lshl_add_u64 v[112:113], v[106:107], 0, v[112:113]
	v_mov_b32_e32 v139, v109
	v_lshlrev_b64 v[138:139], 7, v[138:139]
	v_mov_b32_e32 v137, v1
	v_lshl_add_u64 v[138:139], v[4:5], 0, v[138:139]
	s_waitcnt vmcnt(2)
	v_cvt_pk_bf16_f32 v91, v91, s0
	global_store_short v[112:113], v91, off sc1
	v_or_b32_e32 v91, 2, v87
	v_and_or_b32 v91, v91, s5, v0
	v_lshlrev_b32_e32 v136, 1, v91
	v_lshl_add_u64 v[136:137], v[106:107], 0, v[136:137]
	s_waitcnt vmcnt(2)
	v_cvt_pk_bf16_f32 v95, v95, s0
	global_store_short v[138:139], v95, off sc1
	s_waitcnt vmcnt(2)
	v_cvt_pk_bf16_f32 v93, v93, s0
	global_store_short v[136:137], v93, off sc1
	v_or_b32_e32 v136, v110, v89
	v_mov_b32_e32 v137, v111
	v_lshlrev_b64 v[136:137], 9, v[136:137]
	v_or_b32_e32 v136, v136, v37
	v_lshl_add_u64 v[138:139], s[8:9], 0, v[136:137]
	v_lshl_add_u64 v[136:137], s[10:11], 0, v[136:137]
	global_load_dword v91, v[138:139], off
	v_or_b32_e32 v138, v108, v89
	global_load_dword v89, v[136:137], off
	v_mov_b32_e32 v139, v109
	v_lshlrev_b64 v[138:139], 7, v[138:139]
	v_lshl_add_u64 v[138:139], v[4:5], 0, v[138:139]
	s_waitcnt vmcnt(1)
	v_cvt_pk_bf16_f32 v91, v91, s0
	global_store_short v[138:139], v91, off sc1
	s_waitcnt vmcnt(1)
	v_cvt_pk_bf16_f32 v89, v89, s0
	global_store_short v[112:113], v89, off offset:16 sc1
	v_or_b32_e32 v89, 6, v87
	v_bitop3_b32 v87, v87, s4, 6 bitop3:0xc8
	v_or_b32_e32 v110, v110, v87
	v_lshlrev_b64 v[110:111], 9, v[110:111]
	v_or_b32_e32 v110, v110, v37
	v_lshl_add_u64 v[112:113], s[8:9], 0, v[110:111]
	global_load_dword v91, v[112:113], off
	v_or_b32_e32 v108, v108, v87
	v_lshlrev_b64 v[108:109], 7, v[108:109]
	v_lshl_add_u64 v[108:109], v[4:5], 0, v[108:109]
	v_and_or_b32 v0, v89, s5, v0
	s_waitcnt vmcnt(0)
	v_cvt_pk_bf16_f32 v91, v91, s0
	global_store_short v[108:109], v91, off sc1
	v_lshl_add_u64 v[108:109], s[10:11], 0, v[110:111]
	global_load_dword v87, v[108:109], off
	v_lshlrev_b32_e32 v108, 1, v0
	v_mov_b32_e32 v109, v1
	v_lshl_add_u64 v[106:107], v[106:107], 0, v[108:109]
	s_waitcnt vmcnt(0)
	v_cvt_pk_bf16_f32 v87, v87, s0
	global_store_short v[106:107], v87, off offset:16 sc1

.LBB0_371:
	s_or_b64 exec, exec, s[2:3]
	v_add_u32_e32 v87, 0xfffff000, v35
	v_lshrrev_b32_e32 v87, 12, v87
	v_ashrrev_i32_e32 v89, 6, v158
	s_waitcnt vmcnt(26)
	v_mul_f32_e32 v154, v141, v141
	v_cndmask_b32_e64 v216, v87, v89, s[50:51]
	v_and_b32_e32 v89, 64, v188
	v_mov_b32_dpp v154, v154 quad_perm:[1,0,3,2] row_mask:0xf bank_mask:0xf bound_ctrl:1
	v_xor_b32_e32 v87, 16, v188
	v_add_u32_e32 v89, 64, v89
	v_fmac_f32_e32 v154, v141, v141
	v_cmp_lt_i32_e32 vcc, v87, v89
	v_xor_b32_e32 v152, 32, v188
	v_add_f32_dpp v154, v154, v154 quad_perm:[2,3,0,1] row_mask:0xf bank_mask:0xf bound_ctrl:1
	v_cndmask_b32_e32 v87, v188, v87, vcc
	v_lshlrev_b32_e32 v87, 2, v87
	v_add_f32_dpp v154, v154, v154 row_half_mirror row_mask:0xf bank_mask:0xf bound_ctrl:1
	v_cmp_lt_i32_e32 vcc, v152, v89
	s_mov_b32 s2, 0x358637bd
	v_add_f32_dpp v154, v154, v154 row_mirror row_mask:0xf bank_mask:0xf bound_ctrl:1
	ds_bpermute_b32 v155, v87, v154
	v_cndmask_b32_e32 v89, v188, v152, vcc
	v_lshlrev_b32_e32 v89, 2, v89
	v_lshlrev_b64 v[152:153], 10, v[106:107]
	v_lshl_add_u64 v[152:153], v[10:11], 0, v[152:153]
	s_waitcnt lgkmcnt(0)
	v_add_f32_e32 v154, v154, v155
	ds_bpermute_b32 v155, v89, v154
	v_readlane_b32 s4, v252, 48
	v_readlane_b32 s5, v252, 49
	v_readlane_b32 s6, v252, 50
	v_readlane_b32 s7, v252, 51
	s_waitcnt lgkmcnt(0)
	v_add_f32_e32 v154, v154, v155
	v_fmamk_f32 v154, v154, 0x3c800000, v186
	v_cmp_gt_f32_e32 vcc, s31, v154
	v_mul_f32_e32 v155, 0x4b800000, v154
	v_readlane_b32 s8, v252, 52
	v_cndmask_b32_e32 v154, v154, v155, vcc
	v_rsq_f32_e32 v154, v154
	v_readlane_b32 s9, v252, 53
	v_readlane_b32 s10, v252, 54
	v_readlane_b32 s11, v252, 55
	v_mul_f32_e32 v155, 0x45800000, v154
	v_cndmask_b32_e32 v154, v154, v155, vcc
	v_mul_f32_e32 v141, v141, v154
	v_mul_f32_e32 v141, v215, v141
	ds_bpermute_b32 v154, v87, v141
	v_mul_f32_e32 v141, v142, v141
	v_readlane_b32 s12, v252, 56
	v_readlane_b32 s13, v252, 57
	v_readlane_b32 s14, v252, 58
	s_waitcnt lgkmcnt(0)
	v_fmac_f32_e32 v141, v143, v154
	s_waitcnt vmcnt(24)
	v_pk_mul_f32 v[154:155], v[150:151], v[150:151]
	v_mul_f32_e32 v141, 0x3e38aa3b, v141
	v_cvt_pk_bf16_f32 v141, v141, s0
	v_mov_b32_dpp v155, v155 quad_perm:[1,0,3,2] row_mask:0xf bank_mask:0xf bound_ctrl:1
	v_mov_b32_dpp v154, v154 quad_perm:[1,0,3,2] row_mask:0xf bank_mask:0xf bound_ctrl:1
	v_pk_fma_f32 v[154:155], v[150:151], v[150:151], v[154:155]
	global_store_short v[152:153], v141, off sc1
	v_readlane_b32 s15, v252, 59
	v_mov_b32_dpp v195, v155 quad_perm:[2,3,0,1] row_mask:0xf bank_mask:0xf bound_ctrl:1
	v_mov_b32_dpp v194, v154 quad_perm:[2,3,0,1] row_mask:0xf bank_mask:0xf bound_ctrl:1
	v_pk_add_f32 v[154:155], v[154:155], v[194:195]
	v_readlane_b32 s16, v252, 60
	v_readlane_b32 s17, v252, 61
	v_mov_b32_dpp v195, v155 row_half_mirror row_mask:0xf bank_mask:0xf bound_ctrl:1
	v_mov_b32_dpp v194, v154 row_half_mirror row_mask:0xf bank_mask:0xf bound_ctrl:1
	v_pk_add_f32 v[154:155], v[154:155], v[194:195]
	v_readlane_b32 s18, v252, 62
	v_readlane_b32 s19, v252, 63
	v_mov_b32_dpp v195, v155 row_mirror row_mask:0xf bank_mask:0xf bound_ctrl:1
	v_mov_b32_dpp v194, v154 row_mirror row_mask:0xf bank_mask:0xf bound_ctrl:1
	v_pk_add_f32 v[154:155], v[154:155], v[194:195]
	ds_bpermute_b32 v195, v87, v155
	ds_bpermute_b32 v194, v87, v154
	s_waitcnt lgkmcnt(0)
	v_pk_add_f32 v[154:155], v[154:155], v[194:195]
	ds_bpermute_b32 v195, v89, v155
	ds_bpermute_b32 v194, v89, v154
	s_waitcnt lgkmcnt(0)
	v_pk_add_f32 v[194:195], v[154:155], v[194:195]
	v_mov_b64_e32 v[154:155], s[2:3]
	s_mov_b32 s2, 0x3c800000
	v_pk_fma_f32 v[194:195], v[194:195], s[2:3], v[154:155] op_sel_hi:[1,0,0]
	s_nop 0
	v_mul_f32_e32 v141, 0x4b800000, v195
	v_cmp_gt_f32_e64 s[50:51], s31, v195
	v_cmp_gt_f32_e32 vcc, s31, v194
	s_nop 0
	v_cndmask_b32_e64 v141, v195, v141, s[50:51]
	v_rsq_f32_e32 v141, v141
	s_nop 0
	v_mul_f32_e32 v195, 0x45800000, v141
	v_cndmask_b32_e64 v141, v141, v195, s[50:51]
	v_mul_f32_e32 v141, v151, v141
	v_mul_f32_e32 v141, v215, v141
	ds_bpermute_b32 v151, v87, v141
	v_mul_f32_e32 v141, v142, v141
	s_waitcnt lgkmcnt(0)
	v_fmac_f32_e32 v141, v143, v151
	v_mul_f32_e32 v141, 0x3e38aa3b, v141
	v_cvt_pk_bf16_f32 v141, v141, s0
	global_store_short v[152:153], v141, off offset:128 sc1
	v_mul_f32_e32 v141, 0x4b800000, v194
	v_cndmask_b32_e32 v141, v194, v141, vcc
	v_rsq_f32_e32 v141, v141
	s_nop 0
	v_mul_f32_e32 v151, 0x45800000, v141
	v_cndmask_b32_e32 v141, v141, v151, vcc
	v_mul_f32_e32 v141, v150, v141
	v_mul_f32_e32 v141, v215, v141
	ds_bpermute_b32 v150, v87, v141
	v_mul_f32_e32 v141, v142, v141
	s_waitcnt lgkmcnt(0)
	v_fmac_f32_e32 v141, v143, v150
	s_waitcnt vmcnt(20)
	v_pk_mul_f32 v[150:151], v[148:149], v[148:149]
	v_mul_f32_e32 v141, 0x3e38aa3b, v141
	v_cvt_pk_bf16_f32 v141, v141, s0
	v_mov_b32_dpp v151, v151 quad_perm:[1,0,3,2] row_mask:0xf bank_mask:0xf bound_ctrl:1
	v_mov_b32_dpp v150, v150 quad_perm:[1,0,3,2] row_mask:0xf bank_mask:0xf bound_ctrl:1
	v_pk_fma_f32 v[150:151], v[148:149], v[148:149], v[150:151]
	global_store_short v[152:153], v141, off offset:256 sc1
	s_nop 0
	v_mov_b32_dpp v195, v151 quad_perm:[2,3,0,1] row_mask:0xf bank_mask:0xf bound_ctrl:1
	v_mov_b32_dpp v194, v150 quad_perm:[2,3,0,1] row_mask:0xf bank_mask:0xf bound_ctrl:1
	v_pk_add_f32 v[150:151], v[150:151], v[194:195]
	s_nop 1
	v_mov_b32_dpp v195, v151 row_half_mirror row_mask:0xf bank_mask:0xf bound_ctrl:1
	v_mov_b32_dpp v194, v150 row_half_mirror row_mask:0xf bank_mask:0xf bound_ctrl:1
	v_pk_add_f32 v[150:151], v[150:151], v[194:195]
	s_nop 1
	v_mov_b32_dpp v195, v151 row_mirror row_mask:0xf bank_mask:0xf bound_ctrl:1
	v_mov_b32_dpp v194, v150 row_mirror row_mask:0xf bank_mask:0xf bound_ctrl:1
	v_pk_add_f32 v[150:151], v[150:151], v[194:195]
	ds_bpermute_b32 v195, v87, v151
	ds_bpermute_b32 v194, v87, v150
	s_waitcnt lgkmcnt(0)
	v_pk_add_f32 v[150:151], v[150:151], v[194:195]
	ds_bpermute_b32 v195, v89, v151
	ds_bpermute_b32 v194, v89, v150
	s_waitcnt lgkmcnt(0)
	v_pk_add_f32 v[150:151], v[150:151], v[194:195]
	s_nop 0
	v_pk_fma_f32 v[150:151], v[150:151], s[2:3], v[154:155] op_sel_hi:[1,0,0]
	s_waitcnt vmcnt(20)
	v_pk_mul_f32 v[194:195], v[144:145], v[144:145]
	v_mul_f32_e32 v141, 0x4b800000, v151
	v_cmp_gt_f32_e64 s[50:51], s31, v151
	v_cmp_gt_f32_e32 vcc, s31, v150
	v_mov_b32_dpp v195, v195 quad_perm:[1,0,3,2] row_mask:0xf bank_mask:0xf bound_ctrl:1
	v_cndmask_b32_e64 v141, v151, v141, s[50:51]
	v_rsq_f32_e32 v141, v141
	v_mov_b32_dpp v194, v194 quad_perm:[1,0,3,2] row_mask:0xf bank_mask:0xf bound_ctrl:1
	v_pk_fma_f32 v[194:195], v[144:145], v[144:145], v[194:195]
	v_mul_f32_e32 v151, 0x45800000, v141
	v_cndmask_b32_e64 v141, v141, v151, s[50:51]
	v_mul_f32_e32 v141, v149, v141
	v_mul_f32_e32 v141, v215, v141
	ds_bpermute_b32 v149, v87, v141
	v_mul_f32_e32 v141, v142, v141
	v_mov_b32_dpp v197, v195 quad_perm:[2,3,0,1] row_mask:0xf bank_mask:0xf bound_ctrl:1
	v_mov_b32_dpp v196, v194 quad_perm:[2,3,0,1] row_mask:0xf bank_mask:0xf bound_ctrl:1
	v_pk_add_f32 v[194:195], v[194:195], v[196:197]
	s_waitcnt lgkmcnt(0)
	v_fmac_f32_e32 v141, v143, v149
	v_mul_f32_e32 v141, 0x3e38aa3b, v141
	v_cvt_pk_bf16_f32 v141, v141, s0
	global_store_short v[152:153], v141, off offset:384 sc1
	v_mul_f32_e32 v141, 0x4b800000, v150
	v_cndmask_b32_e32 v141, v150, v141, vcc
	v_rsq_f32_e32 v141, v141
	v_mov_b32_dpp v197, v195 row_half_mirror row_mask:0xf bank_mask:0xf bound_ctrl:1
	v_mov_b32_dpp v196, v194 row_half_mirror row_mask:0xf bank_mask:0xf bound_ctrl:1
	v_pk_add_f32 v[194:195], v[194:195], v[196:197]
	v_mul_f32_e32 v149, 0x45800000, v141
	v_cndmask_b32_e32 v141, v141, v149, vcc
	v_mul_f32_e32 v141, v148, v141
	v_mul_f32_e32 v141, v215, v141
	ds_bpermute_b32 v148, v87, v141
	v_mul_f32_e32 v141, v142, v141
	v_mov_b32_dpp v197, v195 row_mirror row_mask:0xf bank_mask:0xf bound_ctrl:1
	v_mov_b32_dpp v196, v194 row_mirror row_mask:0xf bank_mask:0xf bound_ctrl:1
	v_pk_add_f32 v[194:195], v[194:195], v[196:197]
	s_waitcnt lgkmcnt(0)
	v_fmac_f32_e32 v141, v143, v148
	v_pk_mul_f32 v[148:149], v[146:147], v[146:147]
	v_mul_f32_e32 v141, 0x3e38aa3b, v141
	v_cvt_pk_bf16_f32 v141, v141, s0
	v_mov_b32_dpp v149, v149 quad_perm:[1,0,3,2] row_mask:0xf bank_mask:0xf bound_ctrl:1
	v_mov_b32_dpp v148, v148 quad_perm:[1,0,3,2] row_mask:0xf bank_mask:0xf bound_ctrl:1
	v_pk_fma_f32 v[148:149], v[146:147], v[146:147], v[148:149]
	global_store_short v[152:153], v141, off offset:512 sc1
	ds_bpermute_b32 v197, v87, v195
	v_mov_b32_dpp v151, v149 quad_perm:[2,3,0,1] row_mask:0xf bank_mask:0xf bound_ctrl:1
	v_mov_b32_dpp v150, v148 quad_perm:[2,3,0,1] row_mask:0xf bank_mask:0xf bound_ctrl:1
	v_pk_add_f32 v[148:149], v[148:149], v[150:151]
	ds_bpermute_b32 v196, v87, v194
	s_waitcnt lgkmcnt(0)
	v_pk_add_f32 v[194:195], v[194:195], v[196:197]
	v_mov_b32_dpp v151, v149 row_half_mirror row_mask:0xf bank_mask:0xf bound_ctrl:1
	v_mov_b32_dpp v150, v148 row_half_mirror row_mask:0xf bank_mask:0xf bound_ctrl:1
	v_pk_add_f32 v[148:149], v[148:149], v[150:151]
	ds_bpermute_b32 v197, v89, v195
	ds_bpermute_b32 v196, v89, v194
	v_mov_b32_dpp v151, v149 row_mirror row_mask:0xf bank_mask:0xf bound_ctrl:1
	v_mov_b32_dpp v150, v148 row_mirror row_mask:0xf bank_mask:0xf bound_ctrl:1
	v_pk_add_f32 v[148:149], v[148:149], v[150:151]
	ds_bpermute_b32 v151, v87, v149
	ds_bpermute_b32 v150, v87, v148
	s_waitcnt lgkmcnt(2)
	v_pk_add_f32 v[194:195], v[194:195], v[196:197]
	s_waitcnt lgkmcnt(0)
	v_pk_add_f32 v[148:149], v[148:149], v[150:151]
	ds_bpermute_b32 v151, v89, v149
	ds_bpermute_b32 v150, v89, v148
	s_waitcnt lgkmcnt(0)
	v_pk_add_f32 v[148:149], v[148:149], v[150:151]
	s_nop 0
	v_pk_fma_f32 v[148:149], v[148:149], s[2:3], v[154:155] op_sel_hi:[1,0,0]
	v_pk_fma_f32 v[154:155], v[194:195], s[2:3], v[154:155] op_sel_hi:[1,0,0]
	v_mul_f32_e32 v141, 0x4b800000, v149
	v_cmp_gt_f32_e64 s[50:51], s31, v149
	v_cmp_gt_f32_e32 vcc, s31, v148
	v_mov_b32_e32 v151, v1
	v_cndmask_b32_e64 v141, v149, v141, s[50:51]
	v_rsq_f32_e32 v141, v141
	s_nop 0
	v_mul_f32_e32 v149, 0x45800000, v141
	v_cndmask_b32_e64 v141, v141, v149, s[50:51]
	v_mul_f32_e32 v141, v147, v141
	v_mul_f32_e32 v141, v215, v141
	ds_bpermute_b32 v147, v87, v141
	v_mul_f32_e32 v141, v142, v141
	v_cmp_gt_f32_e64 s[50:51], s31, v155
	s_waitcnt lgkmcnt(0)
	v_fmac_f32_e32 v141, v143, v147
	v_mul_f32_e32 v141, 0x3e38aa3b, v141
	v_cvt_pk_bf16_f32 v141, v141, s0
	global_store_short v[152:153], v141, off offset:640 sc1
	v_mul_f32_e32 v141, 0x4b800000, v148
	v_cndmask_b32_e32 v141, v148, v141, vcc
	v_rsq_f32_e32 v141, v141
	v_lshlrev_b32_e32 v148, 1, v216
	v_mul_f32_e32 v147, 0x45800000, v141
	v_cndmask_b32_e32 v141, v141, v147, vcc
	v_mul_f32_e32 v141, v146, v141
	v_mul_f32_e32 v141, v215, v141
	ds_bpermute_b32 v146, v87, v141
	v_mul_f32_e32 v141, v142, v141
	v_and_b32_e32 v147, 0xff3, v0
	v_cmp_gt_f32_e32 vcc, s31, v154
	s_waitcnt lgkmcnt(0)
	v_fmac_f32_e32 v141, v143, v146
	v_mul_f32_e32 v141, 0x3e38aa3b, v141
	v_cvt_pk_bf16_f32 v141, v141, s0
	global_store_short v[152:153], v141, off offset:768 sc1
	v_lshlrev_b32_e32 v141, 1, v0
	v_lshrrev_b32_e32 v146, 1, v35
	v_and_b32_e32 v141, 8, v141
	v_and_b32_e32 v146, 4, v146
	v_or3_b32 v141, v147, v146, v141
	v_lshlrev_b32_e32 v150, 1, v141
	v_mul_f32_e32 v141, 0x4b800000, v155
	v_cndmask_b32_e64 v141, v155, v141, s[50:51]
	v_rsq_f32_e32 v141, v141
	v_lshl_add_u64 v[146:147], s[4:5], 0, v[150:151]
	v_mul_f32_e32 v149, 0x45800000, v141
	v_cndmask_b32_e64 v141, v141, v149, s[50:51]
	v_mul_f32_e32 v141, v145, v141
	v_mul_f32_e32 v141, v215, v141
	ds_bpermute_b32 v145, v87, v141
	v_mul_f32_e32 v141, v142, v141
	v_ashrrev_i32_e32 v149, 31, v148
	s_waitcnt lgkmcnt(0)
	v_fmac_f32_e32 v141, v143, v145
	v_mul_f32_e32 v141, 0x3e38aa3b, v141
	v_cvt_pk_bf16_f32 v141, v141, s0
	global_store_short v[152:153], v141, off offset:896 sc1
	v_mul_f32_e32 v141, 0x4b800000, v154
	v_cndmask_b32_e32 v141, v154, v141, vcc
	v_rsq_f32_e32 v141, v141
	s_nop 0
	v_mul_f32_e32 v145, 0x45800000, v141
	v_cndmask_b32_e32 v141, v141, v145, vcc
	v_mul_f32_e32 v141, v144, v141
	v_mul_f32_e32 v154, v206, v141
	ds_bpermute_b32 v141, v87, v154
	v_mul_f32_e32 v155, v142, v154
	s_waitcnt lgkmcnt(0)
	v_fmac_f32_e32 v155, v143, v141
	s_and_saveexec_b64 s[2:3], s[48:49]
	s_xor_b64 s[2:3], exec, s[2:3]
	s_cbranch_execz .LBB0_373
	s_movk_i32 s4, 0x1100
	v_mad_i64_i32 v[144:145], s[20:21], v148, s4, v[0:1]
	v_lshlrev_b64 v[144:145], 7, v[144:145]
	v_cvt_pk_bf16_f32 v141, v155, s0
	v_lshl_add_u64 v[144:145], v[4:5], 0, v[144:145]
	global_store_short v[144:145], v141, off sc1
	v_lshl_or_b32 v144, v148, 6, v2
	s_movk_i32 s4, 0x2200
	v_mad_u64_u32 v[144:145], s[20:21], v144, s4, v[146:147]
	s_waitcnt vmcnt(25)
	v_cvt_pk_bf16_f32 v141, v214, s0
	v_mad_i32_i24 v145, v149, s4, v145
	global_store_short v[144:145], v141, off sc1
.LBB0_373:
	s_or_saveexec_b64 s[2:3], s[2:3]
	v_add_u32_e32 v144, s0, v148
	v_ashrrev_i32_e32 v145, 31, v144
	v_readlane_b32 s60, v251, 38
	v_lshlrev_b64 v[144:145], 17, v[144:145]
	v_readlane_b32 s61, v251, 39
	v_lshlrev_b32_e32 v152, 9, v0
	v_mov_b32_e32 v153, v1
	v_lshl_add_u64 v[144:145], s[60:61], 0, v[144:145]
	v_lshlrev_b32_e32 v194, 7, v0
	v_mov_b32_e32 v195, v1
	v_lshl_add_u64 v[144:145], v[144:145], 0, v[152:153]
	v_mov_b32_e32 v141, v1
	v_lshl_add_u64 v[152:153], v[144:145], 0, v[140:141]
	v_lshl_add_u64 v[144:145], v[74:75], 0, v[194:195]
	v_lshl_add_u64 v[150:151], v[76:77], 0, v[150:151]
	v_readlane_b32 s62, v251, 40
	v_readlane_b32 s63, v251, 41
	v_readlane_b32 s64, v251, 42
	v_readlane_b32 s65, v251, 43
	v_readlane_b32 s66, v251, 44
	v_readlane_b32 s67, v251, 45
	v_readlane_b32 s68, v251, 46
	v_readlane_b32 s69, v251, 47
	v_readlane_b32 s70, v251, 48
	v_readlane_b32 s71, v251, 49
	v_readlane_b32 s72, v251, 50
	v_readlane_b32 s73, v251, 51
	v_readlane_b32 s74, v251, 52
	v_readlane_b32 s75, v251, 53
	s_xor_b64 exec, exec, s[2:3]
	s_cbranch_execz .LBB0_375
	v_add_co_u32_e32 v194, vcc, 0x3000000, v152
	v_cvt_pk_bf16_f32 v141, v155, s0
	s_nop 0
	v_addc_co_u32_e32 v195, vcc, 0, v153, vcc
	global_store_dword v[194:195], v154, off sc1
	v_add_co_u32_e32 v194, vcc, 0x3400000, v152
	v_lshlrev_b64 v[154:155], 15, v[148:149]
	s_nop 0
	v_addc_co_u32_e32 v195, vcc, 0, v153, vcc
	s_waitcnt vmcnt(25)
	global_store_dword v[194:195], v214, off sc1
	v_lshl_add_u64 v[194:195], v[144:145], 0, v[154:155]
	global_store_short v[194:195], v141, off sc1
	v_cvt_pk_bf16_f32 v141, v214, s0
	v_lshl_add_u64 v[154:155], v[150:151], 0, v[154:155]
	global_store_short v[154:155], v141, off sc1
.LBB0_375:
	s_or_b64 exec, exec, s[2:3]
	v_mul_f32_e32 v141, v213, v213
	s_nop 1
	v_mov_b32_dpp v141, v141 quad_perm:[1,0,3,2] row_mask:0xf bank_mask:0xf bound_ctrl:1
	v_fmac_f32_e32 v141, v213, v213
	s_nop 1
	v_add_f32_dpp v141, v141, v141 quad_perm:[2,3,0,1] row_mask:0xf bank_mask:0xf bound_ctrl:1
	s_nop 1
	v_add_f32_dpp v141, v141, v141 row_half_mirror row_mask:0xf bank_mask:0xf bound_ctrl:1
	s_nop 1
	v_add_f32_dpp v141, v141, v141 row_mirror row_mask:0xf bank_mask:0xf bound_ctrl:1
	ds_bpermute_b32 v149, v87, v141
	s_waitcnt lgkmcnt(0)
	v_add_f32_e32 v141, v141, v149
	ds_bpermute_b32 v149, v89, v141
	s_waitcnt lgkmcnt(0)
	v_add_f32_e32 v141, v141, v149
	v_fmamk_f32 v141, v141, 0x3c800000, v186
	v_cmp_gt_f32_e32 vcc, s31, v141
	v_mul_f32_e32 v149, 0x4b800000, v141
	s_nop 0
	v_cndmask_b32_e32 v141, v141, v149, vcc
	v_rsq_f32_e32 v141, v141
	s_nop 0
	v_mul_f32_e32 v149, 0x45800000, v141
	v_cndmask_b32_e32 v141, v141, v149, vcc
	v_mul_f32_e32 v141, v213, v141
	v_mul_f32_e32 v149, v206, v141
	ds_bpermute_b32 v154, v87, v149
	v_mul_f32_e32 v141, v142, v149
	v_or_b32_e32 v142, 1, v148
	s_waitcnt lgkmcnt(0)
	v_fmac_f32_e32 v141, v143, v154
	v_ashrrev_i32_e32 v143, 31, v142
	s_and_saveexec_b64 s[2:3], s[48:49]
	s_xor_b64 s[2:3], exec, s[2:3]
	s_cbranch_execz .LBB0_377
	s_movk_i32 s4, 0x1100
	v_mad_i64_i32 v[144:145], s[20:21], v142, s4, v[0:1]
	v_lshlrev_b64 v[144:145], 7, v[144:145]
	v_cvt_pk_bf16_f32 v141, v141, s0
	v_lshl_add_u64 v[144:145], v[4:5], 0, v[144:145]
	global_store_short v[144:145], v141, off sc1
	v_lshl_or_b32 v141, v142, 6, v2
	s_movk_i32 s4, 0x2200
	v_mad_u64_u32 v[144:145], s[20:21], v141, s4, v[146:147]
	s_waitcnt vmcnt(24)
	v_cvt_pk_bf16_f32 v0, v208, s0
	v_mad_i32_i24 v145, v143, s4, v145
	global_store_short v[144:145], v0, off sc1
.LBB0_377:
	s_andn2_saveexec_b64 s[2:3], s[2:3]
	s_cbranch_execz .LBB0_379
	v_add_co_u32_e32 v146, vcc, 0x3000000, v152
	v_lshlrev_b64 v[142:143], 15, v[142:143]
	s_nop 0
	v_addc_co_u32_e32 v147, vcc, 0, v153, vcc
	global_store_dword v[146:147], v149, off offset:256 sc1
	v_add_co_u32_e32 v146, vcc, 0x3400000, v152
	v_cvt_pk_bf16_f32 v0, v141, s0
	v_lshl_add_u64 v[144:145], v[144:145], 0, v[142:143]
	v_addc_co_u32_e32 v147, vcc, 0, v153, vcc
	global_store_short v[144:145], v0, off sc1
	s_waitcnt vmcnt(25)
	v_cvt_pk_bf16_f32 v0, v208, s0
	v_lshl_add_u64 v[142:143], v[150:151], 0, v[142:143]
	global_store_dword v[146:147], v208, off offset:256 sc1
	global_store_short v[142:143], v0, off sc1
.LBB0_379:
	s_or_b64 exec, exec, s[2:3]
	global_load_dword v248, v[30:31], off
	global_load_dword v249, v[30:31], off offset:256
	global_load_dword v250, v[30:31], off offset:512
	v_readlane_b32 s4, v252, 48
	v_lshlrev_b64 v[144:145], 11, v[106:107]
	v_readlane_b32 s6, v252, 50
	v_readlane_b32 s7, v252, 51
	s_waitcnt vmcnt(25)
	v_add_f32_e32 v93, v93, v207
	v_fma_f32 v93, v93, 0.5, -v185
	v_lshl_add_u64 v[142:143], s[6:7], 0, v[144:145]
	v_mov_b32_e32 v141, v1
	v_lshl_add_u64 v[146:147], v[142:143], 0, v[140:141]
	s_mov_b64 s[2:3], 0xc00
	v_mov_b32_e32 v230, 0
	v_mov_b32_e32 v231, 0
	v_readlane_b32 s5, v252, 49
	v_readlane_b32 s8, v252, 52
	v_readlane_b32 s9, v252, 53
	v_readlane_b32 s10, v252, 54
	v_readlane_b32 s11, v252, 55
	v_readlane_b32 s12, v252, 56
	v_readlane_b32 s13, v252, 57
	v_readlane_b32 s14, v252, 58
	v_readlane_b32 s15, v252, 59
	v_readlane_b32 s16, v252, 60
	v_readlane_b32 s17, v252, 61
	v_readlane_b32 s18, v252, 62
	v_readlane_b32 s19, v252, 63
	s_waitcnt vmcnt(2)
	v_mov_b32_e32 v0, v248
	v_fmac_f32_e32 v185, v93, v0
	global_store_dword v[146:147], v185, off sc1
	v_add_f32_e32 v93, v204, v210
	v_fma_f32 v93, v93, 0.5, -v205
	s_waitcnt vmcnt(2)
	v_mov_b32_e32 v0, v249
	v_fmac_f32_e32 v205, v93, v0
	global_store_dword v[146:147], v205, off offset:256 sc1
	v_add_f32_e32 v93, v209, v212
	v_fma_f32 v93, v93, 0.5, -v211
	s_waitcnt vmcnt(2)
	v_mov_b32_e32 v0, v250
	v_fmac_f32_e32 v211, v93, v0
	v_lshlrev_b32_e32 v0, 2, v32
	global_store_dword v[146:147], v211, off offset:512 sc1
	v_lshl_add_u64 v[148:149], v[138:139], 0, v[0:1]
	global_load_dword v224, v[148:149], off offset:3072
	v_lshl_add_u64 v[140:141], v[148:149], 0, s[2:3]
	s_and_saveexec_b64 s[2:3], s[44:45]
	s_cbranch_execz .LBB0_381
	v_add_co_u32_e32 v148, vcc, 0xffffe000, v140
	s_nop 1
	v_addc_co_u32_e32 v149, vcc, -1, v141, vcc
	global_load_dword v231, v[148:149], off offset:-3072

.LBB0_489:
	v_readlane_b32 s16, v254, 41
	s_mov_b32 s86, 0x6b015ac0
	v_or_b32_e32 v109, s77, v139
	v_readlane_b32 s17, v254, 42
	s_mov_b32 s87, 0x3f55ac05
	v_add_u32_e32 v108, s76, v145
	v_or_b32_e32 v100, v109, v133
	s_cmp_lt_i32 s45, 2
	s_mov_b64 s[2:3], -1
	s_cbranch_scc1 .LBB0_505
	s_cmp_lt_i32 s45, 3
	s_cbranch_scc1 .LBB0_502
	s_mov_b64 s[56:57], -1
	s_mov_b64 s[2:3], 0
	s_cmp_lt_i32 s45, 5
	s_mov_b64 s[20:21], 0
	s_cbranch_scc1 .LBB0_495
	s_cmp_eq_u32 s45, 5
	s_mov_b64 s[20:21], -1
	s_cbranch_scc0 .LBB0_494
	v_cndmask_b32_e64 v102, v82, v83, s[40:41]
	v_or_b32_e32 v101, v108, v146
	v_and_b32_e32 v104, 0xffffffde, v100
	v_mov_b32_dpp v102, v102 quad_perm:[1,0,3,2] row_mask:0xf bank_mask:0xf bound_ctrl:1
	v_cndmask_b32_e64 v103, v102, v82, s[40:41]
	v_cndmask_b32_e64 v102, v83, v102, s[40:41]
	v_lshlrev_b32_e32 v101, 10, v101
	v_cvt_pk_bf16_f32 v105, v103, v102
	v_add_u32_e32 v102, v104, v101
	v_mov_b32_e32 v103, v1
	v_lshl_add_u64 v[102:103], v[102:103], 1, s[54:55]
	global_store_dword v[102:103], v105, off sc1
	v_cndmask_b32_e64 v102, v84, v85, s[40:41]
	v_or_b32_e32 v106, 0x800, v101
	v_or_b32_e32 v107, 0x2000, v101
	v_mov_b32_dpp v102, v102 quad_perm:[1,0,3,2] row_mask:0xf bank_mask:0xf bound_ctrl:1
	v_cndmask_b32_e64 v103, v102, v84, s[40:41]
	v_cndmask_b32_e64 v102, v85, v102, s[40:41]
	v_cvt_pk_bf16_f32 v105, v103, v102
	v_add_u32_e32 v102, v104, v106
	v_mov_b32_e32 v103, v1
	v_lshl_add_u64 v[102:103], v[102:103], 1, s[54:55]
	global_store_dword v[102:103], v105, off sc1
	v_cndmask_b32_e64 v102, v86, v87, s[40:41]
	v_or_b32_e32 v110, 0x2800, v101
	v_or_b32_e32 v111, 0x4000, v101
	v_mov_b32_dpp v102, v102 quad_perm:[1,0,3,2] row_mask:0xf bank_mask:0xf bound_ctrl:1
	v_cndmask_b32_e64 v103, v102, v86, s[40:41]
	v_cndmask_b32_e64 v102, v87, v102, s[40:41]
	v_cvt_pk_bf16_f32 v105, v103, v102
	v_add_u32_e32 v102, v104, v107
	v_mov_b32_e32 v103, v1
	v_lshl_add_u64 v[102:103], v[102:103], 1, s[54:55]
	global_store_dword v[102:103], v105, off sc1
	v_cndmask_b32_e64 v102, v88, v89, s[40:41]
	v_or_b32_e32 v112, 0x4800, v101
	v_or_b32_e32 v113, 0x6000, v101
	v_mov_b32_dpp v102, v102 quad_perm:[1,0,3,2] row_mask:0xf bank_mask:0xf bound_ctrl:1
	v_cndmask_b32_e64 v103, v102, v88, s[40:41]
	v_cndmask_b32_e64 v102, v89, v102, s[40:41]
	v_cvt_pk_bf16_f32 v105, v103, v102
	v_add_u32_e32 v102, v104, v110
	v_mov_b32_e32 v103, v1
	v_lshl_add_u64 v[102:103], v[102:103], 1, s[54:55]
	global_store_dword v[102:103], v105, off sc1
	v_cndmask_b32_e64 v102, v90, v91, s[40:41]
	v_or_b32_e32 v148, 0x6800, v101
	v_add_u32_e32 v150, 0xe800, v101
	v_mov_b32_dpp v102, v102 quad_perm:[1,0,3,2] row_mask:0xf bank_mask:0xf bound_ctrl:1
	v_cndmask_b32_e64 v103, v102, v90, s[40:41]
	v_cndmask_b32_e64 v102, v91, v102, s[40:41]
	v_cvt_pk_bf16_f32 v105, v103, v102
	v_add_u32_e32 v102, v104, v111
	v_mov_b32_e32 v103, v1
	v_lshl_add_u64 v[102:103], v[102:103], 1, s[54:55]
	global_store_dword v[102:103], v105, off sc1
	v_cndmask_b32_e64 v102, v92, v93, s[40:41]
	s_mov_b64 s[20:21], 0
	s_nop 0
	v_mov_b32_dpp v102, v102 quad_perm:[1,0,3,2] row_mask:0xf bank_mask:0xf bound_ctrl:1
	v_cndmask_b32_e64 v103, v102, v92, s[40:41]
	v_cndmask_b32_e64 v102, v93, v102, s[40:41]
	v_cvt_pk_bf16_f32 v105, v103, v102
	v_add_u32_e32 v102, v104, v112
	v_mov_b32_e32 v103, v1
	v_lshl_add_u64 v[102:103], v[102:103], 1, s[54:55]
	global_store_dword v[102:103], v105, off sc1
	v_cndmask_b32_e64 v102, v94, v95, s[40:41]
	s_nop 1
	v_mov_b32_dpp v102, v102 quad_perm:[1,0,3,2] row_mask:0xf bank_mask:0xf bound_ctrl:1
	v_cndmask_b32_e64 v103, v102, v94, s[40:41]
	v_cndmask_b32_e64 v102, v95, v102, s[40:41]
	v_cvt_pk_bf16_f32 v105, v103, v102
	v_add_u32_e32 v102, v104, v113
	v_mov_b32_e32 v103, v1
	v_lshl_add_u64 v[102:103], v[102:103], 1, s[54:55]
	global_store_dword v[102:103], v105, off sc1
	v_cndmask_b32_e64 v102, v96, v97, s[40:41]
	s_nop 1
	v_mov_b32_dpp v102, v102 quad_perm:[1,0,3,2] row_mask:0xf bank_mask:0xf bound_ctrl:1
	v_cndmask_b32_e64 v103, v102, v96, s[40:41]
	v_cndmask_b32_e64 v102, v97, v102, s[40:41]
	v_cvt_pk_bf16_f32 v105, v103, v102
	v_add_u32_e32 v102, v104, v148
	v_mov_b32_e32 v103, v1
	v_lshl_add_u64 v[102:103], v[102:103], 1, s[54:55]
	global_store_dword v[102:103], v105, off sc1
	v_cndmask_b32_e64 v102, v66, v67, s[40:41]
	v_or_b32_e32 v105, 32, v104
	s_nop 0
	v_mov_b32_dpp v102, v102 quad_perm:[1,0,3,2] row_mask:0xf bank_mask:0xf bound_ctrl:1
	v_cndmask_b32_e64 v103, v102, v66, s[40:41]
	v_cndmask_b32_e64 v102, v67, v102, s[40:41]
	v_cvt_pk_bf16_f32 v149, v103, v102
	v_add_u32_e32 v102, v105, v101
	v_mov_b32_e32 v103, v1
	v_lshl_add_u64 v[102:103], v[102:103], 1, s[54:55]
	global_store_dword v[102:103], v149, off sc1
	v_cndmask_b32_e64 v102, v68, v69, s[40:41]
	s_nop 1
	v_mov_b32_dpp v102, v102 quad_perm:[1,0,3,2] row_mask:0xf bank_mask:0xf bound_ctrl:1
	v_cndmask_b32_e64 v103, v102, v68, s[40:41]
	v_cndmask_b32_e64 v102, v69, v102, s[40:41]
	v_cvt_pk_bf16_f32 v149, v103, v102
	v_add_u32_e32 v102, v105, v106
	v_mov_b32_e32 v103, v1
	v_lshl_add_u64 v[102:103], v[102:103], 1, s[54:55]
	global_store_dword v[102:103], v149, off sc1
	v_cndmask_b32_e64 v102, v70, v71, s[40:41]
	v_add_u32_e32 v149, 0xe000, v101
	s_nop 0
	v_mov_b32_dpp v102, v102 quad_perm:[1,0,3,2] row_mask:0xf bank_mask:0xf bound_ctrl:1
	v_cndmask_b32_e64 v103, v102, v70, s[40:41]
	v_cndmask_b32_e64 v102, v71, v102, s[40:41]
	v_cvt_pk_bf16_f32 v106, v103, v102
	v_add_u32_e32 v102, v105, v107
	v_mov_b32_e32 v103, v1
	v_lshl_add_u64 v[102:103], v[102:103], 1, s[54:55]
	global_store_dword v[102:103], v106, off sc1
	v_cndmask_b32_e64 v102, v72, v73, s[40:41]
	v_add_u32_e32 v107, 0x8000, v101
	s_nop 0
	v_mov_b32_dpp v102, v102 quad_perm:[1,0,3,2] row_mask:0xf bank_mask:0xf bound_ctrl:1
	v_cndmask_b32_e64 v103, v102, v72, s[40:41]
	v_cndmask_b32_e64 v102, v73, v102, s[40:41]
	v_cvt_pk_bf16_f32 v106, v103, v102
	v_add_u32_e32 v102, v105, v110
	v_mov_b32_e32 v103, v1
	v_lshl_add_u64 v[102:103], v[102:103], 1, s[54:55]
	global_store_dword v[102:103], v106, off sc1
	v_cndmask_b32_e64 v102, v74, v75, s[40:41]
	v_add_u32_e32 v110, 0x8800, v101
	s_nop 0
	v_mov_b32_dpp v102, v102 quad_perm:[1,0,3,2] row_mask:0xf bank_mask:0xf bound_ctrl:1
	v_cndmask_b32_e64 v103, v102, v74, s[40:41]
	v_cndmask_b32_e64 v102, v75, v102, s[40:41]
	v_cvt_pk_bf16_f32 v106, v103, v102
	v_add_u32_e32 v102, v105, v111
	v_mov_b32_e32 v103, v1
	v_lshl_add_u64 v[102:103], v[102:103], 1, s[54:55]
	global_store_dword v[102:103], v106, off sc1
	v_cndmask_b32_e64 v102, v76, v77, s[40:41]
	v_add_u32_e32 v111, 0xa000, v101
	s_nop 0
	v_mov_b32_dpp v102, v102 quad_perm:[1,0,3,2] row_mask:0xf bank_mask:0xf bound_ctrl:1
	v_cndmask_b32_e64 v103, v102, v76, s[40:41]
	v_cndmask_b32_e64 v102, v77, v102, s[40:41]
	v_cvt_pk_bf16_f32 v106, v103, v102
	v_add_u32_e32 v102, v105, v112
	v_mov_b32_e32 v103, v1
	v_lshl_add_u64 v[102:103], v[102:103], 1, s[54:55]
	global_store_dword v[102:103], v106, off sc1
	v_cndmask_b32_e64 v102, v78, v79, s[40:41]
	v_add_u32_e32 v112, 0xa800, v101
	s_nop 0
	v_mov_b32_dpp v102, v102 quad_perm:[1,0,3,2] row_mask:0xf bank_mask:0xf bound_ctrl:1
	v_cndmask_b32_e64 v103, v102, v78, s[40:41]
	v_cndmask_b32_e64 v102, v79, v102, s[40:41]
	v_cvt_pk_bf16_f32 v106, v103, v102
	v_add_u32_e32 v102, v105, v113
	v_mov_b32_e32 v103, v1
	v_lshl_add_u64 v[102:103], v[102:103], 1, s[54:55]
	global_store_dword v[102:103], v106, off sc1
	v_cndmask_b32_e64 v102, v80, v81, s[40:41]
	v_add_u32_e32 v113, 0xc000, v101
	s_nop 0
	v_mov_b32_dpp v102, v102 quad_perm:[1,0,3,2] row_mask:0xf bank_mask:0xf bound_ctrl:1
	v_cndmask_b32_e64 v103, v102, v80, s[40:41]
	v_cndmask_b32_e64 v102, v81, v102, s[40:41]
	v_cvt_pk_bf16_f32 v106, v103, v102
	v_add_u32_e32 v102, v105, v148
	v_mov_b32_e32 v103, v1
	v_lshl_add_u64 v[102:103], v[102:103], 1, s[54:55]
	global_store_dword v[102:103], v106, off sc1
	v_cndmask_b32_e64 v102, v50, v51, s[40:41]
	v_add_u32_e32 v148, 0xc800, v101
	s_nop 0
	v_mov_b32_dpp v102, v102 quad_perm:[1,0,3,2] row_mask:0xf bank_mask:0xf bound_ctrl:1
	v_cndmask_b32_e64 v103, v102, v50, s[40:41]
	v_cndmask_b32_e64 v102, v51, v102, s[40:41]
	v_cvt_pk_bf16_f32 v106, v103, v102
	v_add_u32_e32 v102, v104, v107
	v_mov_b32_e32 v103, v1
	v_lshl_add_u64 v[102:103], v[102:103], 1, s[54:55]
	global_store_dword v[102:103], v106, off sc1
	v_cndmask_b32_e64 v102, v52, v53, s[40:41]
	s_nop 1
	v_mov_b32_dpp v102, v102 quad_perm:[1,0,3,2] row_mask:0xf bank_mask:0xf bound_ctrl:1
	v_cndmask_b32_e64 v103, v102, v52, s[40:41]
	v_cndmask_b32_e64 v102, v53, v102, s[40:41]
	v_cvt_pk_bf16_f32 v106, v103, v102
	v_add_u32_e32 v102, v104, v110
	v_mov_b32_e32 v103, v1
	v_lshl_add_u64 v[102:103], v[102:103], 1, s[54:55]
	global_store_dword v[102:103], v106, off sc1
	v_cndmask_b32_e64 v102, v54, v55, s[40:41]
	s_nop 1
	v_mov_b32_dpp v102, v102 quad_perm:[1,0,3,2] row_mask:0xf bank_mask:0xf bound_ctrl:1
	v_cndmask_b32_e64 v103, v102, v54, s[40:41]
	v_cndmask_b32_e64 v102, v55, v102, s[40:41]
	v_cvt_pk_bf16_f32 v106, v103, v102
	v_add_u32_e32 v102, v104, v111
	v_mov_b32_e32 v103, v1
	v_lshl_add_u64 v[102:103], v[102:103], 1, s[54:55]
	global_store_dword v[102:103], v106, off sc1
	v_cndmask_b32_e64 v102, v56, v57, s[40:41]
	s_nop 1
	v_mov_b32_dpp v102, v102 quad_perm:[1,0,3,2] row_mask:0xf bank_mask:0xf bound_ctrl:1
	v_cndmask_b32_e64 v103, v102, v56, s[40:41]
	v_cndmask_b32_e64 v102, v57, v102, s[40:41]
	v_cvt_pk_bf16_f32 v106, v103, v102
	v_add_u32_e32 v102, v104, v112
	v_mov_b32_e32 v103, v1
	v_lshl_add_u64 v[102:103], v[102:103], 1, s[54:55]
	global_store_dword v[102:103], v106, off sc1
	v_cndmask_b32_e64 v102, v58, v59, s[40:41]
	s_nop 1
	v_mov_b32_dpp v102, v102 quad_perm:[1,0,3,2] row_mask:0xf bank_mask:0xf bound_ctrl:1
	v_cndmask_b32_e64 v103, v102, v58, s[40:41]
	v_cndmask_b32_e64 v102, v59, v102, s[40:41]
	v_cvt_pk_bf16_f32 v106, v103, v102
	v_add_u32_e32 v102, v104, v113
	v_mov_b32_e32 v103, v1
	v_lshl_add_u64 v[102:103], v[102:103], 1, s[54:55]
	global_store_dword v[102:103], v106, off sc1
	v_cndmask_b32_e64 v102, v60, v61, s[40:41]
	s_nop 1
	v_mov_b32_dpp v102, v102 quad_perm:[1,0,3,2] row_mask:0xf bank_mask:0xf bound_ctrl:1
	v_cndmask_b32_e64 v103, v102, v60, s[40:41]
	v_cndmask_b32_e64 v102, v61, v102, s[40:41]
	v_cvt_pk_bf16_f32 v106, v103, v102
	v_add_u32_e32 v102, v104, v148
	v_mov_b32_e32 v103, v1
	v_lshl_add_u64 v[102:103], v[102:103], 1, s[54:55]
	global_store_dword v[102:103], v106, off sc1
	v_cndmask_b32_e64 v102, v62, v63, s[40:41]
	s_nop 1
	v_mov_b32_dpp v102, v102 quad_perm:[1,0,3,2] row_mask:0xf bank_mask:0xf bound_ctrl:1
	v_cndmask_b32_e64 v103, v102, v62, s[40:41]
	v_cndmask_b32_e64 v102, v63, v102, s[40:41]
	v_cvt_pk_bf16_f32 v106, v103, v102
	v_add_u32_e32 v102, v104, v149
	v_mov_b32_e32 v103, v1
	v_lshl_add_u64 v[102:103], v[102:103], 1, s[54:55]
	global_store_dword v[102:103], v106, off sc1
	v_cndmask_b32_e64 v102, v64, v65, s[40:41]
	s_nop 1
	v_mov_b32_dpp v102, v102 quad_perm:[1,0,3,2] row_mask:0xf bank_mask:0xf bound_ctrl:1
	v_cndmask_b32_e64 v103, v102, v64, s[40:41]
	v_cndmask_b32_e64 v102, v65, v102, s[40:41]
	v_cvt_pk_bf16_f32 v106, v103, v102
	v_add_u32_e32 v102, v104, v150
	v_mov_b32_e32 v103, v1
	v_lshl_add_u64 v[102:103], v[102:103], 1, s[54:55]
	global_store_dword v[102:103], v106, off sc1
	v_cndmask_b32_e64 v102, v34, v35, s[40:41]
	s_nop 1
	v_mov_b32_dpp v102, v102 quad_perm:[1,0,3,2] row_mask:0xf bank_mask:0xf bound_ctrl:1
	v_cndmask_b32_e64 v103, v102, v34, s[40:41]
	v_cndmask_b32_e64 v102, v35, v102, s[40:41]
	v_cvt_pk_bf16_f32 v106, v103, v102
	v_add_u32_e32 v102, v105, v107
	v_mov_b32_e32 v103, v1
	v_lshl_add_u64 v[102:103], v[102:103], 1, s[54:55]
	global_store_dword v[102:103], v106, off sc1
	v_cndmask_b32_e64 v102, v36, v37, s[40:41]
	v_add_u32_e32 v107, 0x10000, v101
	s_nop 0
	v_mov_b32_dpp v102, v102 quad_perm:[1,0,3,2] row_mask:0xf bank_mask:0xf bound_ctrl:1
	v_cndmask_b32_e64 v103, v102, v36, s[40:41]
	v_cndmask_b32_e64 v102, v37, v102, s[40:41]
	v_cvt_pk_bf16_f32 v106, v103, v102
	v_add_u32_e32 v102, v105, v110
	v_mov_b32_e32 v103, v1
	v_lshl_add_u64 v[102:103], v[102:103], 1, s[54:55]
	global_store_dword v[102:103], v106, off sc1
	v_cndmask_b32_e64 v102, v38, v39, s[40:41]
	v_add_u32_e32 v110, 0x10800, v101
	s_nop 0
	v_mov_b32_dpp v102, v102 quad_perm:[1,0,3,2] row_mask:0xf bank_mask:0xf bound_ctrl:1
	v_cndmask_b32_e64 v103, v102, v38, s[40:41]
	v_cndmask_b32_e64 v102, v39, v102, s[40:41]
	v_cvt_pk_bf16_f32 v106, v103, v102
	v_add_u32_e32 v102, v105, v111
	v_mov_b32_e32 v103, v1
	v_lshl_add_u64 v[102:103], v[102:103], 1, s[54:55]
	global_store_dword v[102:103], v106, off sc1
	v_cndmask_b32_e64 v102, v40, v41, s[40:41]
	v_add_u32_e32 v111, 0x12000, v101
	s_nop 0
	v_mov_b32_dpp v102, v102 quad_perm:[1,0,3,2] row_mask:0xf bank_mask:0xf bound_ctrl:1
	v_cndmask_b32_e64 v103, v102, v40, s[40:41]
	v_cndmask_b32_e64 v102, v41, v102, s[40:41]
	v_cvt_pk_bf16_f32 v106, v103, v102
	v_add_u32_e32 v102, v105, v112
	v_mov_b32_e32 v103, v1
	v_lshl_add_u64 v[102:103], v[102:103], 1, s[54:55]
	global_store_dword v[102:103], v106, off sc1
	v_cndmask_b32_e64 v102, v42, v43, s[40:41]
	v_add_u32_e32 v112, 0x12800, v101
	s_nop 0
	v_mov_b32_dpp v102, v102 quad_perm:[1,0,3,2] row_mask:0xf bank_mask:0xf bound_ctrl:1
	v_cndmask_b32_e64 v103, v102, v42, s[40:41]
	v_cndmask_b32_e64 v102, v43, v102, s[40:41]
	v_cvt_pk_bf16_f32 v106, v103, v102
	v_add_u32_e32 v102, v105, v113
	v_mov_b32_e32 v103, v1
	v_lshl_add_u64 v[102:103], v[102:103], 1, s[54:55]
	global_store_dword v[102:103], v106, off sc1
	v_cndmask_b32_e64 v102, v44, v45, s[40:41]
	v_add_u32_e32 v113, 0x14000, v101
	s_nop 0
	v_mov_b32_dpp v102, v102 quad_perm:[1,0,3,2] row_mask:0xf bank_mask:0xf bound_ctrl:1
	v_cndmask_b32_e64 v103, v102, v44, s[40:41]
	v_cndmask_b32_e64 v102, v45, v102, s[40:41]
	v_cvt_pk_bf16_f32 v106, v103, v102
	v_add_u32_e32 v102, v105, v148
	v_mov_b32_e32 v103, v1
	v_lshl_add_u64 v[102:103], v[102:103], 1, s[54:55]
	global_store_dword v[102:103], v106, off sc1
	v_cndmask_b32_e64 v102, v46, v47, s[40:41]
	v_add_u32_e32 v148, 0x14800, v101
	s_nop 0
	v_mov_b32_dpp v102, v102 quad_perm:[1,0,3,2] row_mask:0xf bank_mask:0xf bound_ctrl:1
	v_cndmask_b32_e64 v103, v102, v46, s[40:41]
	v_cndmask_b32_e64 v102, v47, v102, s[40:41]
	v_cvt_pk_bf16_f32 v106, v103, v102
	v_add_u32_e32 v102, v105, v149
	v_mov_b32_e32 v103, v1
	v_lshl_add_u64 v[102:103], v[102:103], 1, s[54:55]
	global_store_dword v[102:103], v106, off sc1
	v_cndmask_b32_e64 v102, v48, v49, s[40:41]
	v_add_u32_e32 v149, 0x16000, v101
	v_add_u32_e32 v101, 0x16800, v101
	v_mov_b32_dpp v102, v102 quad_perm:[1,0,3,2] row_mask:0xf bank_mask:0xf bound_ctrl:1
	v_cndmask_b32_e64 v103, v102, v48, s[40:41]
	v_cndmask_b32_e64 v102, v49, v102, s[40:41]
	v_cvt_pk_bf16_f32 v106, v103, v102
	v_add_u32_e32 v102, v105, v150
	v_mov_b32_e32 v103, v1
	v_lshl_add_u64 v[102:103], v[102:103], 1, s[54:55]
	global_store_dword v[102:103], v106, off sc1
	v_cndmask_b32_e64 v102, v18, v19, s[40:41]
	s_nop 1
	v_mov_b32_dpp v102, v102 quad_perm:[1,0,3,2] row_mask:0xf bank_mask:0xf bound_ctrl:1
	v_cndmask_b32_e64 v103, v102, v18, s[40:41]
	v_cndmask_b32_e64 v102, v19, v102, s[40:41]
	v_cvt_pk_bf16_f32 v106, v103, v102
	v_add_u32_e32 v102, v104, v107
	v_mov_b32_e32 v103, v1
	v_lshl_add_u64 v[102:103], v[102:103], 1, s[54:55]
	global_store_dword v[102:103], v106, off sc1
	v_cndmask_b32_e64 v102, v20, v21, s[40:41]
	s_nop 1
	v_mov_b32_dpp v102, v102 quad_perm:[1,0,3,2] row_mask:0xf bank_mask:0xf bound_ctrl:1
	v_cndmask_b32_e64 v103, v102, v20, s[40:41]
	v_cndmask_b32_e64 v102, v21, v102, s[40:41]
	v_cvt_pk_bf16_f32 v106, v103, v102
	v_add_u32_e32 v102, v104, v110
	v_mov_b32_e32 v103, v1
	v_lshl_add_u64 v[102:103], v[102:103], 1, s[54:55]
	global_store_dword v[102:103], v106, off sc1
	v_cndmask_b32_e64 v102, v22, v23, s[40:41]
	s_nop 1
	v_mov_b32_dpp v102, v102 quad_perm:[1,0,3,2] row_mask:0xf bank_mask:0xf bound_ctrl:1
	v_cndmask_b32_e64 v103, v102, v22, s[40:41]
	v_cndmask_b32_e64 v102, v23, v102, s[40:41]
	v_cvt_pk_bf16_f32 v106, v103, v102
	v_add_u32_e32 v102, v104, v111
	v_mov_b32_e32 v103, v1
	v_lshl_add_u64 v[102:103], v[102:103], 1, s[54:55]
	global_store_dword v[102:103], v106, off sc1
	v_cndmask_b32_e64 v102, v24, v25, s[40:41]
	s_nop 1
	v_mov_b32_dpp v102, v102 quad_perm:[1,0,3,2] row_mask:0xf bank_mask:0xf bound_ctrl:1
	v_cndmask_b32_e64 v103, v102, v24, s[40:41]
	v_cndmask_b32_e64 v102, v25, v102, s[40:41]
	v_cvt_pk_bf16_f32 v106, v103, v102
	v_add_u32_e32 v102, v104, v112
	v_mov_b32_e32 v103, v1
	v_lshl_add_u64 v[102:103], v[102:103], 1, s[54:55]
	global_store_dword v[102:103], v106, off sc1
	v_cndmask_b32_e64 v102, v26, v27, s[40:41]
	s_nop 1
	v_mov_b32_dpp v102, v102 quad_perm:[1,0,3,2] row_mask:0xf bank_mask:0xf bound_ctrl:1
	v_cndmask_b32_e64 v103, v102, v26, s[40:41]
	v_cndmask_b32_e64 v102, v27, v102, s[40:41]
	v_cvt_pk_bf16_f32 v106, v103, v102
	v_add_u32_e32 v102, v104, v113
	v_mov_b32_e32 v103, v1
	v_lshl_add_u64 v[102:103], v[102:103], 1, s[54:55]
	global_store_dword v[102:103], v106, off sc1
	v_cndmask_b32_e64 v102, v28, v29, s[40:41]
	s_nop 1
	v_mov_b32_dpp v102, v102 quad_perm:[1,0,3,2] row_mask:0xf bank_mask:0xf bound_ctrl:1
	v_cndmask_b32_e64 v103, v102, v28, s[40:41]
	v_cndmask_b32_e64 v102, v29, v102, s[40:41]
	v_cvt_pk_bf16_f32 v106, v103, v102
	v_add_u32_e32 v102, v104, v148
	v_mov_b32_e32 v103, v1
	v_lshl_add_u64 v[102:103], v[102:103], 1, s[54:55]
	global_store_dword v[102:103], v106, off sc1
	v_cndmask_b32_e64 v102, v30, v31, s[40:41]
	s_nop 1
	v_mov_b32_dpp v102, v102 quad_perm:[1,0,3,2] row_mask:0xf bank_mask:0xf bound_ctrl:1
	v_cndmask_b32_e64 v103, v102, v30, s[40:41]
	v_cndmask_b32_e64 v102, v31, v102, s[40:41]
	v_cvt_pk_bf16_f32 v106, v103, v102
	v_add_u32_e32 v102, v104, v149
	v_mov_b32_e32 v103, v1
	v_lshl_add_u64 v[102:103], v[102:103], 1, s[54:55]
	global_store_dword v[102:103], v106, off sc1
	v_cndmask_b32_e64 v102, v32, v33, s[40:41]
	s_nop 1
	v_mov_b32_dpp v102, v102 quad_perm:[1,0,3,2] row_mask:0xf bank_mask:0xf bound_ctrl:1
	v_cndmask_b32_e64 v103, v102, v32, s[40:41]
	v_cndmask_b32_e64 v102, v33, v102, s[40:41]
	v_cvt_pk_bf16_f32 v106, v103, v102
	v_add_u32_e32 v102, v104, v101
	v_mov_b32_e32 v103, v1
	v_lshl_add_u64 v[102:103], v[102:103], 1, s[54:55]
	global_store_dword v[102:103], v106, off sc1
	v_cndmask_b32_e64 v102, v2, v3, s[40:41]
	s_nop 1
	v_mov_b32_dpp v102, v102 quad_perm:[1,0,3,2] row_mask:0xf bank_mask:0xf bound_ctrl:1
	v_cndmask_b32_e64 v103, v102, v2, s[40:41]
	v_cndmask_b32_e64 v102, v3, v102, s[40:41]
	v_cvt_pk_bf16_f32 v104, v103, v102
	v_add_u32_e32 v102, v105, v107
	v_mov_b32_e32 v103, v1
	v_lshl_add_u64 v[102:103], v[102:103], 1, s[54:55]
	global_store_dword v[102:103], v104, off sc1
	v_cndmask_b32_e64 v102, v4, v5, s[40:41]
	s_nop 1
	v_mov_b32_dpp v102, v102 quad_perm:[1,0,3,2] row_mask:0xf bank_mask:0xf bound_ctrl:1
	v_cndmask_b32_e64 v103, v102, v4, s[40:41]
	v_cndmask_b32_e64 v102, v5, v102, s[40:41]
	v_cvt_pk_bf16_f32 v104, v103, v102
	v_add_u32_e32 v102, v105, v110
	v_mov_b32_e32 v103, v1
	v_lshl_add_u64 v[102:103], v[102:103], 1, s[54:55]
	global_store_dword v[102:103], v104, off sc1
	v_cndmask_b32_e64 v102, v6, v7, s[40:41]
	s_nop 1
	v_mov_b32_dpp v102, v102 quad_perm:[1,0,3,2] row_mask:0xf bank_mask:0xf bound_ctrl:1
	v_cndmask_b32_e64 v103, v102, v6, s[40:41]
	v_cndmask_b32_e64 v102, v7, v102, s[40:41]
	v_cvt_pk_bf16_f32 v104, v103, v102
	v_add_u32_e32 v102, v105, v111
	v_mov_b32_e32 v103, v1
	v_lshl_add_u64 v[102:103], v[102:103], 1, s[54:55]
	global_store_dword v[102:103], v104, off sc1
	v_cndmask_b32_e64 v102, v8, v9, s[40:41]
	s_nop 1
	v_mov_b32_dpp v102, v102 quad_perm:[1,0,3,2] row_mask:0xf bank_mask:0xf bound_ctrl:1
	v_cndmask_b32_e64 v103, v102, v8, s[40:41]
	v_cndmask_b32_e64 v102, v9, v102, s[40:41]
	v_cvt_pk_bf16_f32 v104, v103, v102
	v_add_u32_e32 v102, v105, v112
	v_mov_b32_e32 v103, v1
	v_lshl_add_u64 v[102:103], v[102:103], 1, s[54:55]
	global_store_dword v[102:103], v104, off sc1
	v_cndmask_b32_e64 v102, v10, v11, s[40:41]
	s_nop 1
	v_mov_b32_dpp v102, v102 quad_perm:[1,0,3,2] row_mask:0xf bank_mask:0xf bound_ctrl:1
	v_cndmask_b32_e64 v103, v102, v10, s[40:41]
	v_cndmask_b32_e64 v102, v11, v102, s[40:41]
	v_cvt_pk_bf16_f32 v104, v103, v102
	v_add_u32_e32 v102, v105, v113
	v_mov_b32_e32 v103, v1
	v_lshl_add_u64 v[102:103], v[102:103], 1, s[54:55]
	global_store_dword v[102:103], v104, off sc1
	v_cndmask_b32_e64 v102, v12, v13, s[40:41]
	s_nop 1
	v_mov_b32_dpp v102, v102 quad_perm:[1,0,3,2] row_mask:0xf bank_mask:0xf bound_ctrl:1
	v_cndmask_b32_e64 v103, v102, v12, s[40:41]
	v_cndmask_b32_e64 v102, v13, v102, s[40:41]
	v_cvt_pk_bf16_f32 v104, v103, v102
	v_add_u32_e32 v102, v105, v148
	v_mov_b32_e32 v103, v1
	v_lshl_add_u64 v[102:103], v[102:103], 1, s[54:55]
	global_store_dword v[102:103], v104, off sc1
	v_cndmask_b32_e64 v102, v14, v15, s[40:41]
	s_nop 1
	v_mov_b32_dpp v102, v102 quad_perm:[1,0,3,2] row_mask:0xf bank_mask:0xf bound_ctrl:1
	v_cndmask_b32_e64 v103, v102, v14, s[40:41]
	v_cndmask_b32_e64 v102, v15, v102, s[40:41]
	v_cvt_pk_bf16_f32 v104, v103, v102
	v_add_u32_e32 v102, v105, v149
	v_mov_b32_e32 v103, v1
	v_lshl_add_u64 v[102:103], v[102:103], 1, s[54:55]
	global_store_dword v[102:103], v104, off sc1
	v_cndmask_b32_e64 v102, v16, v17, s[40:41]
	s_nop 1
	v_mov_b32_dpp v102, v102 quad_perm:[1,0,3,2] row_mask:0xf bank_mask:0xf bound_ctrl:1
	v_cndmask_b32_e64 v103, v102, v16, s[40:41]
	v_cndmask_b32_e64 v102, v17, v102, s[40:41]
	v_cvt_pk_bf16_f32 v104, v103, v102
	v_add_u32_e32 v102, v105, v101
	v_mov_b32_e32 v103, v1
	v_lshl_add_u64 v[102:103], v[102:103], 1, s[54:55]
	global_store_dword v[102:103], v104, off sc1

.LBB0_497:
	v_lshlrev_b32_e32 v110, 9, v108
	s_andn2_b64 vcc, exec, s[20:21]
	v_ashrrev_i32_e32 v101, 31, v100
	v_add_u32_e32 v102, v100, v110
	v_or_b32_e32 v159, 0x200, v110
	v_or_b32_e32 v158, 0x400, v110
	v_or_b32_e32 v157, 0x600, v110
	v_or_b32_e32 v156, 0x1000, v110
	v_or_b32_e32 v155, 0x1200, v110
	v_or_b32_e32 v154, 0x1400, v110
	v_or_b32_e32 v153, 0x1600, v110
	v_or_b32_e32 v152, 0x2000, v110
	v_or_b32_e32 v151, 0x2200, v110
	v_or_b32_e32 v150, 0x2400, v110
	v_or_b32_e32 v149, 0x2600, v110
	v_or_b32_e32 v148, 0x3000, v110
	v_or_b32_e32 v113, 0x3200, v110
	v_or_b32_e32 v112, 0x3400, v110
	v_or_b32_e32 v111, 0x3600, v110
	s_cbranch_vccnz .LBB0_499
	v_readlane_b32 s4, v252, 52
	v_readlane_b32 s5, v252, 53
	v_readlane_b32 s8, v252, 56
	v_readlane_b32 s9, v252, 57
	v_lshlrev_b64 v[106:107], 2, v[100:101]
	v_lshl_add_u64 v[104:105], s[58:59], 0, v[106:107]
	v_lshl_add_u64 v[106:107], s[0:1], 0, v[106:107]
	global_load_dword v240, v[104:105], off
	global_load_dword v241, v[104:105], off offset:128
	global_load_dword v242, v[106:107], off
	global_load_dword v243, v[106:107], off offset:128
	v_lshlrev_b32_e32 v244, 2, v102
	v_mov_b32_e32 v245, v244
	v_add_u32_e32 v246, 0x1000, v244
	v_add_u32_e32 v247, 0x4000, v244
	v_add_u32_e32 v248, 0x5000, v244
	global_load_dword v204, v245, s[4:5]
	global_load_dword v220, v245, s[8:9]
	global_load_dword v205, v245, s[4:5] offset:128
	global_load_dword v221, v245, s[8:9] offset:128
	global_load_dword v206, v245, s[4:5] offset:2048
	global_load_dword v222, v245, s[8:9] offset:2048
	global_load_dword v207, v245, s[4:5] offset:2176
	global_load_dword v223, v245, s[8:9] offset:2176
	global_load_dword v208, v246, s[4:5]
	global_load_dword v224, v246, s[8:9]
	global_load_dword v209, v246, s[4:5] offset:128
	global_load_dword v225, v246, s[8:9] offset:128
	global_load_dword v210, v246, s[4:5] offset:2048
	global_load_dword v226, v246, s[8:9] offset:2048
	global_load_dword v211, v246, s[4:5] offset:2176
	global_load_dword v227, v246, s[8:9] offset:2176
	global_load_dword v212, v247, s[4:5]
	global_load_dword v228, v247, s[8:9]
	global_load_dword v213, v247, s[4:5] offset:128
	global_load_dword v229, v247, s[8:9] offset:128
	global_load_dword v214, v247, s[4:5] offset:2048
	global_load_dword v230, v247, s[8:9] offset:2048
	global_load_dword v215, v247, s[4:5] offset:2176
	global_load_dword v231, v247, s[8:9] offset:2176
	global_load_dword v216, v248, s[4:5]
	global_load_dword v232, v248, s[8:9]
	global_load_dword v217, v248, s[4:5] offset:128
	global_load_dword v233, v248, s[8:9] offset:128
	global_load_dword v218, v248, s[4:5] offset:2048
	global_load_dword v234, v248, s[8:9] offset:2048
	global_load_dword v219, v248, s[4:5] offset:2176
	global_load_dword v235, v248, s[8:9] offset:2176
	s_waitcnt vmcnt(32)
	v_add_f32_e32 v82, v82, v240
	v_add_f32_e32 v66, v66, v241
	v_add_f32_e32 v83, v83, v240
	v_add_f32_e32 v67, v67, v241
	v_mul_f32_e32 v82, 0xbfb8aa3b, v82
	v_mul_f32_e32 v66, 0xbfb8aa3b, v66
	v_mul_f32_e32 v83, 0xbfb8aa3b, v83
	v_mul_f32_e32 v67, 0xbfb8aa3b, v67
	v_exp_f32_e32 v82, v82
	v_exp_f32_e32 v66, v66
	v_exp_f32_e32 v83, v83
	v_exp_f32_e32 v67, v67
	v_add_f32_e32 v82, 1.0, v82
	v_add_f32_e32 v66, 1.0, v66
	v_add_f32_e32 v83, 1.0, v83
	v_add_f32_e32 v67, 1.0, v67
	v_rcp_f32_e32 v82, v82
	v_rcp_f32_e32 v66, v66
	v_rcp_f32_e32 v83, v83
	v_rcp_f32_e32 v67, v67
	v_add_f32_e32 v84, v84, v240
	v_add_f32_e32 v68, v68, v241
	v_add_f32_e32 v85, v85, v240
	v_add_f32_e32 v69, v69, v241
	v_mul_f32_e32 v84, 0xbfb8aa3b, v84
	v_mul_f32_e32 v68, 0xbfb8aa3b, v68
	v_mul_f32_e32 v85, 0xbfb8aa3b, v85
	v_mul_f32_e32 v69, 0xbfb8aa3b, v69
	v_exp_f32_e32 v84, v84
	v_exp_f32_e32 v68, v68
	v_exp_f32_e32 v85, v85
	v_exp_f32_e32 v69, v69
	v_add_f32_e32 v84, 1.0, v84
	v_add_f32_e32 v68, 1.0, v68
	v_add_f32_e32 v85, 1.0, v85
	v_add_f32_e32 v69, 1.0, v69
	v_rcp_f32_e32 v84, v84
	v_rcp_f32_e32 v68, v68
	v_rcp_f32_e32 v85, v85
	v_rcp_f32_e32 v69, v69
	v_add_f32_e32 v86, v86, v240
	v_add_f32_e32 v70, v70, v241
	v_add_f32_e32 v87, v87, v240
	v_add_f32_e32 v71, v71, v241
	v_mul_f32_e32 v86, 0xbfb8aa3b, v86
	v_mul_f32_e32 v70, 0xbfb8aa3b, v70
	v_mul_f32_e32 v87, 0xbfb8aa3b, v87
	v_mul_f32_e32 v71, 0xbfb8aa3b, v71
	v_exp_f32_e32 v86, v86
	v_exp_f32_e32 v70, v70
	v_exp_f32_e32 v87, v87
	v_exp_f32_e32 v71, v71
	v_add_f32_e32 v86, 1.0, v86
	v_add_f32_e32 v70, 1.0, v70
	v_add_f32_e32 v87, 1.0, v87
	v_add_f32_e32 v71, 1.0, v71
	v_rcp_f32_e32 v86, v86
	v_rcp_f32_e32 v70, v70
	v_rcp_f32_e32 v87, v87
	v_rcp_f32_e32 v71, v71
	v_add_f32_e32 v88, v88, v240
	v_add_f32_e32 v72, v72, v241
	v_add_f32_e32 v89, v89, v240
	v_add_f32_e32 v73, v73, v241
	v_mul_f32_e32 v88, 0xbfb8aa3b, v88
	v_mul_f32_e32 v72, 0xbfb8aa3b, v72
	v_mul_f32_e32 v89, 0xbfb8aa3b, v89
	v_mul_f32_e32 v73, 0xbfb8aa3b, v73
	v_exp_f32_e32 v88, v88
	v_exp_f32_e32 v72, v72
	v_exp_f32_e32 v89, v89
	v_exp_f32_e32 v73, v73
	v_add_f32_e32 v88, 1.0, v88
	v_add_f32_e32 v72, 1.0, v72
	v_add_f32_e32 v89, 1.0, v89
	v_add_f32_e32 v73, 1.0, v73
	v_rcp_f32_e32 v88, v88
	v_rcp_f32_e32 v72, v72
	v_rcp_f32_e32 v89, v89
	v_rcp_f32_e32 v73, v73
	s_waitcnt vmcnt(0)
	v_mul_f32_e32 v204, v82, v204
	v_add_f32_e32 v82, -1.0, v82
	v_mul_f32_e32 v205, v66, v205
	v_add_f32_e32 v66, -1.0, v66
	v_mul_f32_e32 v206, v83, v206
	v_add_f32_e32 v83, -1.0, v83
	v_mul_f32_e32 v207, v67, v207
	v_add_f32_e32 v67, -1.0, v67
	v_mul_f32_e32 v208, v84, v208
	v_add_f32_e32 v84, -1.0, v84
	v_mul_f32_e32 v209, v68, v209
	v_add_f32_e32 v68, -1.0, v68
	v_mul_f32_e32 v210, v85, v210
	v_add_f32_e32 v85, -1.0, v85
	v_mul_f32_e32 v211, v69, v211
	v_add_f32_e32 v69, -1.0, v69
	v_mul_f32_e32 v212, v86, v212
	v_add_f32_e32 v86, -1.0, v86
	v_mul_f32_e32 v213, v70, v213
	v_add_f32_e32 v70, -1.0, v70
	v_mul_f32_e32 v214, v87, v214
	v_add_f32_e32 v87, -1.0, v87
	v_mul_f32_e32 v215, v71, v215
	v_add_f32_e32 v71, -1.0, v71
	v_mul_f32_e32 v216, v88, v216
	v_add_f32_e32 v88, -1.0, v88
	v_mul_f32_e32 v217, v72, v217
	v_add_f32_e32 v72, -1.0, v72
	v_mul_f32_e32 v218, v89, v218
	v_add_f32_e32 v89, -1.0, v89
	v_mul_f32_e32 v219, v73, v219
	v_add_f32_e32 v73, -1.0, v73
	v_fma_f32 v82, v242, v82, 1.0
	v_fma_f32 v66, v243, v66, 1.0
	v_fma_f32 v83, v242, v83, 1.0
	v_fma_f32 v67, v243, v67, 1.0
	v_fma_f32 v84, v242, v84, 1.0
	v_fma_f32 v68, v243, v68, 1.0
	v_fma_f32 v85, v242, v85, 1.0
	v_fma_f32 v69, v243, v69, 1.0
	v_fma_f32 v86, v242, v86, 1.0
	v_fma_f32 v70, v243, v70, 1.0
	v_fma_f32 v87, v242, v87, 1.0
	v_fma_f32 v71, v243, v71, 1.0
	v_fma_f32 v88, v242, v88, 1.0
	v_fma_f32 v72, v243, v72, 1.0
	v_fma_f32 v89, v242, v89, 1.0
	v_fma_f32 v73, v243, v73, 1.0
	v_mul_f32_e32 v220, v82, v220
	v_mul_f32_e32 v221, v66, v221
	v_mul_f32_e32 v222, v83, v222
	v_mul_f32_e32 v223, v67, v223
	v_mul_f32_e32 v224, v84, v224
	v_mul_f32_e32 v225, v68, v225
	v_mul_f32_e32 v226, v85, v226
	v_mul_f32_e32 v227, v69, v227
	v_mul_f32_e32 v228, v86, v228
	v_mul_f32_e32 v229, v70, v229
	v_mul_f32_e32 v230, v87, v230
	v_mul_f32_e32 v231, v71, v231
	v_mul_f32_e32 v232, v88, v232
	v_mul_f32_e32 v233, v72, v233
	v_mul_f32_e32 v234, v89, v234
	v_mul_f32_e32 v235, v73, v235
	global_store_dword v245, v204, s[94:95] sc1
	global_store_dword v245, v220, s[42:43] sc1
	global_store_dword v245, v205, s[94:95] offset:128 sc1
	global_store_dword v245, v221, s[42:43] offset:128 sc1
	global_store_dword v245, v206, s[94:95] offset:2048 sc1
	global_store_dword v245, v222, s[42:43] offset:2048 sc1
	global_store_dword v245, v207, s[94:95] offset:2176 sc1
	global_store_dword v245, v223, s[42:43] offset:2176 sc1
	global_store_dword v246, v208, s[94:95] sc1
	global_store_dword v246, v224, s[42:43] sc1
	global_store_dword v246, v209, s[94:95] offset:128 sc1
	global_store_dword v246, v225, s[42:43] offset:128 sc1
	global_store_dword v246, v210, s[94:95] offset:2048 sc1
	global_store_dword v246, v226, s[42:43] offset:2048 sc1
	global_store_dword v246, v211, s[94:95] offset:2176 sc1
	global_store_dword v246, v227, s[42:43] offset:2176 sc1
	global_store_dword v247, v212, s[94:95] sc1
	global_store_dword v247, v228, s[42:43] sc1
	global_store_dword v247, v213, s[94:95] offset:128 sc1
	global_store_dword v247, v229, s[42:43] offset:128 sc1
	global_store_dword v247, v214, s[94:95] offset:2048 sc1
	global_store_dword v247, v230, s[42:43] offset:2048 sc1
	global_store_dword v247, v215, s[94:95] offset:2176 sc1
	global_store_dword v247, v231, s[42:43] offset:2176 sc1
	global_store_dword v248, v216, s[94:95] sc1
	global_store_dword v248, v232, s[42:43] sc1
	global_store_dword v248, v217, s[94:95] offset:128 sc1
	global_store_dword v248, v233, s[42:43] offset:128 sc1
	global_store_dword v248, v218, s[94:95] offset:2048 sc1
	global_store_dword v248, v234, s[42:43] offset:2048 sc1
	global_store_dword v248, v219, s[94:95] offset:2176 sc1
	global_store_dword v248, v235, s[42:43] offset:2176 sc1
	v_add_u32_e32 v245, 0x8000, v244
	v_add_u32_e32 v246, 0x9000, v244
	v_add_u32_e32 v247, 0xc000, v244
	v_add_u32_e32 v248, 0xd000, v244
	global_load_dword v204, v245, s[4:5]
	global_load_dword v220, v245, s[8:9]
	global_load_dword v205, v245, s[4:5] offset:128
	global_load_dword v221, v245, s[8:9] offset:128
	global_load_dword v206, v245, s[4:5] offset:2048
	global_load_dword v222, v245, s[8:9] offset:2048
	global_load_dword v207, v245, s[4:5] offset:2176
	global_load_dword v223, v245, s[8:9] offset:2176
	global_load_dword v208, v246, s[4:5]
	global_load_dword v224, v246, s[8:9]
	global_load_dword v209, v246, s[4:5] offset:128
	global_load_dword v225, v246, s[8:9] offset:128
	global_load_dword v210, v246, s[4:5] offset:2048
	global_load_dword v226, v246, s[8:9] offset:2048
	global_load_dword v211, v246, s[4:5] offset:2176
	global_load_dword v227, v246, s[8:9] offset:2176
	global_load_dword v212, v247, s[4:5]
	global_load_dword v228, v247, s[8:9]
	global_load_dword v213, v247, s[4:5] offset:128
	global_load_dword v229, v247, s[8:9] offset:128
	global_load_dword v214, v247, s[4:5] offset:2048
	global_load_dword v230, v247, s[8:9] offset:2048
	global_load_dword v215, v247, s[4:5] offset:2176
	global_load_dword v231, v247, s[8:9] offset:2176
	global_load_dword v216, v248, s[4:5]
	global_load_dword v232, v248, s[8:9]
	global_load_dword v217, v248, s[4:5] offset:128
	global_load_dword v233, v248, s[8:9] offset:128
	global_load_dword v218, v248, s[4:5] offset:2048
	global_load_dword v234, v248, s[8:9] offset:2048
	global_load_dword v219, v248, s[4:5] offset:2176
	global_load_dword v235, v248, s[8:9] offset:2176
	v_add_f32_e32 v90, v90, v240
	v_add_f32_e32 v74, v74, v241
	v_add_f32_e32 v91, v91, v240
	v_add_f32_e32 v75, v75, v241
	v_mul_f32_e32 v90, 0xbfb8aa3b, v90
	v_mul_f32_e32 v74, 0xbfb8aa3b, v74
	v_mul_f32_e32 v91, 0xbfb8aa3b, v91
	v_mul_f32_e32 v75, 0xbfb8aa3b, v75
	v_exp_f32_e32 v90, v90
	v_exp_f32_e32 v74, v74
	v_exp_f32_e32 v91, v91
	v_exp_f32_e32 v75, v75
	v_add_f32_e32 v90, 1.0, v90
	v_add_f32_e32 v74, 1.0, v74
	v_add_f32_e32 v91, 1.0, v91
	v_add_f32_e32 v75, 1.0, v75
	v_rcp_f32_e32 v90, v90
	v_rcp_f32_e32 v74, v74
	v_rcp_f32_e32 v91, v91
	v_rcp_f32_e32 v75, v75
	v_add_f32_e32 v92, v92, v240
	v_add_f32_e32 v76, v76, v241
	v_add_f32_e32 v93, v93, v240
	v_add_f32_e32 v77, v77, v241
	v_mul_f32_e32 v92, 0xbfb8aa3b, v92
	v_mul_f32_e32 v76, 0xbfb8aa3b, v76
	v_mul_f32_e32 v93, 0xbfb8aa3b, v93
	v_mul_f32_e32 v77, 0xbfb8aa3b, v77
	v_exp_f32_e32 v92, v92
	v_exp_f32_e32 v76, v76
	v_exp_f32_e32 v93, v93
	v_exp_f32_e32 v77, v77
	v_add_f32_e32 v92, 1.0, v92
	v_add_f32_e32 v76, 1.0, v76
	v_add_f32_e32 v93, 1.0, v93
	v_add_f32_e32 v77, 1.0, v77
	v_rcp_f32_e32 v92, v92
	v_rcp_f32_e32 v76, v76
	v_rcp_f32_e32 v93, v93
	v_rcp_f32_e32 v77, v77
	v_add_f32_e32 v94, v94, v240
	v_add_f32_e32 v78, v78, v241
	v_add_f32_e32 v95, v95, v240
	v_add_f32_e32 v79, v79, v241
	v_mul_f32_e32 v94, 0xbfb8aa3b, v94
	v_mul_f32_e32 v78, 0xbfb8aa3b, v78
	v_mul_f32_e32 v95, 0xbfb8aa3b, v95
	v_mul_f32_e32 v79, 0xbfb8aa3b, v79
	v_exp_f32_e32 v94, v94
	v_exp_f32_e32 v78, v78
	v_exp_f32_e32 v95, v95
	v_exp_f32_e32 v79, v79
	v_add_f32_e32 v94, 1.0, v94
	v_add_f32_e32 v78, 1.0, v78
	v_add_f32_e32 v95, 1.0, v95
	v_add_f32_e32 v79, 1.0, v79
	v_rcp_f32_e32 v94, v94
	v_rcp_f32_e32 v78, v78
	v_rcp_f32_e32 v95, v95
	v_rcp_f32_e32 v79, v79
	v_add_f32_e32 v96, v96, v240
	v_add_f32_e32 v80, v80, v241
	v_add_f32_e32 v97, v97, v240
	v_add_f32_e32 v81, v81, v241
	v_mul_f32_e32 v96, 0xbfb8aa3b, v96
	v_mul_f32_e32 v80, 0xbfb8aa3b, v80
	v_mul_f32_e32 v97, 0xbfb8aa3b, v97
	v_mul_f32_e32 v81, 0xbfb8aa3b, v81
	v_exp_f32_e32 v96, v96
	v_exp_f32_e32 v80, v80
	v_exp_f32_e32 v97, v97
	v_exp_f32_e32 v81, v81
	v_add_f32_e32 v96, 1.0, v96
	v_add_f32_e32 v80, 1.0, v80
	v_add_f32_e32 v97, 1.0, v97
	v_add_f32_e32 v81, 1.0, v81
	v_rcp_f32_e32 v96, v96
	v_rcp_f32_e32 v80, v80
	v_rcp_f32_e32 v97, v97
	v_rcp_f32_e32 v81, v81
	s_waitcnt vmcnt(0)
	v_mul_f32_e32 v204, v90, v204
	v_add_f32_e32 v90, -1.0, v90
	v_mul_f32_e32 v205, v74, v205
	v_add_f32_e32 v74, -1.0, v74
	v_mul_f32_e32 v206, v91, v206
	v_add_f32_e32 v91, -1.0, v91
	v_mul_f32_e32 v207, v75, v207
	v_add_f32_e32 v75, -1.0, v75
	v_mul_f32_e32 v208, v92, v208
	v_add_f32_e32 v92, -1.0, v92
	v_mul_f32_e32 v209, v76, v209
	v_add_f32_e32 v76, -1.0, v76
	v_mul_f32_e32 v210, v93, v210
	v_add_f32_e32 v93, -1.0, v93
	v_mul_f32_e32 v211, v77, v211
	v_add_f32_e32 v77, -1.0, v77
	v_mul_f32_e32 v212, v94, v212
	v_add_f32_e32 v94, -1.0, v94
	v_mul_f32_e32 v213, v78, v213
	v_add_f32_e32 v78, -1.0, v78
	v_mul_f32_e32 v214, v95, v214
	v_add_f32_e32 v95, -1.0, v95
	v_mul_f32_e32 v215, v79, v215
	v_add_f32_e32 v79, -1.0, v79
	v_mul_f32_e32 v216, v96, v216
	v_add_f32_e32 v96, -1.0, v96
	v_mul_f32_e32 v217, v80, v217
	v_add_f32_e32 v80, -1.0, v80
	v_mul_f32_e32 v218, v97, v218
	v_add_f32_e32 v97, -1.0, v97
	v_mul_f32_e32 v219, v81, v219
	v_add_f32_e32 v81, -1.0, v81
	v_fma_f32 v90, v242, v90, 1.0
	v_fma_f32 v74, v243, v74, 1.0
	v_fma_f32 v91, v242, v91, 1.0
	v_fma_f32 v75, v243, v75, 1.0
	v_fma_f32 v92, v242, v92, 1.0
	v_fma_f32 v76, v243, v76, 1.0
	v_fma_f32 v93, v242, v93, 1.0
	v_fma_f32 v77, v243, v77, 1.0
	v_fma_f32 v94, v242, v94, 1.0
	v_fma_f32 v78, v243, v78, 1.0
	v_fma_f32 v95, v242, v95, 1.0
	v_fma_f32 v79, v243, v79, 1.0
	v_fma_f32 v96, v242, v96, 1.0
	v_fma_f32 v80, v243, v80, 1.0
	v_fma_f32 v97, v242, v97, 1.0
	v_fma_f32 v81, v243, v81, 1.0
	v_mul_f32_e32 v220, v90, v220
	v_mul_f32_e32 v221, v74, v221
	v_mul_f32_e32 v222, v91, v222
	v_mul_f32_e32 v223, v75, v223
	v_mul_f32_e32 v224, v92, v224
	v_mul_f32_e32 v225, v76, v225
	v_mul_f32_e32 v226, v93, v226
	v_mul_f32_e32 v227, v77, v227
	v_mul_f32_e32 v228, v94, v228
	v_mul_f32_e32 v229, v78, v229
	v_mul_f32_e32 v230, v95, v230
	v_mul_f32_e32 v231, v79, v231
	v_mul_f32_e32 v232, v96, v232
	v_mul_f32_e32 v233, v80, v233
	v_mul_f32_e32 v234, v97, v234
	v_mul_f32_e32 v235, v81, v235
	global_store_dword v245, v204, s[94:95] sc1
	global_store_dword v245, v220, s[42:43] sc1
	global_store_dword v245, v205, s[94:95] offset:128 sc1
	global_store_dword v245, v221, s[42:43] offset:128 sc1
	global_store_dword v245, v206, s[94:95] offset:2048 sc1
	global_store_dword v245, v222, s[42:43] offset:2048 sc1
	global_store_dword v245, v207, s[94:95] offset:2176 sc1
	global_store_dword v245, v223, s[42:43] offset:2176 sc1
	global_store_dword v246, v208, s[94:95] sc1
	global_store_dword v246, v224, s[42:43] sc1
	global_store_dword v246, v209, s[94:95] offset:128 sc1
	global_store_dword v246, v225, s[42:43] offset:128 sc1
	global_store_dword v246, v210, s[94:95] offset:2048 sc1
	global_store_dword v246, v226, s[42:43] offset:2048 sc1
	global_store_dword v246, v211, s[94:95] offset:2176 sc1
	global_store_dword v246, v227, s[42:43] offset:2176 sc1
	global_store_dword v247, v212, s[94:95] sc1
	global_store_dword v247, v228, s[42:43] sc1
	global_store_dword v247, v213, s[94:95] offset:128 sc1
	global_store_dword v247, v229, s[42:43] offset:128 sc1
	global_store_dword v247, v214, s[94:95] offset:2048 sc1
	global_store_dword v247, v230, s[42:43] offset:2048 sc1
	global_store_dword v247, v215, s[94:95] offset:2176 sc1
	global_store_dword v247, v231, s[42:43] offset:2176 sc1
	global_store_dword v248, v216, s[94:95] sc1
	global_store_dword v248, v232, s[42:43] sc1
	global_store_dword v248, v217, s[94:95] offset:128 sc1
	global_store_dword v248, v233, s[42:43] offset:128 sc1
	global_store_dword v248, v218, s[94:95] offset:2048 sc1
	global_store_dword v248, v234, s[42:43] offset:2048 sc1
	global_store_dword v248, v219, s[94:95] offset:2176 sc1
	global_store_dword v248, v235, s[42:43] offset:2176 sc1
	v_add_u32_e32 v245, 0x10000, v244
	v_add_u32_e32 v246, 0x11000, v244
	v_add_u32_e32 v247, 0x14000, v244
	v_add_u32_e32 v248, 0x15000, v244
	global_load_dword v204, v245, s[4:5]
	global_load_dword v220, v245, s[8:9]
	global_load_dword v205, v245, s[4:5] offset:128
	global_load_dword v221, v245, s[8:9] offset:128
	global_load_dword v206, v245, s[4:5] offset:2048
	global_load_dword v222, v245, s[8:9] offset:2048
	global_load_dword v207, v245, s[4:5] offset:2176
	global_load_dword v223, v245, s[8:9] offset:2176
	global_load_dword v208, v246, s[4:5]
	global_load_dword v224, v246, s[8:9]
	global_load_dword v209, v246, s[4:5] offset:128
	global_load_dword v225, v246, s[8:9] offset:128
	global_load_dword v210, v246, s[4:5] offset:2048
	global_load_dword v226, v246, s[8:9] offset:2048
	global_load_dword v211, v246, s[4:5] offset:2176
	global_load_dword v227, v246, s[8:9] offset:2176
	global_load_dword v212, v247, s[4:5]
	global_load_dword v228, v247, s[8:9]
	global_load_dword v213, v247, s[4:5] offset:128
	global_load_dword v229, v247, s[8:9] offset:128
	global_load_dword v214, v247, s[4:5] offset:2048
	global_load_dword v230, v247, s[8:9] offset:2048
	global_load_dword v215, v247, s[4:5] offset:2176
	global_load_dword v231, v247, s[8:9] offset:2176
	global_load_dword v216, v248, s[4:5]
	global_load_dword v232, v248, s[8:9]
	global_load_dword v217, v248, s[4:5] offset:128
	global_load_dword v233, v248, s[8:9] offset:128
	global_load_dword v218, v248, s[4:5] offset:2048
	global_load_dword v234, v248, s[8:9] offset:2048
	global_load_dword v219, v248, s[4:5] offset:2176
	global_load_dword v235, v248, s[8:9] offset:2176
	v_add_f32_e32 v50, v50, v240
	v_add_f32_e32 v34, v34, v241
	v_add_f32_e32 v51, v51, v240
	v_add_f32_e32 v35, v35, v241
	v_mul_f32_e32 v50, 0xbfb8aa3b, v50
	v_mul_f32_e32 v34, 0xbfb8aa3b, v34
	v_mul_f32_e32 v51, 0xbfb8aa3b, v51
	v_mul_f32_e32 v35, 0xbfb8aa3b, v35
	v_exp_f32_e32 v50, v50
	v_exp_f32_e32 v34, v34
	v_exp_f32_e32 v51, v51
	v_exp_f32_e32 v35, v35
	v_add_f32_e32 v50, 1.0, v50
	v_add_f32_e32 v34, 1.0, v34
	v_add_f32_e32 v51, 1.0, v51
	v_add_f32_e32 v35, 1.0, v35
	v_rcp_f32_e32 v50, v50
	v_rcp_f32_e32 v34, v34
	v_rcp_f32_e32 v51, v51
	v_rcp_f32_e32 v35, v35
	v_add_f32_e32 v52, v52, v240
	v_add_f32_e32 v36, v36, v241
	v_add_f32_e32 v53, v53, v240
	v_add_f32_e32 v37, v37, v241
	v_mul_f32_e32 v52, 0xbfb8aa3b, v52
	v_mul_f32_e32 v36, 0xbfb8aa3b, v36
	v_mul_f32_e32 v53, 0xbfb8aa3b, v53
	v_mul_f32_e32 v37, 0xbfb8aa3b, v37
	v_exp_f32_e32 v52, v52
	v_exp_f32_e32 v36, v36
	v_exp_f32_e32 v53, v53
	v_exp_f32_e32 v37, v37
	v_add_f32_e32 v52, 1.0, v52
	v_add_f32_e32 v36, 1.0, v36
	v_add_f32_e32 v53, 1.0, v53
	v_add_f32_e32 v37, 1.0, v37
	v_rcp_f32_e32 v52, v52
	v_rcp_f32_e32 v36, v36
	v_rcp_f32_e32 v53, v53
	v_rcp_f32_e32 v37, v37
	v_add_f32_e32 v54, v54, v240
	v_add_f32_e32 v38, v38, v241
	v_add_f32_e32 v55, v55, v240
	v_add_f32_e32 v39, v39, v241
	v_mul_f32_e32 v54, 0xbfb8aa3b, v54
	v_mul_f32_e32 v38, 0xbfb8aa3b, v38
	v_mul_f32_e32 v55, 0xbfb8aa3b, v55
	v_mul_f32_e32 v39, 0xbfb8aa3b, v39
	v_exp_f32_e32 v54, v54
	v_exp_f32_e32 v38, v38
	v_exp_f32_e32 v55, v55
	v_exp_f32_e32 v39, v39
	v_add_f32_e32 v54, 1.0, v54
	v_add_f32_e32 v38, 1.0, v38
	v_add_f32_e32 v55, 1.0, v55
	v_add_f32_e32 v39, 1.0, v39
	v_rcp_f32_e32 v54, v54
	v_rcp_f32_e32 v38, v38
	v_rcp_f32_e32 v55, v55
	v_rcp_f32_e32 v39, v39
	v_add_f32_e32 v56, v56, v240
	v_add_f32_e32 v40, v40, v241
	v_add_f32_e32 v57, v57, v240
	v_add_f32_e32 v41, v41, v241
	v_mul_f32_e32 v56, 0xbfb8aa3b, v56
	v_mul_f32_e32 v40, 0xbfb8aa3b, v40
	v_mul_f32_e32 v57, 0xbfb8aa3b, v57
	v_mul_f32_e32 v41, 0xbfb8aa3b, v41
	v_exp_f32_e32 v56, v56
	v_exp_f32_e32 v40, v40
	v_exp_f32_e32 v57, v57
	v_exp_f32_e32 v41, v41
	v_add_f32_e32 v56, 1.0, v56
	v_add_f32_e32 v40, 1.0, v40
	v_add_f32_e32 v57, 1.0, v57
	v_add_f32_e32 v41, 1.0, v41
	v_rcp_f32_e32 v56, v56
	v_rcp_f32_e32 v40, v40
	v_rcp_f32_e32 v57, v57
	v_rcp_f32_e32 v41, v41
	s_waitcnt vmcnt(0)
	v_mul_f32_e32 v204, v50, v204
	v_add_f32_e32 v50, -1.0, v50
	v_mul_f32_e32 v205, v34, v205
	v_add_f32_e32 v34, -1.0, v34
	v_mul_f32_e32 v206, v51, v206
	v_add_f32_e32 v51, -1.0, v51
	v_mul_f32_e32 v207, v35, v207
	v_add_f32_e32 v35, -1.0, v35
	v_mul_f32_e32 v208, v52, v208
	v_add_f32_e32 v52, -1.0, v52
	v_mul_f32_e32 v209, v36, v209
	v_add_f32_e32 v36, -1.0, v36
	v_mul_f32_e32 v210, v53, v210
	v_add_f32_e32 v53, -1.0, v53
	v_mul_f32_e32 v211, v37, v211
	v_add_f32_e32 v37, -1.0, v37
	v_mul_f32_e32 v212, v54, v212
	v_add_f32_e32 v54, -1.0, v54
	v_mul_f32_e32 v213, v38, v213
	v_add_f32_e32 v38, -1.0, v38
	v_mul_f32_e32 v214, v55, v214
	v_add_f32_e32 v55, -1.0, v55
	v_mul_f32_e32 v215, v39, v215
	v_add_f32_e32 v39, -1.0, v39
	v_mul_f32_e32 v216, v56, v216
	v_add_f32_e32 v56, -1.0, v56
	v_mul_f32_e32 v217, v40, v217
	v_add_f32_e32 v40, -1.0, v40
	v_mul_f32_e32 v218, v57, v218
	v_add_f32_e32 v57, -1.0, v57
	v_mul_f32_e32 v219, v41, v219
	v_add_f32_e32 v41, -1.0, v41
	v_fma_f32 v50, v242, v50, 1.0
	v_fma_f32 v34, v243, v34, 1.0
	v_fma_f32 v51, v242, v51, 1.0
	v_fma_f32 v35, v243, v35, 1.0
	v_fma_f32 v52, v242, v52, 1.0
	v_fma_f32 v36, v243, v36, 1.0
	v_fma_f32 v53, v242, v53, 1.0
	v_fma_f32 v37, v243, v37, 1.0
	v_fma_f32 v54, v242, v54, 1.0
	v_fma_f32 v38, v243, v38, 1.0
	v_fma_f32 v55, v242, v55, 1.0
	v_fma_f32 v39, v243, v39, 1.0
	v_fma_f32 v56, v242, v56, 1.0
	v_fma_f32 v40, v243, v40, 1.0
	v_fma_f32 v57, v242, v57, 1.0
	v_fma_f32 v41, v243, v41, 1.0
	v_mul_f32_e32 v220, v50, v220
	v_mul_f32_e32 v221, v34, v221
	v_mul_f32_e32 v222, v51, v222
	v_mul_f32_e32 v223, v35, v223
	v_mul_f32_e32 v224, v52, v224
	v_mul_f32_e32 v225, v36, v225
	v_mul_f32_e32 v226, v53, v226
	v_mul_f32_e32 v227, v37, v227
	v_mul_f32_e32 v228, v54, v228
	v_mul_f32_e32 v229, v38, v229
	v_mul_f32_e32 v230, v55, v230
	v_mul_f32_e32 v231, v39, v231
	v_mul_f32_e32 v232, v56, v232
	v_mul_f32_e32 v233, v40, v233
	v_mul_f32_e32 v234, v57, v234
	v_mul_f32_e32 v235, v41, v235
	global_store_dword v245, v204, s[94:95] sc1
	global_store_dword v245, v220, s[42:43] sc1
	global_store_dword v245, v205, s[94:95] offset:128 sc1
	global_store_dword v245, v221, s[42:43] offset:128 sc1
	global_store_dword v245, v206, s[94:95] offset:2048 sc1
	global_store_dword v245, v222, s[42:43] offset:2048 sc1
	global_store_dword v245, v207, s[94:95] offset:2176 sc1
	global_store_dword v245, v223, s[42:43] offset:2176 sc1
	global_store_dword v246, v208, s[94:95] sc1
	global_store_dword v246, v224, s[42:43] sc1
	global_store_dword v246, v209, s[94:95] offset:128 sc1
	global_store_dword v246, v225, s[42:43] offset:128 sc1
	global_store_dword v246, v210, s[94:95] offset:2048 sc1
	global_store_dword v246, v226, s[42:43] offset:2048 sc1
	global_store_dword v246, v211, s[94:95] offset:2176 sc1
	global_store_dword v246, v227, s[42:43] offset:2176 sc1
	global_store_dword v247, v212, s[94:95] sc1
	global_store_dword v247, v228, s[42:43] sc1
	global_store_dword v247, v213, s[94:95] offset:128 sc1
	global_store_dword v247, v229, s[42:43] offset:128 sc1
	global_store_dword v247, v214, s[94:95] offset:2048 sc1
	global_store_dword v247, v230, s[42:43] offset:2048 sc1
	global_store_dword v247, v215, s[94:95] offset:2176 sc1
	global_store_dword v247, v231, s[42:43] offset:2176 sc1
	global_store_dword v248, v216, s[94:95] sc1
	global_store_dword v248, v232, s[42:43] sc1
	global_store_dword v248, v217, s[94:95] offset:128 sc1
	global_store_dword v248, v233, s[42:43] offset:128 sc1
	global_store_dword v248, v218, s[94:95] offset:2048 sc1
	global_store_dword v248, v234, s[42:43] offset:2048 sc1
	global_store_dword v248, v219, s[94:95] offset:2176 sc1
	global_store_dword v248, v235, s[42:43] offset:2176 sc1
	v_add_u32_e32 v245, 0x18000, v244
	v_add_u32_e32 v246, 0x19000, v244
	v_add_u32_e32 v247, 0x1c000, v244
	v_add_u32_e32 v248, 0x1d000, v244
	global_load_dword v204, v245, s[4:5]
	global_load_dword v220, v245, s[8:9]
	global_load_dword v205, v245, s[4:5] offset:128
	global_load_dword v221, v245, s[8:9] offset:128
	global_load_dword v206, v245, s[4:5] offset:2048
	global_load_dword v222, v245, s[8:9] offset:2048
	global_load_dword v207, v245, s[4:5] offset:2176
	global_load_dword v223, v245, s[8:9] offset:2176
	global_load_dword v208, v246, s[4:5]
	global_load_dword v224, v246, s[8:9]
	global_load_dword v209, v246, s[4:5] offset:128
	global_load_dword v225, v246, s[8:9] offset:128
	global_load_dword v210, v246, s[4:5] offset:2048
	global_load_dword v226, v246, s[8:9] offset:2048
	global_load_dword v211, v246, s[4:5] offset:2176
	global_load_dword v227, v246, s[8:9] offset:2176
	global_load_dword v212, v247, s[4:5]
	global_load_dword v228, v247, s[8:9]
	global_load_dword v213, v247, s[4:5] offset:128
	global_load_dword v229, v247, s[8:9] offset:128
	global_load_dword v214, v247, s[4:5] offset:2048
	global_load_dword v230, v247, s[8:9] offset:2048
	global_load_dword v215, v247, s[4:5] offset:2176
	global_load_dword v231, v247, s[8:9] offset:2176
	global_load_dword v216, v248, s[4:5]
	global_load_dword v232, v248, s[8:9]
	global_load_dword v217, v248, s[4:5] offset:128
	global_load_dword v233, v248, s[8:9] offset:128
	global_load_dword v218, v248, s[4:5] offset:2048
	global_load_dword v234, v248, s[8:9] offset:2048
	global_load_dword v219, v248, s[4:5] offset:2176
	global_load_dword v235, v248, s[8:9] offset:2176
	v_add_f32_e32 v58, v58, v240
	v_add_f32_e32 v42, v42, v241
	v_add_f32_e32 v59, v59, v240
	v_add_f32_e32 v43, v43, v241
	v_mul_f32_e32 v58, 0xbfb8aa3b, v58
	v_mul_f32_e32 v42, 0xbfb8aa3b, v42
	v_mul_f32_e32 v59, 0xbfb8aa3b, v59
	v_mul_f32_e32 v43, 0xbfb8aa3b, v43
	v_exp_f32_e32 v58, v58
	v_exp_f32_e32 v42, v42
	v_exp_f32_e32 v59, v59
	v_exp_f32_e32 v43, v43
	v_add_f32_e32 v58, 1.0, v58
	v_add_f32_e32 v42, 1.0, v42
	v_add_f32_e32 v59, 1.0, v59
	v_add_f32_e32 v43, 1.0, v43
	v_rcp_f32_e32 v58, v58
	v_rcp_f32_e32 v42, v42
	v_rcp_f32_e32 v59, v59
	v_rcp_f32_e32 v43, v43
	v_add_f32_e32 v60, v60, v240
	v_add_f32_e32 v44, v44, v241
	v_add_f32_e32 v61, v61, v240
	v_add_f32_e32 v45, v45, v241
	v_mul_f32_e32 v60, 0xbfb8aa3b, v60
	v_mul_f32_e32 v44, 0xbfb8aa3b, v44
	v_mul_f32_e32 v61, 0xbfb8aa3b, v61
	v_mul_f32_e32 v45, 0xbfb8aa3b, v45
	v_exp_f32_e32 v60, v60
	v_exp_f32_e32 v44, v44
	v_exp_f32_e32 v61, v61
	v_exp_f32_e32 v45, v45
	v_add_f32_e32 v60, 1.0, v60
	v_add_f32_e32 v44, 1.0, v44
	v_add_f32_e32 v61, 1.0, v61
	v_add_f32_e32 v45, 1.0, v45
	v_rcp_f32_e32 v60, v60
	v_rcp_f32_e32 v44, v44
	v_rcp_f32_e32 v61, v61
	v_rcp_f32_e32 v45, v45
	v_add_f32_e32 v62, v62, v240
	v_add_f32_e32 v46, v46, v241
	v_add_f32_e32 v63, v63, v240
	v_add_f32_e32 v47, v47, v241
	v_mul_f32_e32 v62, 0xbfb8aa3b, v62
	v_mul_f32_e32 v46, 0xbfb8aa3b, v46
	v_mul_f32_e32 v63, 0xbfb8aa3b, v63
	v_mul_f32_e32 v47, 0xbfb8aa3b, v47
	v_exp_f32_e32 v62, v62
	v_exp_f32_e32 v46, v46
	v_exp_f32_e32 v63, v63
	v_exp_f32_e32 v47, v47
	v_add_f32_e32 v62, 1.0, v62
	v_add_f32_e32 v46, 1.0, v46
	v_add_f32_e32 v63, 1.0, v63
	v_add_f32_e32 v47, 1.0, v47
	v_rcp_f32_e32 v62, v62
	v_rcp_f32_e32 v46, v46
	v_rcp_f32_e32 v63, v63
	v_rcp_f32_e32 v47, v47
	v_add_f32_e32 v64, v64, v240
	v_add_f32_e32 v48, v48, v241
	v_add_f32_e32 v65, v65, v240
	v_add_f32_e32 v49, v49, v241
	v_mul_f32_e32 v64, 0xbfb8aa3b, v64
	v_mul_f32_e32 v48, 0xbfb8aa3b, v48
	v_mul_f32_e32 v65, 0xbfb8aa3b, v65
	v_mul_f32_e32 v49, 0xbfb8aa3b, v49
	v_exp_f32_e32 v64, v64
	v_exp_f32_e32 v48, v48
	v_exp_f32_e32 v65, v65
	v_exp_f32_e32 v49, v49
	v_add_f32_e32 v64, 1.0, v64
	v_add_f32_e32 v48, 1.0, v48
	v_add_f32_e32 v65, 1.0, v65
	v_add_f32_e32 v49, 1.0, v49
	v_rcp_f32_e32 v64, v64
	v_rcp_f32_e32 v48, v48
	v_rcp_f32_e32 v65, v65
	v_rcp_f32_e32 v49, v49
	s_waitcnt vmcnt(0)
	v_mul_f32_e32 v204, v58, v204
	v_add_f32_e32 v58, -1.0, v58
	v_mul_f32_e32 v205, v42, v205
	v_add_f32_e32 v42, -1.0, v42
	v_mul_f32_e32 v206, v59, v206
	v_add_f32_e32 v59, -1.0, v59
	v_mul_f32_e32 v207, v43, v207
	v_add_f32_e32 v43, -1.0, v43
	v_mul_f32_e32 v208, v60, v208
	v_add_f32_e32 v60, -1.0, v60
	v_mul_f32_e32 v209, v44, v209
	v_add_f32_e32 v44, -1.0, v44
	v_mul_f32_e32 v210, v61, v210
	v_add_f32_e32 v61, -1.0, v61
	v_mul_f32_e32 v211, v45, v211
	v_add_f32_e32 v45, -1.0, v45
	v_mul_f32_e32 v212, v62, v212
	v_add_f32_e32 v62, -1.0, v62
	v_mul_f32_e32 v213, v46, v213
	v_add_f32_e32 v46, -1.0, v46
	v_mul_f32_e32 v214, v63, v214
	v_add_f32_e32 v63, -1.0, v63
	v_mul_f32_e32 v215, v47, v215
	v_add_f32_e32 v47, -1.0, v47
	v_mul_f32_e32 v216, v64, v216
	v_add_f32_e32 v64, -1.0, v64
	v_mul_f32_e32 v217, v48, v217
	v_add_f32_e32 v48, -1.0, v48
	v_mul_f32_e32 v218, v65, v218
	v_add_f32_e32 v65, -1.0, v65
	v_mul_f32_e32 v219, v49, v219
	v_add_f32_e32 v49, -1.0, v49
	v_fma_f32 v58, v242, v58, 1.0
	v_fma_f32 v42, v243, v42, 1.0
	v_fma_f32 v59, v242, v59, 1.0
	v_fma_f32 v43, v243, v43, 1.0
	v_fma_f32 v60, v242, v60, 1.0
	v_fma_f32 v44, v243, v44, 1.0
	v_fma_f32 v61, v242, v61, 1.0
	v_fma_f32 v45, v243, v45, 1.0
	v_fma_f32 v62, v242, v62, 1.0
	v_fma_f32 v46, v243, v46, 1.0
	v_fma_f32 v63, v242, v63, 1.0
	v_fma_f32 v47, v243, v47, 1.0
	v_fma_f32 v64, v242, v64, 1.0
	v_fma_f32 v48, v243, v48, 1.0
	v_fma_f32 v65, v242, v65, 1.0
	v_fma_f32 v49, v243, v49, 1.0
	v_mul_f32_e32 v220, v58, v220
	v_mul_f32_e32 v221, v42, v221
	v_mul_f32_e32 v222, v59, v222
	v_mul_f32_e32 v223, v43, v223
	v_mul_f32_e32 v224, v60, v224
	v_mul_f32_e32 v225, v44, v225
	v_mul_f32_e32 v226, v61, v226
	v_mul_f32_e32 v227, v45, v227
	v_mul_f32_e32 v228, v62, v228
	v_mul_f32_e32 v229, v46, v229
	v_mul_f32_e32 v230, v63, v230
	v_mul_f32_e32 v231, v47, v231
	v_mul_f32_e32 v232, v64, v232
	v_mul_f32_e32 v233, v48, v233
	v_mul_f32_e32 v234, v65, v234
	v_mul_f32_e32 v235, v49, v235
	global_store_dword v245, v204, s[94:95] sc1
	global_store_dword v245, v220, s[42:43] sc1
	global_store_dword v245, v205, s[94:95] offset:128 sc1
	global_store_dword v245, v221, s[42:43] offset:128 sc1
	global_store_dword v245, v206, s[94:95] offset:2048 sc1
	global_store_dword v245, v222, s[42:43] offset:2048 sc1
	global_store_dword v245, v207, s[94:95] offset:2176 sc1
	global_store_dword v245, v223, s[42:43] offset:2176 sc1
	global_store_dword v246, v208, s[94:95] sc1
	global_store_dword v246, v224, s[42:43] sc1
	global_store_dword v246, v209, s[94:95] offset:128 sc1
	global_store_dword v246, v225, s[42:43] offset:128 sc1
	global_store_dword v246, v210, s[94:95] offset:2048 sc1
	global_store_dword v246, v226, s[42:43] offset:2048 sc1
	global_store_dword v246, v211, s[94:95] offset:2176 sc1
	global_store_dword v246, v227, s[42:43] offset:2176 sc1
	global_store_dword v247, v212, s[94:95] sc1
	global_store_dword v247, v228, s[42:43] sc1
	global_store_dword v247, v213, s[94:95] offset:128 sc1
	global_store_dword v247, v229, s[42:43] offset:128 sc1
	global_store_dword v247, v214, s[94:95] offset:2048 sc1
	global_store_dword v247, v230, s[42:43] offset:2048 sc1
	global_store_dword v247, v215, s[94:95] offset:2176 sc1
	global_store_dword v247, v231, s[42:43] offset:2176 sc1
	global_store_dword v248, v216, s[94:95] sc1
	global_store_dword v248, v232, s[42:43] sc1
	global_store_dword v248, v217, s[94:95] offset:128 sc1
	global_store_dword v248, v233, s[42:43] offset:128 sc1
	global_store_dword v248, v218, s[94:95] offset:2048 sc1
	global_store_dword v248, v234, s[42:43] offset:2048 sc1
	global_store_dword v248, v219, s[94:95] offset:2176 sc1
	global_store_dword v248, v235, s[42:43] offset:2176 sc1
	v_add_u32_e32 v245, 0x20000, v244
	v_add_u32_e32 v246, 0x21000, v244
	v_add_u32_e32 v247, 0x24000, v244
	v_add_u32_e32 v248, 0x25000, v244
	global_load_dword v204, v245, s[4:5]
	global_load_dword v220, v245, s[8:9]
	global_load_dword v205, v245, s[4:5] offset:128
	global_load_dword v221, v245, s[8:9] offset:128
	global_load_dword v206, v245, s[4:5] offset:2048
	global_load_dword v222, v245, s[8:9] offset:2048
	global_load_dword v207, v245, s[4:5] offset:2176
	global_load_dword v223, v245, s[8:9] offset:2176
	global_load_dword v208, v246, s[4:5]
	global_load_dword v224, v246, s[8:9]
	global_load_dword v209, v246, s[4:5] offset:128
	global_load_dword v225, v246, s[8:9] offset:128
	global_load_dword v210, v246, s[4:5] offset:2048
	global_load_dword v226, v246, s[8:9] offset:2048
	global_load_dword v211, v246, s[4:5] offset:2176
	global_load_dword v227, v246, s[8:9] offset:2176
	global_load_dword v212, v247, s[4:5]
	global_load_dword v228, v247, s[8:9]
	global_load_dword v213, v247, s[4:5] offset:128
	global_load_dword v229, v247, s[8:9] offset:128
	global_load_dword v214, v247, s[4:5] offset:2048
	global_load_dword v230, v247, s[8:9] offset:2048
	global_load_dword v215, v247, s[4:5] offset:2176
	global_load_dword v231, v247, s[8:9] offset:2176
	global_load_dword v216, v248, s[4:5]
	global_load_dword v232, v248, s[8:9]
	global_load_dword v217, v248, s[4:5] offset:128
	global_load_dword v233, v248, s[8:9] offset:128
	global_load_dword v218, v248, s[4:5] offset:2048
	global_load_dword v234, v248, s[8:9] offset:2048
	global_load_dword v219, v248, s[4:5] offset:2176
	global_load_dword v235, v248, s[8:9] offset:2176
	v_add_f32_e32 v18, v18, v240
	v_add_f32_e32 v2, v2, v241
	v_add_f32_e32 v19, v19, v240
	v_add_f32_e32 v3, v3, v241
	v_mul_f32_e32 v18, 0xbfb8aa3b, v18
	v_mul_f32_e32 v2, 0xbfb8aa3b, v2
	v_mul_f32_e32 v19, 0xbfb8aa3b, v19
	v_mul_f32_e32 v3, 0xbfb8aa3b, v3
	v_exp_f32_e32 v18, v18
	v_exp_f32_e32 v2, v2
	v_exp_f32_e32 v19, v19
	v_exp_f32_e32 v3, v3
	v_add_f32_e32 v18, 1.0, v18
	v_add_f32_e32 v2, 1.0, v2
	v_add_f32_e32 v19, 1.0, v19
	v_add_f32_e32 v3, 1.0, v3
	v_rcp_f32_e32 v18, v18
	v_rcp_f32_e32 v2, v2
	v_rcp_f32_e32 v19, v19
	v_rcp_f32_e32 v3, v3
	v_add_f32_e32 v20, v20, v240
	v_add_f32_e32 v4, v4, v241
	v_add_f32_e32 v21, v21, v240
	v_add_f32_e32 v5, v5, v241
	v_mul_f32_e32 v20, 0xbfb8aa3b, v20
	v_mul_f32_e32 v4, 0xbfb8aa3b, v4
	v_mul_f32_e32 v21, 0xbfb8aa3b, v21
	v_mul_f32_e32 v5, 0xbfb8aa3b, v5
	v_exp_f32_e32 v20, v20
	v_exp_f32_e32 v4, v4
	v_exp_f32_e32 v21, v21
	v_exp_f32_e32 v5, v5
	v_add_f32_e32 v20, 1.0, v20
	v_add_f32_e32 v4, 1.0, v4
	v_add_f32_e32 v21, 1.0, v21
	v_add_f32_e32 v5, 1.0, v5
	v_rcp_f32_e32 v20, v20
	v_rcp_f32_e32 v4, v4
	v_rcp_f32_e32 v21, v21
	v_rcp_f32_e32 v5, v5
	v_add_f32_e32 v22, v22, v240
	v_add_f32_e32 v6, v6, v241
	v_add_f32_e32 v23, v23, v240
	v_add_f32_e32 v7, v7, v241
	v_mul_f32_e32 v22, 0xbfb8aa3b, v22
	v_mul_f32_e32 v6, 0xbfb8aa3b, v6
	v_mul_f32_e32 v23, 0xbfb8aa3b, v23
	v_mul_f32_e32 v7, 0xbfb8aa3b, v7
	v_exp_f32_e32 v22, v22
	v_exp_f32_e32 v6, v6
	v_exp_f32_e32 v23, v23
	v_exp_f32_e32 v7, v7
	v_add_f32_e32 v22, 1.0, v22
	v_add_f32_e32 v6, 1.0, v6
	v_add_f32_e32 v23, 1.0, v23
	v_add_f32_e32 v7, 1.0, v7
	v_rcp_f32_e32 v22, v22
	v_rcp_f32_e32 v6, v6
	v_rcp_f32_e32 v23, v23
	v_rcp_f32_e32 v7, v7
	v_add_f32_e32 v24, v24, v240
	v_add_f32_e32 v8, v8, v241
	v_add_f32_e32 v25, v25, v240
	v_add_f32_e32 v9, v9, v241
	v_mul_f32_e32 v24, 0xbfb8aa3b, v24
	v_mul_f32_e32 v8, 0xbfb8aa3b, v8
	v_mul_f32_e32 v25, 0xbfb8aa3b, v25
	v_mul_f32_e32 v9, 0xbfb8aa3b, v9
	v_exp_f32_e32 v24, v24
	v_exp_f32_e32 v8, v8
	v_exp_f32_e32 v25, v25
	v_exp_f32_e32 v9, v9
	v_add_f32_e32 v24, 1.0, v24
	v_add_f32_e32 v8, 1.0, v8
	v_add_f32_e32 v25, 1.0, v25
	v_add_f32_e32 v9, 1.0, v9
	v_rcp_f32_e32 v24, v24
	v_rcp_f32_e32 v8, v8
	v_rcp_f32_e32 v25, v25
	v_rcp_f32_e32 v9, v9
	s_waitcnt vmcnt(0)
	v_mul_f32_e32 v204, v18, v204
	v_add_f32_e32 v18, -1.0, v18
	v_mul_f32_e32 v205, v2, v205
	v_add_f32_e32 v2, -1.0, v2
	v_mul_f32_e32 v206, v19, v206
	v_add_f32_e32 v19, -1.0, v19
	v_mul_f32_e32 v207, v3, v207
	v_add_f32_e32 v3, -1.0, v3
	v_mul_f32_e32 v208, v20, v208
	v_add_f32_e32 v20, -1.0, v20
	v_mul_f32_e32 v209, v4, v209
	v_add_f32_e32 v4, -1.0, v4
	v_mul_f32_e32 v210, v21, v210
	v_add_f32_e32 v21, -1.0, v21
	v_mul_f32_e32 v211, v5, v211
	v_add_f32_e32 v5, -1.0, v5
	v_mul_f32_e32 v212, v22, v212
	v_add_f32_e32 v22, -1.0, v22
	v_mul_f32_e32 v213, v6, v213
	v_add_f32_e32 v6, -1.0, v6
	v_mul_f32_e32 v214, v23, v214
	v_add_f32_e32 v23, -1.0, v23
	v_mul_f32_e32 v215, v7, v215
	v_add_f32_e32 v7, -1.0, v7
	v_mul_f32_e32 v216, v24, v216
	v_add_f32_e32 v24, -1.0, v24
	v_mul_f32_e32 v217, v8, v217
	v_add_f32_e32 v8, -1.0, v8
	v_mul_f32_e32 v218, v25, v218
	v_add_f32_e32 v25, -1.0, v25
	v_mul_f32_e32 v219, v9, v219
	v_add_f32_e32 v9, -1.0, v9
	v_fma_f32 v18, v242, v18, 1.0
	v_fma_f32 v2, v243, v2, 1.0
	v_fma_f32 v19, v242, v19, 1.0
	v_fma_f32 v3, v243, v3, 1.0
	v_fma_f32 v20, v242, v20, 1.0
	v_fma_f32 v4, v243, v4, 1.0
	v_fma_f32 v21, v242, v21, 1.0
	v_fma_f32 v5, v243, v5, 1.0
	v_fma_f32 v22, v242, v22, 1.0
	v_fma_f32 v6, v243, v6, 1.0
	v_fma_f32 v23, v242, v23, 1.0
	v_fma_f32 v7, v243, v7, 1.0
	v_fma_f32 v24, v242, v24, 1.0
	v_fma_f32 v8, v243, v8, 1.0
	v_fma_f32 v25, v242, v25, 1.0
	v_fma_f32 v9, v243, v9, 1.0
	v_mul_f32_e32 v220, v18, v220
	v_mul_f32_e32 v221, v2, v221
	v_mul_f32_e32 v222, v19, v222
	v_mul_f32_e32 v223, v3, v223
	v_mul_f32_e32 v224, v20, v224
	v_mul_f32_e32 v225, v4, v225
	v_mul_f32_e32 v226, v21, v226
	v_mul_f32_e32 v227, v5, v227
	v_mul_f32_e32 v228, v22, v228
	v_mul_f32_e32 v229, v6, v229
	v_mul_f32_e32 v230, v23, v230
	v_mul_f32_e32 v231, v7, v231
	v_mul_f32_e32 v232, v24, v232
	v_mul_f32_e32 v233, v8, v233
	v_mul_f32_e32 v234, v25, v234
	v_mul_f32_e32 v235, v9, v235
	global_store_dword v245, v204, s[94:95] sc1
	global_store_dword v245, v220, s[42:43] sc1
	global_store_dword v245, v205, s[94:95] offset:128 sc1
	global_store_dword v245, v221, s[42:43] offset:128 sc1
	global_store_dword v245, v206, s[94:95] offset:2048 sc1
	global_store_dword v245, v222, s[42:43] offset:2048 sc1
	global_store_dword v245, v207, s[94:95] offset:2176 sc1
	global_store_dword v245, v223, s[42:43] offset:2176 sc1
	global_store_dword v246, v208, s[94:95] sc1
	global_store_dword v246, v224, s[42:43] sc1
	global_store_dword v246, v209, s[94:95] offset:128 sc1
	global_store_dword v246, v225, s[42:43] offset:128 sc1
	global_store_dword v246, v210, s[94:95] offset:2048 sc1
	global_store_dword v246, v226, s[42:43] offset:2048 sc1
	global_store_dword v246, v211, s[94:95] offset:2176 sc1
	global_store_dword v246, v227, s[42:43] offset:2176 sc1
	global_store_dword v247, v212, s[94:95] sc1
	global_store_dword v247, v228, s[42:43] sc1
	global_store_dword v247, v213, s[94:95] offset:128 sc1
	global_store_dword v247, v229, s[42:43] offset:128 sc1
	global_store_dword v247, v214, s[94:95] offset:2048 sc1
	global_store_dword v247, v230, s[42:43] offset:2048 sc1
	global_store_dword v247, v215, s[94:95] offset:2176 sc1
	global_store_dword v247, v231, s[42:43] offset:2176 sc1
	global_store_dword v248, v216, s[94:95] sc1
	global_store_dword v248, v232, s[42:43] sc1
	global_store_dword v248, v217, s[94:95] offset:128 sc1
	global_store_dword v248, v233, s[42:43] offset:128 sc1
	global_store_dword v248, v218, s[94:95] offset:2048 sc1
	global_store_dword v248, v234, s[42:43] offset:2048 sc1
	global_store_dword v248, v219, s[94:95] offset:2176 sc1
	global_store_dword v248, v235, s[42:43] offset:2176 sc1
	v_add_u32_e32 v245, 0x28000, v244
	v_add_u32_e32 v246, 0x29000, v244
	v_add_u32_e32 v247, 0x2c000, v244
	v_add_u32_e32 v248, 0x2d000, v244
	global_load_dword v204, v245, s[4:5]
	global_load_dword v220, v245, s[8:9]
	global_load_dword v205, v245, s[4:5] offset:128
	global_load_dword v221, v245, s[8:9] offset:128
	global_load_dword v206, v245, s[4:5] offset:2048
	global_load_dword v222, v245, s[8:9] offset:2048
	global_load_dword v207, v245, s[4:5] offset:2176
	global_load_dword v223, v245, s[8:9] offset:2176
	global_load_dword v208, v246, s[4:5]
	global_load_dword v224, v246, s[8:9]
	global_load_dword v209, v246, s[4:5] offset:128
	global_load_dword v225, v246, s[8:9] offset:128
	global_load_dword v210, v246, s[4:5] offset:2048
	global_load_dword v226, v246, s[8:9] offset:2048
	global_load_dword v211, v246, s[4:5] offset:2176
	global_load_dword v227, v246, s[8:9] offset:2176
	global_load_dword v212, v247, s[4:5]
	global_load_dword v228, v247, s[8:9]
	global_load_dword v213, v247, s[4:5] offset:128
	global_load_dword v229, v247, s[8:9] offset:128
	global_load_dword v214, v247, s[4:5] offset:2048
	global_load_dword v230, v247, s[8:9] offset:2048
	global_load_dword v215, v247, s[4:5] offset:2176
	global_load_dword v231, v247, s[8:9] offset:2176
	global_load_dword v216, v248, s[4:5]
	global_load_dword v232, v248, s[8:9]
	global_load_dword v217, v248, s[4:5] offset:128
	global_load_dword v233, v248, s[8:9] offset:128
	global_load_dword v218, v248, s[4:5] offset:2048
	global_load_dword v234, v248, s[8:9] offset:2048
	global_load_dword v219, v248, s[4:5] offset:2176
	global_load_dword v235, v248, s[8:9] offset:2176
	v_add_f32_e32 v26, v26, v240
	v_add_f32_e32 v10, v10, v241
	v_add_f32_e32 v27, v27, v240
	v_add_f32_e32 v11, v11, v241
	v_mul_f32_e32 v26, 0xbfb8aa3b, v26
	v_mul_f32_e32 v10, 0xbfb8aa3b, v10
	v_mul_f32_e32 v27, 0xbfb8aa3b, v27
	v_mul_f32_e32 v11, 0xbfb8aa3b, v11
	v_exp_f32_e32 v26, v26
	v_exp_f32_e32 v10, v10
	v_exp_f32_e32 v27, v27
	v_exp_f32_e32 v11, v11
	v_add_f32_e32 v26, 1.0, v26
	v_add_f32_e32 v10, 1.0, v10
	v_add_f32_e32 v27, 1.0, v27
	v_add_f32_e32 v11, 1.0, v11
	v_rcp_f32_e32 v26, v26
	v_rcp_f32_e32 v10, v10
	v_rcp_f32_e32 v27, v27
	v_rcp_f32_e32 v11, v11
	v_add_f32_e32 v28, v28, v240
	v_add_f32_e32 v12, v12, v241
	v_add_f32_e32 v29, v29, v240
	v_add_f32_e32 v13, v13, v241
	v_mul_f32_e32 v28, 0xbfb8aa3b, v28
	v_mul_f32_e32 v12, 0xbfb8aa3b, v12
	v_mul_f32_e32 v29, 0xbfb8aa3b, v29
	v_mul_f32_e32 v13, 0xbfb8aa3b, v13
	v_exp_f32_e32 v28, v28
	v_exp_f32_e32 v12, v12
	v_exp_f32_e32 v29, v29
	v_exp_f32_e32 v13, v13
	v_add_f32_e32 v28, 1.0, v28
	v_add_f32_e32 v12, 1.0, v12
	v_add_f32_e32 v29, 1.0, v29
	v_add_f32_e32 v13, 1.0, v13
	v_rcp_f32_e32 v28, v28
	v_rcp_f32_e32 v12, v12
	v_rcp_f32_e32 v29, v29
	v_rcp_f32_e32 v13, v13
	v_add_f32_e32 v30, v30, v240
	v_add_f32_e32 v14, v14, v241
	v_add_f32_e32 v31, v31, v240
	v_add_f32_e32 v15, v15, v241
	v_mul_f32_e32 v30, 0xbfb8aa3b, v30
	v_mul_f32_e32 v14, 0xbfb8aa3b, v14
	v_mul_f32_e32 v31, 0xbfb8aa3b, v31
	v_mul_f32_e32 v15, 0xbfb8aa3b, v15
	v_exp_f32_e32 v30, v30
	v_exp_f32_e32 v14, v14
	v_exp_f32_e32 v31, v31
	v_exp_f32_e32 v15, v15
	v_add_f32_e32 v30, 1.0, v30
	v_add_f32_e32 v14, 1.0, v14
	v_add_f32_e32 v31, 1.0, v31
	v_add_f32_e32 v15, 1.0, v15
	v_rcp_f32_e32 v30, v30
	v_rcp_f32_e32 v14, v14
	v_rcp_f32_e32 v31, v31
	v_rcp_f32_e32 v15, v15
	v_add_f32_e32 v32, v32, v240
	v_add_f32_e32 v16, v16, v241
	v_add_f32_e32 v33, v33, v240
	v_add_f32_e32 v17, v17, v241
	v_mul_f32_e32 v32, 0xbfb8aa3b, v32
	v_mul_f32_e32 v16, 0xbfb8aa3b, v16
	v_mul_f32_e32 v33, 0xbfb8aa3b, v33
	v_mul_f32_e32 v17, 0xbfb8aa3b, v17
	v_exp_f32_e32 v32, v32
	v_exp_f32_e32 v16, v16
	v_exp_f32_e32 v33, v33
	v_exp_f32_e32 v17, v17
	v_add_f32_e32 v32, 1.0, v32
	v_add_f32_e32 v16, 1.0, v16
	v_add_f32_e32 v33, 1.0, v33
	v_add_f32_e32 v17, 1.0, v17
	v_rcp_f32_e32 v32, v32
	v_rcp_f32_e32 v16, v16
	v_rcp_f32_e32 v33, v33
	v_rcp_f32_e32 v17, v17
	s_waitcnt vmcnt(0)
	v_mul_f32_e32 v204, v26, v204
	v_add_f32_e32 v26, -1.0, v26
	v_mul_f32_e32 v205, v10, v205
	v_add_f32_e32 v10, -1.0, v10
	v_mul_f32_e32 v206, v27, v206
	v_add_f32_e32 v27, -1.0, v27
	v_mul_f32_e32 v207, v11, v207
	v_add_f32_e32 v11, -1.0, v11
	v_mul_f32_e32 v208, v28, v208
	v_add_f32_e32 v28, -1.0, v28
	v_mul_f32_e32 v209, v12, v209
	v_add_f32_e32 v12, -1.0, v12
	v_mul_f32_e32 v210, v29, v210
	v_add_f32_e32 v29, -1.0, v29
	v_mul_f32_e32 v211, v13, v211
	v_add_f32_e32 v13, -1.0, v13
	v_mul_f32_e32 v212, v30, v212
	v_add_f32_e32 v30, -1.0, v30
	v_mul_f32_e32 v213, v14, v213
	v_add_f32_e32 v14, -1.0, v14
	v_mul_f32_e32 v214, v31, v214
	v_add_f32_e32 v31, -1.0, v31
	v_mul_f32_e32 v215, v15, v215
	v_add_f32_e32 v15, -1.0, v15
	v_mul_f32_e32 v216, v32, v216
	v_add_f32_e32 v32, -1.0, v32
	v_mul_f32_e32 v217, v16, v217
	v_add_f32_e32 v16, -1.0, v16
	v_mul_f32_e32 v218, v33, v218
	v_add_f32_e32 v33, -1.0, v33
	v_mul_f32_e32 v219, v17, v219
	v_add_f32_e32 v17, -1.0, v17
	v_fma_f32 v26, v242, v26, 1.0
	v_fma_f32 v10, v243, v10, 1.0
	v_fma_f32 v27, v242, v27, 1.0
	v_fma_f32 v11, v243, v11, 1.0
	v_fma_f32 v28, v242, v28, 1.0
	v_fma_f32 v12, v243, v12, 1.0
	v_fma_f32 v29, v242, v29, 1.0
	v_fma_f32 v13, v243, v13, 1.0
	v_fma_f32 v30, v242, v30, 1.0
	v_fma_f32 v14, v243, v14, 1.0
	v_fma_f32 v31, v242, v31, 1.0
	v_fma_f32 v15, v243, v15, 1.0
	v_fma_f32 v32, v242, v32, 1.0
	v_fma_f32 v16, v243, v16, 1.0
	v_fma_f32 v33, v242, v33, 1.0
	v_fma_f32 v17, v243, v17, 1.0
	v_mul_f32_e32 v220, v26, v220
	v_mul_f32_e32 v221, v10, v221
	v_mul_f32_e32 v222, v27, v222
	v_mul_f32_e32 v223, v11, v223
	v_mul_f32_e32 v224, v28, v224
	v_mul_f32_e32 v225, v12, v225
	v_mul_f32_e32 v226, v29, v226
	v_mul_f32_e32 v227, v13, v227
	v_mul_f32_e32 v228, v30, v228
	v_mul_f32_e32 v229, v14, v229
	v_mul_f32_e32 v230, v31, v230
	v_mul_f32_e32 v231, v15, v231
	v_mul_f32_e32 v232, v32, v232
	v_mul_f32_e32 v233, v16, v233
	v_mul_f32_e32 v234, v33, v234
	v_mul_f32_e32 v235, v17, v235
	global_store_dword v245, v204, s[94:95] sc1
	global_store_dword v245, v220, s[42:43] sc1
	global_store_dword v245, v205, s[94:95] offset:128 sc1
	global_store_dword v245, v221, s[42:43] offset:128 sc1
	global_store_dword v245, v206, s[94:95] offset:2048 sc1
	global_store_dword v245, v222, s[42:43] offset:2048 sc1
	global_store_dword v245, v207, s[94:95] offset:2176 sc1
	global_store_dword v245, v223, s[42:43] offset:2176 sc1
	global_store_dword v246, v208, s[94:95] sc1
	global_store_dword v246, v224, s[42:43] sc1
	global_store_dword v246, v209, s[94:95] offset:128 sc1
	global_store_dword v246, v225, s[42:43] offset:128 sc1
	global_store_dword v246, v210, s[94:95] offset:2048 sc1
	global_store_dword v246, v226, s[42:43] offset:2048 sc1
	global_store_dword v246, v211, s[94:95] offset:2176 sc1
	global_store_dword v246, v227, s[42:43] offset:2176 sc1
	global_store_dword v247, v212, s[94:95] sc1
	global_store_dword v247, v228, s[42:43] sc1
	global_store_dword v247, v213, s[94:95] offset:128 sc1
	global_store_dword v247, v229, s[42:43] offset:128 sc1
	global_store_dword v247, v214, s[94:95] offset:2048 sc1
	global_store_dword v247, v230, s[42:43] offset:2048 sc1
	global_store_dword v247, v215, s[94:95] offset:2176 sc1
	global_store_dword v247, v231, s[42:43] offset:2176 sc1
	global_store_dword v248, v216, s[94:95] sc1
	global_store_dword v248, v232, s[42:43] sc1
	global_store_dword v248, v217, s[94:95] offset:128 sc1
	global_store_dword v248, v233, s[42:43] offset:128 sc1
	global_store_dword v248, v218, s[94:95] offset:2048 sc1
	global_store_dword v248, v234, s[42:43] offset:2048 sc1
	global_store_dword v248, v219, s[94:95] offset:2176 sc1
	global_store_dword v248, v235, s[42:43] offset:2176 sc1
	s_mov_b64 s[2:3], 0
.LBB0_499:
	s_andn2_b64 vcc, exec, s[2:3]
	s_cbranch_vccnz .LBB0_501
	v_lshl_add_u64 v[104:105], v[100:101], 2, s[58:59]
	global_load_dword v236, v[104:105], off
	global_load_dword v237, v[104:105], off offset:128
	s_nop 0
	s_waitcnt vmcnt(0)
	v_mov_b32_e32 v101, v236
	v_add_f32_e32 v103, v82, v101
	s_mov_b32 s0, 0xbfb8aa3b
	v_max_f32_e64 v106, -v103, 0
	v_mul_f32_e64 v103, |v103|, s0
	v_exp_f32_e32 v103, v103
	s_mov_b32 s1, 0x3f317217
	v_add_f32_e32 v103, 1.0, v103
	v_cmp_gt_f32_e32 vcc, s31, v103
	s_nop 1
	v_cndmask_b32_e64 v107, 0, 32, vcc
	v_ldexp_f32 v103, v103, v107
	v_log_f32_e32 v103, v103
	s_nop 0
	v_mul_f32_e32 v107, 0x3f317217, v103
	v_fma_f32 v107, v103, s1, -v107
	v_fmac_f32_e32 v107, 0x3377d1cf, v103
	v_fmac_f32_e32 v107, 0x3f317217, v103
	v_cmp_lt_f32_e64 s[42:43], |v103|, s33
	s_nop 1
	v_cndmask_b32_e64 v103, v103, v107, s[42:43]
	v_cndmask_b32_e32 v107, 0, v199, vcc
	v_sub_f32_e32 v103, v103, v107
	v_add_f32_e32 v103, v106, v103
	v_sub_f32_e32 v103, -0.5, v103
	v_mul_f32_e32 v103, 0x3fb8aa3b, v103
	v_exp_f32_e32 v103, v103
	s_nop 0
	v_mul_f32_e32 v103, 0xbfb8aa3b, v103
	v_exp_f32_e32 v106, v103
	v_mov_b32_e32 v103, v1
	v_lshl_add_u64 v[102:103], v[102:103], 2, s[48:49]
	global_store_dword v[102:103], v106, off sc1
	v_add_f32_e32 v102, v83, v101
	v_max_f32_e64 v103, -v102, 0
	v_mul_f32_e64 v102, |v102|, s0
	v_exp_f32_e32 v102, v102
	s_nop 0
	v_add_f32_e32 v102, 1.0, v102
	v_cmp_gt_f32_e32 vcc, s31, v102
	s_nop 1
	v_cndmask_b32_e64 v106, 0, 32, vcc
	v_ldexp_f32 v102, v102, v106
	v_log_f32_e32 v102, v102
	s_nop 0
	v_mul_f32_e32 v106, 0x3f317217, v102
	v_fma_f32 v106, v102, s1, -v106
	v_fmac_f32_e32 v106, 0x3377d1cf, v102
	v_fmac_f32_e32 v106, 0x3f317217, v102
	v_cmp_lt_f32_e64 s[42:43], |v102|, s33
	s_nop 1
	v_cndmask_b32_e64 v102, v102, v106, s[42:43]
	v_cndmask_b32_e32 v106, 0, v199, vcc
	v_sub_f32_e32 v102, v102, v106
	v_add_f32_e32 v102, v103, v102
	v_sub_f32_e32 v102, -0.5, v102
	v_mul_f32_e32 v102, 0x3fb8aa3b, v102
	v_exp_f32_e32 v102, v102
	v_mov_b32_e32 v103, v1
	v_mul_f32_e32 v102, 0xbfb8aa3b, v102
	v_exp_f32_e32 v106, v102
	v_add_u32_e32 v102, v100, v159
	v_lshl_add_u64 v[102:103], v[102:103], 2, s[48:49]
	global_store_dword v[102:103], v106, off sc1
	v_add_f32_e32 v102, v84, v101
	v_max_f32_e64 v103, -v102, 0
	v_mul_f32_e64 v102, |v102|, s0
	v_exp_f32_e32 v102, v102
	s_nop 0
	v_add_f32_e32 v102, 1.0, v102
	v_cmp_gt_f32_e32 vcc, s31, v102
	s_nop 1
	v_cndmask_b32_e64 v106, 0, 32, vcc
	v_ldexp_f32 v102, v102, v106
	v_log_f32_e32 v102, v102
	s_nop 0
	v_mul_f32_e32 v106, 0x3f317217, v102
	v_fma_f32 v106, v102, s1, -v106
	v_fmac_f32_e32 v106, 0x3377d1cf, v102
	v_fmac_f32_e32 v106, 0x3f317217, v102
	v_cmp_lt_f32_e64 s[42:43], |v102|, s33
	s_nop 1
	v_cndmask_b32_e64 v102, v102, v106, s[42:43]
	v_cndmask_b32_e32 v106, 0, v199, vcc
	v_sub_f32_e32 v102, v102, v106
	v_add_f32_e32 v102, v103, v102
	v_sub_f32_e32 v102, -0.5, v102
	v_mul_f32_e32 v102, 0x3fb8aa3b, v102
	v_exp_f32_e32 v102, v102
	v_mov_b32_e32 v103, v1
	v_mul_f32_e32 v102, 0xbfb8aa3b, v102
	v_exp_f32_e32 v106, v102
	v_add_u32_e32 v102, v100, v158
	v_lshl_add_u64 v[102:103], v[102:103], 2, s[48:49]
	global_store_dword v[102:103], v106, off sc1
	v_add_f32_e32 v102, v85, v101
	v_max_f32_e64 v103, -v102, 0
	v_mul_f32_e64 v102, |v102|, s0
	v_exp_f32_e32 v102, v102
	s_nop 0
	v_add_f32_e32 v102, 1.0, v102
	v_cmp_gt_f32_e32 vcc, s31, v102
	s_nop 1
	v_cndmask_b32_e64 v106, 0, 32, vcc
	v_ldexp_f32 v102, v102, v106
	v_log_f32_e32 v102, v102
	s_nop 0
	v_mul_f32_e32 v106, 0x3f317217, v102
	v_fma_f32 v106, v102, s1, -v106
	v_fmac_f32_e32 v106, 0x3377d1cf, v102
	v_fmac_f32_e32 v106, 0x3f317217, v102
	v_cmp_lt_f32_e64 s[42:43], |v102|, s33
	s_nop 1
	v_cndmask_b32_e64 v102, v102, v106, s[42:43]
	v_cndmask_b32_e32 v106, 0, v199, vcc
	v_sub_f32_e32 v102, v102, v106
	v_add_f32_e32 v102, v103, v102
	v_sub_f32_e32 v102, -0.5, v102
	v_mul_f32_e32 v102, 0x3fb8aa3b, v102
	v_exp_f32_e32 v102, v102
	v_mov_b32_e32 v103, v1
	v_mul_f32_e32 v102, 0xbfb8aa3b, v102
	v_exp_f32_e32 v106, v102
	v_add_u32_e32 v102, v100, v157
	v_lshl_add_u64 v[102:103], v[102:103], 2, s[48:49]
	global_store_dword v[102:103], v106, off sc1
	v_add_f32_e32 v102, v86, v101
	v_max_f32_e64 v103, -v102, 0
	v_mul_f32_e64 v102, |v102|, s0
	v_exp_f32_e32 v102, v102
	s_nop 0
	v_add_f32_e32 v102, 1.0, v102
	v_cmp_gt_f32_e32 vcc, s31, v102
	s_nop 1
	v_cndmask_b32_e64 v106, 0, 32, vcc
	v_ldexp_f32 v102, v102, v106
	v_log_f32_e32 v102, v102
	s_nop 0
	v_mul_f32_e32 v106, 0x3f317217, v102
	v_fma_f32 v106, v102, s1, -v106
	v_fmac_f32_e32 v106, 0x3377d1cf, v102
	v_fmac_f32_e32 v106, 0x3f317217, v102
	v_cmp_lt_f32_e64 s[42:43], |v102|, s33
	s_nop 1
	v_cndmask_b32_e64 v102, v102, v106, s[42:43]
	v_cndmask_b32_e32 v106, 0, v199, vcc
	v_sub_f32_e32 v102, v102, v106
	v_add_f32_e32 v102, v103, v102
	v_sub_f32_e32 v102, -0.5, v102
	v_mul_f32_e32 v102, 0x3fb8aa3b, v102
	v_exp_f32_e32 v102, v102
	v_mov_b32_e32 v103, v1
	v_mul_f32_e32 v102, 0xbfb8aa3b, v102
	v_exp_f32_e32 v106, v102
	v_add_u32_e32 v102, v100, v156
	v_lshl_add_u64 v[102:103], v[102:103], 2, s[48:49]
	global_store_dword v[102:103], v106, off sc1
	v_add_f32_e32 v102, v87, v101
	v_max_f32_e64 v103, -v102, 0
	v_mul_f32_e64 v102, |v102|, s0
	v_exp_f32_e32 v102, v102
	s_nop 0
	v_add_f32_e32 v102, 1.0, v102
	v_cmp_gt_f32_e32 vcc, s31, v102
	s_nop 1
	v_cndmask_b32_e64 v106, 0, 32, vcc
	v_ldexp_f32 v102, v102, v106
	v_log_f32_e32 v102, v102
	s_nop 0
	v_mul_f32_e32 v106, 0x3f317217, v102
	v_fma_f32 v106, v102, s1, -v106
	v_fmac_f32_e32 v106, 0x3377d1cf, v102
	v_fmac_f32_e32 v106, 0x3f317217, v102
	v_cmp_lt_f32_e64 s[42:43], |v102|, s33
	s_nop 1
	v_cndmask_b32_e64 v102, v102, v106, s[42:43]
	v_cndmask_b32_e32 v106, 0, v199, vcc
	v_sub_f32_e32 v102, v102, v106
	v_add_f32_e32 v102, v103, v102
	v_sub_f32_e32 v102, -0.5, v102
	v_mul_f32_e32 v102, 0x3fb8aa3b, v102
	v_exp_f32_e32 v102, v102
	v_mov_b32_e32 v103, v1
	v_mul_f32_e32 v102, 0xbfb8aa3b, v102
	v_exp_f32_e32 v106, v102
	v_add_u32_e32 v102, v100, v155
	v_lshl_add_u64 v[102:103], v[102:103], 2, s[48:49]
	global_store_dword v[102:103], v106, off sc1
	v_add_f32_e32 v102, v88, v101
	v_max_f32_e64 v103, -v102, 0
	v_mul_f32_e64 v102, |v102|, s0
	v_exp_f32_e32 v102, v102
	s_nop 0
	v_add_f32_e32 v102, 1.0, v102
	v_cmp_gt_f32_e32 vcc, s31, v102
	s_nop 1
	v_cndmask_b32_e64 v106, 0, 32, vcc
	v_ldexp_f32 v102, v102, v106
	v_log_f32_e32 v102, v102
	s_nop 0
	v_mul_f32_e32 v106, 0x3f317217, v102
	v_fma_f32 v106, v102, s1, -v106
	v_fmac_f32_e32 v106, 0x3377d1cf, v102
	v_fmac_f32_e32 v106, 0x3f317217, v102
	v_cmp_lt_f32_e64 s[42:43], |v102|, s33
	s_nop 1
	v_cndmask_b32_e64 v102, v102, v106, s[42:43]
	v_cndmask_b32_e32 v106, 0, v199, vcc
	v_sub_f32_e32 v102, v102, v106
	v_add_f32_e32 v102, v103, v102
	v_sub_f32_e32 v102, -0.5, v102
	v_mul_f32_e32 v102, 0x3fb8aa3b, v102
	v_exp_f32_e32 v102, v102
	v_mov_b32_e32 v103, v1
	v_mul_f32_e32 v102, 0xbfb8aa3b, v102
	v_exp_f32_e32 v106, v102
	v_add_u32_e32 v102, v100, v154
	v_lshl_add_u64 v[102:103], v[102:103], 2, s[48:49]
	global_store_dword v[102:103], v106, off sc1
	v_add_f32_e32 v102, v89, v101
	v_max_f32_e64 v103, -v102, 0
	v_mul_f32_e64 v102, |v102|, s0
	v_exp_f32_e32 v102, v102
	s_nop 0
	v_add_f32_e32 v102, 1.0, v102
	v_cmp_gt_f32_e32 vcc, s31, v102
	s_nop 1
	v_cndmask_b32_e64 v106, 0, 32, vcc
	v_ldexp_f32 v102, v102, v106
	v_log_f32_e32 v102, v102
	s_nop 0
	v_mul_f32_e32 v106, 0x3f317217, v102
	v_fma_f32 v106, v102, s1, -v106
	v_fmac_f32_e32 v106, 0x3377d1cf, v102
	v_fmac_f32_e32 v106, 0x3f317217, v102
	v_cmp_lt_f32_e64 s[42:43], |v102|, s33
	s_nop 1
	v_cndmask_b32_e64 v102, v102, v106, s[42:43]
	v_cndmask_b32_e32 v106, 0, v199, vcc
	v_sub_f32_e32 v102, v102, v106
	v_add_f32_e32 v102, v103, v102
	v_sub_f32_e32 v102, -0.5, v102
	v_mul_f32_e32 v102, 0x3fb8aa3b, v102
	v_exp_f32_e32 v102, v102
	v_mov_b32_e32 v103, v1
	v_mul_f32_e32 v102, 0xbfb8aa3b, v102
	v_exp_f32_e32 v106, v102
	v_add_u32_e32 v102, v100, v153
	v_lshl_add_u64 v[102:103], v[102:103], 2, s[48:49]
	global_store_dword v[102:103], v106, off sc1
	v_add_f32_e32 v102, v90, v101
	v_max_f32_e64 v103, -v102, 0
	v_mul_f32_e64 v102, |v102|, s0
	v_exp_f32_e32 v102, v102
	s_nop 0
	v_add_f32_e32 v102, 1.0, v102
	v_cmp_gt_f32_e32 vcc, s31, v102
	s_nop 1
	v_cndmask_b32_e64 v106, 0, 32, vcc
	v_ldexp_f32 v102, v102, v106
	v_log_f32_e32 v102, v102
	s_nop 0
	v_mul_f32_e32 v106, 0x3f317217, v102
	v_fma_f32 v106, v102, s1, -v106
	v_fmac_f32_e32 v106, 0x3377d1cf, v102
	v_fmac_f32_e32 v106, 0x3f317217, v102
	v_cmp_lt_f32_e64 s[42:43], |v102|, s33
	s_nop 1
	v_cndmask_b32_e64 v102, v102, v106, s[42:43]
	v_cndmask_b32_e32 v106, 0, v199, vcc
	v_sub_f32_e32 v102, v102, v106
	v_add_f32_e32 v102, v103, v102
	v_sub_f32_e32 v102, -0.5, v102
	v_mul_f32_e32 v102, 0x3fb8aa3b, v102
	v_exp_f32_e32 v102, v102
	v_mov_b32_e32 v103, v1
	v_mul_f32_e32 v102, 0xbfb8aa3b, v102
	v_exp_f32_e32 v106, v102
	v_add_u32_e32 v102, v100, v152
	v_lshl_add_u64 v[102:103], v[102:103], 2, s[48:49]
	global_store_dword v[102:103], v106, off sc1
	v_add_f32_e32 v102, v91, v101
	v_max_f32_e64 v103, -v102, 0
	v_mul_f32_e64 v102, |v102|, s0
	v_exp_f32_e32 v102, v102
	s_nop 0
	v_add_f32_e32 v102, 1.0, v102
	v_cmp_gt_f32_e32 vcc, s31, v102
	s_nop 1
	v_cndmask_b32_e64 v106, 0, 32, vcc
	v_ldexp_f32 v102, v102, v106
	v_log_f32_e32 v102, v102
	s_nop 0
	v_mul_f32_e32 v106, 0x3f317217, v102
	v_fma_f32 v106, v102, s1, -v106
	v_fmac_f32_e32 v106, 0x3377d1cf, v102
	v_fmac_f32_e32 v106, 0x3f317217, v102
	v_cmp_lt_f32_e64 s[42:43], |v102|, s33
	s_nop 1
	v_cndmask_b32_e64 v102, v102, v106, s[42:43]
	v_cndmask_b32_e32 v106, 0, v199, vcc
	v_sub_f32_e32 v102, v102, v106
	v_add_f32_e32 v102, v103, v102
	v_sub_f32_e32 v102, -0.5, v102
	v_mul_f32_e32 v102, 0x3fb8aa3b, v102
	v_exp_f32_e32 v102, v102
	v_mov_b32_e32 v103, v1
	v_mul_f32_e32 v102, 0xbfb8aa3b, v102
	v_exp_f32_e32 v106, v102
	v_add_u32_e32 v102, v100, v151
	v_lshl_add_u64 v[102:103], v[102:103], 2, s[48:49]
	global_store_dword v[102:103], v106, off sc1
	v_add_f32_e32 v102, v92, v101
	v_max_f32_e64 v103, -v102, 0
	v_mul_f32_e64 v102, |v102|, s0
	v_exp_f32_e32 v102, v102
	s_nop 0
	v_add_f32_e32 v102, 1.0, v102
	v_cmp_gt_f32_e32 vcc, s31, v102
	s_nop 1
	v_cndmask_b32_e64 v106, 0, 32, vcc
	v_ldexp_f32 v102, v102, v106
	v_log_f32_e32 v102, v102
	s_nop 0
	v_mul_f32_e32 v106, 0x3f317217, v102
	v_fma_f32 v106, v102, s1, -v106
	v_fmac_f32_e32 v106, 0x3377d1cf, v102
	v_fmac_f32_e32 v106, 0x3f317217, v102
	v_cmp_lt_f32_e64 s[42:43], |v102|, s33
	s_nop 1
	v_cndmask_b32_e64 v102, v102, v106, s[42:43]
	v_cndmask_b32_e32 v106, 0, v199, vcc
	v_sub_f32_e32 v102, v102, v106
	v_add_f32_e32 v102, v103, v102
	v_sub_f32_e32 v102, -0.5, v102
	v_mul_f32_e32 v102, 0x3fb8aa3b, v102
	v_exp_f32_e32 v102, v102
	v_mov_b32_e32 v103, v1
	v_mul_f32_e32 v102, 0xbfb8aa3b, v102
	v_exp_f32_e32 v106, v102
	v_add_u32_e32 v102, v100, v150
	v_lshl_add_u64 v[102:103], v[102:103], 2, s[48:49]
	global_store_dword v[102:103], v106, off sc1
	v_add_f32_e32 v102, v93, v101
	v_max_f32_e64 v103, -v102, 0
	v_mul_f32_e64 v102, |v102|, s0
	v_exp_f32_e32 v102, v102
	s_nop 0
	v_add_f32_e32 v102, 1.0, v102
	v_cmp_gt_f32_e32 vcc, s31, v102
	s_nop 1
	v_cndmask_b32_e64 v106, 0, 32, vcc
	v_ldexp_f32 v102, v102, v106
	v_log_f32_e32 v102, v102
	s_nop 0
	v_mul_f32_e32 v106, 0x3f317217, v102
	v_fma_f32 v106, v102, s1, -v106
	v_fmac_f32_e32 v106, 0x3377d1cf, v102
	v_fmac_f32_e32 v106, 0x3f317217, v102
	v_cmp_lt_f32_e64 s[42:43], |v102|, s33
	s_nop 1
	v_cndmask_b32_e64 v102, v102, v106, s[42:43]
	v_cndmask_b32_e32 v106, 0, v199, vcc
	v_sub_f32_e32 v102, v102, v106
	v_add_f32_e32 v102, v103, v102
	v_sub_f32_e32 v102, -0.5, v102
	v_mul_f32_e32 v102, 0x3fb8aa3b, v102
	v_exp_f32_e32 v102, v102
	v_mov_b32_e32 v103, v1
	v_mul_f32_e32 v102, 0xbfb8aa3b, v102
	v_exp_f32_e32 v106, v102
	v_add_u32_e32 v102, v100, v149
	v_lshl_add_u64 v[102:103], v[102:103], 2, s[48:49]
	global_store_dword v[102:103], v106, off sc1
	v_add_f32_e32 v102, v94, v101
	v_max_f32_e64 v103, -v102, 0
	v_mul_f32_e64 v102, |v102|, s0
	v_exp_f32_e32 v102, v102
	s_nop 0
	v_add_f32_e32 v102, 1.0, v102
	v_cmp_gt_f32_e32 vcc, s31, v102
	s_nop 1
	v_cndmask_b32_e64 v106, 0, 32, vcc
	v_ldexp_f32 v102, v102, v106
	v_log_f32_e32 v102, v102
	s_nop 0
	v_mul_f32_e32 v106, 0x3f317217, v102
	v_fma_f32 v106, v102, s1, -v106
	v_fmac_f32_e32 v106, 0x3377d1cf, v102
	v_fmac_f32_e32 v106, 0x3f317217, v102
	v_cmp_lt_f32_e64 s[42:43], |v102|, s33
	s_nop 1
	v_cndmask_b32_e64 v102, v102, v106, s[42:43]
	v_cndmask_b32_e32 v106, 0, v199, vcc
	v_sub_f32_e32 v102, v102, v106
	v_add_f32_e32 v102, v103, v102
	v_sub_f32_e32 v102, -0.5, v102
	v_mul_f32_e32 v102, 0x3fb8aa3b, v102
	v_exp_f32_e32 v102, v102
	v_mov_b32_e32 v103, v1
	v_mul_f32_e32 v102, 0xbfb8aa3b, v102
	v_exp_f32_e32 v106, v102
	v_add_u32_e32 v102, v100, v148
	v_lshl_add_u64 v[102:103], v[102:103], 2, s[48:49]
	global_store_dword v[102:103], v106, off sc1
	v_add_f32_e32 v102, v95, v101
	v_max_f32_e64 v103, -v102, 0
	v_mul_f32_e64 v102, |v102|, s0
	v_exp_f32_e32 v102, v102
	s_nop 0
	v_add_f32_e32 v102, 1.0, v102
	v_cmp_gt_f32_e32 vcc, s31, v102
	s_nop 1
	v_cndmask_b32_e64 v106, 0, 32, vcc
	v_ldexp_f32 v102, v102, v106
	v_log_f32_e32 v102, v102
	s_nop 0
	v_mul_f32_e32 v106, 0x3f317217, v102
	v_fma_f32 v106, v102, s1, -v106
	v_fmac_f32_e32 v106, 0x3377d1cf, v102
	v_fmac_f32_e32 v106, 0x3f317217, v102
	v_cmp_lt_f32_e64 s[42:43], |v102|, s33
	s_nop 1
	v_cndmask_b32_e64 v102, v102, v106, s[42:43]
	v_cndmask_b32_e32 v106, 0, v199, vcc
	v_sub_f32_e32 v102, v102, v106
	v_add_f32_e32 v102, v103, v102
	v_sub_f32_e32 v102, -0.5, v102
	v_mul_f32_e32 v102, 0x3fb8aa3b, v102
	v_exp_f32_e32 v102, v102
	v_mov_b32_e32 v103, v1
	v_mul_f32_e32 v102, 0xbfb8aa3b, v102
	v_exp_f32_e32 v106, v102
	v_add_u32_e32 v102, v100, v113
	v_lshl_add_u64 v[102:103], v[102:103], 2, s[48:49]
	global_store_dword v[102:103], v106, off sc1
	v_add_f32_e32 v102, v96, v101
	v_max_f32_e64 v103, -v102, 0
	v_mul_f32_e64 v102, |v102|, s0
	v_exp_f32_e32 v102, v102
	v_add_f32_e32 v101, v97, v101
	v_add_f32_e32 v102, 1.0, v102
	v_cmp_gt_f32_e32 vcc, s31, v102
	s_nop 1
	v_cndmask_b32_e64 v106, 0, 32, vcc
	v_ldexp_f32 v102, v102, v106
	v_log_f32_e32 v102, v102
	s_nop 0
	v_mul_f32_e32 v106, 0x3f317217, v102
	v_fma_f32 v106, v102, s1, -v106
	v_fmac_f32_e32 v106, 0x3377d1cf, v102
	v_fmac_f32_e32 v106, 0x3f317217, v102
	v_cmp_lt_f32_e64 s[42:43], |v102|, s33
	s_nop 1
	v_cndmask_b32_e64 v102, v102, v106, s[42:43]
	v_cndmask_b32_e32 v106, 0, v199, vcc
	v_sub_f32_e32 v102, v102, v106
	v_add_f32_e32 v102, v103, v102
	v_sub_f32_e32 v102, -0.5, v102
	v_mul_f32_e32 v102, 0x3fb8aa3b, v102
	v_exp_f32_e32 v102, v102
	v_mov_b32_e32 v103, v1
	v_mul_f32_e32 v102, 0xbfb8aa3b, v102
	v_exp_f32_e32 v106, v102
	v_add_u32_e32 v102, v100, v112
	v_lshl_add_u64 v[102:103], v[102:103], 2, s[48:49]
	global_store_dword v[102:103], v106, off sc1
	v_max_f32_e64 v102, -v101, 0
	v_mul_f32_e64 v101, |v101|, s0
	v_exp_f32_e32 v101, v101
	s_nop 0
	v_add_f32_e32 v101, 1.0, v101
	v_cmp_gt_f32_e32 vcc, s31, v101
	s_nop 1
	v_cndmask_b32_e64 v103, 0, 32, vcc
	v_ldexp_f32 v101, v101, v103
	v_log_f32_e32 v101, v101
	s_nop 0
	v_mul_f32_e32 v103, 0x3f317217, v101
	v_fma_f32 v103, v101, s1, -v103
	v_fmac_f32_e32 v103, 0x3377d1cf, v101
	v_fmac_f32_e32 v103, 0x3f317217, v101
	v_cmp_lt_f32_e64 s[42:43], |v101|, s33
	s_nop 1
	v_cndmask_b32_e64 v101, v101, v103, s[42:43]
	v_cndmask_b32_e32 v103, 0, v199, vcc
	v_sub_f32_e32 v101, v101, v103
	v_add_f32_e32 v101, v102, v101
	v_sub_f32_e32 v101, -0.5, v101
	v_mul_f32_e32 v101, 0x3fb8aa3b, v101
	v_exp_f32_e32 v101, v101
	v_add_u32_e32 v102, v100, v111
	v_mov_b32_e32 v103, v1
	v_lshl_add_u64 v[102:103], v[102:103], 2, s[48:49]
	v_mul_f32_e32 v101, 0xbfb8aa3b, v101
	v_exp_f32_e32 v101, v101
	global_store_dword v[102:103], v101, off sc1
	v_or_b32_e32 v101, 32, v100
	v_mov_b32_e32 v102, v237
	v_add_f32_e32 v103, v66, v102
	v_max_f32_e64 v106, -v103, 0
	v_mul_f32_e64 v103, |v103|, s0
	v_exp_f32_e32 v103, v103
	s_nop 0
	v_add_f32_e32 v103, 1.0, v103
	v_cmp_gt_f32_e32 vcc, s31, v103
	s_nop 1
	v_cndmask_b32_e64 v107, 0, 32, vcc
	v_ldexp_f32 v103, v103, v107
	v_log_f32_e32 v103, v103
	s_nop 0
	v_mul_f32_e32 v107, 0x3f317217, v103
	v_fma_f32 v107, v103, s1, -v107
	v_fmac_f32_e32 v107, 0x3377d1cf, v103
	v_fmac_f32_e32 v107, 0x3f317217, v103
	v_cmp_lt_f32_e64 s[42:43], |v103|, s33
	s_nop 1
	v_cndmask_b32_e64 v103, v103, v107, s[42:43]
	v_cndmask_b32_e32 v107, 0, v199, vcc
	v_sub_f32_e32 v103, v103, v107
	v_add_f32_e32 v103, v106, v103
	v_sub_f32_e32 v103, -0.5, v103
	v_mul_f32_e32 v103, 0x3fb8aa3b, v103
	v_exp_f32_e32 v103, v103
	v_add_u32_e32 v106, v101, v110
	v_mov_b32_e32 v107, v1
	v_lshl_add_u64 v[106:107], v[106:107], 2, s[48:49]
	v_mul_f32_e32 v103, 0xbfb8aa3b, v103
	v_exp_f32_e32 v103, v103
	global_store_dword v[106:107], v103, off sc1
	v_add_f32_e32 v103, v67, v102
	v_max_f32_e64 v106, -v103, 0
	v_mul_f32_e64 v103, |v103|, s0
	v_exp_f32_e32 v103, v103
	s_nop 0
	v_add_f32_e32 v103, 1.0, v103
	v_cmp_gt_f32_e32 vcc, s31, v103
	s_nop 1
	v_cndmask_b32_e64 v107, 0, 32, vcc
	v_ldexp_f32 v103, v103, v107
	v_log_f32_e32 v103, v103
	s_nop 0
	v_mul_f32_e32 v107, 0x3f317217, v103
	v_fma_f32 v107, v103, s1, -v107
	v_fmac_f32_e32 v107, 0x3377d1cf, v103
	v_fmac_f32_e32 v107, 0x3f317217, v103
	v_cmp_lt_f32_e64 s[42:43], |v103|, s33
	s_nop 1
	v_cndmask_b32_e64 v103, v103, v107, s[42:43]
	v_cndmask_b32_e32 v107, 0, v199, vcc
	v_sub_f32_e32 v103, v103, v107
	v_add_f32_e32 v103, v106, v103
	v_sub_f32_e32 v103, -0.5, v103
	v_mul_f32_e32 v103, 0x3fb8aa3b, v103
	v_exp_f32_e32 v103, v103
	v_add_u32_e32 v106, v101, v159
	v_mov_b32_e32 v107, v1
	v_lshl_add_u64 v[106:107], v[106:107], 2, s[48:49]
	v_mul_f32_e32 v103, 0xbfb8aa3b, v103
	v_exp_f32_e32 v103, v103
	global_store_dword v[106:107], v103, off sc1
	v_add_f32_e32 v103, v68, v102
	v_max_f32_e64 v106, -v103, 0
	v_mul_f32_e64 v103, |v103|, s0
	v_exp_f32_e32 v103, v103
	s_nop 0
	v_add_f32_e32 v103, 1.0, v103
	v_cmp_gt_f32_e32 vcc, s31, v103
	s_nop 1
	v_cndmask_b32_e64 v107, 0, 32, vcc
	v_ldexp_f32 v103, v103, v107
	v_log_f32_e32 v103, v103
	s_nop 0
	v_mul_f32_e32 v107, 0x3f317217, v103
	v_fma_f32 v107, v103, s1, -v107
	v_fmac_f32_e32 v107, 0x3377d1cf, v103
	v_fmac_f32_e32 v107, 0x3f317217, v103
	v_cmp_lt_f32_e64 s[42:43], |v103|, s33
	s_nop 1
	v_cndmask_b32_e64 v103, v103, v107, s[42:43]
	v_cndmask_b32_e32 v107, 0, v199, vcc
	v_sub_f32_e32 v103, v103, v107
	v_add_f32_e32 v103, v106, v103
	v_sub_f32_e32 v103, -0.5, v103
	v_mul_f32_e32 v103, 0x3fb8aa3b, v103
	v_exp_f32_e32 v103, v103
	v_add_u32_e32 v106, v101, v158
	v_mov_b32_e32 v107, v1
	v_lshl_add_u64 v[106:107], v[106:107], 2, s[48:49]
	v_mul_f32_e32 v103, 0xbfb8aa3b, v103
	v_exp_f32_e32 v103, v103
	global_store_dword v[106:107], v103, off sc1
	v_add_f32_e32 v103, v69, v102
	v_max_f32_e64 v106, -v103, 0
	v_mul_f32_e64 v103, |v103|, s0
	v_exp_f32_e32 v103, v103
	s_nop 0
	v_add_f32_e32 v103, 1.0, v103
	v_cmp_gt_f32_e32 vcc, s31, v103
	s_nop 1
	v_cndmask_b32_e64 v107, 0, 32, vcc
	v_ldexp_f32 v103, v103, v107
	v_log_f32_e32 v103, v103
	s_nop 0
	v_mul_f32_e32 v107, 0x3f317217, v103
	v_fma_f32 v107, v103, s1, -v107
	v_fmac_f32_e32 v107, 0x3377d1cf, v103
	v_fmac_f32_e32 v107, 0x3f317217, v103
	v_cmp_lt_f32_e64 s[42:43], |v103|, s33
	s_nop 1
	v_cndmask_b32_e64 v103, v103, v107, s[42:43]
	v_cndmask_b32_e32 v107, 0, v199, vcc
	v_sub_f32_e32 v103, v103, v107
	v_add_f32_e32 v103, v106, v103
	v_sub_f32_e32 v103, -0.5, v103
	v_mul_f32_e32 v103, 0x3fb8aa3b, v103
	v_exp_f32_e32 v103, v103
	v_add_u32_e32 v106, v101, v157
	v_mov_b32_e32 v107, v1
	v_lshl_add_u64 v[106:107], v[106:107], 2, s[48:49]
	v_mul_f32_e32 v103, 0xbfb8aa3b, v103
	v_exp_f32_e32 v103, v103
	global_store_dword v[106:107], v103, off sc1
	v_add_f32_e32 v103, v70, v102
	v_max_f32_e64 v106, -v103, 0
	v_mul_f32_e64 v103, |v103|, s0
	v_exp_f32_e32 v103, v103
	s_nop 0
	v_add_f32_e32 v103, 1.0, v103
	v_cmp_gt_f32_e32 vcc, s31, v103
	s_nop 1
	v_cndmask_b32_e64 v107, 0, 32, vcc
	v_ldexp_f32 v103, v103, v107
	v_log_f32_e32 v103, v103
	s_nop 0
	v_mul_f32_e32 v107, 0x3f317217, v103
	v_fma_f32 v107, v103, s1, -v107
	v_fmac_f32_e32 v107, 0x3377d1cf, v103
	v_fmac_f32_e32 v107, 0x3f317217, v103
	v_cmp_lt_f32_e64 s[42:43], |v103|, s33
	s_nop 1
	v_cndmask_b32_e64 v103, v103, v107, s[42:43]
	v_cndmask_b32_e32 v107, 0, v199, vcc
	v_sub_f32_e32 v103, v103, v107
	v_add_f32_e32 v103, v106, v103
	v_sub_f32_e32 v103, -0.5, v103
	v_mul_f32_e32 v103, 0x3fb8aa3b, v103
	v_exp_f32_e32 v103, v103
	v_add_u32_e32 v106, v101, v156
	v_mov_b32_e32 v107, v1
	v_lshl_add_u64 v[106:107], v[106:107], 2, s[48:49]
	v_mul_f32_e32 v103, 0xbfb8aa3b, v103
	v_exp_f32_e32 v103, v103
	global_store_dword v[106:107], v103, off sc1
	v_add_f32_e32 v103, v71, v102
	v_max_f32_e64 v106, -v103, 0
	v_mul_f32_e64 v103, |v103|, s0
	v_exp_f32_e32 v103, v103
	s_nop 0
	v_add_f32_e32 v103, 1.0, v103
	v_cmp_gt_f32_e32 vcc, s31, v103
	s_nop 1
	v_cndmask_b32_e64 v107, 0, 32, vcc
	v_ldexp_f32 v103, v103, v107
	v_log_f32_e32 v103, v103
	s_nop 0
	v_mul_f32_e32 v107, 0x3f317217, v103
	v_fma_f32 v107, v103, s1, -v107
	v_fmac_f32_e32 v107, 0x3377d1cf, v103
	v_fmac_f32_e32 v107, 0x3f317217, v103
	v_cmp_lt_f32_e64 s[42:43], |v103|, s33
	s_nop 1
	v_cndmask_b32_e64 v103, v103, v107, s[42:43]
	v_cndmask_b32_e32 v107, 0, v199, vcc
	v_sub_f32_e32 v103, v103, v107
	v_add_f32_e32 v103, v106, v103
	v_sub_f32_e32 v103, -0.5, v103
	v_mul_f32_e32 v103, 0x3fb8aa3b, v103
	v_exp_f32_e32 v103, v103
	v_add_u32_e32 v106, v101, v155
	v_mov_b32_e32 v107, v1
	v_lshl_add_u64 v[106:107], v[106:107], 2, s[48:49]
	v_mul_f32_e32 v103, 0xbfb8aa3b, v103
	v_exp_f32_e32 v103, v103
	global_store_dword v[106:107], v103, off sc1
	v_add_f32_e32 v103, v72, v102
	v_max_f32_e64 v106, -v103, 0
	v_mul_f32_e64 v103, |v103|, s0
	v_exp_f32_e32 v103, v103
	s_nop 0
	v_add_f32_e32 v103, 1.0, v103
	v_cmp_gt_f32_e32 vcc, s31, v103
	s_nop 1
	v_cndmask_b32_e64 v107, 0, 32, vcc
	v_ldexp_f32 v103, v103, v107
	v_log_f32_e32 v103, v103
	s_nop 0
	v_mul_f32_e32 v107, 0x3f317217, v103
	v_fma_f32 v107, v103, s1, -v107
	v_fmac_f32_e32 v107, 0x3377d1cf, v103
	v_fmac_f32_e32 v107, 0x3f317217, v103
	v_cmp_lt_f32_e64 s[42:43], |v103|, s33
	s_nop 1
	v_cndmask_b32_e64 v103, v103, v107, s[42:43]
	v_cndmask_b32_e32 v107, 0, v199, vcc
	v_sub_f32_e32 v103, v103, v107
	v_add_f32_e32 v103, v106, v103
	v_sub_f32_e32 v103, -0.5, v103
	v_mul_f32_e32 v103, 0x3fb8aa3b, v103
	v_exp_f32_e32 v103, v103
	v_add_u32_e32 v106, v101, v154
	v_mov_b32_e32 v107, v1
	v_lshl_add_u64 v[106:107], v[106:107], 2, s[48:49]
	v_mul_f32_e32 v103, 0xbfb8aa3b, v103
	v_exp_f32_e32 v103, v103
	global_store_dword v[106:107], v103, off sc1
	v_add_f32_e32 v103, v73, v102
	v_max_f32_e64 v106, -v103, 0
	v_mul_f32_e64 v103, |v103|, s0
	v_exp_f32_e32 v103, v103
	s_nop 0
	v_add_f32_e32 v103, 1.0, v103
	v_cmp_gt_f32_e32 vcc, s31, v103
	s_nop 1
	v_cndmask_b32_e64 v107, 0, 32, vcc
	v_ldexp_f32 v103, v103, v107
	v_log_f32_e32 v103, v103
	s_nop 0
	v_mul_f32_e32 v107, 0x3f317217, v103
	v_fma_f32 v107, v103, s1, -v107
	v_fmac_f32_e32 v107, 0x3377d1cf, v103
	v_fmac_f32_e32 v107, 0x3f317217, v103
	v_cmp_lt_f32_e64 s[42:43], |v103|, s33
	s_nop 1
	v_cndmask_b32_e64 v103, v103, v107, s[42:43]
	v_cndmask_b32_e32 v107, 0, v199, vcc
	v_sub_f32_e32 v103, v103, v107
	v_add_f32_e32 v103, v106, v103
	v_sub_f32_e32 v103, -0.5, v103
	v_mul_f32_e32 v103, 0x3fb8aa3b, v103
	v_exp_f32_e32 v103, v103
	v_add_u32_e32 v106, v101, v153
	v_mov_b32_e32 v107, v1
	v_lshl_add_u64 v[106:107], v[106:107], 2, s[48:49]
	v_mul_f32_e32 v103, 0xbfb8aa3b, v103
	v_exp_f32_e32 v103, v103
	global_store_dword v[106:107], v103, off sc1
	v_add_f32_e32 v103, v74, v102
	v_max_f32_e64 v106, -v103, 0
	v_mul_f32_e64 v103, |v103|, s0
	v_exp_f32_e32 v103, v103
	s_nop 0
	v_add_f32_e32 v103, 1.0, v103
	v_cmp_gt_f32_e32 vcc, s31, v103
	s_nop 1
	v_cndmask_b32_e64 v107, 0, 32, vcc
	v_ldexp_f32 v103, v103, v107
	v_log_f32_e32 v103, v103
	s_nop 0
	v_mul_f32_e32 v107, 0x3f317217, v103
	v_fma_f32 v107, v103, s1, -v107
	v_fmac_f32_e32 v107, 0x3377d1cf, v103
	v_fmac_f32_e32 v107, 0x3f317217, v103
	v_cmp_lt_f32_e64 s[42:43], |v103|, s33
	s_nop 1
	v_cndmask_b32_e64 v103, v103, v107, s[42:43]
	v_cndmask_b32_e32 v107, 0, v199, vcc
	v_sub_f32_e32 v103, v103, v107
	v_add_f32_e32 v103, v106, v103
	v_sub_f32_e32 v103, -0.5, v103
	v_mul_f32_e32 v103, 0x3fb8aa3b, v103
	v_exp_f32_e32 v103, v103
	v_add_u32_e32 v106, v101, v152
	v_mov_b32_e32 v107, v1
	v_lshl_add_u64 v[106:107], v[106:107], 2, s[48:49]
	v_mul_f32_e32 v103, 0xbfb8aa3b, v103
	v_exp_f32_e32 v103, v103
	global_store_dword v[106:107], v103, off sc1
	v_add_f32_e32 v103, v75, v102
	v_max_f32_e64 v106, -v103, 0
	v_mul_f32_e64 v103, |v103|, s0
	v_exp_f32_e32 v103, v103
	s_nop 0
	v_add_f32_e32 v103, 1.0, v103
	v_cmp_gt_f32_e32 vcc, s31, v103
	s_nop 1
	v_cndmask_b32_e64 v107, 0, 32, vcc
	v_ldexp_f32 v103, v103, v107
	v_log_f32_e32 v103, v103
	s_nop 0
	v_mul_f32_e32 v107, 0x3f317217, v103
	v_fma_f32 v107, v103, s1, -v107
	v_fmac_f32_e32 v107, 0x3377d1cf, v103
	v_fmac_f32_e32 v107, 0x3f317217, v103
	v_cmp_lt_f32_e64 s[42:43], |v103|, s33
	s_nop 1
	v_cndmask_b32_e64 v103, v103, v107, s[42:43]
	v_cndmask_b32_e32 v107, 0, v199, vcc
	v_sub_f32_e32 v103, v103, v107
	v_add_f32_e32 v103, v106, v103
	v_sub_f32_e32 v103, -0.5, v103
	v_mul_f32_e32 v103, 0x3fb8aa3b, v103
	v_exp_f32_e32 v103, v103
	v_add_u32_e32 v106, v101, v151
	v_mov_b32_e32 v107, v1
	v_lshl_add_u64 v[106:107], v[106:107], 2, s[48:49]
	v_mul_f32_e32 v103, 0xbfb8aa3b, v103
	v_exp_f32_e32 v103, v103
	global_store_dword v[106:107], v103, off sc1
	v_add_f32_e32 v103, v76, v102
	v_max_f32_e64 v106, -v103, 0
	v_mul_f32_e64 v103, |v103|, s0
	v_exp_f32_e32 v103, v103
	s_nop 0
	v_add_f32_e32 v103, 1.0, v103
	v_cmp_gt_f32_e32 vcc, s31, v103
	s_nop 1
	v_cndmask_b32_e64 v107, 0, 32, vcc
	v_ldexp_f32 v103, v103, v107
	v_log_f32_e32 v103, v103
	s_nop 0
	v_mul_f32_e32 v107, 0x3f317217, v103
	v_fma_f32 v107, v103, s1, -v107
	v_fmac_f32_e32 v107, 0x3377d1cf, v103
	v_fmac_f32_e32 v107, 0x3f317217, v103
	v_cmp_lt_f32_e64 s[42:43], |v103|, s33
	s_nop 1
	v_cndmask_b32_e64 v103, v103, v107, s[42:43]
	v_cndmask_b32_e32 v107, 0, v199, vcc
	v_sub_f32_e32 v103, v103, v107
	v_add_f32_e32 v103, v106, v103
	v_sub_f32_e32 v103, -0.5, v103
	v_mul_f32_e32 v103, 0x3fb8aa3b, v103
	v_exp_f32_e32 v103, v103
	v_add_u32_e32 v106, v101, v150
	v_mov_b32_e32 v107, v1
	v_lshl_add_u64 v[106:107], v[106:107], 2, s[48:49]
	v_mul_f32_e32 v103, 0xbfb8aa3b, v103
	v_exp_f32_e32 v103, v103
	global_store_dword v[106:107], v103, off sc1
	v_add_f32_e32 v103, v77, v102
	v_max_f32_e64 v106, -v103, 0
	v_mul_f32_e64 v103, |v103|, s0
	v_exp_f32_e32 v103, v103
	s_nop 0
	v_add_f32_e32 v103, 1.0, v103
	v_cmp_gt_f32_e32 vcc, s31, v103
	s_nop 1
	v_cndmask_b32_e64 v107, 0, 32, vcc
	v_ldexp_f32 v103, v103, v107
	v_log_f32_e32 v103, v103
	s_nop 0
	v_mul_f32_e32 v107, 0x3f317217, v103
	v_fma_f32 v107, v103, s1, -v107
	v_fmac_f32_e32 v107, 0x3377d1cf, v103
	v_fmac_f32_e32 v107, 0x3f317217, v103
	v_cmp_lt_f32_e64 s[42:43], |v103|, s33
	s_nop 1
	v_cndmask_b32_e64 v103, v103, v107, s[42:43]
	v_cndmask_b32_e32 v107, 0, v199, vcc
	v_sub_f32_e32 v103, v103, v107
	v_add_f32_e32 v103, v106, v103
	v_sub_f32_e32 v103, -0.5, v103
	v_mul_f32_e32 v103, 0x3fb8aa3b, v103
	v_exp_f32_e32 v103, v103
	v_add_u32_e32 v106, v101, v149
	v_mov_b32_e32 v107, v1
	v_lshl_add_u64 v[106:107], v[106:107], 2, s[48:49]
	v_mul_f32_e32 v103, 0xbfb8aa3b, v103
	v_exp_f32_e32 v103, v103
	global_store_dword v[106:107], v103, off sc1
	v_add_f32_e32 v103, v78, v102
	v_max_f32_e64 v106, -v103, 0
	v_mul_f32_e64 v103, |v103|, s0
	v_exp_f32_e32 v103, v103
	s_nop 0
	v_add_f32_e32 v103, 1.0, v103
	v_cmp_gt_f32_e32 vcc, s31, v103
	s_nop 1
	v_cndmask_b32_e64 v107, 0, 32, vcc
	v_ldexp_f32 v103, v103, v107
	v_log_f32_e32 v103, v103
	s_nop 0
	v_mul_f32_e32 v107, 0x3f317217, v103
	v_fma_f32 v107, v103, s1, -v107
	v_fmac_f32_e32 v107, 0x3377d1cf, v103
	v_fmac_f32_e32 v107, 0x3f317217, v103
	v_cmp_lt_f32_e64 s[42:43], |v103|, s33
	s_nop 1
	v_cndmask_b32_e64 v103, v103, v107, s[42:43]
	v_cndmask_b32_e32 v107, 0, v199, vcc
	v_sub_f32_e32 v103, v103, v107
	v_add_f32_e32 v103, v106, v103
	v_sub_f32_e32 v103, -0.5, v103
	v_mul_f32_e32 v103, 0x3fb8aa3b, v103
	v_exp_f32_e32 v103, v103
	v_add_u32_e32 v106, v101, v148
	v_mov_b32_e32 v107, v1
	v_lshl_add_u64 v[106:107], v[106:107], 2, s[48:49]
	v_mul_f32_e32 v103, 0xbfb8aa3b, v103
	v_exp_f32_e32 v103, v103
	global_store_dword v[106:107], v103, off sc1
	v_add_f32_e32 v103, v79, v102
	v_max_f32_e64 v106, -v103, 0
	v_mul_f32_e64 v103, |v103|, s0
	v_exp_f32_e32 v103, v103
	s_nop 0
	v_add_f32_e32 v103, 1.0, v103
	v_cmp_gt_f32_e32 vcc, s31, v103
	s_nop 1
	v_cndmask_b32_e64 v107, 0, 32, vcc
	v_ldexp_f32 v103, v103, v107
	v_log_f32_e32 v103, v103
	s_nop 0
	v_mul_f32_e32 v107, 0x3f317217, v103
	v_fma_f32 v107, v103, s1, -v107
	v_fmac_f32_e32 v107, 0x3377d1cf, v103
	v_fmac_f32_e32 v107, 0x3f317217, v103
	v_cmp_lt_f32_e64 s[42:43], |v103|, s33
	s_nop 1
	v_cndmask_b32_e64 v103, v103, v107, s[42:43]
	v_cndmask_b32_e32 v107, 0, v199, vcc
	v_sub_f32_e32 v103, v103, v107
	v_add_f32_e32 v103, v106, v103
	v_sub_f32_e32 v103, -0.5, v103
	v_mul_f32_e32 v103, 0x3fb8aa3b, v103
	v_exp_f32_e32 v103, v103
	v_add_u32_e32 v106, v101, v113
	v_mov_b32_e32 v107, v1
	v_lshl_add_u64 v[106:107], v[106:107], 2, s[48:49]
	v_mul_f32_e32 v103, 0xbfb8aa3b, v103
	v_exp_f32_e32 v103, v103
	global_store_dword v[106:107], v103, off sc1
	v_add_f32_e32 v103, v80, v102
	v_max_f32_e64 v106, -v103, 0
	v_mul_f32_e64 v103, |v103|, s0
	v_exp_f32_e32 v103, v103
	v_add_f32_e32 v102, v81, v102
	v_add_f32_e32 v103, 1.0, v103
	v_cmp_gt_f32_e32 vcc, s31, v103
	s_nop 1
	v_cndmask_b32_e64 v107, 0, 32, vcc
	v_ldexp_f32 v103, v103, v107
	v_log_f32_e32 v103, v103
	s_nop 0
	v_mul_f32_e32 v107, 0x3f317217, v103
	v_fma_f32 v107, v103, s1, -v107
	v_fmac_f32_e32 v107, 0x3377d1cf, v103
	v_fmac_f32_e32 v107, 0x3f317217, v103
	v_cmp_lt_f32_e64 s[42:43], |v103|, s33
	s_nop 1
	v_cndmask_b32_e64 v103, v103, v107, s[42:43]
	v_cndmask_b32_e32 v107, 0, v199, vcc
	v_sub_f32_e32 v103, v103, v107
	v_add_f32_e32 v103, v106, v103
	v_sub_f32_e32 v103, -0.5, v103
	v_mul_f32_e32 v103, 0x3fb8aa3b, v103
	v_exp_f32_e32 v103, v103
	v_add_u32_e32 v106, v101, v112
	v_mov_b32_e32 v107, v1
	v_lshl_add_u64 v[106:107], v[106:107], 2, s[48:49]
	v_mul_f32_e32 v103, 0xbfb8aa3b, v103
	v_exp_f32_e32 v103, v103
	global_store_dword v[106:107], v103, off sc1
	v_max_f32_e64 v103, -v102, 0
	v_mul_f32_e64 v102, |v102|, s0
	v_exp_f32_e32 v102, v102
	s_nop 0
	v_add_f32_e32 v102, 1.0, v102
	v_cmp_gt_f32_e32 vcc, s31, v102
	s_nop 1
	v_cndmask_b32_e64 v106, 0, 32, vcc
	v_ldexp_f32 v102, v102, v106
	v_log_f32_e32 v102, v102
	s_nop 0
	v_mul_f32_e32 v106, 0x3f317217, v102
	v_fma_f32 v106, v102, s1, -v106
	v_fmac_f32_e32 v106, 0x3377d1cf, v102
	v_fmac_f32_e32 v106, 0x3f317217, v102
	v_cmp_lt_f32_e64 s[42:43], |v102|, s33
	s_nop 1
	v_cndmask_b32_e64 v102, v102, v106, s[42:43]
	v_cndmask_b32_e32 v106, 0, v199, vcc
	v_sub_f32_e32 v102, v102, v106
	v_add_f32_e32 v102, v103, v102
	v_sub_f32_e32 v102, -0.5, v102
	v_mul_f32_e32 v102, 0x3fb8aa3b, v102
	v_exp_f32_e32 v102, v102
	v_mov_b32_e32 v103, v1
	v_mul_f32_e32 v102, 0xbfb8aa3b, v102
	v_exp_f32_e32 v106, v102
	v_add_u32_e32 v102, v101, v111
	v_lshl_add_u64 v[102:103], v[102:103], 2, s[48:49]
	global_store_dword v[102:103], v106, off sc1
	v_mov_b32_e32 v111, v236
	v_add_f32_e32 v102, v50, v111
	v_mul_f32_e64 v103, |v102|, s0
	v_exp_f32_e32 v103, v103
	v_max_f32_e64 v102, -v102, 0
	v_add_f32_e32 v106, v51, v111
	v_add_u32_e32 v157, 0x4000, v110
	v_add_f32_e32 v103, 1.0, v103
	v_cmp_gt_f32_e32 vcc, s31, v103
	v_add_u32_e32 v156, 0x4200, v110
	v_add_u32_e32 v155, 0x4400, v110
	v_cndmask_b32_e64 v107, 0, 32, vcc
	v_ldexp_f32 v103, v103, v107
	v_log_f32_e32 v103, v103
	v_cndmask_b32_e32 v112, 0, v199, vcc
	v_mul_f32_e64 v107, |v106|, s0
	v_max_f32_e64 v106, -v106, 0
	v_mul_f32_e32 v113, 0x3f317217, v103
	v_fma_f32 v113, v103, s1, -v113
	v_fmac_f32_e32 v113, 0x3377d1cf, v103
	v_fmac_f32_e32 v113, 0x3f317217, v103
	v_cmp_lt_f32_e64 vcc, |v103|, s33
	v_add_u32_e32 v153, 0x4600, v110
	s_nop 0
	v_cndmask_b32_e32 v103, v103, v113, vcc
	v_sub_f32_e32 v103, v103, v112
	v_add_f32_e32 v102, v102, v103
	v_sub_f32_e32 v102, -0.5, v102
	v_mul_f32_e32 v102, 0x3fb8aa3b, v102
	v_exp_f32_e32 v103, v107
	v_exp_f32_e32 v102, v102
	v_add_f32_e32 v103, 1.0, v103
	v_mul_f32_e32 v102, 0xbfb8aa3b, v102
	v_cmp_gt_f32_e32 vcc, s31, v103
	v_exp_f32_e32 v107, v102
	s_nop 0
	v_cndmask_b32_e64 v102, 0, 32, vcc
	v_ldexp_f32 v102, v103, v102
	v_log_f32_e32 v103, v102
	v_add_u32_e32 v102, v100, v157
	v_mul_f32_e32 v112, 0x3f317217, v103
	v_fma_f32 v112, v103, s1, -v112
	v_fmac_f32_e32 v112, 0x3377d1cf, v103
	v_fmac_f32_e32 v112, 0x3f317217, v103
	v_cmp_lt_f32_e64 s[42:43], |v103|, s33
	s_nop 1
	v_cndmask_b32_e64 v103, v103, v112, s[42:43]
	v_cndmask_b32_e32 v112, 0, v199, vcc
	v_sub_f32_e32 v103, v103, v112
	v_add_f32_e32 v103, v106, v103
	v_sub_f32_e32 v103, -0.5, v103
	v_mul_f32_e32 v103, 0x3fb8aa3b, v103
	v_exp_f32_e32 v106, v103
	v_mov_b32_e32 v103, v1
	v_lshl_add_u64 v[102:103], v[102:103], 2, s[48:49]
	global_store_dword v[102:103], v107, off sc1
	v_mul_f32_e32 v102, 0xbfb8aa3b, v106
	v_add_f32_e32 v106, v52, v111
	v_mul_f32_e64 v103, |v106|, s0
	v_exp_f32_e32 v103, v103
	v_max_f32_e64 v106, -v106, 0
	v_exp_f32_e32 v107, v102
	v_add_u32_e32 v102, v100, v156
	v_add_f32_e32 v103, 1.0, v103
	v_cmp_gt_f32_e32 vcc, s31, v103
	s_nop 1
	v_cndmask_b32_e64 v112, 0, 32, vcc
	v_ldexp_f32 v103, v103, v112
	v_log_f32_e32 v112, v103
	v_mov_b32_e32 v103, v1
	v_lshl_add_u64 v[102:103], v[102:103], 2, s[48:49]
	global_store_dword v[102:103], v107, off sc1
	v_mul_f32_e32 v113, 0x3f317217, v112
	v_fma_f32 v113, v112, s1, -v113
	v_fmac_f32_e32 v113, 0x3377d1cf, v112
	v_fmac_f32_e32 v113, 0x3f317217, v112
	v_cmp_lt_f32_e64 s[42:43], |v112|, s33
	s_nop 1
	v_cndmask_b32_e64 v112, v112, v113, s[42:43]
	v_cndmask_b32_e32 v113, 0, v199, vcc
	v_sub_f32_e32 v112, v112, v113
	v_add_f32_e32 v106, v106, v112
	v_sub_f32_e32 v106, -0.5, v106
	v_mul_f32_e32 v106, 0x3fb8aa3b, v106
	v_add_f32_e32 v112, v53, v111
	v_exp_f32_e32 v106, v106
	v_mul_f32_e64 v113, |v112|, s0
	v_exp_f32_e32 v113, v113
	v_max_f32_e64 v107, -v112, 0
	v_mul_f32_e32 v102, 0xbfb8aa3b, v106
	v_exp_f32_e32 v106, v102
	v_add_f32_e32 v102, 1.0, v113
	v_cmp_gt_f32_e32 vcc, s31, v102
	s_nop 1
	v_cndmask_b32_e64 v103, 0, 32, vcc
	v_ldexp_f32 v102, v102, v103
	v_log_f32_e32 v103, v102
	v_add_u32_e32 v102, v100, v155
	v_mul_f32_e32 v112, 0x3f317217, v103
	v_fma_f32 v112, v103, s1, -v112
	v_fmac_f32_e32 v112, 0x3377d1cf, v103
	v_fmac_f32_e32 v112, 0x3f317217, v103
	v_cmp_lt_f32_e64 s[42:43], |v103|, s33
	s_nop 1
	v_cndmask_b32_e64 v103, v103, v112, s[42:43]
	v_cndmask_b32_e32 v112, 0, v199, vcc
	v_sub_f32_e32 v103, v103, v112
	v_add_f32_e32 v103, v107, v103
	v_sub_f32_e32 v103, -0.5, v103
	v_mul_f32_e32 v103, 0x3fb8aa3b, v103
	v_exp_f32_e32 v107, v103
	v_mov_b32_e32 v103, v1
	v_lshl_add_u64 v[102:103], v[102:103], 2, s[48:49]
	global_store_dword v[102:103], v106, off sc1
	v_mul_f32_e32 v102, 0xbfb8aa3b, v107
	v_exp_f32_e32 v106, v102
	v_add_u32_e32 v102, v100, v153
	v_mov_b32_e32 v103, v1
	v_lshl_add_u64 v[102:103], v[102:103], 2, s[48:49]
	global_store_dword v[102:103], v106, off sc1
	v_add_f32_e32 v102, v54, v111
	v_mul_f32_e64 v103, |v102|, s0
	v_exp_f32_e32 v103, v103
	v_max_f32_e64 v102, -v102, 0
	v_add_f32_e32 v106, v55, v111
	v_add_u32_e32 v154, 0x5000, v110
	v_add_f32_e32 v103, 1.0, v103
	v_cmp_gt_f32_e32 vcc, s31, v103
	v_add_u32_e32 v152, 0x5200, v110
	v_add_u32_e32 v151, 0x5400, v110
	v_cndmask_b32_e64 v107, 0, 32, vcc
	v_ldexp_f32 v103, v103, v107
	v_log_f32_e32 v103, v103
	v_cndmask_b32_e32 v112, 0, v199, vcc
	v_mul_f32_e64 v107, |v106|, s0
	v_max_f32_e64 v106, -v106, 0
	v_mul_f32_e32 v113, 0x3f317217, v103
	v_fma_f32 v113, v103, s1, -v113
	v_fmac_f32_e32 v113, 0x3377d1cf, v103
	v_fmac_f32_e32 v113, 0x3f317217, v103
	v_cmp_lt_f32_e64 vcc, |v103|, s33
	v_add_u32_e32 v149, 0x5600, v110
	s_nop 0
	v_cndmask_b32_e32 v103, v103, v113, vcc
	v_sub_f32_e32 v103, v103, v112
	v_add_f32_e32 v102, v102, v103
	v_sub_f32_e32 v102, -0.5, v102
	v_mul_f32_e32 v102, 0x3fb8aa3b, v102
	v_exp_f32_e32 v103, v107
	v_exp_f32_e32 v102, v102
	v_add_f32_e32 v103, 1.0, v103
	v_mul_f32_e32 v102, 0xbfb8aa3b, v102
	v_cmp_gt_f32_e32 vcc, s31, v103
	v_exp_f32_e32 v107, v102
	s_nop 0
	v_cndmask_b32_e64 v102, 0, 32, vcc
	v_ldexp_f32 v102, v103, v102
	v_log_f32_e32 v103, v102
	v_add_u32_e32 v102, v100, v154
	v_mul_f32_e32 v112, 0x3f317217, v103
	v_fma_f32 v112, v103, s1, -v112
	v_fmac_f32_e32 v112, 0x3377d1cf, v103
	v_fmac_f32_e32 v112, 0x3f317217, v103
	v_cmp_lt_f32_e64 s[42:43], |v103|, s33
	s_nop 1
	v_cndmask_b32_e64 v103, v103, v112, s[42:43]
	v_cndmask_b32_e32 v112, 0, v199, vcc
	v_sub_f32_e32 v103, v103, v112
	v_add_f32_e32 v103, v106, v103
	v_sub_f32_e32 v103, -0.5, v103
	v_mul_f32_e32 v103, 0x3fb8aa3b, v103
	v_exp_f32_e32 v106, v103
	v_mov_b32_e32 v103, v1
	v_lshl_add_u64 v[102:103], v[102:103], 2, s[48:49]
	global_store_dword v[102:103], v107, off sc1
	v_mul_f32_e32 v102, 0xbfb8aa3b, v106
	v_add_f32_e32 v106, v56, v111
	v_mul_f32_e64 v103, |v106|, s0
	v_exp_f32_e32 v103, v103
	v_max_f32_e64 v106, -v106, 0
	v_exp_f32_e32 v107, v102
	v_add_u32_e32 v102, v100, v152
	v_add_f32_e32 v103, 1.0, v103
	v_cmp_gt_f32_e32 vcc, s31, v103
	s_nop 1
	v_cndmask_b32_e64 v112, 0, 32, vcc
	v_ldexp_f32 v103, v103, v112
	v_log_f32_e32 v112, v103
	v_mov_b32_e32 v103, v1
	v_lshl_add_u64 v[102:103], v[102:103], 2, s[48:49]
	global_store_dword v[102:103], v107, off sc1
	v_mul_f32_e32 v113, 0x3f317217, v112
	v_fma_f32 v113, v112, s1, -v113
	v_fmac_f32_e32 v113, 0x3377d1cf, v112
	v_fmac_f32_e32 v113, 0x3f317217, v112
	v_cmp_lt_f32_e64 s[42:43], |v112|, s33
	s_nop 1
	v_cndmask_b32_e64 v112, v112, v113, s[42:43]
	v_cndmask_b32_e32 v113, 0, v199, vcc
	v_sub_f32_e32 v112, v112, v113
	v_add_f32_e32 v106, v106, v112
	v_sub_f32_e32 v106, -0.5, v106
	v_mul_f32_e32 v106, 0x3fb8aa3b, v106
	v_add_f32_e32 v112, v57, v111
	v_exp_f32_e32 v106, v106
	v_mul_f32_e64 v113, |v112|, s0
	v_exp_f32_e32 v113, v113
	v_max_f32_e64 v107, -v112, 0
	v_mul_f32_e32 v102, 0xbfb8aa3b, v106
	v_exp_f32_e32 v106, v102
	v_add_f32_e32 v102, 1.0, v113
	v_cmp_gt_f32_e32 vcc, s31, v102
	s_nop 1
	v_cndmask_b32_e64 v103, 0, 32, vcc
	v_ldexp_f32 v102, v102, v103
	v_log_f32_e32 v103, v102
	v_add_u32_e32 v102, v100, v151
	v_mul_f32_e32 v112, 0x3f317217, v103
	v_fma_f32 v112, v103, s1, -v112
	v_fmac_f32_e32 v112, 0x3377d1cf, v103
	v_fmac_f32_e32 v112, 0x3f317217, v103
	v_cmp_lt_f32_e64 s[42:43], |v103|, s33
	s_nop 1
	v_cndmask_b32_e64 v103, v103, v112, s[42:43]
	v_cndmask_b32_e32 v112, 0, v199, vcc
	v_sub_f32_e32 v103, v103, v112
	v_add_f32_e32 v103, v107, v103
	v_sub_f32_e32 v103, -0.5, v103
	v_mul_f32_e32 v103, 0x3fb8aa3b, v103
	v_exp_f32_e32 v107, v103
	v_mov_b32_e32 v103, v1
	v_lshl_add_u64 v[102:103], v[102:103], 2, s[48:49]
	global_store_dword v[102:103], v106, off sc1
	v_mul_f32_e32 v102, 0xbfb8aa3b, v107
	v_exp_f32_e32 v106, v102
	v_add_u32_e32 v102, v100, v149
	v_mov_b32_e32 v103, v1
	v_lshl_add_u64 v[102:103], v[102:103], 2, s[48:49]
	global_store_dword v[102:103], v106, off sc1
	v_add_f32_e32 v102, v58, v111
	v_mul_f32_e64 v103, |v102|, s0
	v_exp_f32_e32 v103, v103
	v_max_f32_e64 v102, -v102, 0
	v_add_f32_e32 v106, v59, v111
	v_add_u32_e32 v150, 0x6000, v110
	v_add_f32_e32 v103, 1.0, v103
	v_cmp_gt_f32_e32 vcc, s31, v103
	v_add_u32_e32 v148, 0x6200, v110
	s_nop 0
	v_cndmask_b32_e64 v107, 0, 32, vcc
	v_ldexp_f32 v103, v103, v107
	v_log_f32_e32 v103, v103
	v_cndmask_b32_e32 v112, 0, v199, vcc
	v_mul_f32_e64 v107, |v106|, s0
	v_max_f32_e64 v106, -v106, 0
	v_mul_f32_e32 v113, 0x3f317217, v103
	v_fma_f32 v113, v103, s1, -v113
	v_fmac_f32_e32 v113, 0x3377d1cf, v103
	v_fmac_f32_e32 v113, 0x3f317217, v103
	v_cmp_lt_f32_e64 vcc, |v103|, s33
	s_nop 1
	v_cndmask_b32_e32 v103, v103, v113, vcc
	v_sub_f32_e32 v103, v103, v112
	v_add_f32_e32 v102, v102, v103
	v_sub_f32_e32 v102, -0.5, v102
	v_mul_f32_e32 v102, 0x3fb8aa3b, v102
	v_exp_f32_e32 v103, v107
	v_exp_f32_e32 v102, v102
	v_add_f32_e32 v103, 1.0, v103
	v_mul_f32_e32 v102, 0xbfb8aa3b, v102
	v_cmp_gt_f32_e32 vcc, s31, v103
	v_exp_f32_e32 v107, v102
	s_nop 0
	v_cndmask_b32_e64 v102, 0, 32, vcc
	v_ldexp_f32 v102, v103, v102
	v_log_f32_e32 v103, v102
	v_add_u32_e32 v102, v100, v150
	v_mul_f32_e32 v112, 0x3f317217, v103
	v_fma_f32 v112, v103, s1, -v112
	v_fmac_f32_e32 v112, 0x3377d1cf, v103
	v_fmac_f32_e32 v112, 0x3f317217, v103
	v_cmp_lt_f32_e64 s[42:43], |v103|, s33
	s_nop 1
	v_cndmask_b32_e64 v103, v103, v112, s[42:43]
	v_cndmask_b32_e32 v112, 0, v199, vcc
	v_sub_f32_e32 v103, v103, v112
	v_add_f32_e32 v103, v106, v103
	v_sub_f32_e32 v103, -0.5, v103
	v_mul_f32_e32 v103, 0x3fb8aa3b, v103
	v_exp_f32_e32 v106, v103
	v_mov_b32_e32 v103, v1
	v_lshl_add_u64 v[102:103], v[102:103], 2, s[48:49]
	global_store_dword v[102:103], v107, off sc1
	v_mul_f32_e32 v102, 0xbfb8aa3b, v106
	v_add_f32_e32 v106, v60, v111
	v_mul_f32_e64 v103, |v106|, s0
	v_exp_f32_e32 v103, v103
	v_max_f32_e64 v106, -v106, 0
	v_exp_f32_e32 v107, v102
	v_add_u32_e32 v102, v100, v148
	v_add_f32_e32 v103, 1.0, v103
	v_cmp_gt_f32_e32 vcc, s31, v103
	s_nop 1
	v_cndmask_b32_e64 v112, 0, 32, vcc
	v_ldexp_f32 v103, v103, v112
	v_log_f32_e32 v112, v103
	v_mov_b32_e32 v103, v1
	v_lshl_add_u64 v[102:103], v[102:103], 2, s[48:49]
	global_store_dword v[102:103], v107, off sc1
	v_mul_f32_e32 v113, 0x3f317217, v112
	v_fma_f32 v113, v112, s1, -v113
	v_fmac_f32_e32 v113, 0x3377d1cf, v112
	v_fmac_f32_e32 v113, 0x3f317217, v112
	v_cmp_lt_f32_e64 s[42:43], |v112|, s33
	s_nop 1
	v_cndmask_b32_e64 v112, v112, v113, s[42:43]
	v_cndmask_b32_e32 v113, 0, v199, vcc
	v_sub_f32_e32 v112, v112, v113
	v_add_f32_e32 v106, v106, v112
	v_sub_f32_e32 v106, -0.5, v106
	v_mul_f32_e32 v106, 0x3fb8aa3b, v106
	v_add_f32_e32 v113, v61, v111
	v_exp_f32_e32 v106, v106
	v_mul_f32_e64 v112, |v113|, s0
	v_exp_f32_e32 v112, v112
	v_max_f32_e64 v107, -v113, 0
	v_mul_f32_e32 v102, 0xbfb8aa3b, v106
	v_exp_f32_e32 v106, v102
	v_add_f32_e32 v102, 1.0, v112
	v_cmp_gt_f32_e32 vcc, s31, v102
	v_add_u32_e32 v112, 0x6400, v110
	s_nop 0
	v_cndmask_b32_e64 v103, 0, 32, vcc
	v_ldexp_f32 v102, v102, v103
	v_log_f32_e32 v103, v102
	v_add_u32_e32 v102, v100, v112
	v_mul_f32_e32 v113, 0x3f317217, v103
	v_fma_f32 v113, v103, s1, -v113
	v_fmac_f32_e32 v113, 0x3377d1cf, v103
	v_fmac_f32_e32 v113, 0x3f317217, v103
	v_cmp_lt_f32_e64 s[42:43], |v103|, s33
	s_nop 1
	v_cndmask_b32_e64 v103, v103, v113, s[42:43]
	v_cndmask_b32_e32 v113, 0, v199, vcc
	v_sub_f32_e32 v103, v103, v113
	v_add_f32_e32 v103, v107, v103
	v_sub_f32_e32 v103, -0.5, v103
	v_mul_f32_e32 v103, 0x3fb8aa3b, v103
	v_exp_f32_e32 v107, v103
	v_mov_b32_e32 v103, v1
	v_lshl_add_u64 v[102:103], v[102:103], 2, s[48:49]
	global_store_dword v[102:103], v106, off sc1
	v_mul_f32_e32 v102, 0xbfb8aa3b, v107
	v_exp_f32_e32 v103, v102
	v_add_u32_e32 v102, 0x6600, v110
	v_add_u32_e32 v106, v100, v102
	v_mov_b32_e32 v107, v1
	v_lshl_add_u64 v[106:107], v[106:107], 2, s[48:49]
	global_store_dword v[106:107], v103, off sc1
	v_add_f32_e32 v103, v62, v111
	v_max_f32_e64 v106, -v103, 0
	v_mul_f32_e64 v103, |v103|, s0
	v_exp_f32_e32 v103, v103
	v_mov_b32_e32 v159, v1
	v_add_f32_e32 v103, 1.0, v103
	v_cmp_gt_f32_e32 vcc, s31, v103
	s_nop 1
	v_cndmask_b32_e64 v107, 0, 32, vcc
	v_ldexp_f32 v103, v103, v107
	v_log_f32_e32 v103, v103
	s_nop 0
	v_mul_f32_e32 v107, 0x3f317217, v103
	v_fma_f32 v107, v103, s1, -v107
	v_fmac_f32_e32 v107, 0x3377d1cf, v103
	v_fmac_f32_e32 v107, 0x3f317217, v103
	v_cmp_lt_f32_e64 s[42:43], |v103|, s33
	s_nop 1
	v_cndmask_b32_e64 v103, v103, v107, s[42:43]
	v_cndmask_b32_e32 v107, 0, v199, vcc
	v_sub_f32_e32 v103, v103, v107
	v_add_f32_e32 v103, v106, v103
	v_sub_f32_e32 v103, -0.5, v103
	v_mul_f32_e32 v103, 0x3fb8aa3b, v103
	v_exp_f32_e32 v103, v103
	v_mov_b32_e32 v107, v1
	v_mul_f32_e32 v103, 0xbfb8aa3b, v103
	v_exp_f32_e32 v113, v103
	v_add_u32_e32 v103, 0x7000, v110
	v_add_u32_e32 v106, v100, v103
	v_lshl_add_u64 v[106:107], v[106:107], 2, s[48:49]
	global_store_dword v[106:107], v113, off sc1
	v_add_f32_e32 v106, v63, v111
	v_max_f32_e64 v107, -v106, 0
	v_mul_f32_e64 v106, |v106|, s0
	v_exp_f32_e32 v106, v106
	s_nop 0
	v_add_f32_e32 v106, 1.0, v106
	v_cmp_gt_f32_e32 vcc, s31, v106
	s_nop 1
	v_cndmask_b32_e64 v113, 0, 32, vcc
	v_ldexp_f32 v106, v106, v113
	v_log_f32_e32 v106, v106
	s_nop 0
	v_mul_f32_e32 v113, 0x3f317217, v106
	v_fma_f32 v113, v106, s1, -v113
	v_fmac_f32_e32 v113, 0x3377d1cf, v106
	v_fmac_f32_e32 v113, 0x3f317217, v106
	v_cmp_lt_f32_e64 s[42:43], |v106|, s33
	s_nop 1
	v_cndmask_b32_e64 v106, v106, v113, s[42:43]
	v_cndmask_b32_e32 v113, 0, v199, vcc
	v_sub_f32_e32 v106, v106, v113
	v_add_f32_e32 v106, v107, v106
	v_sub_f32_e32 v106, -0.5, v106
	v_mul_f32_e32 v106, 0x3fb8aa3b, v106
	v_exp_f32_e32 v106, v106
	s_nop 0
	v_mul_f32_e32 v106, 0xbfb8aa3b, v106
	v_exp_f32_e32 v107, v106
	v_add_u32_e32 v106, 0x7200, v110
	v_add_u32_e32 v158, v100, v106
	v_lshl_add_u64 v[158:159], v[158:159], 2, s[48:49]
	global_store_dword v[158:159], v107, off sc1
	v_add_f32_e32 v107, v64, v111
	v_max_f32_e64 v113, -v107, 0
	v_mul_f32_e64 v107, |v107|, s0
	v_exp_f32_e32 v107, v107
	v_mov_b32_e32 v159, v1
	v_add_f32_e32 v111, v65, v111
	v_add_f32_e32 v107, 1.0, v107
	v_cmp_gt_f32_e32 vcc, s31, v107
	s_nop 1
	v_cndmask_b32_e64 v158, 0, 32, vcc
	v_ldexp_f32 v107, v107, v158
	v_log_f32_e32 v107, v107
	s_nop 0
	v_mul_f32_e32 v158, 0x3f317217, v107
	v_fma_f32 v158, v107, s1, -v158
	v_fmac_f32_e32 v158, 0x3377d1cf, v107
	v_fmac_f32_e32 v158, 0x3f317217, v107
	v_cmp_lt_f32_e64 s[42:43], |v107|, s33
	s_nop 1
	v_cndmask_b32_e64 v107, v107, v158, s[42:43]
	v_cndmask_b32_e32 v158, 0, v199, vcc
	v_sub_f32_e32 v107, v107, v158
	v_add_f32_e32 v107, v113, v107
	v_sub_f32_e32 v107, -0.5, v107
	v_mul_f32_e32 v107, 0x3fb8aa3b, v107
	v_exp_f32_e32 v107, v107
	s_nop 0
	v_mul_f32_e32 v107, 0xbfb8aa3b, v107
	v_exp_f32_e32 v113, v107
	v_add_u32_e32 v107, 0x7400, v110
	v_add_u32_e32 v158, v100, v107
	v_lshl_add_u64 v[158:159], v[158:159], 2, s[48:49]
	global_store_dword v[158:159], v113, off sc1
	v_max_f32_e64 v113, -v111, 0
	v_mul_f32_e64 v111, |v111|, s0
	v_exp_f32_e32 v111, v111
	v_mov_b32_e32 v159, v1
	v_add_f32_e32 v111, 1.0, v111
	v_cmp_gt_f32_e32 vcc, s31, v111
	s_nop 1
	v_cndmask_b32_e64 v158, 0, 32, vcc
	v_ldexp_f32 v111, v111, v158
	v_log_f32_e32 v111, v111
	s_nop 0
	v_mul_f32_e32 v158, 0x3f317217, v111
	v_fma_f32 v158, v111, s1, -v158
	v_fmac_f32_e32 v158, 0x3377d1cf, v111
	v_fmac_f32_e32 v158, 0x3f317217, v111
	v_cmp_lt_f32_e64 s[42:43], |v111|, s33
	s_nop 1
	v_cndmask_b32_e64 v111, v111, v158, s[42:43]
	v_cndmask_b32_e32 v158, 0, v199, vcc
	v_sub_f32_e32 v111, v111, v158
	v_add_f32_e32 v111, v113, v111
	v_sub_f32_e32 v111, -0.5, v111
	v_mul_f32_e32 v111, 0x3fb8aa3b, v111
	v_exp_f32_e32 v111, v111
	s_nop 0
	v_mul_f32_e32 v111, 0xbfb8aa3b, v111
	v_exp_f32_e32 v113, v111
	v_add_u32_e32 v111, 0x7600, v110
	v_add_u32_e32 v158, v100, v111
	v_lshl_add_u64 v[158:159], v[158:159], 2, s[48:49]
	global_store_dword v[158:159], v113, off sc1
	v_mov_b32_e32 v113, v237
	v_add_f32_e32 v158, v34, v113
	v_max_f32_e64 v159, -v158, 0
	v_mul_f32_e64 v158, |v158|, s0
	v_exp_f32_e32 v158, v158
	v_add_u32_e32 v156, v101, v156
	v_add_f32_e32 v158, 1.0, v158
	v_cmp_gt_f32_e32 vcc, s31, v158
	s_nop 1
	v_cndmask_b32_e64 v160, 0, 32, vcc
	v_ldexp_f32 v158, v158, v160
	v_log_f32_e32 v158, v158
	s_nop 0
	v_mul_f32_e32 v160, 0x3f317217, v158
	v_fma_f32 v160, v158, s1, -v160
	v_fmac_f32_e32 v160, 0x3377d1cf, v158
	v_fmac_f32_e32 v160, 0x3f317217, v158
	v_cmp_lt_f32_e64 s[42:43], |v158|, s33
	s_nop 1
	v_cndmask_b32_e64 v158, v158, v160, s[42:43]
	v_cndmask_b32_e32 v160, 0, v199, vcc
	v_sub_f32_e32 v158, v158, v160
	v_add_f32_e32 v158, v159, v158
	v_sub_f32_e32 v158, -0.5, v158
	v_mul_f32_e32 v158, 0x3fb8aa3b, v158
	v_exp_f32_e32 v158, v158
	v_mov_b32_e32 v159, v1
	v_mul_f32_e32 v158, 0xbfb8aa3b, v158
	v_exp_f32_e32 v160, v158
	v_add_u32_e32 v158, v101, v157
	v_lshl_add_u64 v[158:159], v[158:159], 2, s[48:49]
	v_add_f32_e32 v157, v35, v113
	global_store_dword v[158:159], v160, off sc1
	v_max_f32_e64 v158, -v157, 0
	v_mul_f32_e64 v157, |v157|, s0
	v_exp_f32_e32 v157, v157
	s_nop 0
	v_add_f32_e32 v157, 1.0, v157
	v_cmp_gt_f32_e32 vcc, s31, v157
	s_nop 1
	v_cndmask_b32_e64 v159, 0, 32, vcc
	v_ldexp_f32 v157, v157, v159
	v_log_f32_e32 v157, v157
	s_nop 0
	v_mul_f32_e32 v159, 0x3f317217, v157
	v_fma_f32 v159, v157, s1, -v159
	v_fmac_f32_e32 v159, 0x3377d1cf, v157
	v_fmac_f32_e32 v159, 0x3f317217, v157
	v_cmp_lt_f32_e64 s[42:43], |v157|, s33
	s_nop 1
	v_cndmask_b32_e64 v157, v157, v159, s[42:43]
	v_cndmask_b32_e32 v159, 0, v199, vcc
	v_sub_f32_e32 v157, v157, v159
	v_add_f32_e32 v157, v158, v157
	v_sub_f32_e32 v157, -0.5, v157
	v_mul_f32_e32 v157, 0x3fb8aa3b, v157
	v_exp_f32_e32 v157, v157
	s_nop 0
	v_mul_f32_e32 v157, 0xbfb8aa3b, v157
	v_exp_f32_e32 v158, v157
	v_mov_b32_e32 v157, v1
	v_lshl_add_u64 v[156:157], v[156:157], 2, s[48:49]
	global_store_dword v[156:157], v158, off sc1
	v_add_f32_e32 v156, v36, v113
	v_max_f32_e64 v157, -v156, 0
	v_mul_f32_e64 v156, |v156|, s0
	v_exp_f32_e32 v156, v156
	s_nop 0
	v_add_f32_e32 v156, 1.0, v156
	v_cmp_gt_f32_e32 vcc, s31, v156
	s_nop 1
	v_cndmask_b32_e64 v158, 0, 32, vcc
	v_ldexp_f32 v156, v156, v158
	v_log_f32_e32 v156, v156
	s_nop 0
	v_mul_f32_e32 v158, 0x3f317217, v156
	v_fma_f32 v158, v156, s1, -v158
	v_fmac_f32_e32 v158, 0x3377d1cf, v156
	v_fmac_f32_e32 v158, 0x3f317217, v156
	v_cmp_lt_f32_e64 s[42:43], |v156|, s33
	s_nop 1
	v_cndmask_b32_e64 v156, v156, v158, s[42:43]
	v_cndmask_b32_e32 v158, 0, v199, vcc
	v_sub_f32_e32 v156, v156, v158
	v_add_f32_e32 v156, v157, v156
	v_sub_f32_e32 v156, -0.5, v156
	v_mul_f32_e32 v156, 0x3fb8aa3b, v156
	v_exp_f32_e32 v156, v156
	v_mov_b32_e32 v157, v1
	v_mul_f32_e32 v156, 0xbfb8aa3b, v156
	v_exp_f32_e32 v158, v156
	v_add_u32_e32 v156, v101, v155
	v_lshl_add_u64 v[156:157], v[156:157], 2, s[48:49]
	v_add_f32_e32 v155, v37, v113
	global_store_dword v[156:157], v158, off sc1
	v_max_f32_e64 v156, -v155, 0
	v_mul_f32_e64 v155, |v155|, s0
	v_exp_f32_e32 v155, v155
	s_nop 0
	v_add_f32_e32 v155, 1.0, v155
	v_cmp_gt_f32_e32 vcc, s31, v155
	s_nop 1
	v_cndmask_b32_e64 v157, 0, 32, vcc
	v_ldexp_f32 v155, v155, v157
	v_log_f32_e32 v155, v155
	s_nop 0
	v_mul_f32_e32 v157, 0x3f317217, v155
	v_fma_f32 v157, v155, s1, -v157
	v_fmac_f32_e32 v157, 0x3377d1cf, v155
	v_fmac_f32_e32 v157, 0x3f317217, v155
	v_cmp_lt_f32_e64 s[42:43], |v155|, s33
	s_nop 1
	v_cndmask_b32_e64 v155, v155, v157, s[42:43]
	v_cndmask_b32_e32 v157, 0, v199, vcc
	v_sub_f32_e32 v155, v155, v157
	v_add_f32_e32 v155, v156, v155
	v_sub_f32_e32 v155, -0.5, v155
	v_mul_f32_e32 v155, 0x3fb8aa3b, v155
	v_exp_f32_e32 v155, v155
	v_add_u32_e32 v156, v101, v153
	v_mov_b32_e32 v157, v1
	v_lshl_add_u64 v[156:157], v[156:157], 2, s[48:49]
	v_mul_f32_e32 v155, 0xbfb8aa3b, v155
	v_exp_f32_e32 v155, v155
	global_store_dword v[156:157], v155, off sc1
	v_add_f32_e32 v153, v38, v113
	v_max_f32_e64 v155, -v153, 0
	v_mul_f32_e64 v153, |v153|, s0
	v_exp_f32_e32 v153, v153
	v_add_u32_e32 v154, v101, v154
	v_add_u32_e32 v152, v101, v152
	v_add_f32_e32 v153, 1.0, v153
	v_cmp_gt_f32_e32 vcc, s31, v153
	s_nop 1
	v_cndmask_b32_e64 v156, 0, 32, vcc
	v_ldexp_f32 v153, v153, v156
	v_log_f32_e32 v153, v153
	s_nop 0
	v_mul_f32_e32 v156, 0x3f317217, v153
	v_fma_f32 v156, v153, s1, -v156
	v_fmac_f32_e32 v156, 0x3377d1cf, v153
	v_fmac_f32_e32 v156, 0x3f317217, v153
	v_cmp_lt_f32_e64 s[42:43], |v153|, s33
	s_nop 1
	v_cndmask_b32_e64 v153, v153, v156, s[42:43]
	v_cndmask_b32_e32 v156, 0, v199, vcc
	v_sub_f32_e32 v153, v153, v156
	v_add_f32_e32 v153, v155, v153
	v_sub_f32_e32 v153, -0.5, v153
	v_mul_f32_e32 v153, 0x3fb8aa3b, v153
	v_exp_f32_e32 v153, v153
	v_mov_b32_e32 v155, v1
	v_lshl_add_u64 v[154:155], v[154:155], 2, s[48:49]
	v_mul_f32_e32 v153, 0xbfb8aa3b, v153
	v_exp_f32_e32 v153, v153
	global_store_dword v[154:155], v153, off sc1
	v_add_f32_e32 v153, v39, v113
	v_max_f32_e64 v154, -v153, 0
	v_mul_f32_e64 v153, |v153|, s0
	v_exp_f32_e32 v153, v153
	s_nop 0
	v_add_f32_e32 v153, 1.0, v153
	v_cmp_gt_f32_e32 vcc, s31, v153
	s_nop 1
	v_cndmask_b32_e64 v155, 0, 32, vcc
	v_ldexp_f32 v153, v153, v155
	v_log_f32_e32 v153, v153
	s_nop 0
	v_mul_f32_e32 v155, 0x3f317217, v153
	v_fma_f32 v155, v153, s1, -v155
	v_fmac_f32_e32 v155, 0x3377d1cf, v153
	v_fmac_f32_e32 v155, 0x3f317217, v153
	v_cmp_lt_f32_e64 s[42:43], |v153|, s33
	s_nop 1
	v_cndmask_b32_e64 v153, v153, v155, s[42:43]
	v_cndmask_b32_e32 v155, 0, v199, vcc
	v_sub_f32_e32 v153, v153, v155
	v_add_f32_e32 v153, v154, v153
	v_sub_f32_e32 v153, -0.5, v153
	v_mul_f32_e32 v153, 0x3fb8aa3b, v153
	v_exp_f32_e32 v153, v153
	s_nop 0
	v_mul_f32_e32 v153, 0xbfb8aa3b, v153
	v_exp_f32_e32 v154, v153
	v_mov_b32_e32 v153, v1
	v_lshl_add_u64 v[152:153], v[152:153], 2, s[48:49]
	global_store_dword v[152:153], v154, off sc1
	v_add_f32_e32 v152, v40, v113
	v_max_f32_e64 v153, -v152, 0
	v_mul_f32_e64 v152, |v152|, s0
	v_exp_f32_e32 v152, v152
	s_nop 0
	v_add_f32_e32 v152, 1.0, v152
	v_cmp_gt_f32_e32 vcc, s31, v152
	s_nop 1
	v_cndmask_b32_e64 v154, 0, 32, vcc
	v_ldexp_f32 v152, v152, v154
	v_log_f32_e32 v152, v152
	s_nop 0
	v_mul_f32_e32 v154, 0x3f317217, v152
	v_fma_f32 v154, v152, s1, -v154
	v_fmac_f32_e32 v154, 0x3377d1cf, v152
	v_fmac_f32_e32 v154, 0x3f317217, v152
	v_cmp_lt_f32_e64 s[42:43], |v152|, s33
	s_nop 1
	v_cndmask_b32_e64 v152, v152, v154, s[42:43]
	v_cndmask_b32_e32 v154, 0, v199, vcc
	v_sub_f32_e32 v152, v152, v154
	v_add_f32_e32 v152, v153, v152
	v_sub_f32_e32 v152, -0.5, v152
	v_mul_f32_e32 v152, 0x3fb8aa3b, v152
	v_exp_f32_e32 v152, v152
	v_mov_b32_e32 v153, v1
	v_mul_f32_e32 v152, 0xbfb8aa3b, v152
	v_exp_f32_e32 v154, v152
	v_add_u32_e32 v152, v101, v151
	v_lshl_add_u64 v[152:153], v[152:153], 2, s[48:49]
	v_add_f32_e32 v151, v41, v113
	global_store_dword v[152:153], v154, off sc1
	v_max_f32_e64 v152, -v151, 0
	v_mul_f32_e64 v151, |v151|, s0
	v_exp_f32_e32 v151, v151
	s_nop 0
	v_add_f32_e32 v151, 1.0, v151
	v_cmp_gt_f32_e32 vcc, s31, v151
	s_nop 1
	v_cndmask_b32_e64 v153, 0, 32, vcc
	v_ldexp_f32 v151, v151, v153
	v_log_f32_e32 v151, v151
	s_nop 0
	v_mul_f32_e32 v153, 0x3f317217, v151
	v_fma_f32 v153, v151, s1, -v153
	v_fmac_f32_e32 v153, 0x3377d1cf, v151
	v_fmac_f32_e32 v153, 0x3f317217, v151
	v_cmp_lt_f32_e64 s[42:43], |v151|, s33
	s_nop 1
	v_cndmask_b32_e64 v151, v151, v153, s[42:43]
	v_cndmask_b32_e32 v153, 0, v199, vcc
	v_sub_f32_e32 v151, v151, v153
	v_add_f32_e32 v151, v152, v151
	v_sub_f32_e32 v151, -0.5, v151
	v_mul_f32_e32 v151, 0x3fb8aa3b, v151
	v_exp_f32_e32 v151, v151
	v_add_u32_e32 v152, v101, v149
	v_mov_b32_e32 v153, v1
	v_lshl_add_u64 v[152:153], v[152:153], 2, s[48:49]
	v_mul_f32_e32 v151, 0xbfb8aa3b, v151
	v_exp_f32_e32 v151, v151
	global_store_dword v[152:153], v151, off sc1
	v_add_f32_e32 v149, v42, v113
	v_max_f32_e64 v151, -v149, 0
	v_mul_f32_e64 v149, |v149|, s0
	v_exp_f32_e32 v149, v149
	v_add_u32_e32 v150, v101, v150
	v_add_u32_e32 v148, v101, v148
	v_add_f32_e32 v149, 1.0, v149
	v_cmp_gt_f32_e32 vcc, s31, v149
	s_nop 1
	v_cndmask_b32_e64 v152, 0, 32, vcc
	v_ldexp_f32 v149, v149, v152
	v_log_f32_e32 v149, v149
	s_nop 0
	v_mul_f32_e32 v152, 0x3f317217, v149
	v_fma_f32 v152, v149, s1, -v152
	v_fmac_f32_e32 v152, 0x3377d1cf, v149
	v_fmac_f32_e32 v152, 0x3f317217, v149
	v_cmp_lt_f32_e64 s[42:43], |v149|, s33
	s_nop 1
	v_cndmask_b32_e64 v149, v149, v152, s[42:43]
	v_cndmask_b32_e32 v152, 0, v199, vcc
	v_sub_f32_e32 v149, v149, v152
	v_add_f32_e32 v149, v151, v149
	v_sub_f32_e32 v149, -0.5, v149
	v_mul_f32_e32 v149, 0x3fb8aa3b, v149
	v_exp_f32_e32 v149, v149
	v_mov_b32_e32 v151, v1
	v_lshl_add_u64 v[150:151], v[150:151], 2, s[48:49]
	v_mul_f32_e32 v149, 0xbfb8aa3b, v149
	v_exp_f32_e32 v149, v149
	global_store_dword v[150:151], v149, off sc1
	v_add_f32_e32 v149, v43, v113
	v_max_f32_e64 v150, -v149, 0
	v_mul_f32_e64 v149, |v149|, s0
	v_exp_f32_e32 v149, v149
	s_nop 0
	v_add_f32_e32 v149, 1.0, v149
	v_cmp_gt_f32_e32 vcc, s31, v149
	s_nop 1
	v_cndmask_b32_e64 v151, 0, 32, vcc
	v_ldexp_f32 v149, v149, v151
	v_log_f32_e32 v149, v149
	s_nop 0
	v_mul_f32_e32 v151, 0x3f317217, v149
	v_fma_f32 v151, v149, s1, -v151
	v_fmac_f32_e32 v151, 0x3377d1cf, v149
	v_fmac_f32_e32 v151, 0x3f317217, v149
	v_cmp_lt_f32_e64 s[42:43], |v149|, s33
	s_nop 1
	v_cndmask_b32_e64 v149, v149, v151, s[42:43]
	v_cndmask_b32_e32 v151, 0, v199, vcc
	v_sub_f32_e32 v149, v149, v151
	v_add_f32_e32 v149, v150, v149
	v_sub_f32_e32 v149, -0.5, v149
	v_mul_f32_e32 v149, 0x3fb8aa3b, v149
	v_exp_f32_e32 v149, v149
	s_nop 0
	v_mul_f32_e32 v149, 0xbfb8aa3b, v149
	v_exp_f32_e32 v150, v149
	v_mov_b32_e32 v149, v1
	v_lshl_add_u64 v[148:149], v[148:149], 2, s[48:49]
	global_store_dword v[148:149], v150, off sc1
	v_add_f32_e32 v148, v44, v113
	v_max_f32_e64 v149, -v148, 0
	v_mul_f32_e64 v148, |v148|, s0
	v_exp_f32_e32 v148, v148
	s_nop 0
	v_add_f32_e32 v148, 1.0, v148
	v_cmp_gt_f32_e32 vcc, s31, v148
	s_nop 1
	v_cndmask_b32_e64 v150, 0, 32, vcc
	v_ldexp_f32 v148, v148, v150
	v_log_f32_e32 v148, v148
	s_nop 0
	v_mul_f32_e32 v150, 0x3f317217, v148
	v_fma_f32 v150, v148, s1, -v150
	v_fmac_f32_e32 v150, 0x3377d1cf, v148
	v_fmac_f32_e32 v150, 0x3f317217, v148
	v_cmp_lt_f32_e64 s[42:43], |v148|, s33
	s_nop 1
	v_cndmask_b32_e64 v148, v148, v150, s[42:43]
	v_cndmask_b32_e32 v150, 0, v199, vcc
	v_sub_f32_e32 v148, v148, v150
	v_add_f32_e32 v148, v149, v148
	v_sub_f32_e32 v148, -0.5, v148
	v_mul_f32_e32 v148, 0x3fb8aa3b, v148
	v_exp_f32_e32 v148, v148
	v_mov_b32_e32 v149, v1
	v_mul_f32_e32 v148, 0xbfb8aa3b, v148
	v_exp_f32_e32 v150, v148
	v_add_u32_e32 v148, v101, v112
	v_lshl_add_u64 v[148:149], v[148:149], 2, s[48:49]
	v_add_f32_e32 v112, v45, v113
	global_store_dword v[148:149], v150, off sc1
	v_max_f32_e64 v148, -v112, 0
	v_mul_f32_e64 v112, |v112|, s0
	v_exp_f32_e32 v112, v112
	s_nop 0
	v_add_f32_e32 v112, 1.0, v112
	v_cmp_gt_f32_e32 vcc, s31, v112
	s_nop 1
	v_cndmask_b32_e64 v149, 0, 32, vcc
	v_ldexp_f32 v112, v112, v149
	v_log_f32_e32 v112, v112
	s_nop 0
	v_mul_f32_e32 v149, 0x3f317217, v112
	v_fma_f32 v149, v112, s1, -v149
	v_fmac_f32_e32 v149, 0x3377d1cf, v112
	v_fmac_f32_e32 v149, 0x3f317217, v112
	v_cmp_lt_f32_e64 s[42:43], |v112|, s33
	s_nop 1
	v_cndmask_b32_e64 v112, v112, v149, s[42:43]
	v_cndmask_b32_e32 v149, 0, v199, vcc
	v_sub_f32_e32 v112, v112, v149
	v_add_f32_e32 v112, v148, v112
	v_sub_f32_e32 v112, -0.5, v112
	v_mul_f32_e32 v112, 0x3fb8aa3b, v112
	v_exp_f32_e32 v112, v112
	v_add_u32_e32 v148, v101, v102
	v_mov_b32_e32 v149, v1
	v_lshl_add_u64 v[148:149], v[148:149], 2, s[48:49]
	v_mul_f32_e32 v112, 0xbfb8aa3b, v112
	v_exp_f32_e32 v112, v112
	global_store_dword v[148:149], v112, off sc1
	v_add_f32_e32 v102, v46, v113
	v_max_f32_e64 v112, -v102, 0
	v_mul_f32_e64 v102, |v102|, s0
	v_exp_f32_e32 v102, v102
	s_nop 0
	v_add_f32_e32 v102, 1.0, v102
	v_cmp_gt_f32_e32 vcc, s31, v102
	s_nop 1
	v_cndmask_b32_e64 v148, 0, 32, vcc
	v_ldexp_f32 v102, v102, v148
	v_log_f32_e32 v102, v102
	s_nop 0
	v_mul_f32_e32 v148, 0x3f317217, v102
	v_fma_f32 v148, v102, s1, -v148
	v_fmac_f32_e32 v148, 0x3377d1cf, v102
	v_fmac_f32_e32 v148, 0x3f317217, v102
	v_cmp_lt_f32_e64 s[42:43], |v102|, s33
	s_nop 1
	v_cndmask_b32_e64 v102, v102, v148, s[42:43]
	v_cndmask_b32_e32 v148, 0, v199, vcc
	v_sub_f32_e32 v102, v102, v148
	v_add_f32_e32 v102, v112, v102
	v_sub_f32_e32 v102, -0.5, v102
	v_mul_f32_e32 v102, 0x3fb8aa3b, v102
	v_exp_f32_e32 v102, v102
	s_nop 0
	v_mul_f32_e32 v102, 0xbfb8aa3b, v102
	v_exp_f32_e32 v112, v102
	v_add_u32_e32 v102, v101, v103
	v_mov_b32_e32 v103, v1
	v_lshl_add_u64 v[102:103], v[102:103], 2, s[48:49]
	global_store_dword v[102:103], v112, off sc1
	v_add_f32_e32 v102, v47, v113
	v_max_f32_e64 v103, -v102, 0
	v_mul_f32_e64 v102, |v102|, s0
	v_exp_f32_e32 v102, v102
	s_nop 0
	v_add_f32_e32 v102, 1.0, v102
	v_cmp_gt_f32_e32 vcc, s31, v102
	s_nop 1
	v_cndmask_b32_e64 v112, 0, 32, vcc
	v_ldexp_f32 v102, v102, v112
	v_log_f32_e32 v102, v102
	s_nop 0
	v_mul_f32_e32 v112, 0x3f317217, v102
	v_fma_f32 v112, v102, s1, -v112
	v_fmac_f32_e32 v112, 0x3377d1cf, v102
	v_fmac_f32_e32 v112, 0x3f317217, v102
	v_cmp_lt_f32_e64 s[42:43], |v102|, s33
	s_nop 1
	v_cndmask_b32_e64 v102, v102, v112, s[42:43]
	v_cndmask_b32_e32 v112, 0, v199, vcc
	v_sub_f32_e32 v102, v102, v112
	v_add_f32_e32 v102, v103, v102
	v_sub_f32_e32 v102, -0.5, v102
	v_mul_f32_e32 v102, 0x3fb8aa3b, v102
	v_exp_f32_e32 v102, v102
	v_mov_b32_e32 v103, v1
	v_mul_f32_e32 v102, 0xbfb8aa3b, v102
	v_exp_f32_e32 v112, v102
	v_add_u32_e32 v102, v101, v106
	v_lshl_add_u64 v[102:103], v[102:103], 2, s[48:49]
	global_store_dword v[102:103], v112, off sc1
	v_add_f32_e32 v102, v48, v113
	v_max_f32_e64 v103, -v102, 0
	v_mul_f32_e64 v102, |v102|, s0
	v_exp_f32_e32 v102, v102
	s_nop 0
	v_add_f32_e32 v102, 1.0, v102
	v_cmp_gt_f32_e32 vcc, s31, v102
	s_nop 1
	v_cndmask_b32_e64 v106, 0, 32, vcc
	v_ldexp_f32 v102, v102, v106
	v_log_f32_e32 v102, v102
	s_nop 0
	v_mul_f32_e32 v106, 0x3f317217, v102
	v_fma_f32 v106, v102, s1, -v106
	v_fmac_f32_e32 v106, 0x3377d1cf, v102
	v_fmac_f32_e32 v106, 0x3f317217, v102
	v_cmp_lt_f32_e64 s[42:43], |v102|, s33
	s_nop 1
	v_cndmask_b32_e64 v102, v102, v106, s[42:43]
	v_cndmask_b32_e32 v106, 0, v199, vcc
	v_sub_f32_e32 v102, v102, v106
	v_add_f32_e32 v102, v103, v102
	v_sub_f32_e32 v102, -0.5, v102
	v_mul_f32_e32 v102, 0x3fb8aa3b, v102
	v_exp_f32_e32 v102, v102
	v_mov_b32_e32 v103, v1
	v_mul_f32_e32 v102, 0xbfb8aa3b, v102
	v_exp_f32_e32 v106, v102
	v_add_u32_e32 v102, v101, v107
	v_lshl_add_u64 v[102:103], v[102:103], 2, s[48:49]
	global_store_dword v[102:103], v106, off sc1
	v_add_f32_e32 v102, v49, v113
	v_max_f32_e64 v103, -v102, 0
	v_mul_f32_e64 v102, |v102|, s0
	v_exp_f32_e32 v102, v102
	s_nop 0
	v_add_f32_e32 v102, 1.0, v102
	v_cmp_gt_f32_e32 vcc, s31, v102
	s_nop 1
	v_cndmask_b32_e64 v106, 0, 32, vcc
	v_ldexp_f32 v102, v102, v106
	v_log_f32_e32 v102, v102
	s_nop 0
	v_mul_f32_e32 v106, 0x3f317217, v102
	v_fma_f32 v106, v102, s1, -v106
	v_fmac_f32_e32 v106, 0x3377d1cf, v102
	v_fmac_f32_e32 v106, 0x3f317217, v102
	v_cmp_lt_f32_e64 s[42:43], |v102|, s33
	s_nop 1
	v_cndmask_b32_e64 v102, v102, v106, s[42:43]
	v_cndmask_b32_e32 v106, 0, v199, vcc
	v_sub_f32_e32 v102, v102, v106
	v_add_f32_e32 v102, v103, v102
	v_sub_f32_e32 v102, -0.5, v102
	v_mul_f32_e32 v102, 0x3fb8aa3b, v102
	v_exp_f32_e32 v102, v102
	v_mov_b32_e32 v103, v1
	v_mul_f32_e32 v102, 0xbfb8aa3b, v102
	v_exp_f32_e32 v106, v102
	v_add_u32_e32 v102, v101, v111
	v_lshl_add_u64 v[102:103], v[102:103], 2, s[48:49]
	global_store_dword v[102:103], v106, off sc1
	v_mov_b32_e32 v156, v236
	v_add_f32_e32 v102, v18, v156
	v_mul_f32_e64 v103, |v102|, s0
	v_exp_f32_e32 v103, v103
	v_max_f32_e64 v102, -v102, 0
	v_add_f32_e32 v106, v19, v156
	v_add_u32_e32 v155, 0x8000, v110
	v_add_f32_e32 v103, 1.0, v103
	v_cmp_gt_f32_e32 vcc, s31, v103
	v_add_u32_e32 v154, 0x8200, v110
	v_add_u32_e32 v153, 0x8400, v110
	v_cndmask_b32_e64 v107, 0, 32, vcc
	v_ldexp_f32 v103, v103, v107
	v_log_f32_e32 v103, v103
	v_cndmask_b32_e32 v111, 0, v199, vcc
	v_mul_f32_e64 v107, |v106|, s0
	v_max_f32_e64 v106, -v106, 0
	v_mul_f32_e32 v112, 0x3f317217, v103
	v_fma_f32 v112, v103, s1, -v112
	v_fmac_f32_e32 v112, 0x3377d1cf, v103
	v_fmac_f32_e32 v112, 0x3f317217, v103
	v_cmp_lt_f32_e64 vcc, |v103|, s33
	v_add_u32_e32 v151, 0x8600, v110
	s_nop 0
	v_cndmask_b32_e32 v103, v103, v112, vcc
	v_sub_f32_e32 v103, v103, v111
	v_add_f32_e32 v102, v102, v103
	v_sub_f32_e32 v102, -0.5, v102
	v_mul_f32_e32 v102, 0x3fb8aa3b, v102
	v_exp_f32_e32 v103, v107
	v_exp_f32_e32 v102, v102
	v_add_f32_e32 v103, 1.0, v103
	v_mul_f32_e32 v102, 0xbfb8aa3b, v102
	v_cmp_gt_f32_e32 vcc, s31, v103
	v_exp_f32_e32 v107, v102
	s_nop 0
	v_cndmask_b32_e64 v102, 0, 32, vcc
	v_ldexp_f32 v102, v103, v102
	v_log_f32_e32 v103, v102
	v_add_u32_e32 v102, v100, v155
	v_mul_f32_e32 v111, 0x3f317217, v103
	v_fma_f32 v111, v103, s1, -v111
	v_fmac_f32_e32 v111, 0x3377d1cf, v103
	v_fmac_f32_e32 v111, 0x3f317217, v103
	v_cmp_lt_f32_e64 s[42:43], |v103|, s33
	s_nop 1
	v_cndmask_b32_e64 v103, v103, v111, s[42:43]
	v_cndmask_b32_e32 v111, 0, v199, vcc
	v_sub_f32_e32 v103, v103, v111
	v_add_f32_e32 v103, v106, v103
	v_sub_f32_e32 v103, -0.5, v103
	v_mul_f32_e32 v103, 0x3fb8aa3b, v103
	v_exp_f32_e32 v106, v103
	v_mov_b32_e32 v103, v1
	v_lshl_add_u64 v[102:103], v[102:103], 2, s[48:49]
	global_store_dword v[102:103], v107, off sc1
	v_mul_f32_e32 v102, 0xbfb8aa3b, v106
	v_add_f32_e32 v106, v20, v156
	v_mul_f32_e64 v103, |v106|, s0
	v_exp_f32_e32 v103, v103
	v_max_f32_e64 v106, -v106, 0
	v_exp_f32_e32 v107, v102
	v_add_u32_e32 v102, v100, v154
	v_add_f32_e32 v103, 1.0, v103
	v_cmp_gt_f32_e32 vcc, s31, v103
	s_nop 1
	v_cndmask_b32_e64 v111, 0, 32, vcc
	v_ldexp_f32 v103, v103, v111
	v_log_f32_e32 v111, v103
	v_mov_b32_e32 v103, v1
	v_lshl_add_u64 v[102:103], v[102:103], 2, s[48:49]
	global_store_dword v[102:103], v107, off sc1
	v_mul_f32_e32 v112, 0x3f317217, v111
	v_fma_f32 v112, v111, s1, -v112
	v_fmac_f32_e32 v112, 0x3377d1cf, v111
	v_fmac_f32_e32 v112, 0x3f317217, v111
	v_cmp_lt_f32_e64 s[42:43], |v111|, s33
	s_nop 1
	v_cndmask_b32_e64 v111, v111, v112, s[42:43]
	v_cndmask_b32_e32 v112, 0, v199, vcc
	v_sub_f32_e32 v111, v111, v112
	v_add_f32_e32 v106, v106, v111
	v_sub_f32_e32 v106, -0.5, v106
	v_mul_f32_e32 v106, 0x3fb8aa3b, v106
	v_add_f32_e32 v111, v21, v156
	v_exp_f32_e32 v106, v106
	v_mul_f32_e64 v112, |v111|, s0
	v_exp_f32_e32 v112, v112
	v_max_f32_e64 v107, -v111, 0
	v_mul_f32_e32 v102, 0xbfb8aa3b, v106
	v_exp_f32_e32 v106, v102
	v_add_f32_e32 v102, 1.0, v112
	v_cmp_gt_f32_e32 vcc, s31, v102
	s_nop 1
	v_cndmask_b32_e64 v103, 0, 32, vcc
	v_ldexp_f32 v102, v102, v103
	v_log_f32_e32 v103, v102
	v_add_u32_e32 v102, v100, v153
	v_mul_f32_e32 v111, 0x3f317217, v103
	v_fma_f32 v111, v103, s1, -v111
	v_fmac_f32_e32 v111, 0x3377d1cf, v103
	v_fmac_f32_e32 v111, 0x3f317217, v103
	v_cmp_lt_f32_e64 s[42:43], |v103|, s33
	s_nop 1
	v_cndmask_b32_e64 v103, v103, v111, s[42:43]
	v_cndmask_b32_e32 v111, 0, v199, vcc
	v_sub_f32_e32 v103, v103, v111
	v_add_f32_e32 v103, v107, v103
	v_sub_f32_e32 v103, -0.5, v103
	v_mul_f32_e32 v103, 0x3fb8aa3b, v103
	v_exp_f32_e32 v107, v103
	v_mov_b32_e32 v103, v1
	v_lshl_add_u64 v[102:103], v[102:103], 2, s[48:49]
	global_store_dword v[102:103], v106, off sc1
	v_mul_f32_e32 v102, 0xbfb8aa3b, v107
	v_exp_f32_e32 v106, v102
	v_add_u32_e32 v102, v100, v151
	v_mov_b32_e32 v103, v1
	v_lshl_add_u64 v[102:103], v[102:103], 2, s[48:49]
	global_store_dword v[102:103], v106, off sc1
	v_add_f32_e32 v102, v22, v156
	v_mul_f32_e64 v103, |v102|, s0
	v_exp_f32_e32 v103, v103
	v_max_f32_e64 v102, -v102, 0
	v_add_f32_e32 v106, v23, v156
	v_add_u32_e32 v152, 0x9000, v110
	v_add_f32_e32 v103, 1.0, v103
	v_cmp_gt_f32_e32 vcc, s31, v103
	v_add_u32_e32 v150, 0x9200, v110
	v_add_u32_e32 v149, 0x9400, v110
	v_cndmask_b32_e64 v107, 0, 32, vcc
	v_ldexp_f32 v103, v103, v107
	v_log_f32_e32 v103, v103
	v_cndmask_b32_e32 v111, 0, v199, vcc
	v_mul_f32_e64 v107, |v106|, s0
	v_max_f32_e64 v106, -v106, 0
	v_mul_f32_e32 v112, 0x3f317217, v103
	v_fma_f32 v112, v103, s1, -v112
	v_fmac_f32_e32 v112, 0x3377d1cf, v103
	v_fmac_f32_e32 v112, 0x3f317217, v103
	v_cmp_lt_f32_e64 vcc, |v103|, s33
	v_add_u32_e32 v113, 0x9600, v110
	s_nop 0
	v_cndmask_b32_e32 v103, v103, v112, vcc
	v_sub_f32_e32 v103, v103, v111
	v_add_f32_e32 v102, v102, v103
	v_sub_f32_e32 v102, -0.5, v102
	v_mul_f32_e32 v102, 0x3fb8aa3b, v102
	v_exp_f32_e32 v103, v107
	v_exp_f32_e32 v102, v102
	v_add_f32_e32 v103, 1.0, v103
	v_mul_f32_e32 v102, 0xbfb8aa3b, v102
	v_cmp_gt_f32_e32 vcc, s31, v103
	v_exp_f32_e32 v107, v102
	s_nop 0
	v_cndmask_b32_e64 v102, 0, 32, vcc
	v_ldexp_f32 v102, v103, v102
	v_log_f32_e32 v103, v102
	v_add_u32_e32 v102, v100, v152
	v_mul_f32_e32 v111, 0x3f317217, v103
	v_fma_f32 v111, v103, s1, -v111
	v_fmac_f32_e32 v111, 0x3377d1cf, v103
	v_fmac_f32_e32 v111, 0x3f317217, v103
	v_cmp_lt_f32_e64 s[42:43], |v103|, s33
	s_nop 1
	v_cndmask_b32_e64 v103, v103, v111, s[42:43]
	v_cndmask_b32_e32 v111, 0, v199, vcc
	v_sub_f32_e32 v103, v103, v111
	v_add_f32_e32 v103, v106, v103
	v_sub_f32_e32 v103, -0.5, v103
	v_mul_f32_e32 v103, 0x3fb8aa3b, v103
	v_exp_f32_e32 v106, v103
	v_mov_b32_e32 v103, v1
	v_lshl_add_u64 v[102:103], v[102:103], 2, s[48:49]
	global_store_dword v[102:103], v107, off sc1
	v_mul_f32_e32 v102, 0xbfb8aa3b, v106
	v_add_f32_e32 v106, v24, v156
	v_mul_f32_e64 v103, |v106|, s0
	v_exp_f32_e32 v103, v103
	v_max_f32_e64 v106, -v106, 0
	v_exp_f32_e32 v107, v102
	v_add_u32_e32 v102, v100, v150
	v_add_f32_e32 v103, 1.0, v103
	v_cmp_gt_f32_e32 vcc, s31, v103
	s_nop 1
	v_cndmask_b32_e64 v111, 0, 32, vcc
	v_ldexp_f32 v103, v103, v111
	v_log_f32_e32 v111, v103
	v_mov_b32_e32 v103, v1
	v_lshl_add_u64 v[102:103], v[102:103], 2, s[48:49]
	global_store_dword v[102:103], v107, off sc1
	v_mul_f32_e32 v112, 0x3f317217, v111
	v_fma_f32 v112, v111, s1, -v112
	v_fmac_f32_e32 v112, 0x3377d1cf, v111
	v_fmac_f32_e32 v112, 0x3f317217, v111
	v_cmp_lt_f32_e64 s[42:43], |v111|, s33
	s_nop 1
	v_cndmask_b32_e64 v111, v111, v112, s[42:43]
	v_cndmask_b32_e32 v112, 0, v199, vcc
	v_sub_f32_e32 v111, v111, v112
	v_add_f32_e32 v106, v106, v111
	v_sub_f32_e32 v106, -0.5, v106
	v_mul_f32_e32 v106, 0x3fb8aa3b, v106
	v_add_f32_e32 v111, v25, v156
	v_exp_f32_e32 v106, v106
	v_mul_f32_e64 v112, |v111|, s0
	v_exp_f32_e32 v112, v112
	v_max_f32_e64 v107, -v111, 0
	v_mul_f32_e32 v102, 0xbfb8aa3b, v106
	v_exp_f32_e32 v106, v102
	v_add_f32_e32 v102, 1.0, v112
	v_cmp_gt_f32_e32 vcc, s31, v102
	s_nop 1
	v_cndmask_b32_e64 v103, 0, 32, vcc
	v_ldexp_f32 v102, v102, v103
	v_log_f32_e32 v103, v102
	v_add_u32_e32 v102, v100, v149
	v_mul_f32_e32 v111, 0x3f317217, v103
	v_fma_f32 v111, v103, s1, -v111
	v_fmac_f32_e32 v111, 0x3377d1cf, v103
	v_fmac_f32_e32 v111, 0x3f317217, v103
	v_cmp_lt_f32_e64 s[42:43], |v103|, s33
	s_nop 1
	v_cndmask_b32_e64 v103, v103, v111, s[42:43]
	v_cndmask_b32_e32 v111, 0, v199, vcc
	v_sub_f32_e32 v103, v103, v111
	v_add_f32_e32 v103, v107, v103
	v_sub_f32_e32 v103, -0.5, v103
	v_mul_f32_e32 v103, 0x3fb8aa3b, v103
	v_exp_f32_e32 v107, v103
	v_mov_b32_e32 v103, v1
	v_lshl_add_u64 v[102:103], v[102:103], 2, s[48:49]
	global_store_dword v[102:103], v106, off sc1
	v_mul_f32_e32 v102, 0xbfb8aa3b, v107
	v_exp_f32_e32 v106, v102
	v_add_u32_e32 v102, v100, v113
	v_mov_b32_e32 v103, v1
	v_lshl_add_u64 v[102:103], v[102:103], 2, s[48:49]
	global_store_dword v[102:103], v106, off sc1
	v_add_f32_e32 v102, v26, v156
	v_mul_f32_e64 v103, |v102|, s0
	v_exp_f32_e32 v103, v103
	v_max_f32_e64 v102, -v102, 0
	v_add_f32_e32 v106, v27, v156
	v_add_u32_e32 v148, 0xa000, v110
	v_add_f32_e32 v103, 1.0, v103
	v_cmp_gt_f32_e32 vcc, s31, v103
	s_nop 1
	v_cndmask_b32_e64 v107, 0, 32, vcc
	v_ldexp_f32 v103, v103, v107
	v_log_f32_e32 v103, v103
	v_cndmask_b32_e32 v111, 0, v199, vcc
	v_mul_f32_e64 v107, |v106|, s0
	v_max_f32_e64 v106, -v106, 0
	v_mul_f32_e32 v112, 0x3f317217, v103
	v_fma_f32 v112, v103, s1, -v112
	v_fmac_f32_e32 v112, 0x3377d1cf, v103
	v_fmac_f32_e32 v112, 0x3f317217, v103
	v_cmp_lt_f32_e64 vcc, |v103|, s33
	s_nop 1
	v_cndmask_b32_e32 v103, v103, v112, vcc
	v_sub_f32_e32 v103, v103, v111
	v_add_f32_e32 v102, v102, v103
	v_sub_f32_e32 v102, -0.5, v102
	v_mul_f32_e32 v102, 0x3fb8aa3b, v102
	v_exp_f32_e32 v103, v107
	v_exp_f32_e32 v102, v102
	v_add_u32_e32 v112, 0xa200, v110
	v_add_f32_e32 v103, 1.0, v103
	v_mul_f32_e32 v102, 0xbfb8aa3b, v102
	v_cmp_gt_f32_e32 vcc, s31, v103
	v_exp_f32_e32 v107, v102
	s_nop 0
	v_cndmask_b32_e64 v102, 0, 32, vcc
	v_ldexp_f32 v102, v103, v102
	v_log_f32_e32 v103, v102
	v_add_u32_e32 v102, v100, v148
	v_mul_f32_e32 v111, 0x3f317217, v103
	v_fma_f32 v111, v103, s1, -v111
	v_fmac_f32_e32 v111, 0x3377d1cf, v103
	v_fmac_f32_e32 v111, 0x3f317217, v103
	v_cmp_lt_f32_e64 s[42:43], |v103|, s33
	s_nop 1
	v_cndmask_b32_e64 v103, v103, v111, s[42:43]
	v_cndmask_b32_e32 v111, 0, v199, vcc
	v_sub_f32_e32 v103, v103, v111
	v_add_f32_e32 v103, v106, v103
	v_sub_f32_e32 v103, -0.5, v103
	v_mul_f32_e32 v103, 0x3fb8aa3b, v103
	v_exp_f32_e32 v106, v103
	v_mov_b32_e32 v103, v1
	v_lshl_add_u64 v[102:103], v[102:103], 2, s[48:49]
	global_store_dword v[102:103], v107, off sc1
	v_mul_f32_e32 v102, 0xbfb8aa3b, v106
	v_add_f32_e32 v106, v28, v156
	v_mul_f32_e64 v103, |v106|, s0
	v_exp_f32_e32 v103, v103
	v_max_f32_e64 v106, -v106, 0
	v_exp_f32_e32 v107, v102
	v_add_u32_e32 v102, v100, v112
	v_add_f32_e32 v103, 1.0, v103
	v_cmp_gt_f32_e32 vcc, s31, v103
	s_nop 1
	v_cndmask_b32_e64 v111, 0, 32, vcc
	v_ldexp_f32 v103, v103, v111
	v_log_f32_e32 v111, v103
	v_mov_b32_e32 v103, v1
	v_lshl_add_u64 v[102:103], v[102:103], 2, s[48:49]
	global_store_dword v[102:103], v107, off sc1
	v_mul_f32_e32 v157, 0x3f317217, v111
	v_fma_f32 v157, v111, s1, -v157
	v_fmac_f32_e32 v157, 0x3377d1cf, v111
	v_fmac_f32_e32 v157, 0x3f317217, v111
	v_cmp_lt_f32_e64 s[42:43], |v111|, s33
	s_nop 1
	v_cndmask_b32_e64 v111, v111, v157, s[42:43]
	v_cndmask_b32_e32 v157, 0, v199, vcc
	v_sub_f32_e32 v111, v111, v157
	v_add_f32_e32 v106, v106, v111
	v_sub_f32_e32 v106, -0.5, v106
	v_mul_f32_e32 v106, 0x3fb8aa3b, v106
	v_add_f32_e32 v157, v29, v156
	v_exp_f32_e32 v106, v106
	v_mul_f32_e64 v111, |v157|, s0
	v_exp_f32_e32 v111, v111
	v_max_f32_e64 v107, -v157, 0
	v_mul_f32_e32 v102, 0xbfb8aa3b, v106
	v_exp_f32_e32 v106, v102
	v_add_f32_e32 v102, 1.0, v111
	v_cmp_gt_f32_e32 vcc, s31, v102
	v_add_u32_e32 v111, 0xa400, v110
	s_nop 0
	v_cndmask_b32_e64 v103, 0, 32, vcc
	v_ldexp_f32 v102, v102, v103
	v_log_f32_e32 v103, v102
	v_add_u32_e32 v102, v100, v111
	v_mul_f32_e32 v157, 0x3f317217, v103
	v_fma_f32 v157, v103, s1, -v157
	v_fmac_f32_e32 v157, 0x3377d1cf, v103
	v_fmac_f32_e32 v157, 0x3f317217, v103
	v_cmp_lt_f32_e64 s[42:43], |v103|, s33
	s_nop 1
	v_cndmask_b32_e64 v103, v103, v157, s[42:43]
	v_cndmask_b32_e32 v157, 0, v199, vcc
	v_sub_f32_e32 v103, v103, v157
	v_add_f32_e32 v103, v107, v103
	v_sub_f32_e32 v103, -0.5, v103
	v_mul_f32_e32 v103, 0x3fb8aa3b, v103
	v_exp_f32_e32 v107, v103
	v_mov_b32_e32 v103, v1
	v_lshl_add_u64 v[102:103], v[102:103], 2, s[48:49]
	global_store_dword v[102:103], v106, off sc1
	v_mul_f32_e32 v102, 0xbfb8aa3b, v107
	v_exp_f32_e32 v103, v102
	v_add_u32_e32 v102, 0xa600, v110
	v_add_u32_e32 v106, v100, v102
	v_mov_b32_e32 v107, v1
	v_lshl_add_u64 v[106:107], v[106:107], 2, s[48:49]
	global_store_dword v[106:107], v103, off sc1
	v_add_f32_e32 v103, v30, v156
	v_max_f32_e64 v106, -v103, 0
	v_mul_f32_e64 v103, |v103|, s0
	v_exp_f32_e32 v103, v103
	v_mov_b32_e32 v159, v1
	v_add_f32_e32 v103, 1.0, v103
	v_cmp_gt_f32_e32 vcc, s31, v103
	s_nop 1
	v_cndmask_b32_e64 v107, 0, 32, vcc
	v_ldexp_f32 v103, v103, v107
	v_log_f32_e32 v103, v103
	s_nop 0
	v_mul_f32_e32 v107, 0x3f317217, v103
	v_fma_f32 v107, v103, s1, -v107
	v_fmac_f32_e32 v107, 0x3377d1cf, v103
	v_fmac_f32_e32 v107, 0x3f317217, v103
	v_cmp_lt_f32_e64 s[42:43], |v103|, s33
	s_nop 1
	v_cndmask_b32_e64 v103, v103, v107, s[42:43]
	v_cndmask_b32_e32 v107, 0, v199, vcc
	v_sub_f32_e32 v103, v103, v107
	v_add_f32_e32 v103, v106, v103
	v_sub_f32_e32 v103, -0.5, v103
	v_mul_f32_e32 v103, 0x3fb8aa3b, v103
	v_exp_f32_e32 v103, v103
	v_mov_b32_e32 v107, v1
	v_mul_f32_e32 v103, 0xbfb8aa3b, v103
	v_exp_f32_e32 v157, v103
	v_add_u32_e32 v103, 0xb000, v110
	v_add_u32_e32 v106, v100, v103
	v_lshl_add_u64 v[106:107], v[106:107], 2, s[48:49]
	global_store_dword v[106:107], v157, off sc1
	v_add_f32_e32 v106, v31, v156
	v_max_f32_e64 v107, -v106, 0
	v_mul_f32_e64 v106, |v106|, s0
	v_exp_f32_e32 v106, v106
	s_nop 0
	v_add_f32_e32 v106, 1.0, v106
	v_cmp_gt_f32_e32 vcc, s31, v106
	s_nop 1
	v_cndmask_b32_e64 v157, 0, 32, vcc
	v_ldexp_f32 v106, v106, v157
	v_log_f32_e32 v106, v106
	s_nop 0
	v_mul_f32_e32 v157, 0x3f317217, v106
	v_fma_f32 v157, v106, s1, -v157
	v_fmac_f32_e32 v157, 0x3377d1cf, v106
	v_fmac_f32_e32 v157, 0x3f317217, v106
	v_cmp_lt_f32_e64 s[42:43], |v106|, s33
	s_nop 1
	v_cndmask_b32_e64 v106, v106, v157, s[42:43]
	v_cndmask_b32_e32 v157, 0, v199, vcc
	v_sub_f32_e32 v106, v106, v157
	v_add_f32_e32 v106, v107, v106
	v_sub_f32_e32 v106, -0.5, v106
	v_mul_f32_e32 v106, 0x3fb8aa3b, v106
	v_exp_f32_e32 v106, v106
	s_nop 0
	v_mul_f32_e32 v106, 0xbfb8aa3b, v106
	v_exp_f32_e32 v107, v106
	v_add_u32_e32 v106, 0xb200, v110
	v_add_u32_e32 v158, v100, v106
	v_lshl_add_u64 v[158:159], v[158:159], 2, s[48:49]
	global_store_dword v[158:159], v107, off sc1
	v_add_f32_e32 v107, v32, v156
	v_max_f32_e64 v157, -v107, 0
	v_mul_f32_e64 v107, |v107|, s0
	v_exp_f32_e32 v107, v107
	v_mov_b32_e32 v159, v1
	v_add_f32_e32 v156, v33, v156
	v_add_f32_e32 v107, 1.0, v107
	v_cmp_gt_f32_e32 vcc, s31, v107
	s_nop 1
	v_cndmask_b32_e64 v158, 0, 32, vcc
	v_ldexp_f32 v107, v107, v158
	v_log_f32_e32 v107, v107
	s_nop 0
	v_mul_f32_e32 v158, 0x3f317217, v107
	v_fma_f32 v158, v107, s1, -v158
	v_fmac_f32_e32 v158, 0x3377d1cf, v107
	v_fmac_f32_e32 v158, 0x3f317217, v107
	v_cmp_lt_f32_e64 s[42:43], |v107|, s33
	s_nop 1
	v_cndmask_b32_e64 v107, v107, v158, s[42:43]
	v_cndmask_b32_e32 v158, 0, v199, vcc
	v_sub_f32_e32 v107, v107, v158
	v_add_f32_e32 v107, v157, v107
	v_sub_f32_e32 v107, -0.5, v107
	v_mul_f32_e32 v107, 0x3fb8aa3b, v107
	v_exp_f32_e32 v107, v107
	s_nop 0
	v_mul_f32_e32 v107, 0xbfb8aa3b, v107
	v_exp_f32_e32 v157, v107
	v_add_u32_e32 v107, 0xb400, v110
	v_add_u32_e32 v158, v100, v107
	v_lshl_add_u64 v[158:159], v[158:159], 2, s[48:49]
	global_store_dword v[158:159], v157, off sc1
	v_max_f32_e64 v157, -v156, 0
	v_mul_f32_e64 v156, |v156|, s0
	v_exp_f32_e32 v156, v156
	v_add_u32_e32 v110, 0xb600, v110
	v_add_f32_e32 v156, 1.0, v156
	v_cmp_gt_f32_e32 vcc, s31, v156
	s_nop 1
	v_cndmask_b32_e64 v158, 0, 32, vcc
	v_ldexp_f32 v156, v156, v158
	v_log_f32_e32 v156, v156
	s_nop 0
	v_mul_f32_e32 v158, 0x3f317217, v156
	v_fma_f32 v158, v156, s1, -v158
	v_fmac_f32_e32 v158, 0x3377d1cf, v156
	v_fmac_f32_e32 v158, 0x3f317217, v156
	v_cmp_lt_f32_e64 s[42:43], |v156|, s33
	s_nop 1
	v_cndmask_b32_e64 v156, v156, v158, s[42:43]
	v_cndmask_b32_e32 v158, 0, v199, vcc
	v_sub_f32_e32 v156, v156, v158
	v_add_f32_e32 v156, v157, v156
	v_sub_f32_e32 v156, -0.5, v156
	v_mul_f32_e32 v156, 0x3fb8aa3b, v156
	v_exp_f32_e32 v156, v156
	v_mov_b32_e32 v157, v1
	v_mul_f32_e32 v156, 0xbfb8aa3b, v156
	v_exp_f32_e32 v158, v156
	v_add_u32_e32 v156, v100, v110
	v_lshl_add_u64 v[156:157], v[156:157], 2, s[48:49]
	global_store_dword v[156:157], v158, off sc1
	v_mov_b32_e32 v104, v237
	v_add_f32_e32 v105, v2, v104
	v_max_f32_e64 v156, -v105, 0
	v_mul_f32_e64 v105, |v105|, s0
	v_exp_f32_e32 v105, v105
	v_add_u32_e32 v154, v101, v154
	v_add_f32_e32 v105, 1.0, v105
	v_cmp_gt_f32_e32 vcc, s31, v105
	s_nop 1
	v_cndmask_b32_e64 v157, 0, 32, vcc
	v_ldexp_f32 v105, v105, v157
	v_log_f32_e32 v105, v105
	s_nop 0
	v_mul_f32_e32 v157, 0x3f317217, v105
	v_fma_f32 v157, v105, s1, -v157
	v_fmac_f32_e32 v157, 0x3377d1cf, v105
	v_fmac_f32_e32 v157, 0x3f317217, v105
	v_cmp_lt_f32_e64 s[42:43], |v105|, s33
	s_nop 1
	v_cndmask_b32_e64 v105, v105, v157, s[42:43]
	v_cndmask_b32_e32 v157, 0, v199, vcc
	v_sub_f32_e32 v105, v105, v157
	v_add_f32_e32 v105, v156, v105
	v_sub_f32_e32 v105, -0.5, v105
	v_mul_f32_e32 v105, 0x3fb8aa3b, v105
	v_exp_f32_e32 v105, v105
	v_add_u32_e32 v156, v101, v155
	v_mov_b32_e32 v157, v1
	v_lshl_add_u64 v[156:157], v[156:157], 2, s[48:49]
	v_mul_f32_e32 v105, 0xbfb8aa3b, v105
	v_exp_f32_e32 v105, v105
	global_store_dword v[156:157], v105, off sc1
	v_add_f32_e32 v105, v3, v104
	v_max_f32_e64 v155, -v105, 0
	v_mul_f32_e64 v105, |v105|, s0
	v_exp_f32_e32 v105, v105
	s_nop 0
	v_add_f32_e32 v105, 1.0, v105
	v_cmp_gt_f32_e32 vcc, s31, v105
	s_nop 1
	v_cndmask_b32_e64 v156, 0, 32, vcc
	v_ldexp_f32 v105, v105, v156
	v_log_f32_e32 v105, v105
	s_nop 0
	v_mul_f32_e32 v156, 0x3f317217, v105
	v_fma_f32 v156, v105, s1, -v156
	v_fmac_f32_e32 v156, 0x3377d1cf, v105
	v_fmac_f32_e32 v156, 0x3f317217, v105
	v_cmp_lt_f32_e64 s[42:43], |v105|, s33
	s_nop 1
	v_cndmask_b32_e64 v105, v105, v156, s[42:43]
	v_cndmask_b32_e32 v156, 0, v199, vcc
	v_sub_f32_e32 v105, v105, v156
	v_add_f32_e32 v105, v155, v105
	v_sub_f32_e32 v105, -0.5, v105
	v_mul_f32_e32 v105, 0x3fb8aa3b, v105
	v_exp_f32_e32 v105, v105
	v_mov_b32_e32 v155, v1
	v_lshl_add_u64 v[154:155], v[154:155], 2, s[48:49]
	v_mul_f32_e32 v105, 0xbfb8aa3b, v105
	v_exp_f32_e32 v105, v105
	global_store_dword v[154:155], v105, off sc1
	v_add_f32_e32 v105, v4, v104
	v_max_f32_e64 v154, -v105, 0
	v_mul_f32_e64 v105, |v105|, s0
	v_exp_f32_e32 v105, v105
	s_nop 0
	v_add_f32_e32 v105, 1.0, v105
	v_cmp_gt_f32_e32 vcc, s31, v105
	s_nop 1
	v_cndmask_b32_e64 v155, 0, 32, vcc
	v_ldexp_f32 v105, v105, v155
	v_log_f32_e32 v105, v105
	s_nop 0
	v_mul_f32_e32 v155, 0x3f317217, v105
	v_fma_f32 v155, v105, s1, -v155
	v_fmac_f32_e32 v155, 0x3377d1cf, v105
	v_fmac_f32_e32 v155, 0x3f317217, v105
	v_cmp_lt_f32_e64 s[42:43], |v105|, s33
	s_nop 1
	v_cndmask_b32_e64 v105, v105, v155, s[42:43]
	v_cndmask_b32_e32 v155, 0, v199, vcc
	v_sub_f32_e32 v105, v105, v155
	v_add_f32_e32 v105, v154, v105
	v_sub_f32_e32 v105, -0.5, v105
	v_mul_f32_e32 v105, 0x3fb8aa3b, v105
	v_exp_f32_e32 v105, v105
	v_add_u32_e32 v154, v101, v153
	v_mov_b32_e32 v155, v1
	v_lshl_add_u64 v[154:155], v[154:155], 2, s[48:49]
	v_mul_f32_e32 v105, 0xbfb8aa3b, v105
	v_exp_f32_e32 v105, v105
	global_store_dword v[154:155], v105, off sc1
	v_add_f32_e32 v105, v5, v104
	v_max_f32_e64 v153, -v105, 0
	v_mul_f32_e64 v105, |v105|, s0
	v_exp_f32_e32 v105, v105
	v_mov_b32_e32 v155, v1
	v_add_f32_e32 v105, 1.0, v105
	v_cmp_gt_f32_e32 vcc, s31, v105
	s_nop 1
	v_cndmask_b32_e64 v154, 0, 32, vcc
	v_ldexp_f32 v105, v105, v154
	v_log_f32_e32 v105, v105
	s_nop 0
	v_mul_f32_e32 v154, 0x3f317217, v105
	v_fma_f32 v154, v105, s1, -v154
	v_fmac_f32_e32 v154, 0x3377d1cf, v105
	v_fmac_f32_e32 v154, 0x3f317217, v105
	v_cmp_lt_f32_e64 s[42:43], |v105|, s33
	s_nop 1
	v_cndmask_b32_e64 v105, v105, v154, s[42:43]
	v_cndmask_b32_e32 v154, 0, v199, vcc
	v_sub_f32_e32 v105, v105, v154
	v_add_f32_e32 v105, v153, v105
	v_sub_f32_e32 v105, -0.5, v105
	v_mul_f32_e32 v105, 0x3fb8aa3b, v105
	v_exp_f32_e32 v105, v105
	v_add_u32_e32 v154, v101, v151
	v_lshl_add_u64 v[154:155], v[154:155], 2, s[48:49]
	v_mul_f32_e32 v105, 0xbfb8aa3b, v105
	v_exp_f32_e32 v105, v105
	global_store_dword v[154:155], v105, off sc1
	v_add_f32_e32 v105, v6, v104
	v_max_f32_e64 v151, -v105, 0
	v_mul_f32_e64 v105, |v105|, s0
	v_exp_f32_e32 v105, v105
	v_add_u32_e32 v152, v101, v152
	v_add_u32_e32 v150, v101, v150
	v_add_f32_e32 v105, 1.0, v105
	v_cmp_gt_f32_e32 vcc, s31, v105
	s_nop 1
	v_cndmask_b32_e64 v153, 0, 32, vcc
	v_ldexp_f32 v105, v105, v153
	v_log_f32_e32 v105, v105
	s_nop 0
	v_mul_f32_e32 v153, 0x3f317217, v105
	v_fma_f32 v153, v105, s1, -v153
	v_fmac_f32_e32 v153, 0x3377d1cf, v105
	v_fmac_f32_e32 v153, 0x3f317217, v105
	v_cmp_lt_f32_e64 s[42:43], |v105|, s33
	s_nop 1
	v_cndmask_b32_e64 v105, v105, v153, s[42:43]
	v_cndmask_b32_e32 v153, 0, v199, vcc
	v_sub_f32_e32 v105, v105, v153
	v_add_f32_e32 v105, v151, v105
	v_sub_f32_e32 v105, -0.5, v105
	v_mul_f32_e32 v105, 0x3fb8aa3b, v105
	v_exp_f32_e32 v105, v105
	v_mov_b32_e32 v153, v1
	v_lshl_add_u64 v[152:153], v[152:153], 2, s[48:49]
	v_mul_f32_e32 v105, 0xbfb8aa3b, v105
	v_exp_f32_e32 v105, v105
	global_store_dword v[152:153], v105, off sc1
	v_add_f32_e32 v105, v7, v104
	v_max_f32_e64 v151, -v105, 0
	v_mul_f32_e64 v105, |v105|, s0
	v_exp_f32_e32 v105, v105
	s_nop 0
	v_add_f32_e32 v105, 1.0, v105
	v_cmp_gt_f32_e32 vcc, s31, v105
	s_nop 1
	v_cndmask_b32_e64 v152, 0, 32, vcc
	v_ldexp_f32 v105, v105, v152
	v_log_f32_e32 v105, v105
	s_nop 0
	v_mul_f32_e32 v152, 0x3f317217, v105
	v_fma_f32 v152, v105, s1, -v152
	v_fmac_f32_e32 v152, 0x3377d1cf, v105
	v_fmac_f32_e32 v152, 0x3f317217, v105
	v_cmp_lt_f32_e64 s[42:43], |v105|, s33
	s_nop 1
	v_cndmask_b32_e64 v105, v105, v152, s[42:43]
	v_cndmask_b32_e32 v152, 0, v199, vcc
	v_sub_f32_e32 v105, v105, v152
	v_add_f32_e32 v105, v151, v105
	v_sub_f32_e32 v105, -0.5, v105
	v_mul_f32_e32 v105, 0x3fb8aa3b, v105
	v_exp_f32_e32 v105, v105
	v_mov_b32_e32 v151, v1
	v_lshl_add_u64 v[150:151], v[150:151], 2, s[48:49]
	v_mul_f32_e32 v105, 0xbfb8aa3b, v105
	v_exp_f32_e32 v105, v105
	global_store_dword v[150:151], v105, off sc1
	v_add_f32_e32 v105, v8, v104
	v_max_f32_e64 v150, -v105, 0
	v_mul_f32_e64 v105, |v105|, s0
	v_exp_f32_e32 v105, v105
	s_nop 0
	v_add_f32_e32 v105, 1.0, v105
	v_cmp_gt_f32_e32 vcc, s31, v105
	s_nop 1
	v_cndmask_b32_e64 v151, 0, 32, vcc
	v_ldexp_f32 v105, v105, v151
	v_log_f32_e32 v105, v105
	s_nop 0
	v_mul_f32_e32 v151, 0x3f317217, v105
	v_fma_f32 v151, v105, s1, -v151
	v_fmac_f32_e32 v151, 0x3377d1cf, v105
	v_fmac_f32_e32 v151, 0x3f317217, v105
	v_cmp_lt_f32_e64 s[42:43], |v105|, s33
	s_nop 1
	v_cndmask_b32_e64 v105, v105, v151, s[42:43]
	v_cndmask_b32_e32 v151, 0, v199, vcc
	v_sub_f32_e32 v105, v105, v151
	v_add_f32_e32 v105, v150, v105
	v_sub_f32_e32 v105, -0.5, v105
	v_mul_f32_e32 v105, 0x3fb8aa3b, v105
	v_exp_f32_e32 v105, v105
	v_add_u32_e32 v150, v101, v149
	v_mov_b32_e32 v151, v1
	v_lshl_add_u64 v[150:151], v[150:151], 2, s[48:49]
	v_mul_f32_e32 v105, 0xbfb8aa3b, v105
	v_exp_f32_e32 v105, v105
	global_store_dword v[150:151], v105, off sc1
	v_add_f32_e32 v105, v9, v104
	v_max_f32_e64 v149, -v105, 0
	v_mul_f32_e64 v105, |v105|, s0
	v_exp_f32_e32 v105, v105
	v_mov_b32_e32 v151, v1
	v_add_f32_e32 v105, 1.0, v105
	v_cmp_gt_f32_e32 vcc, s31, v105
	s_nop 1
	v_cndmask_b32_e64 v150, 0, 32, vcc
	v_ldexp_f32 v105, v105, v150
	v_log_f32_e32 v105, v105
	s_nop 0
	v_mul_f32_e32 v150, 0x3f317217, v105
	v_fma_f32 v150, v105, s1, -v150
	v_fmac_f32_e32 v150, 0x3377d1cf, v105
	v_fmac_f32_e32 v150, 0x3f317217, v105
	v_cmp_lt_f32_e64 s[42:43], |v105|, s33
	s_nop 1
	v_cndmask_b32_e64 v105, v105, v150, s[42:43]
	v_cndmask_b32_e32 v150, 0, v199, vcc
	v_sub_f32_e32 v105, v105, v150
	v_add_f32_e32 v105, v149, v105
	v_sub_f32_e32 v105, -0.5, v105
	v_mul_f32_e32 v105, 0x3fb8aa3b, v105
	v_exp_f32_e32 v105, v105
	v_add_u32_e32 v150, v101, v113
	v_lshl_add_u64 v[150:151], v[150:151], 2, s[48:49]
	v_mul_f32_e32 v105, 0xbfb8aa3b, v105
	v_exp_f32_e32 v105, v105
	global_store_dword v[150:151], v105, off sc1
	v_add_f32_e32 v105, v10, v104
	v_max_f32_e64 v113, -v105, 0
	v_mul_f32_e64 v105, |v105|, s0
	v_exp_f32_e32 v105, v105
	v_add_u32_e32 v148, v101, v148
	v_add_u32_e32 v112, v101, v112
	v_add_f32_e32 v105, 1.0, v105
	v_cmp_gt_f32_e32 vcc, s31, v105
	s_nop 1
	v_cndmask_b32_e64 v149, 0, 32, vcc
	v_ldexp_f32 v105, v105, v149
	v_log_f32_e32 v105, v105
	s_nop 0
	v_mul_f32_e32 v149, 0x3f317217, v105
	v_fma_f32 v149, v105, s1, -v149
	v_fmac_f32_e32 v149, 0x3377d1cf, v105
	v_fmac_f32_e32 v149, 0x3f317217, v105
	v_cmp_lt_f32_e64 s[42:43], |v105|, s33
	s_nop 1
	v_cndmask_b32_e64 v105, v105, v149, s[42:43]
	v_cndmask_b32_e32 v149, 0, v199, vcc
	v_sub_f32_e32 v105, v105, v149
	v_add_f32_e32 v105, v113, v105
	v_sub_f32_e32 v105, -0.5, v105
	v_mul_f32_e32 v105, 0x3fb8aa3b, v105
	v_exp_f32_e32 v105, v105
	v_mov_b32_e32 v149, v1
	v_lshl_add_u64 v[148:149], v[148:149], 2, s[48:49]
	v_mul_f32_e32 v105, 0xbfb8aa3b, v105
	v_exp_f32_e32 v105, v105
	global_store_dword v[148:149], v105, off sc1
	v_add_f32_e32 v105, v11, v104
	v_max_f32_e64 v113, -v105, 0
	v_mul_f32_e64 v105, |v105|, s0
	v_exp_f32_e32 v105, v105
	s_nop 0
	v_add_f32_e32 v105, 1.0, v105
	v_cmp_gt_f32_e32 vcc, s31, v105
	s_nop 1
	v_cndmask_b32_e64 v148, 0, 32, vcc
	v_ldexp_f32 v105, v105, v148
	v_log_f32_e32 v105, v105
	s_nop 0
	v_mul_f32_e32 v148, 0x3f317217, v105
	v_fma_f32 v148, v105, s1, -v148
	v_fmac_f32_e32 v148, 0x3377d1cf, v105
	v_fmac_f32_e32 v148, 0x3f317217, v105
	v_cmp_lt_f32_e64 s[42:43], |v105|, s33
	s_nop 1
	v_cndmask_b32_e64 v105, v105, v148, s[42:43]
	v_cndmask_b32_e32 v148, 0, v199, vcc
	v_sub_f32_e32 v105, v105, v148
	v_add_f32_e32 v105, v113, v105
	v_sub_f32_e32 v105, -0.5, v105
	v_mul_f32_e32 v105, 0x3fb8aa3b, v105
	v_exp_f32_e32 v105, v105
	v_mov_b32_e32 v113, v1
	v_lshl_add_u64 v[112:113], v[112:113], 2, s[48:49]
	v_mul_f32_e32 v105, 0xbfb8aa3b, v105
	v_exp_f32_e32 v105, v105
	global_store_dword v[112:113], v105, off sc1
	v_add_f32_e32 v105, v12, v104
	v_max_f32_e64 v112, -v105, 0
	v_mul_f32_e64 v105, |v105|, s0
	v_exp_f32_e32 v105, v105
	s_nop 0
	v_add_f32_e32 v105, 1.0, v105
	v_cmp_gt_f32_e32 vcc, s31, v105
	s_nop 1
	v_cndmask_b32_e64 v113, 0, 32, vcc
	v_ldexp_f32 v105, v105, v113
	v_log_f32_e32 v105, v105
	s_nop 0
	v_mul_f32_e32 v113, 0x3f317217, v105
	v_fma_f32 v113, v105, s1, -v113
	v_fmac_f32_e32 v113, 0x3377d1cf, v105
	v_fmac_f32_e32 v113, 0x3f317217, v105
	v_cmp_lt_f32_e64 s[42:43], |v105|, s33
	s_nop 1
	v_cndmask_b32_e64 v105, v105, v113, s[42:43]
	v_cndmask_b32_e32 v113, 0, v199, vcc
	v_sub_f32_e32 v105, v105, v113
	v_add_f32_e32 v105, v112, v105
	v_sub_f32_e32 v105, -0.5, v105
	v_mul_f32_e32 v105, 0x3fb8aa3b, v105
	v_exp_f32_e32 v105, v105
	v_add_u32_e32 v112, v101, v111
	v_mov_b32_e32 v113, v1
	v_lshl_add_u64 v[112:113], v[112:113], 2, s[48:49]
	v_mul_f32_e32 v105, 0xbfb8aa3b, v105
	v_exp_f32_e32 v105, v105
	global_store_dword v[112:113], v105, off sc1
	v_add_f32_e32 v105, v13, v104
	v_max_f32_e64 v111, -v105, 0
	v_mul_f32_e64 v105, |v105|, s0
	v_exp_f32_e32 v105, v105
	v_mov_b32_e32 v113, v1
	v_add_f32_e32 v105, 1.0, v105
	v_cmp_gt_f32_e32 vcc, s31, v105
	s_nop 1
	v_cndmask_b32_e64 v112, 0, 32, vcc
	v_ldexp_f32 v105, v105, v112
	v_log_f32_e32 v105, v105
	s_nop 0
	v_mul_f32_e32 v112, 0x3f317217, v105
	v_fma_f32 v112, v105, s1, -v112
	v_fmac_f32_e32 v112, 0x3377d1cf, v105
	v_fmac_f32_e32 v112, 0x3f317217, v105
	v_cmp_lt_f32_e64 s[42:43], |v105|, s33
	s_nop 1
	v_cndmask_b32_e64 v105, v105, v112, s[42:43]
	v_cndmask_b32_e32 v112, 0, v199, vcc
	v_sub_f32_e32 v105, v105, v112
	v_add_f32_e32 v105, v111, v105
	v_sub_f32_e32 v105, -0.5, v105
	v_mul_f32_e32 v105, 0x3fb8aa3b, v105
	v_exp_f32_e32 v105, v105
	v_add_u32_e32 v112, v101, v102
	v_lshl_add_u64 v[112:113], v[112:113], 2, s[48:49]
	v_mul_f32_e32 v105, 0xbfb8aa3b, v105
	v_exp_f32_e32 v105, v105
	global_store_dword v[112:113], v105, off sc1
	v_add_f32_e32 v102, v14, v104
	v_max_f32_e64 v105, -v102, 0
	v_mul_f32_e64 v102, |v102|, s0
	v_exp_f32_e32 v102, v102
	s_nop 0
	v_add_f32_e32 v102, 1.0, v102
	v_cmp_gt_f32_e32 vcc, s31, v102
	s_nop 1
	v_cndmask_b32_e64 v111, 0, 32, vcc
	v_ldexp_f32 v102, v102, v111
	v_log_f32_e32 v102, v102
	s_nop 0
	v_mul_f32_e32 v111, 0x3f317217, v102
	v_fma_f32 v111, v102, s1, -v111
	v_fmac_f32_e32 v111, 0x3377d1cf, v102
	v_fmac_f32_e32 v111, 0x3f317217, v102
	v_cmp_lt_f32_e64 s[42:43], |v102|, s33
	s_nop 1
	v_cndmask_b32_e64 v102, v102, v111, s[42:43]
	v_cndmask_b32_e32 v111, 0, v199, vcc
	v_sub_f32_e32 v102, v102, v111
	v_add_f32_e32 v102, v105, v102
	v_sub_f32_e32 v102, -0.5, v102
	v_mul_f32_e32 v102, 0x3fb8aa3b, v102
	v_exp_f32_e32 v102, v102
	s_nop 0
	v_mul_f32_e32 v102, 0xbfb8aa3b, v102
	v_exp_f32_e32 v105, v102
	v_add_u32_e32 v102, v101, v103
	v_mov_b32_e32 v103, v1
	v_lshl_add_u64 v[102:103], v[102:103], 2, s[48:49]
	global_store_dword v[102:103], v105, off sc1
	v_add_f32_e32 v102, v15, v104
	v_max_f32_e64 v103, -v102, 0
	v_mul_f32_e64 v102, |v102|, s0
	v_exp_f32_e32 v102, v102
	s_nop 0
	v_add_f32_e32 v102, 1.0, v102
	v_cmp_gt_f32_e32 vcc, s31, v102
	s_nop 1
	v_cndmask_b32_e64 v105, 0, 32, vcc
	v_ldexp_f32 v102, v102, v105
	v_log_f32_e32 v102, v102
	s_nop 0
	v_mul_f32_e32 v105, 0x3f317217, v102
	v_fma_f32 v105, v102, s1, -v105
	v_fmac_f32_e32 v105, 0x3377d1cf, v102
	v_fmac_f32_e32 v105, 0x3f317217, v102
	v_cmp_lt_f32_e64 s[42:43], |v102|, s33
	s_nop 1
	v_cndmask_b32_e64 v102, v102, v105, s[42:43]
	v_cndmask_b32_e32 v105, 0, v199, vcc
	v_sub_f32_e32 v102, v102, v105
	v_add_f32_e32 v102, v103, v102
	v_sub_f32_e32 v102, -0.5, v102
	v_mul_f32_e32 v102, 0x3fb8aa3b, v102
	v_exp_f32_e32 v102, v102
	v_mov_b32_e32 v103, v1
	v_mul_f32_e32 v102, 0xbfb8aa3b, v102
	v_exp_f32_e32 v105, v102
	v_add_u32_e32 v102, v101, v106
	v_lshl_add_u64 v[102:103], v[102:103], 2, s[48:49]
	global_store_dword v[102:103], v105, off sc1
	v_add_f32_e32 v102, v16, v104
	v_max_f32_e64 v103, -v102, 0
	v_mul_f32_e64 v102, |v102|, s0
	v_exp_f32_e32 v102, v102
	s_nop 0
	v_add_f32_e32 v102, 1.0, v102
	v_cmp_gt_f32_e32 vcc, s31, v102
	s_nop 1
	v_cndmask_b32_e64 v105, 0, 32, vcc
	v_ldexp_f32 v102, v102, v105
	v_log_f32_e32 v102, v102
	s_nop 0
	v_mul_f32_e32 v105, 0x3f317217, v102
	v_fma_f32 v105, v102, s1, -v105
	v_fmac_f32_e32 v105, 0x3377d1cf, v102
	v_fmac_f32_e32 v105, 0x3f317217, v102
	v_cmp_lt_f32_e64 s[42:43], |v102|, s33
	s_nop 1
	v_cndmask_b32_e64 v102, v102, v105, s[42:43]
	v_cndmask_b32_e32 v105, 0, v199, vcc
	v_sub_f32_e32 v102, v102, v105
	v_add_f32_e32 v102, v103, v102
	v_sub_f32_e32 v102, -0.5, v102
	v_mul_f32_e32 v102, 0x3fb8aa3b, v102
	v_exp_f32_e32 v102, v102
	v_mov_b32_e32 v103, v1
	v_mul_f32_e32 v102, 0xbfb8aa3b, v102
	v_exp_f32_e32 v105, v102
	v_add_u32_e32 v102, v101, v107
	v_lshl_add_u64 v[102:103], v[102:103], 2, s[48:49]
	global_store_dword v[102:103], v105, off sc1
	v_add_f32_e32 v102, v17, v104
	v_max_f32_e64 v103, -v102, 0
	v_mul_f32_e64 v102, |v102|, s0
	v_exp_f32_e32 v102, v102
	s_nop 0
	v_add_f32_e32 v102, 1.0, v102
	v_cmp_gt_f32_e32 vcc, s31, v102
	s_nop 1
	v_cndmask_b32_e64 v104, 0, 32, vcc
	v_ldexp_f32 v102, v102, v104
	v_log_f32_e32 v102, v102
	s_nop 0
	v_mul_f32_e32 v104, 0x3f317217, v102
	v_fma_f32 v104, v102, s1, -v104
	v_fmac_f32_e32 v104, 0x3377d1cf, v102
	v_fmac_f32_e32 v104, 0x3f317217, v102
	v_cmp_lt_f32_e64 s[42:43], |v102|, s33
	s_nop 1
	v_cndmask_b32_e64 v102, v102, v104, s[42:43]
	v_cndmask_b32_e32 v104, 0, v199, vcc
	v_sub_f32_e32 v102, v102, v104
	v_add_f32_e32 v102, v103, v102
	v_sub_f32_e32 v102, -0.5, v102
	v_mul_f32_e32 v102, 0x3fb8aa3b, v102
	v_exp_f32_e32 v102, v102
	v_mov_b32_e32 v103, v1
	v_mul_f32_e32 v102, 0xbfb8aa3b, v102
	v_exp_f32_e32 v104, v102
	v_add_u32_e32 v102, v101, v110
	v_lshl_add_u64 v[102:103], v[102:103], 2, s[48:49]
	global_store_dword v[102:103], v104, off sc1

.LBB0_502:
	s_andn2_b64 vcc, exec, s[2:3]
	s_cbranch_vccnz .LBB0_504
	v_lshlrev_b32_e32 v244, 11, v108
	v_lshl_add_u32 v244, v100, 1, v244
	v_or_b32_e32 v249, v108, v146
	v_lshlrev_b32_e32 v249, 11, v249
	v_and_b32_e32 v250, -2, v100
	v_lshl_add_u32 v249, v250, 1, v249
	v_mov_b32_e32 v245, v244
	v_mov_b32_e32 v236, v249
	v_add_u32_e32 v246, 0x1000, v244
	v_add_u32_e32 v237, 0x1000, v249
	v_add_u32_e32 v247, 0x4000, v244
	v_add_u32_e32 v238, 0x4000, v249
	v_add_u32_e32 v248, 0x5000, v244
	v_add_u32_e32 v239, 0x5000, v249
	global_load_ushort v204, v245, s[52:53]
	global_load_ushort v205, v245, s[52:53] offset:2048
	global_load_ushort v206, v245, s[52:53] offset:64
	global_load_ushort v207, v245, s[52:53] offset:2112
	global_load_ushort v208, v246, s[52:53]
	global_load_ushort v209, v246, s[52:53] offset:2048
	global_load_ushort v210, v246, s[52:53] offset:64
	global_load_ushort v211, v246, s[52:53] offset:2112
	global_load_ushort v212, v247, s[52:53]
	global_load_ushort v213, v247, s[52:53] offset:2048
	global_load_ushort v214, v247, s[52:53] offset:64
	global_load_ushort v215, v247, s[52:53] offset:2112
	global_load_ushort v216, v248, s[52:53]
	global_load_ushort v217, v248, s[52:53] offset:2048
	global_load_ushort v218, v248, s[52:53] offset:64
	global_load_ushort v219, v248, s[52:53] offset:2112
	v_mul_f32_e32 v82, 0xbfb8aa3b, v82
	v_mul_f32_e32 v83, 0xbfb8aa3b, v83
	v_mul_f32_e32 v66, 0xbfb8aa3b, v66
	v_mul_f32_e32 v67, 0xbfb8aa3b, v67
	v_exp_f32_e32 v82, v82
	v_exp_f32_e32 v83, v83
	v_exp_f32_e32 v66, v66
	v_exp_f32_e32 v67, v67
	v_add_f32_e32 v82, 1.0, v82
	v_add_f32_e32 v83, 1.0, v83
	v_add_f32_e32 v66, 1.0, v66
	v_add_f32_e32 v67, 1.0, v67
	v_rcp_f32_e32 v82, v82
	v_rcp_f32_e32 v83, v83
	v_rcp_f32_e32 v66, v66
	v_rcp_f32_e32 v67, v67
	v_mul_f32_e32 v84, 0xbfb8aa3b, v84
	v_mul_f32_e32 v85, 0xbfb8aa3b, v85
	v_mul_f32_e32 v68, 0xbfb8aa3b, v68
	v_mul_f32_e32 v69, 0xbfb8aa3b, v69
	v_exp_f32_e32 v84, v84
	v_exp_f32_e32 v85, v85
	v_exp_f32_e32 v68, v68
	v_exp_f32_e32 v69, v69
	v_add_f32_e32 v84, 1.0, v84
	v_add_f32_e32 v85, 1.0, v85
	v_add_f32_e32 v68, 1.0, v68
	v_add_f32_e32 v69, 1.0, v69
	v_rcp_f32_e32 v84, v84
	v_rcp_f32_e32 v85, v85
	v_rcp_f32_e32 v68, v68
	v_rcp_f32_e32 v69, v69
	v_mul_f32_e32 v86, 0xbfb8aa3b, v86
	v_mul_f32_e32 v87, 0xbfb8aa3b, v87
	v_mul_f32_e32 v70, 0xbfb8aa3b, v70
	v_mul_f32_e32 v71, 0xbfb8aa3b, v71
	v_exp_f32_e32 v86, v86
	v_exp_f32_e32 v87, v87
	v_exp_f32_e32 v70, v70
	v_exp_f32_e32 v71, v71
	v_add_f32_e32 v86, 1.0, v86
	v_add_f32_e32 v87, 1.0, v87
	v_add_f32_e32 v70, 1.0, v70
	v_add_f32_e32 v71, 1.0, v71
	v_rcp_f32_e32 v86, v86
	v_rcp_f32_e32 v87, v87
	v_rcp_f32_e32 v70, v70
	v_rcp_f32_e32 v71, v71
	v_mul_f32_e32 v88, 0xbfb8aa3b, v88
	v_mul_f32_e32 v89, 0xbfb8aa3b, v89
	v_mul_f32_e32 v72, 0xbfb8aa3b, v72
	v_mul_f32_e32 v73, 0xbfb8aa3b, v73
	v_exp_f32_e32 v88, v88
	v_exp_f32_e32 v89, v89
	v_exp_f32_e32 v72, v72
	v_exp_f32_e32 v73, v73
	v_add_f32_e32 v88, 1.0, v88
	v_add_f32_e32 v89, 1.0, v89
	v_add_f32_e32 v72, 1.0, v72
	v_add_f32_e32 v73, 1.0, v73
	v_rcp_f32_e32 v88, v88
	v_rcp_f32_e32 v89, v89
	v_rcp_f32_e32 v72, v72
	v_rcp_f32_e32 v73, v73
	s_waitcnt vmcnt(0)
	v_lshlrev_b32_e32 v204, 16, v204
	v_lshlrev_b32_e32 v205, 16, v205
	v_lshlrev_b32_e32 v206, 16, v206
	v_lshlrev_b32_e32 v207, 16, v207
	v_lshlrev_b32_e32 v208, 16, v208
	v_lshlrev_b32_e32 v209, 16, v209
	v_lshlrev_b32_e32 v210, 16, v210
	v_lshlrev_b32_e32 v211, 16, v211
	v_lshlrev_b32_e32 v212, 16, v212
	v_lshlrev_b32_e32 v213, 16, v213
	v_lshlrev_b32_e32 v214, 16, v214
	v_lshlrev_b32_e32 v215, 16, v215
	v_lshlrev_b32_e32 v216, 16, v216
	v_lshlrev_b32_e32 v217, 16, v217
	v_lshlrev_b32_e32 v218, 16, v218
	v_lshlrev_b32_e32 v219, 16, v219
	v_mul_f32_e32 v204, v82, v204
	v_mul_f32_e32 v205, v83, v205
	v_mul_f32_e32 v206, v66, v206
	v_mul_f32_e32 v207, v67, v207
	v_mul_f32_e32 v208, v84, v208
	v_mul_f32_e32 v209, v85, v209
	v_mul_f32_e32 v210, v68, v210
	v_mul_f32_e32 v211, v69, v211
	v_mul_f32_e32 v212, v86, v212
	v_mul_f32_e32 v213, v87, v213
	v_mul_f32_e32 v214, v70, v214
	v_mul_f32_e32 v215, v71, v215
	v_mul_f32_e32 v216, v88, v216
	v_mul_f32_e32 v217, v89, v217
	v_mul_f32_e32 v218, v72, v218
	v_mul_f32_e32 v219, v73, v219
	v_cndmask_b32_e64 v220, v204, v205, s[40:41]
	v_cndmask_b32_e64 v221, v206, v207, s[40:41]
	v_cndmask_b32_e64 v222, v208, v209, s[40:41]
	v_cndmask_b32_e64 v223, v210, v211, s[40:41]
	v_cndmask_b32_e64 v224, v212, v213, s[40:41]
	v_cndmask_b32_e64 v225, v214, v215, s[40:41]
	v_cndmask_b32_e64 v226, v216, v217, s[40:41]
	v_cndmask_b32_e64 v227, v218, v219, s[40:41]
	v_mov_b32_dpp v220, v220 quad_perm:[1,0,3,2] row_mask:0xf bank_mask:0xf bound_ctrl:1
	v_mov_b32_dpp v221, v221 quad_perm:[1,0,3,2] row_mask:0xf bank_mask:0xf bound_ctrl:1
	v_mov_b32_dpp v222, v222 quad_perm:[1,0,3,2] row_mask:0xf bank_mask:0xf bound_ctrl:1
	v_mov_b32_dpp v223, v223 quad_perm:[1,0,3,2] row_mask:0xf bank_mask:0xf bound_ctrl:1
	v_mov_b32_dpp v224, v224 quad_perm:[1,0,3,2] row_mask:0xf bank_mask:0xf bound_ctrl:1
	v_mov_b32_dpp v225, v225 quad_perm:[1,0,3,2] row_mask:0xf bank_mask:0xf bound_ctrl:1
	v_mov_b32_dpp v226, v226 quad_perm:[1,0,3,2] row_mask:0xf bank_mask:0xf bound_ctrl:1
	v_mov_b32_dpp v227, v227 quad_perm:[1,0,3,2] row_mask:0xf bank_mask:0xf bound_ctrl:1
	v_cndmask_b32_e64 v204, v220, v204, s[40:41]
	v_cndmask_b32_e64 v205, v205, v220, s[40:41]
	v_cndmask_b32_e64 v206, v221, v206, s[40:41]
	v_cndmask_b32_e64 v207, v207, v221, s[40:41]
	v_cndmask_b32_e64 v208, v222, v208, s[40:41]
	v_cndmask_b32_e64 v209, v209, v222, s[40:41]
	v_cndmask_b32_e64 v210, v223, v210, s[40:41]
	v_cndmask_b32_e64 v211, v211, v223, s[40:41]
	v_cndmask_b32_e64 v212, v224, v212, s[40:41]
	v_cndmask_b32_e64 v213, v213, v224, s[40:41]
	v_cndmask_b32_e64 v214, v225, v214, s[40:41]
	v_cndmask_b32_e64 v215, v215, v225, s[40:41]
	v_cndmask_b32_e64 v216, v226, v216, s[40:41]
	v_cndmask_b32_e64 v217, v217, v226, s[40:41]
	v_cndmask_b32_e64 v218, v227, v218, s[40:41]
	v_cndmask_b32_e64 v219, v219, v227, s[40:41]
	v_cvt_pk_bf16_f32 v204, v204, v205
	v_cvt_pk_bf16_f32 v206, v206, v207
	v_cvt_pk_bf16_f32 v208, v208, v209
	v_cvt_pk_bf16_f32 v210, v210, v211
	v_cvt_pk_bf16_f32 v212, v212, v213
	v_cvt_pk_bf16_f32 v214, v214, v215
	v_cvt_pk_bf16_f32 v216, v216, v217
	v_cvt_pk_bf16_f32 v218, v218, v219
	global_store_dword v236, v204, s[54:55] sc1
	global_store_dword v236, v206, s[54:55] offset:64 sc1
	global_store_dword v237, v208, s[54:55] sc1
	global_store_dword v237, v210, s[54:55] offset:64 sc1
	global_store_dword v238, v212, s[54:55] sc1
	global_store_dword v238, v214, s[54:55] offset:64 sc1
	global_store_dword v239, v216, s[54:55] sc1
	global_store_dword v239, v218, s[54:55] offset:64 sc1
	v_add_u32_e32 v245, 0x8000, v244
	v_add_u32_e32 v236, 0x8000, v249
	v_add_u32_e32 v246, 0x9000, v244
	v_add_u32_e32 v237, 0x9000, v249
	v_add_u32_e32 v247, 0xc000, v244
	v_add_u32_e32 v238, 0xc000, v249
	v_add_u32_e32 v248, 0xd000, v244
	v_add_u32_e32 v239, 0xd000, v249
	global_load_ushort v204, v245, s[52:53]
	global_load_ushort v205, v245, s[52:53] offset:2048
	global_load_ushort v206, v245, s[52:53] offset:64
	global_load_ushort v207, v245, s[52:53] offset:2112
	global_load_ushort v208, v246, s[52:53]
	global_load_ushort v209, v246, s[52:53] offset:2048
	global_load_ushort v210, v246, s[52:53] offset:64
	global_load_ushort v211, v246, s[52:53] offset:2112
	global_load_ushort v212, v247, s[52:53]
	global_load_ushort v213, v247, s[52:53] offset:2048
	global_load_ushort v214, v247, s[52:53] offset:64
	global_load_ushort v215, v247, s[52:53] offset:2112
	global_load_ushort v216, v248, s[52:53]
	global_load_ushort v217, v248, s[52:53] offset:2048
	global_load_ushort v218, v248, s[52:53] offset:64
	global_load_ushort v219, v248, s[52:53] offset:2112
	v_mul_f32_e32 v90, 0xbfb8aa3b, v90
	v_mul_f32_e32 v91, 0xbfb8aa3b, v91
	v_mul_f32_e32 v74, 0xbfb8aa3b, v74
	v_mul_f32_e32 v75, 0xbfb8aa3b, v75
	v_exp_f32_e32 v90, v90
	v_exp_f32_e32 v91, v91
	v_exp_f32_e32 v74, v74
	v_exp_f32_e32 v75, v75
	v_add_f32_e32 v90, 1.0, v90
	v_add_f32_e32 v91, 1.0, v91
	v_add_f32_e32 v74, 1.0, v74
	v_add_f32_e32 v75, 1.0, v75
	v_rcp_f32_e32 v90, v90
	v_rcp_f32_e32 v91, v91
	v_rcp_f32_e32 v74, v74
	v_rcp_f32_e32 v75, v75
	v_mul_f32_e32 v92, 0xbfb8aa3b, v92
	v_mul_f32_e32 v93, 0xbfb8aa3b, v93
	v_mul_f32_e32 v76, 0xbfb8aa3b, v76
	v_mul_f32_e32 v77, 0xbfb8aa3b, v77
	v_exp_f32_e32 v92, v92
	v_exp_f32_e32 v93, v93
	v_exp_f32_e32 v76, v76
	v_exp_f32_e32 v77, v77
	v_add_f32_e32 v92, 1.0, v92
	v_add_f32_e32 v93, 1.0, v93
	v_add_f32_e32 v76, 1.0, v76
	v_add_f32_e32 v77, 1.0, v77
	v_rcp_f32_e32 v92, v92
	v_rcp_f32_e32 v93, v93
	v_rcp_f32_e32 v76, v76
	v_rcp_f32_e32 v77, v77
	v_mul_f32_e32 v94, 0xbfb8aa3b, v94
	v_mul_f32_e32 v95, 0xbfb8aa3b, v95
	v_mul_f32_e32 v78, 0xbfb8aa3b, v78
	v_mul_f32_e32 v79, 0xbfb8aa3b, v79
	v_exp_f32_e32 v94, v94
	v_exp_f32_e32 v95, v95
	v_exp_f32_e32 v78, v78
	v_exp_f32_e32 v79, v79
	v_add_f32_e32 v94, 1.0, v94
	v_add_f32_e32 v95, 1.0, v95
	v_add_f32_e32 v78, 1.0, v78
	v_add_f32_e32 v79, 1.0, v79
	v_rcp_f32_e32 v94, v94
	v_rcp_f32_e32 v95, v95
	v_rcp_f32_e32 v78, v78
	v_rcp_f32_e32 v79, v79
	v_mul_f32_e32 v96, 0xbfb8aa3b, v96
	v_mul_f32_e32 v97, 0xbfb8aa3b, v97
	v_mul_f32_e32 v80, 0xbfb8aa3b, v80
	v_mul_f32_e32 v81, 0xbfb8aa3b, v81
	v_exp_f32_e32 v96, v96
	v_exp_f32_e32 v97, v97
	v_exp_f32_e32 v80, v80
	v_exp_f32_e32 v81, v81
	v_add_f32_e32 v96, 1.0, v96
	v_add_f32_e32 v97, 1.0, v97
	v_add_f32_e32 v80, 1.0, v80
	v_add_f32_e32 v81, 1.0, v81
	v_rcp_f32_e32 v96, v96
	v_rcp_f32_e32 v97, v97
	v_rcp_f32_e32 v80, v80
	v_rcp_f32_e32 v81, v81
	s_waitcnt vmcnt(0)
	v_lshlrev_b32_e32 v204, 16, v204
	v_lshlrev_b32_e32 v205, 16, v205
	v_lshlrev_b32_e32 v206, 16, v206
	v_lshlrev_b32_e32 v207, 16, v207
	v_lshlrev_b32_e32 v208, 16, v208
	v_lshlrev_b32_e32 v209, 16, v209
	v_lshlrev_b32_e32 v210, 16, v210
	v_lshlrev_b32_e32 v211, 16, v211
	v_lshlrev_b32_e32 v212, 16, v212
	v_lshlrev_b32_e32 v213, 16, v213
	v_lshlrev_b32_e32 v214, 16, v214
	v_lshlrev_b32_e32 v215, 16, v215
	v_lshlrev_b32_e32 v216, 16, v216
	v_lshlrev_b32_e32 v217, 16, v217
	v_lshlrev_b32_e32 v218, 16, v218
	v_lshlrev_b32_e32 v219, 16, v219
	v_mul_f32_e32 v204, v90, v204
	v_mul_f32_e32 v205, v91, v205
	v_mul_f32_e32 v206, v74, v206
	v_mul_f32_e32 v207, v75, v207
	v_mul_f32_e32 v208, v92, v208
	v_mul_f32_e32 v209, v93, v209
	v_mul_f32_e32 v210, v76, v210
	v_mul_f32_e32 v211, v77, v211
	v_mul_f32_e32 v212, v94, v212
	v_mul_f32_e32 v213, v95, v213
	v_mul_f32_e32 v214, v78, v214
	v_mul_f32_e32 v215, v79, v215
	v_mul_f32_e32 v216, v96, v216
	v_mul_f32_e32 v217, v97, v217
	v_mul_f32_e32 v218, v80, v218
	v_mul_f32_e32 v219, v81, v219
	v_cndmask_b32_e64 v220, v204, v205, s[40:41]
	v_cndmask_b32_e64 v221, v206, v207, s[40:41]
	v_cndmask_b32_e64 v222, v208, v209, s[40:41]
	v_cndmask_b32_e64 v223, v210, v211, s[40:41]
	v_cndmask_b32_e64 v224, v212, v213, s[40:41]
	v_cndmask_b32_e64 v225, v214, v215, s[40:41]
	v_cndmask_b32_e64 v226, v216, v217, s[40:41]
	v_cndmask_b32_e64 v227, v218, v219, s[40:41]
	v_mov_b32_dpp v220, v220 quad_perm:[1,0,3,2] row_mask:0xf bank_mask:0xf bound_ctrl:1
	v_mov_b32_dpp v221, v221 quad_perm:[1,0,3,2] row_mask:0xf bank_mask:0xf bound_ctrl:1
	v_mov_b32_dpp v222, v222 quad_perm:[1,0,3,2] row_mask:0xf bank_mask:0xf bound_ctrl:1
	v_mov_b32_dpp v223, v223 quad_perm:[1,0,3,2] row_mask:0xf bank_mask:0xf bound_ctrl:1
	v_mov_b32_dpp v224, v224 quad_perm:[1,0,3,2] row_mask:0xf bank_mask:0xf bound_ctrl:1
	v_mov_b32_dpp v225, v225 quad_perm:[1,0,3,2] row_mask:0xf bank_mask:0xf bound_ctrl:1
	v_mov_b32_dpp v226, v226 quad_perm:[1,0,3,2] row_mask:0xf bank_mask:0xf bound_ctrl:1
	v_mov_b32_dpp v227, v227 quad_perm:[1,0,3,2] row_mask:0xf bank_mask:0xf bound_ctrl:1
	v_cndmask_b32_e64 v204, v220, v204, s[40:41]
	v_cndmask_b32_e64 v205, v205, v220, s[40:41]
	v_cndmask_b32_e64 v206, v221, v206, s[40:41]
	v_cndmask_b32_e64 v207, v207, v221, s[40:41]
	v_cndmask_b32_e64 v208, v222, v208, s[40:41]
	v_cndmask_b32_e64 v209, v209, v222, s[40:41]
	v_cndmask_b32_e64 v210, v223, v210, s[40:41]
	v_cndmask_b32_e64 v211, v211, v223, s[40:41]
	v_cndmask_b32_e64 v212, v224, v212, s[40:41]
	v_cndmask_b32_e64 v213, v213, v224, s[40:41]
	v_cndmask_b32_e64 v214, v225, v214, s[40:41]
	v_cndmask_b32_e64 v215, v215, v225, s[40:41]
	v_cndmask_b32_e64 v216, v226, v216, s[40:41]
	v_cndmask_b32_e64 v217, v217, v226, s[40:41]
	v_cndmask_b32_e64 v218, v227, v218, s[40:41]
	v_cndmask_b32_e64 v219, v219, v227, s[40:41]
	v_cvt_pk_bf16_f32 v204, v204, v205
	v_cvt_pk_bf16_f32 v206, v206, v207
	v_cvt_pk_bf16_f32 v208, v208, v209
	v_cvt_pk_bf16_f32 v210, v210, v211
	v_cvt_pk_bf16_f32 v212, v212, v213
	v_cvt_pk_bf16_f32 v214, v214, v215
	v_cvt_pk_bf16_f32 v216, v216, v217
	v_cvt_pk_bf16_f32 v218, v218, v219
	global_store_dword v236, v204, s[54:55] sc1
	global_store_dword v236, v206, s[54:55] offset:64 sc1
	global_store_dword v237, v208, s[54:55] sc1
	global_store_dword v237, v210, s[54:55] offset:64 sc1
	global_store_dword v238, v212, s[54:55] sc1
	global_store_dword v238, v214, s[54:55] offset:64 sc1
	global_store_dword v239, v216, s[54:55] sc1
	global_store_dword v239, v218, s[54:55] offset:64 sc1
	v_add_u32_e32 v245, 0x10000, v244
	v_add_u32_e32 v236, 0x10000, v249
	v_add_u32_e32 v246, 0x11000, v244
	v_add_u32_e32 v237, 0x11000, v249
	v_add_u32_e32 v247, 0x14000, v244
	v_add_u32_e32 v238, 0x14000, v249
	v_add_u32_e32 v248, 0x15000, v244
	v_add_u32_e32 v239, 0x15000, v249
	global_load_ushort v204, v245, s[52:53]
	global_load_ushort v205, v245, s[52:53] offset:2048
	global_load_ushort v206, v245, s[52:53] offset:64
	global_load_ushort v207, v245, s[52:53] offset:2112
	global_load_ushort v208, v246, s[52:53]
	global_load_ushort v209, v246, s[52:53] offset:2048
	global_load_ushort v210, v246, s[52:53] offset:64
	global_load_ushort v211, v246, s[52:53] offset:2112
	global_load_ushort v212, v247, s[52:53]
	global_load_ushort v213, v247, s[52:53] offset:2048
	global_load_ushort v214, v247, s[52:53] offset:64
	global_load_ushort v215, v247, s[52:53] offset:2112
	global_load_ushort v216, v248, s[52:53]
	global_load_ushort v217, v248, s[52:53] offset:2048
	global_load_ushort v218, v248, s[52:53] offset:64
	global_load_ushort v219, v248, s[52:53] offset:2112
	v_mul_f32_e32 v50, 0xbfb8aa3b, v50
	v_mul_f32_e32 v51, 0xbfb8aa3b, v51
	v_mul_f32_e32 v34, 0xbfb8aa3b, v34
	v_mul_f32_e32 v35, 0xbfb8aa3b, v35
	v_exp_f32_e32 v50, v50
	v_exp_f32_e32 v51, v51
	v_exp_f32_e32 v34, v34
	v_exp_f32_e32 v35, v35
	v_add_f32_e32 v50, 1.0, v50
	v_add_f32_e32 v51, 1.0, v51
	v_add_f32_e32 v34, 1.0, v34
	v_add_f32_e32 v35, 1.0, v35
	v_rcp_f32_e32 v50, v50
	v_rcp_f32_e32 v51, v51
	v_rcp_f32_e32 v34, v34
	v_rcp_f32_e32 v35, v35
	v_mul_f32_e32 v52, 0xbfb8aa3b, v52
	v_mul_f32_e32 v53, 0xbfb8aa3b, v53
	v_mul_f32_e32 v36, 0xbfb8aa3b, v36
	v_mul_f32_e32 v37, 0xbfb8aa3b, v37
	v_exp_f32_e32 v52, v52
	v_exp_f32_e32 v53, v53
	v_exp_f32_e32 v36, v36
	v_exp_f32_e32 v37, v37
	v_add_f32_e32 v52, 1.0, v52
	v_add_f32_e32 v53, 1.0, v53
	v_add_f32_e32 v36, 1.0, v36
	v_add_f32_e32 v37, 1.0, v37
	v_rcp_f32_e32 v52, v52
	v_rcp_f32_e32 v53, v53
	v_rcp_f32_e32 v36, v36
	v_rcp_f32_e32 v37, v37
	v_mul_f32_e32 v54, 0xbfb8aa3b, v54
	v_mul_f32_e32 v55, 0xbfb8aa3b, v55
	v_mul_f32_e32 v38, 0xbfb8aa3b, v38
	v_mul_f32_e32 v39, 0xbfb8aa3b, v39
	v_exp_f32_e32 v54, v54
	v_exp_f32_e32 v55, v55
	v_exp_f32_e32 v38, v38
	v_exp_f32_e32 v39, v39
	v_add_f32_e32 v54, 1.0, v54
	v_add_f32_e32 v55, 1.0, v55
	v_add_f32_e32 v38, 1.0, v38
	v_add_f32_e32 v39, 1.0, v39
	v_rcp_f32_e32 v54, v54
	v_rcp_f32_e32 v55, v55
	v_rcp_f32_e32 v38, v38
	v_rcp_f32_e32 v39, v39
	v_mul_f32_e32 v56, 0xbfb8aa3b, v56
	v_mul_f32_e32 v57, 0xbfb8aa3b, v57
	v_mul_f32_e32 v40, 0xbfb8aa3b, v40
	v_mul_f32_e32 v41, 0xbfb8aa3b, v41
	v_exp_f32_e32 v56, v56
	v_exp_f32_e32 v57, v57
	v_exp_f32_e32 v40, v40
	v_exp_f32_e32 v41, v41
	v_add_f32_e32 v56, 1.0, v56
	v_add_f32_e32 v57, 1.0, v57
	v_add_f32_e32 v40, 1.0, v40
	v_add_f32_e32 v41, 1.0, v41
	v_rcp_f32_e32 v56, v56
	v_rcp_f32_e32 v57, v57
	v_rcp_f32_e32 v40, v40
	v_rcp_f32_e32 v41, v41
	s_waitcnt vmcnt(0)
	v_lshlrev_b32_e32 v204, 16, v204
	v_lshlrev_b32_e32 v205, 16, v205
	v_lshlrev_b32_e32 v206, 16, v206
	v_lshlrev_b32_e32 v207, 16, v207
	v_lshlrev_b32_e32 v208, 16, v208
	v_lshlrev_b32_e32 v209, 16, v209
	v_lshlrev_b32_e32 v210, 16, v210
	v_lshlrev_b32_e32 v211, 16, v211
	v_lshlrev_b32_e32 v212, 16, v212
	v_lshlrev_b32_e32 v213, 16, v213
	v_lshlrev_b32_e32 v214, 16, v214
	v_lshlrev_b32_e32 v215, 16, v215
	v_lshlrev_b32_e32 v216, 16, v216
	v_lshlrev_b32_e32 v217, 16, v217
	v_lshlrev_b32_e32 v218, 16, v218
	v_lshlrev_b32_e32 v219, 16, v219
	v_mul_f32_e32 v204, v50, v204
	v_mul_f32_e32 v205, v51, v205
	v_mul_f32_e32 v206, v34, v206
	v_mul_f32_e32 v207, v35, v207
	v_mul_f32_e32 v208, v52, v208
	v_mul_f32_e32 v209, v53, v209
	v_mul_f32_e32 v210, v36, v210
	v_mul_f32_e32 v211, v37, v211
	v_mul_f32_e32 v212, v54, v212
	v_mul_f32_e32 v213, v55, v213
	v_mul_f32_e32 v214, v38, v214
	v_mul_f32_e32 v215, v39, v215
	v_mul_f32_e32 v216, v56, v216
	v_mul_f32_e32 v217, v57, v217
	v_mul_f32_e32 v218, v40, v218
	v_mul_f32_e32 v219, v41, v219
	v_cndmask_b32_e64 v220, v204, v205, s[40:41]
	v_cndmask_b32_e64 v221, v206, v207, s[40:41]
	v_cndmask_b32_e64 v222, v208, v209, s[40:41]
	v_cndmask_b32_e64 v223, v210, v211, s[40:41]
	v_cndmask_b32_e64 v224, v212, v213, s[40:41]
	v_cndmask_b32_e64 v225, v214, v215, s[40:41]
	v_cndmask_b32_e64 v226, v216, v217, s[40:41]
	v_cndmask_b32_e64 v227, v218, v219, s[40:41]
	v_mov_b32_dpp v220, v220 quad_perm:[1,0,3,2] row_mask:0xf bank_mask:0xf bound_ctrl:1
	v_mov_b32_dpp v221, v221 quad_perm:[1,0,3,2] row_mask:0xf bank_mask:0xf bound_ctrl:1
	v_mov_b32_dpp v222, v222 quad_perm:[1,0,3,2] row_mask:0xf bank_mask:0xf bound_ctrl:1
	v_mov_b32_dpp v223, v223 quad_perm:[1,0,3,2] row_mask:0xf bank_mask:0xf bound_ctrl:1
	v_mov_b32_dpp v224, v224 quad_perm:[1,0,3,2] row_mask:0xf bank_mask:0xf bound_ctrl:1
	v_mov_b32_dpp v225, v225 quad_perm:[1,0,3,2] row_mask:0xf bank_mask:0xf bound_ctrl:1
	v_mov_b32_dpp v226, v226 quad_perm:[1,0,3,2] row_mask:0xf bank_mask:0xf bound_ctrl:1
	v_mov_b32_dpp v227, v227 quad_perm:[1,0,3,2] row_mask:0xf bank_mask:0xf bound_ctrl:1
	v_cndmask_b32_e64 v204, v220, v204, s[40:41]
	v_cndmask_b32_e64 v205, v205, v220, s[40:41]
	v_cndmask_b32_e64 v206, v221, v206, s[40:41]
	v_cndmask_b32_e64 v207, v207, v221, s[40:41]
	v_cndmask_b32_e64 v208, v222, v208, s[40:41]
	v_cndmask_b32_e64 v209, v209, v222, s[40:41]
	v_cndmask_b32_e64 v210, v223, v210, s[40:41]
	v_cndmask_b32_e64 v211, v211, v223, s[40:41]
	v_cndmask_b32_e64 v212, v224, v212, s[40:41]
	v_cndmask_b32_e64 v213, v213, v224, s[40:41]
	v_cndmask_b32_e64 v214, v225, v214, s[40:41]
	v_cndmask_b32_e64 v215, v215, v225, s[40:41]
	v_cndmask_b32_e64 v216, v226, v216, s[40:41]
	v_cndmask_b32_e64 v217, v217, v226, s[40:41]
	v_cndmask_b32_e64 v218, v227, v218, s[40:41]
	v_cndmask_b32_e64 v219, v219, v227, s[40:41]
	v_cvt_pk_bf16_f32 v204, v204, v205
	v_cvt_pk_bf16_f32 v206, v206, v207
	v_cvt_pk_bf16_f32 v208, v208, v209
	v_cvt_pk_bf16_f32 v210, v210, v211
	v_cvt_pk_bf16_f32 v212, v212, v213
	v_cvt_pk_bf16_f32 v214, v214, v215
	v_cvt_pk_bf16_f32 v216, v216, v217
	v_cvt_pk_bf16_f32 v218, v218, v219
	global_store_dword v236, v204, s[54:55] sc1
	global_store_dword v236, v206, s[54:55] offset:64 sc1
	global_store_dword v237, v208, s[54:55] sc1
	global_store_dword v237, v210, s[54:55] offset:64 sc1
	global_store_dword v238, v212, s[54:55] sc1
	global_store_dword v238, v214, s[54:55] offset:64 sc1
	global_store_dword v239, v216, s[54:55] sc1
	global_store_dword v239, v218, s[54:55] offset:64 sc1
	v_add_u32_e32 v245, 0x18000, v244
	v_add_u32_e32 v236, 0x18000, v249
	v_add_u32_e32 v246, 0x19000, v244
	v_add_u32_e32 v237, 0x19000, v249
	v_add_u32_e32 v247, 0x1c000, v244
	v_add_u32_e32 v238, 0x1c000, v249
	v_add_u32_e32 v248, 0x1d000, v244
	v_add_u32_e32 v239, 0x1d000, v249
	global_load_ushort v204, v245, s[52:53]
	global_load_ushort v205, v245, s[52:53] offset:2048
	global_load_ushort v206, v245, s[52:53] offset:64
	global_load_ushort v207, v245, s[52:53] offset:2112
	global_load_ushort v208, v246, s[52:53]
	global_load_ushort v209, v246, s[52:53] offset:2048
	global_load_ushort v210, v246, s[52:53] offset:64
	global_load_ushort v211, v246, s[52:53] offset:2112
	global_load_ushort v212, v247, s[52:53]
	global_load_ushort v213, v247, s[52:53] offset:2048
	global_load_ushort v214, v247, s[52:53] offset:64
	global_load_ushort v215, v247, s[52:53] offset:2112
	global_load_ushort v216, v248, s[52:53]
	global_load_ushort v217, v248, s[52:53] offset:2048
	global_load_ushort v218, v248, s[52:53] offset:64
	global_load_ushort v219, v248, s[52:53] offset:2112
	v_mul_f32_e32 v58, 0xbfb8aa3b, v58
	v_mul_f32_e32 v59, 0xbfb8aa3b, v59
	v_mul_f32_e32 v42, 0xbfb8aa3b, v42
	v_mul_f32_e32 v43, 0xbfb8aa3b, v43
	v_exp_f32_e32 v58, v58
	v_exp_f32_e32 v59, v59
	v_exp_f32_e32 v42, v42
	v_exp_f32_e32 v43, v43
	v_add_f32_e32 v58, 1.0, v58
	v_add_f32_e32 v59, 1.0, v59
	v_add_f32_e32 v42, 1.0, v42
	v_add_f32_e32 v43, 1.0, v43
	v_rcp_f32_e32 v58, v58
	v_rcp_f32_e32 v59, v59
	v_rcp_f32_e32 v42, v42
	v_rcp_f32_e32 v43, v43
	v_mul_f32_e32 v60, 0xbfb8aa3b, v60
	v_mul_f32_e32 v61, 0xbfb8aa3b, v61
	v_mul_f32_e32 v44, 0xbfb8aa3b, v44
	v_mul_f32_e32 v45, 0xbfb8aa3b, v45
	v_exp_f32_e32 v60, v60
	v_exp_f32_e32 v61, v61
	v_exp_f32_e32 v44, v44
	v_exp_f32_e32 v45, v45
	v_add_f32_e32 v60, 1.0, v60
	v_add_f32_e32 v61, 1.0, v61
	v_add_f32_e32 v44, 1.0, v44
	v_add_f32_e32 v45, 1.0, v45
	v_rcp_f32_e32 v60, v60
	v_rcp_f32_e32 v61, v61
	v_rcp_f32_e32 v44, v44
	v_rcp_f32_e32 v45, v45
	v_mul_f32_e32 v62, 0xbfb8aa3b, v62
	v_mul_f32_e32 v63, 0xbfb8aa3b, v63
	v_mul_f32_e32 v46, 0xbfb8aa3b, v46
	v_mul_f32_e32 v47, 0xbfb8aa3b, v47
	v_exp_f32_e32 v62, v62
	v_exp_f32_e32 v63, v63
	v_exp_f32_e32 v46, v46
	v_exp_f32_e32 v47, v47
	v_add_f32_e32 v62, 1.0, v62
	v_add_f32_e32 v63, 1.0, v63
	v_add_f32_e32 v46, 1.0, v46
	v_add_f32_e32 v47, 1.0, v47
	v_rcp_f32_e32 v62, v62
	v_rcp_f32_e32 v63, v63
	v_rcp_f32_e32 v46, v46
	v_rcp_f32_e32 v47, v47
	v_mul_f32_e32 v64, 0xbfb8aa3b, v64
	v_mul_f32_e32 v65, 0xbfb8aa3b, v65
	v_mul_f32_e32 v48, 0xbfb8aa3b, v48
	v_mul_f32_e32 v49, 0xbfb8aa3b, v49
	v_exp_f32_e32 v64, v64
	v_exp_f32_e32 v65, v65
	v_exp_f32_e32 v48, v48
	v_exp_f32_e32 v49, v49
	v_add_f32_e32 v64, 1.0, v64
	v_add_f32_e32 v65, 1.0, v65
	v_add_f32_e32 v48, 1.0, v48
	v_add_f32_e32 v49, 1.0, v49
	v_rcp_f32_e32 v64, v64
	v_rcp_f32_e32 v65, v65
	v_rcp_f32_e32 v48, v48
	v_rcp_f32_e32 v49, v49
	s_waitcnt vmcnt(0)
	v_lshlrev_b32_e32 v204, 16, v204
	v_lshlrev_b32_e32 v205, 16, v205
	v_lshlrev_b32_e32 v206, 16, v206
	v_lshlrev_b32_e32 v207, 16, v207
	v_lshlrev_b32_e32 v208, 16, v208
	v_lshlrev_b32_e32 v209, 16, v209
	v_lshlrev_b32_e32 v210, 16, v210
	v_lshlrev_b32_e32 v211, 16, v211
	v_lshlrev_b32_e32 v212, 16, v212
	v_lshlrev_b32_e32 v213, 16, v213
	v_lshlrev_b32_e32 v214, 16, v214
	v_lshlrev_b32_e32 v215, 16, v215
	v_lshlrev_b32_e32 v216, 16, v216
	v_lshlrev_b32_e32 v217, 16, v217
	v_lshlrev_b32_e32 v218, 16, v218
	v_lshlrev_b32_e32 v219, 16, v219
	v_mul_f32_e32 v204, v58, v204
	v_mul_f32_e32 v205, v59, v205
	v_mul_f32_e32 v206, v42, v206
	v_mul_f32_e32 v207, v43, v207
	v_mul_f32_e32 v208, v60, v208
	v_mul_f32_e32 v209, v61, v209
	v_mul_f32_e32 v210, v44, v210
	v_mul_f32_e32 v211, v45, v211
	v_mul_f32_e32 v212, v62, v212
	v_mul_f32_e32 v213, v63, v213
	v_mul_f32_e32 v214, v46, v214
	v_mul_f32_e32 v215, v47, v215
	v_mul_f32_e32 v216, v64, v216
	v_mul_f32_e32 v217, v65, v217
	v_mul_f32_e32 v218, v48, v218
	v_mul_f32_e32 v219, v49, v219
	v_cndmask_b32_e64 v220, v204, v205, s[40:41]
	v_cndmask_b32_e64 v221, v206, v207, s[40:41]
	v_cndmask_b32_e64 v222, v208, v209, s[40:41]
	v_cndmask_b32_e64 v223, v210, v211, s[40:41]
	v_cndmask_b32_e64 v224, v212, v213, s[40:41]
	v_cndmask_b32_e64 v225, v214, v215, s[40:41]
	v_cndmask_b32_e64 v226, v216, v217, s[40:41]
	v_cndmask_b32_e64 v227, v218, v219, s[40:41]
	v_mov_b32_dpp v220, v220 quad_perm:[1,0,3,2] row_mask:0xf bank_mask:0xf bound_ctrl:1
	v_mov_b32_dpp v221, v221 quad_perm:[1,0,3,2] row_mask:0xf bank_mask:0xf bound_ctrl:1
	v_mov_b32_dpp v222, v222 quad_perm:[1,0,3,2] row_mask:0xf bank_mask:0xf bound_ctrl:1
	v_mov_b32_dpp v223, v223 quad_perm:[1,0,3,2] row_mask:0xf bank_mask:0xf bound_ctrl:1
	v_mov_b32_dpp v224, v224 quad_perm:[1,0,3,2] row_mask:0xf bank_mask:0xf bound_ctrl:1
	v_mov_b32_dpp v225, v225 quad_perm:[1,0,3,2] row_mask:0xf bank_mask:0xf bound_ctrl:1
	v_mov_b32_dpp v226, v226 quad_perm:[1,0,3,2] row_mask:0xf bank_mask:0xf bound_ctrl:1
	v_mov_b32_dpp v227, v227 quad_perm:[1,0,3,2] row_mask:0xf bank_mask:0xf bound_ctrl:1
	v_cndmask_b32_e64 v204, v220, v204, s[40:41]
	v_cndmask_b32_e64 v205, v205, v220, s[40:41]
	v_cndmask_b32_e64 v206, v221, v206, s[40:41]
	v_cndmask_b32_e64 v207, v207, v221, s[40:41]
	v_cndmask_b32_e64 v208, v222, v208, s[40:41]
	v_cndmask_b32_e64 v209, v209, v222, s[40:41]
	v_cndmask_b32_e64 v210, v223, v210, s[40:41]
	v_cndmask_b32_e64 v211, v211, v223, s[40:41]
	v_cndmask_b32_e64 v212, v224, v212, s[40:41]
	v_cndmask_b32_e64 v213, v213, v224, s[40:41]
	v_cndmask_b32_e64 v214, v225, v214, s[40:41]
	v_cndmask_b32_e64 v215, v215, v225, s[40:41]
	v_cndmask_b32_e64 v216, v226, v216, s[40:41]
	v_cndmask_b32_e64 v217, v217, v226, s[40:41]
	v_cndmask_b32_e64 v218, v227, v218, s[40:41]
	v_cndmask_b32_e64 v219, v219, v227, s[40:41]
	v_cvt_pk_bf16_f32 v204, v204, v205
	v_cvt_pk_bf16_f32 v206, v206, v207
	v_cvt_pk_bf16_f32 v208, v208, v209
	v_cvt_pk_bf16_f32 v210, v210, v211
	v_cvt_pk_bf16_f32 v212, v212, v213
	v_cvt_pk_bf16_f32 v214, v214, v215
	v_cvt_pk_bf16_f32 v216, v216, v217
	v_cvt_pk_bf16_f32 v218, v218, v219
	global_store_dword v236, v204, s[54:55] sc1
	global_store_dword v236, v206, s[54:55] offset:64 sc1
	global_store_dword v237, v208, s[54:55] sc1
	global_store_dword v237, v210, s[54:55] offset:64 sc1
	global_store_dword v238, v212, s[54:55] sc1
	global_store_dword v238, v214, s[54:55] offset:64 sc1
	global_store_dword v239, v216, s[54:55] sc1
	global_store_dword v239, v218, s[54:55] offset:64 sc1
	v_add_u32_e32 v245, 0x20000, v244
	v_add_u32_e32 v236, 0x20000, v249
	v_add_u32_e32 v246, 0x21000, v244
	v_add_u32_e32 v237, 0x21000, v249
	v_add_u32_e32 v247, 0x24000, v244
	v_add_u32_e32 v238, 0x24000, v249
	v_add_u32_e32 v248, 0x25000, v244
	v_add_u32_e32 v239, 0x25000, v249
	global_load_ushort v204, v245, s[52:53]
	global_load_ushort v205, v245, s[52:53] offset:2048
	global_load_ushort v206, v245, s[52:53] offset:64
	global_load_ushort v207, v245, s[52:53] offset:2112
	global_load_ushort v208, v246, s[52:53]
	global_load_ushort v209, v246, s[52:53] offset:2048
	global_load_ushort v210, v246, s[52:53] offset:64
	global_load_ushort v211, v246, s[52:53] offset:2112
	global_load_ushort v212, v247, s[52:53]
	global_load_ushort v213, v247, s[52:53] offset:2048
	global_load_ushort v214, v247, s[52:53] offset:64
	global_load_ushort v215, v247, s[52:53] offset:2112
	global_load_ushort v216, v248, s[52:53]
	global_load_ushort v217, v248, s[52:53] offset:2048
	global_load_ushort v218, v248, s[52:53] offset:64
	global_load_ushort v219, v248, s[52:53] offset:2112
	v_mul_f32_e32 v18, 0xbfb8aa3b, v18
	v_mul_f32_e32 v19, 0xbfb8aa3b, v19
	v_mul_f32_e32 v2, 0xbfb8aa3b, v2
	v_mul_f32_e32 v3, 0xbfb8aa3b, v3
	v_exp_f32_e32 v18, v18
	v_exp_f32_e32 v19, v19
	v_exp_f32_e32 v2, v2
	v_exp_f32_e32 v3, v3
	v_add_f32_e32 v18, 1.0, v18
	v_add_f32_e32 v19, 1.0, v19
	v_add_f32_e32 v2, 1.0, v2
	v_add_f32_e32 v3, 1.0, v3
	v_rcp_f32_e32 v18, v18
	v_rcp_f32_e32 v19, v19
	v_rcp_f32_e32 v2, v2
	v_rcp_f32_e32 v3, v3
	v_mul_f32_e32 v20, 0xbfb8aa3b, v20
	v_mul_f32_e32 v21, 0xbfb8aa3b, v21
	v_mul_f32_e32 v4, 0xbfb8aa3b, v4
	v_mul_f32_e32 v5, 0xbfb8aa3b, v5
	v_exp_f32_e32 v20, v20
	v_exp_f32_e32 v21, v21
	v_exp_f32_e32 v4, v4
	v_exp_f32_e32 v5, v5
	v_add_f32_e32 v20, 1.0, v20
	v_add_f32_e32 v21, 1.0, v21
	v_add_f32_e32 v4, 1.0, v4
	v_add_f32_e32 v5, 1.0, v5
	v_rcp_f32_e32 v20, v20
	v_rcp_f32_e32 v21, v21
	v_rcp_f32_e32 v4, v4
	v_rcp_f32_e32 v5, v5
	v_mul_f32_e32 v22, 0xbfb8aa3b, v22
	v_mul_f32_e32 v23, 0xbfb8aa3b, v23
	v_mul_f32_e32 v6, 0xbfb8aa3b, v6
	v_mul_f32_e32 v7, 0xbfb8aa3b, v7
	v_exp_f32_e32 v22, v22
	v_exp_f32_e32 v23, v23
	v_exp_f32_e32 v6, v6
	v_exp_f32_e32 v7, v7
	v_add_f32_e32 v22, 1.0, v22
	v_add_f32_e32 v23, 1.0, v23
	v_add_f32_e32 v6, 1.0, v6
	v_add_f32_e32 v7, 1.0, v7
	v_rcp_f32_e32 v22, v22
	v_rcp_f32_e32 v23, v23
	v_rcp_f32_e32 v6, v6
	v_rcp_f32_e32 v7, v7
	v_mul_f32_e32 v24, 0xbfb8aa3b, v24
	v_mul_f32_e32 v25, 0xbfb8aa3b, v25
	v_mul_f32_e32 v8, 0xbfb8aa3b, v8
	v_mul_f32_e32 v9, 0xbfb8aa3b, v9
	v_exp_f32_e32 v24, v24
	v_exp_f32_e32 v25, v25
	v_exp_f32_e32 v8, v8
	v_exp_f32_e32 v9, v9
	v_add_f32_e32 v24, 1.0, v24
	v_add_f32_e32 v25, 1.0, v25
	v_add_f32_e32 v8, 1.0, v8
	v_add_f32_e32 v9, 1.0, v9
	v_rcp_f32_e32 v24, v24
	v_rcp_f32_e32 v25, v25
	v_rcp_f32_e32 v8, v8
	v_rcp_f32_e32 v9, v9
	s_waitcnt vmcnt(0)
	v_lshlrev_b32_e32 v204, 16, v204
	v_lshlrev_b32_e32 v205, 16, v205
	v_lshlrev_b32_e32 v206, 16, v206
	v_lshlrev_b32_e32 v207, 16, v207
	v_lshlrev_b32_e32 v208, 16, v208
	v_lshlrev_b32_e32 v209, 16, v209
	v_lshlrev_b32_e32 v210, 16, v210
	v_lshlrev_b32_e32 v211, 16, v211
	v_lshlrev_b32_e32 v212, 16, v212
	v_lshlrev_b32_e32 v213, 16, v213
	v_lshlrev_b32_e32 v214, 16, v214
	v_lshlrev_b32_e32 v215, 16, v215
	v_lshlrev_b32_e32 v216, 16, v216
	v_lshlrev_b32_e32 v217, 16, v217
	v_lshlrev_b32_e32 v218, 16, v218
	v_lshlrev_b32_e32 v219, 16, v219
	v_mul_f32_e32 v204, v18, v204
	v_mul_f32_e32 v205, v19, v205
	v_mul_f32_e32 v206, v2, v206
	v_mul_f32_e32 v207, v3, v207
	v_mul_f32_e32 v208, v20, v208
	v_mul_f32_e32 v209, v21, v209
	v_mul_f32_e32 v210, v4, v210
	v_mul_f32_e32 v211, v5, v211
	v_mul_f32_e32 v212, v22, v212
	v_mul_f32_e32 v213, v23, v213
	v_mul_f32_e32 v214, v6, v214
	v_mul_f32_e32 v215, v7, v215
	v_mul_f32_e32 v216, v24, v216
	v_mul_f32_e32 v217, v25, v217
	v_mul_f32_e32 v218, v8, v218
	v_mul_f32_e32 v219, v9, v219
	v_cndmask_b32_e64 v220, v204, v205, s[40:41]
	v_cndmask_b32_e64 v221, v206, v207, s[40:41]
	v_cndmask_b32_e64 v222, v208, v209, s[40:41]
	v_cndmask_b32_e64 v223, v210, v211, s[40:41]
	v_cndmask_b32_e64 v224, v212, v213, s[40:41]
	v_cndmask_b32_e64 v225, v214, v215, s[40:41]
	v_cndmask_b32_e64 v226, v216, v217, s[40:41]
	v_cndmask_b32_e64 v227, v218, v219, s[40:41]
	v_mov_b32_dpp v220, v220 quad_perm:[1,0,3,2] row_mask:0xf bank_mask:0xf bound_ctrl:1
	v_mov_b32_dpp v221, v221 quad_perm:[1,0,3,2] row_mask:0xf bank_mask:0xf bound_ctrl:1
	v_mov_b32_dpp v222, v222 quad_perm:[1,0,3,2] row_mask:0xf bank_mask:0xf bound_ctrl:1
	v_mov_b32_dpp v223, v223 quad_perm:[1,0,3,2] row_mask:0xf bank_mask:0xf bound_ctrl:1
	v_mov_b32_dpp v224, v224 quad_perm:[1,0,3,2] row_mask:0xf bank_mask:0xf bound_ctrl:1
	v_mov_b32_dpp v225, v225 quad_perm:[1,0,3,2] row_mask:0xf bank_mask:0xf bound_ctrl:1
	v_mov_b32_dpp v226, v226 quad_perm:[1,0,3,2] row_mask:0xf bank_mask:0xf bound_ctrl:1
	v_mov_b32_dpp v227, v227 quad_perm:[1,0,3,2] row_mask:0xf bank_mask:0xf bound_ctrl:1
	v_cndmask_b32_e64 v204, v220, v204, s[40:41]
	v_cndmask_b32_e64 v205, v205, v220, s[40:41]
	v_cndmask_b32_e64 v206, v221, v206, s[40:41]
	v_cndmask_b32_e64 v207, v207, v221, s[40:41]
	v_cndmask_b32_e64 v208, v222, v208, s[40:41]
	v_cndmask_b32_e64 v209, v209, v222, s[40:41]
	v_cndmask_b32_e64 v210, v223, v210, s[40:41]
	v_cndmask_b32_e64 v211, v211, v223, s[40:41]
	v_cndmask_b32_e64 v212, v224, v212, s[40:41]
	v_cndmask_b32_e64 v213, v213, v224, s[40:41]
	v_cndmask_b32_e64 v214, v225, v214, s[40:41]
	v_cndmask_b32_e64 v215, v215, v225, s[40:41]
	v_cndmask_b32_e64 v216, v226, v216, s[40:41]
	v_cndmask_b32_e64 v217, v217, v226, s[40:41]
	v_cndmask_b32_e64 v218, v227, v218, s[40:41]
	v_cndmask_b32_e64 v219, v219, v227, s[40:41]
	v_cvt_pk_bf16_f32 v204, v204, v205
	v_cvt_pk_bf16_f32 v206, v206, v207
	v_cvt_pk_bf16_f32 v208, v208, v209
	v_cvt_pk_bf16_f32 v210, v210, v211
	v_cvt_pk_bf16_f32 v212, v212, v213
	v_cvt_pk_bf16_f32 v214, v214, v215
	v_cvt_pk_bf16_f32 v216, v216, v217
	v_cvt_pk_bf16_f32 v218, v218, v219
	global_store_dword v236, v204, s[54:55] sc1
	global_store_dword v236, v206, s[54:55] offset:64 sc1
	global_store_dword v237, v208, s[54:55] sc1
	global_store_dword v237, v210, s[54:55] offset:64 sc1
	global_store_dword v238, v212, s[54:55] sc1
	global_store_dword v238, v214, s[54:55] offset:64 sc1
	global_store_dword v239, v216, s[54:55] sc1
	global_store_dword v239, v218, s[54:55] offset:64 sc1
	v_add_u32_e32 v245, 0x28000, v244
	v_add_u32_e32 v236, 0x28000, v249
	v_add_u32_e32 v246, 0x29000, v244
	v_add_u32_e32 v237, 0x29000, v249
	v_add_u32_e32 v247, 0x2c000, v244
	v_add_u32_e32 v238, 0x2c000, v249
	v_add_u32_e32 v248, 0x2d000, v244
	v_add_u32_e32 v239, 0x2d000, v249
	global_load_ushort v204, v245, s[52:53]
	global_load_ushort v205, v245, s[52:53] offset:2048
	global_load_ushort v206, v245, s[52:53] offset:64
	global_load_ushort v207, v245, s[52:53] offset:2112
	global_load_ushort v208, v246, s[52:53]
	global_load_ushort v209, v246, s[52:53] offset:2048
	global_load_ushort v210, v246, s[52:53] offset:64
	global_load_ushort v211, v246, s[52:53] offset:2112
	global_load_ushort v212, v247, s[52:53]
	global_load_ushort v213, v247, s[52:53] offset:2048
	global_load_ushort v214, v247, s[52:53] offset:64
	global_load_ushort v215, v247, s[52:53] offset:2112
	global_load_ushort v216, v248, s[52:53]
	global_load_ushort v217, v248, s[52:53] offset:2048
	global_load_ushort v218, v248, s[52:53] offset:64
	global_load_ushort v219, v248, s[52:53] offset:2112
	v_mul_f32_e32 v26, 0xbfb8aa3b, v26
	v_mul_f32_e32 v27, 0xbfb8aa3b, v27
	v_mul_f32_e32 v10, 0xbfb8aa3b, v10
	v_mul_f32_e32 v11, 0xbfb8aa3b, v11
	v_exp_f32_e32 v26, v26
	v_exp_f32_e32 v27, v27
	v_exp_f32_e32 v10, v10
	v_exp_f32_e32 v11, v11
	v_add_f32_e32 v26, 1.0, v26
	v_add_f32_e32 v27, 1.0, v27
	v_add_f32_e32 v10, 1.0, v10
	v_add_f32_e32 v11, 1.0, v11
	v_rcp_f32_e32 v26, v26
	v_rcp_f32_e32 v27, v27
	v_rcp_f32_e32 v10, v10
	v_rcp_f32_e32 v11, v11
	v_mul_f32_e32 v28, 0xbfb8aa3b, v28
	v_mul_f32_e32 v29, 0xbfb8aa3b, v29
	v_mul_f32_e32 v12, 0xbfb8aa3b, v12
	v_mul_f32_e32 v13, 0xbfb8aa3b, v13
	v_exp_f32_e32 v28, v28
	v_exp_f32_e32 v29, v29
	v_exp_f32_e32 v12, v12
	v_exp_f32_e32 v13, v13
	v_add_f32_e32 v28, 1.0, v28
	v_add_f32_e32 v29, 1.0, v29
	v_add_f32_e32 v12, 1.0, v12
	v_add_f32_e32 v13, 1.0, v13
	v_rcp_f32_e32 v28, v28
	v_rcp_f32_e32 v29, v29
	v_rcp_f32_e32 v12, v12
	v_rcp_f32_e32 v13, v13
	v_mul_f32_e32 v30, 0xbfb8aa3b, v30
	v_mul_f32_e32 v31, 0xbfb8aa3b, v31
	v_mul_f32_e32 v14, 0xbfb8aa3b, v14
	v_mul_f32_e32 v15, 0xbfb8aa3b, v15
	v_exp_f32_e32 v30, v30
	v_exp_f32_e32 v31, v31
	v_exp_f32_e32 v14, v14
	v_exp_f32_e32 v15, v15
	v_add_f32_e32 v30, 1.0, v30
	v_add_f32_e32 v31, 1.0, v31
	v_add_f32_e32 v14, 1.0, v14
	v_add_f32_e32 v15, 1.0, v15
	v_rcp_f32_e32 v30, v30
	v_rcp_f32_e32 v31, v31
	v_rcp_f32_e32 v14, v14
	v_rcp_f32_e32 v15, v15
	v_mul_f32_e32 v32, 0xbfb8aa3b, v32
	v_mul_f32_e32 v33, 0xbfb8aa3b, v33
	v_mul_f32_e32 v16, 0xbfb8aa3b, v16
	v_mul_f32_e32 v17, 0xbfb8aa3b, v17
	v_exp_f32_e32 v32, v32
	v_exp_f32_e32 v33, v33
	v_exp_f32_e32 v16, v16
	v_exp_f32_e32 v17, v17
	v_add_f32_e32 v32, 1.0, v32
	v_add_f32_e32 v33, 1.0, v33
	v_add_f32_e32 v16, 1.0, v16
	v_add_f32_e32 v17, 1.0, v17
	v_rcp_f32_e32 v32, v32
	v_rcp_f32_e32 v33, v33
	v_rcp_f32_e32 v16, v16
	v_rcp_f32_e32 v17, v17
	s_waitcnt vmcnt(0)
	v_lshlrev_b32_e32 v204, 16, v204
	v_lshlrev_b32_e32 v205, 16, v205
	v_lshlrev_b32_e32 v206, 16, v206
	v_lshlrev_b32_e32 v207, 16, v207
	v_lshlrev_b32_e32 v208, 16, v208
	v_lshlrev_b32_e32 v209, 16, v209
	v_lshlrev_b32_e32 v210, 16, v210
	v_lshlrev_b32_e32 v211, 16, v211
	v_lshlrev_b32_e32 v212, 16, v212
	v_lshlrev_b32_e32 v213, 16, v213
	v_lshlrev_b32_e32 v214, 16, v214
	v_lshlrev_b32_e32 v215, 16, v215
	v_lshlrev_b32_e32 v216, 16, v216
	v_lshlrev_b32_e32 v217, 16, v217
	v_lshlrev_b32_e32 v218, 16, v218
	v_lshlrev_b32_e32 v219, 16, v219
	v_mul_f32_e32 v204, v26, v204
	v_mul_f32_e32 v205, v27, v205
	v_mul_f32_e32 v206, v10, v206
	v_mul_f32_e32 v207, v11, v207
	v_mul_f32_e32 v208, v28, v208
	v_mul_f32_e32 v209, v29, v209
	v_mul_f32_e32 v210, v12, v210
	v_mul_f32_e32 v211, v13, v211
	v_mul_f32_e32 v212, v30, v212
	v_mul_f32_e32 v213, v31, v213
	v_mul_f32_e32 v214, v14, v214
	v_mul_f32_e32 v215, v15, v215
	v_mul_f32_e32 v216, v32, v216
	v_mul_f32_e32 v217, v33, v217
	v_mul_f32_e32 v218, v16, v218
	v_mul_f32_e32 v219, v17, v219
	v_cndmask_b32_e64 v220, v204, v205, s[40:41]
	v_cndmask_b32_e64 v221, v206, v207, s[40:41]
	v_cndmask_b32_e64 v222, v208, v209, s[40:41]
	v_cndmask_b32_e64 v223, v210, v211, s[40:41]
	v_cndmask_b32_e64 v224, v212, v213, s[40:41]
	v_cndmask_b32_e64 v225, v214, v215, s[40:41]
	v_cndmask_b32_e64 v226, v216, v217, s[40:41]
	v_cndmask_b32_e64 v227, v218, v219, s[40:41]
	v_mov_b32_dpp v220, v220 quad_perm:[1,0,3,2] row_mask:0xf bank_mask:0xf bound_ctrl:1
	v_mov_b32_dpp v221, v221 quad_perm:[1,0,3,2] row_mask:0xf bank_mask:0xf bound_ctrl:1
	v_mov_b32_dpp v222, v222 quad_perm:[1,0,3,2] row_mask:0xf bank_mask:0xf bound_ctrl:1
	v_mov_b32_dpp v223, v223 quad_perm:[1,0,3,2] row_mask:0xf bank_mask:0xf bound_ctrl:1
	v_mov_b32_dpp v224, v224 quad_perm:[1,0,3,2] row_mask:0xf bank_mask:0xf bound_ctrl:1
	v_mov_b32_dpp v225, v225 quad_perm:[1,0,3,2] row_mask:0xf bank_mask:0xf bound_ctrl:1
	v_mov_b32_dpp v226, v226 quad_perm:[1,0,3,2] row_mask:0xf bank_mask:0xf bound_ctrl:1
	v_mov_b32_dpp v227, v227 quad_perm:[1,0,3,2] row_mask:0xf bank_mask:0xf bound_ctrl:1
	v_cndmask_b32_e64 v204, v220, v204, s[40:41]
	v_cndmask_b32_e64 v205, v205, v220, s[40:41]
	v_cndmask_b32_e64 v206, v221, v206, s[40:41]
	v_cndmask_b32_e64 v207, v207, v221, s[40:41]
	v_cndmask_b32_e64 v208, v222, v208, s[40:41]
	v_cndmask_b32_e64 v209, v209, v222, s[40:41]
	v_cndmask_b32_e64 v210, v223, v210, s[40:41]
	v_cndmask_b32_e64 v211, v211, v223, s[40:41]
	v_cndmask_b32_e64 v212, v224, v212, s[40:41]
	v_cndmask_b32_e64 v213, v213, v224, s[40:41]
	v_cndmask_b32_e64 v214, v225, v214, s[40:41]
	v_cndmask_b32_e64 v215, v215, v225, s[40:41]
	v_cndmask_b32_e64 v216, v226, v216, s[40:41]
	v_cndmask_b32_e64 v217, v217, v226, s[40:41]
	v_cndmask_b32_e64 v218, v227, v218, s[40:41]
	v_cndmask_b32_e64 v219, v219, v227, s[40:41]
	v_cvt_pk_bf16_f32 v204, v204, v205
	v_cvt_pk_bf16_f32 v206, v206, v207
	v_cvt_pk_bf16_f32 v208, v208, v209
	v_cvt_pk_bf16_f32 v210, v210, v211
	v_cvt_pk_bf16_f32 v212, v212, v213
	v_cvt_pk_bf16_f32 v214, v214, v215
	v_cvt_pk_bf16_f32 v216, v216, v217
	v_cvt_pk_bf16_f32 v218, v218, v219
	global_store_dword v236, v204, s[54:55] sc1
	global_store_dword v236, v206, s[54:55] offset:64 sc1
	global_store_dword v237, v208, s[54:55] sc1
	global_store_dword v237, v210, s[54:55] offset:64 sc1
	global_store_dword v238, v212, s[54:55] sc1
	global_store_dword v238, v214, s[54:55] offset:64 sc1
	global_store_dword v239, v216, s[54:55] sc1
	global_store_dword v239, v218, s[54:55] offset:64 sc1

.LBB0_505:
	s_andn2_b64 vcc, exec, s[2:3]
	s_mov_b64 s[94:95], s[16:17]
	s_cbranch_vccnz .LBB0_450
	s_cmp_gt_i32 s45, 0
	s_mov_b64 s[0:1], -1
	s_cbranch_scc0 .LBB0_508
	v_ashrrev_i32_e32 v101, 1, v109
	v_or_b32_e32 v102, v101, v147
	v_mul_f32_e32 v101, 0xbfb8aa3b, v82
	v_mul_f32_e32 v104, 0xbfb8aa3b, v83
	v_exp_f32_e32 v101, v101
	v_exp_f32_e32 v104, v104
	v_or_b32_e32 v103, v108, v146
	s_movk_i32 s0, 0xb00
	v_add_f32_e32 v101, 1.0, v101
	v_add_f32_e32 v104, 1.0, v104
	v_rcp_f32_e32 v101, v101
	v_rcp_f32_e32 v104, v104
	v_mad_u64_u32 v[102:103], s[0:1], v103, s0, v[102:103]
	v_mul_f32_e32 v101, v82, v101
	v_mul_f32_e32 v104, v83, v104
	v_mul_f32_e32 v101, v66, v101
	v_mul_f32_e32 v104, v67, v104
	v_cndmask_b32_e64 v105, v101, v104, s[40:41]
	v_mov_b32_e32 v103, v1
	s_mov_b64 s[0:1], 0
	v_mov_b32_dpp v105, v105 quad_perm:[1,0,3,2] row_mask:0xf bank_mask:0xf bound_ctrl:1
	v_cndmask_b32_e64 v101, v105, v101, s[40:41]
	v_cndmask_b32_e64 v104, v104, v105, s[40:41]
	v_cvt_pk_bf16_f32 v101, v101, v104
	v_lshl_add_u64 v[104:105], v[102:103], 1, s[54:55]
	global_store_dword v[104:105], v101, off sc1
	v_mul_f32_e32 v101, 0xbfb8aa3b, v84
	v_mul_f32_e32 v103, 0xbfb8aa3b, v85
	v_exp_f32_e32 v101, v101
	v_exp_f32_e32 v103, v103
	v_mov_b32_e32 v105, v1
	v_add_f32_e32 v101, 1.0, v101
	v_add_f32_e32 v103, 1.0, v103
	v_rcp_f32_e32 v101, v101
	v_rcp_f32_e32 v103, v103
	v_mul_f32_e32 v101, v84, v101
	v_mul_f32_e32 v103, v85, v103
	v_mul_f32_e32 v101, v68, v101
	v_mul_f32_e32 v103, v69, v103
	v_cndmask_b32_e64 v104, v101, v103, s[40:41]
	s_nop 1
	v_mov_b32_dpp v104, v104 quad_perm:[1,0,3,2] row_mask:0xf bank_mask:0xf bound_ctrl:1
	v_cndmask_b32_e64 v101, v104, v101, s[40:41]
	v_cndmask_b32_e64 v103, v103, v104, s[40:41]
	v_add_u32_e32 v104, 0x1600, v102
	v_cvt_pk_bf16_f32 v101, v101, v103
	v_lshl_add_u64 v[104:105], v[104:105], 1, s[54:55]
	global_store_dword v[104:105], v101, off sc1
	v_mul_f32_e32 v101, 0xbfb8aa3b, v86
	v_mul_f32_e32 v103, 0xbfb8aa3b, v87
	v_exp_f32_e32 v101, v101
	v_exp_f32_e32 v103, v103
	v_mov_b32_e32 v105, v1
	v_add_f32_e32 v101, 1.0, v101
	v_add_f32_e32 v103, 1.0, v103
	v_rcp_f32_e32 v101, v101
	v_rcp_f32_e32 v103, v103
	v_mul_f32_e32 v101, v86, v101
	v_mul_f32_e32 v103, v87, v103
	v_mul_f32_e32 v101, v70, v101
	v_mul_f32_e32 v103, v71, v103
	v_cndmask_b32_e64 v104, v101, v103, s[40:41]
	s_nop 1
	v_mov_b32_dpp v104, v104 quad_perm:[1,0,3,2] row_mask:0xf bank_mask:0xf bound_ctrl:1
	v_cndmask_b32_e64 v101, v104, v101, s[40:41]
	v_cndmask_b32_e64 v103, v103, v104, s[40:41]
	v_add_u32_e32 v104, 0x5800, v102
	v_cvt_pk_bf16_f32 v101, v101, v103
	v_lshl_add_u64 v[104:105], v[104:105], 1, s[54:55]
	global_store_dword v[104:105], v101, off sc1
	v_mul_f32_e32 v101, 0xbfb8aa3b, v88
	v_mul_f32_e32 v103, 0xbfb8aa3b, v89
	v_exp_f32_e32 v101, v101
	v_exp_f32_e32 v103, v103
	v_mov_b32_e32 v105, v1
	v_add_f32_e32 v101, 1.0, v101
	v_add_f32_e32 v103, 1.0, v103
	v_rcp_f32_e32 v101, v101
	v_rcp_f32_e32 v103, v103
	v_mul_f32_e32 v101, v88, v101
	v_mul_f32_e32 v103, v89, v103
	v_mul_f32_e32 v101, v72, v101
	v_mul_f32_e32 v103, v73, v103
	v_cndmask_b32_e64 v104, v101, v103, s[40:41]
	s_nop 1
	v_mov_b32_dpp v104, v104 quad_perm:[1,0,3,2] row_mask:0xf bank_mask:0xf bound_ctrl:1
	v_cndmask_b32_e64 v101, v104, v101, s[40:41]
	v_cndmask_b32_e64 v103, v103, v104, s[40:41]
	v_add_u32_e32 v104, 0x6e00, v102
	v_cvt_pk_bf16_f32 v101, v101, v103
	v_lshl_add_u64 v[104:105], v[104:105], 1, s[54:55]
	global_store_dword v[104:105], v101, off sc1
	v_mul_f32_e32 v101, 0xbfb8aa3b, v90
	v_mul_f32_e32 v103, 0xbfb8aa3b, v91
	v_exp_f32_e32 v101, v101
	v_exp_f32_e32 v103, v103
	v_mov_b32_e32 v105, v1
	v_add_f32_e32 v101, 1.0, v101
	v_add_f32_e32 v103, 1.0, v103
	v_rcp_f32_e32 v101, v101
	v_rcp_f32_e32 v103, v103
	v_mul_f32_e32 v101, v90, v101
	v_mul_f32_e32 v103, v91, v103
	v_mul_f32_e32 v101, v74, v101
	v_mul_f32_e32 v103, v75, v103
	v_cndmask_b32_e64 v104, v101, v103, s[40:41]
	s_nop 1
	v_mov_b32_dpp v104, v104 quad_perm:[1,0,3,2] row_mask:0xf bank_mask:0xf bound_ctrl:1
	v_cndmask_b32_e64 v101, v104, v101, s[40:41]
	v_cndmask_b32_e64 v103, v103, v104, s[40:41]
	v_add_u32_e32 v104, 0xb000, v102
	v_cvt_pk_bf16_f32 v101, v101, v103
	v_lshl_add_u64 v[104:105], v[104:105], 1, s[54:55]
	global_store_dword v[104:105], v101, off sc1
	v_mul_f32_e32 v101, 0xbfb8aa3b, v92
	v_mul_f32_e32 v103, 0xbfb8aa3b, v93
	v_exp_f32_e32 v101, v101
	v_exp_f32_e32 v103, v103
	v_mov_b32_e32 v105, v1
	v_add_f32_e32 v101, 1.0, v101
	v_add_f32_e32 v103, 1.0, v103
	v_rcp_f32_e32 v101, v101
	v_rcp_f32_e32 v103, v103
	v_mul_f32_e32 v101, v92, v101
	v_mul_f32_e32 v103, v93, v103
	v_mul_f32_e32 v101, v76, v101
	v_mul_f32_e32 v103, v77, v103
	v_cndmask_b32_e64 v104, v101, v103, s[40:41]
	s_nop 1
	v_mov_b32_dpp v104, v104 quad_perm:[1,0,3,2] row_mask:0xf bank_mask:0xf bound_ctrl:1
	v_cndmask_b32_e64 v101, v104, v101, s[40:41]
	v_cndmask_b32_e64 v103, v103, v104, s[40:41]
	v_add_u32_e32 v104, 0xc600, v102
	v_cvt_pk_bf16_f32 v101, v101, v103
	v_lshl_add_u64 v[104:105], v[104:105], 1, s[54:55]
	global_store_dword v[104:105], v101, off sc1
	v_mul_f32_e32 v101, 0xbfb8aa3b, v94
	v_mul_f32_e32 v103, 0xbfb8aa3b, v95
	v_exp_f32_e32 v101, v101
	v_exp_f32_e32 v103, v103
	v_mov_b32_e32 v105, v1
	v_add_f32_e32 v101, 1.0, v101
	v_add_f32_e32 v103, 1.0, v103
	v_rcp_f32_e32 v101, v101
	v_rcp_f32_e32 v103, v103
	v_mul_f32_e32 v101, v94, v101
	v_mul_f32_e32 v103, v95, v103
	v_mul_f32_e32 v101, v78, v101
	v_mul_f32_e32 v103, v79, v103
	v_cndmask_b32_e64 v104, v101, v103, s[40:41]
	s_nop 1
	v_mov_b32_dpp v104, v104 quad_perm:[1,0,3,2] row_mask:0xf bank_mask:0xf bound_ctrl:1
	v_cndmask_b32_e64 v101, v104, v101, s[40:41]
	v_cndmask_b32_e64 v103, v103, v104, s[40:41]
	v_add_u32_e32 v104, 0x10800, v102
	v_cvt_pk_bf16_f32 v101, v101, v103
	v_lshl_add_u64 v[104:105], v[104:105], 1, s[54:55]
	global_store_dword v[104:105], v101, off sc1
	v_mul_f32_e32 v101, 0xbfb8aa3b, v96
	v_mul_f32_e32 v103, 0xbfb8aa3b, v97
	v_exp_f32_e32 v101, v101
	v_exp_f32_e32 v103, v103
	v_mov_b32_e32 v105, v1
	v_add_f32_e32 v101, 1.0, v101
	v_add_f32_e32 v103, 1.0, v103
	v_rcp_f32_e32 v101, v101
	v_rcp_f32_e32 v103, v103
	v_mul_f32_e32 v101, v96, v101
	v_mul_f32_e32 v103, v97, v103
	v_mul_f32_e32 v101, v80, v101
	v_mul_f32_e32 v103, v81, v103
	v_cndmask_b32_e64 v104, v101, v103, s[40:41]
	s_nop 1
	v_mov_b32_dpp v104, v104 quad_perm:[1,0,3,2] row_mask:0xf bank_mask:0xf bound_ctrl:1
	v_cndmask_b32_e64 v101, v104, v101, s[40:41]
	v_cndmask_b32_e64 v103, v103, v104, s[40:41]
	v_add_u32_e32 v104, 0x11e00, v102
	v_cvt_pk_bf16_f32 v101, v101, v103
	v_lshl_add_u64 v[104:105], v[104:105], 1, s[54:55]
	global_store_dword v[104:105], v101, off sc1
	v_mul_f32_e32 v101, 0xbfb8aa3b, v50
	v_mul_f32_e32 v103, 0xbfb8aa3b, v51
	v_exp_f32_e32 v101, v101
	v_exp_f32_e32 v103, v103
	v_mov_b32_e32 v105, v1
	v_add_f32_e32 v101, 1.0, v101
	v_add_f32_e32 v103, 1.0, v103
	v_rcp_f32_e32 v101, v101
	v_rcp_f32_e32 v103, v103
	v_mul_f32_e32 v101, v50, v101
	v_mul_f32_e32 v103, v51, v103
	v_mul_f32_e32 v101, v34, v101
	v_mul_f32_e32 v103, v35, v103
	v_cndmask_b32_e64 v104, v101, v103, s[40:41]
	s_nop 1
	v_mov_b32_dpp v104, v104 quad_perm:[1,0,3,2] row_mask:0xf bank_mask:0xf bound_ctrl:1
	v_cndmask_b32_e64 v101, v104, v101, s[40:41]
	v_cndmask_b32_e64 v103, v103, v104, s[40:41]
	v_add_u32_e32 v104, 0x16000, v102
	v_cvt_pk_bf16_f32 v101, v101, v103
	v_lshl_add_u64 v[104:105], v[104:105], 1, s[54:55]
	global_store_dword v[104:105], v101, off sc1
	v_mul_f32_e32 v101, 0xbfb8aa3b, v52
	v_mul_f32_e32 v103, 0xbfb8aa3b, v53
	v_exp_f32_e32 v101, v101
	v_exp_f32_e32 v103, v103
	v_mov_b32_e32 v105, v1
	v_add_f32_e32 v101, 1.0, v101
	v_add_f32_e32 v103, 1.0, v103
	v_rcp_f32_e32 v101, v101
	v_rcp_f32_e32 v103, v103
	v_mul_f32_e32 v101, v52, v101
	v_mul_f32_e32 v103, v53, v103
	v_mul_f32_e32 v101, v36, v101
	v_mul_f32_e32 v103, v37, v103
	v_cndmask_b32_e64 v104, v101, v103, s[40:41]
	s_nop 1
	v_mov_b32_dpp v104, v104 quad_perm:[1,0,3,2] row_mask:0xf bank_mask:0xf bound_ctrl:1
	v_cndmask_b32_e64 v101, v104, v101, s[40:41]
	v_cndmask_b32_e64 v103, v103, v104, s[40:41]
	v_add_u32_e32 v104, 0x17600, v102
	v_cvt_pk_bf16_f32 v101, v101, v103
	v_lshl_add_u64 v[104:105], v[104:105], 1, s[54:55]
	global_store_dword v[104:105], v101, off sc1
	v_mul_f32_e32 v101, 0xbfb8aa3b, v54
	v_mul_f32_e32 v103, 0xbfb8aa3b, v55
	v_exp_f32_e32 v101, v101
	v_exp_f32_e32 v103, v103
	v_mov_b32_e32 v105, v1
	v_add_f32_e32 v101, 1.0, v101
	v_add_f32_e32 v103, 1.0, v103
	v_rcp_f32_e32 v101, v101
	v_rcp_f32_e32 v103, v103
	v_mul_f32_e32 v101, v54, v101
	v_mul_f32_e32 v103, v55, v103
	v_mul_f32_e32 v101, v38, v101
	v_mul_f32_e32 v103, v39, v103
	v_cndmask_b32_e64 v104, v101, v103, s[40:41]
	s_nop 1
	v_mov_b32_dpp v104, v104 quad_perm:[1,0,3,2] row_mask:0xf bank_mask:0xf bound_ctrl:1
	v_cndmask_b32_e64 v101, v104, v101, s[40:41]
	v_cndmask_b32_e64 v103, v103, v104, s[40:41]
	v_add_u32_e32 v104, 0x1b800, v102
	v_cvt_pk_bf16_f32 v101, v101, v103
	v_lshl_add_u64 v[104:105], v[104:105], 1, s[54:55]
	global_store_dword v[104:105], v101, off sc1
	v_mul_f32_e32 v101, 0xbfb8aa3b, v56
	v_mul_f32_e32 v103, 0xbfb8aa3b, v57
	v_exp_f32_e32 v101, v101
	v_exp_f32_e32 v103, v103
	v_mov_b32_e32 v105, v1
	v_add_f32_e32 v101, 1.0, v101
	v_add_f32_e32 v103, 1.0, v103
	v_rcp_f32_e32 v101, v101
	v_rcp_f32_e32 v103, v103
	v_mul_f32_e32 v101, v56, v101
	v_mul_f32_e32 v103, v57, v103
	v_mul_f32_e32 v101, v40, v101
	v_mul_f32_e32 v103, v41, v103
	v_cndmask_b32_e64 v104, v101, v103, s[40:41]
	s_nop 1
	v_mov_b32_dpp v104, v104 quad_perm:[1,0,3,2] row_mask:0xf bank_mask:0xf bound_ctrl:1
	v_cndmask_b32_e64 v101, v104, v101, s[40:41]
	v_cndmask_b32_e64 v103, v103, v104, s[40:41]
	v_add_u32_e32 v104, 0x1ce00, v102
	v_cvt_pk_bf16_f32 v101, v101, v103
	v_lshl_add_u64 v[104:105], v[104:105], 1, s[54:55]
	global_store_dword v[104:105], v101, off sc1
	v_mul_f32_e32 v101, 0xbfb8aa3b, v58
	v_mul_f32_e32 v103, 0xbfb8aa3b, v59
	v_exp_f32_e32 v101, v101
	v_exp_f32_e32 v103, v103
	v_mov_b32_e32 v105, v1
	v_add_f32_e32 v101, 1.0, v101
	v_add_f32_e32 v103, 1.0, v103
	v_rcp_f32_e32 v101, v101
	v_rcp_f32_e32 v103, v103
	v_mul_f32_e32 v101, v58, v101
	v_mul_f32_e32 v103, v59, v103
	v_mul_f32_e32 v101, v42, v101
	v_mul_f32_e32 v103, v43, v103
	v_cndmask_b32_e64 v104, v101, v103, s[40:41]
	s_nop 1
	v_mov_b32_dpp v104, v104 quad_perm:[1,0,3,2] row_mask:0xf bank_mask:0xf bound_ctrl:1
	v_cndmask_b32_e64 v101, v104, v101, s[40:41]
	v_cndmask_b32_e64 v103, v103, v104, s[40:41]
	v_add_u32_e32 v104, 0x21000, v102
	v_cvt_pk_bf16_f32 v101, v101, v103
	v_lshl_add_u64 v[104:105], v[104:105], 1, s[54:55]
	global_store_dword v[104:105], v101, off sc1
	v_mul_f32_e32 v101, 0xbfb8aa3b, v60
	v_mul_f32_e32 v103, 0xbfb8aa3b, v61
	v_exp_f32_e32 v101, v101
	v_exp_f32_e32 v103, v103
	v_mov_b32_e32 v105, v1
	v_add_f32_e32 v101, 1.0, v101
	v_add_f32_e32 v103, 1.0, v103
	v_rcp_f32_e32 v101, v101
	v_rcp_f32_e32 v103, v103
	v_mul_f32_e32 v101, v60, v101
	v_mul_f32_e32 v103, v61, v103
	v_mul_f32_e32 v101, v44, v101
	v_mul_f32_e32 v103, v45, v103
	v_cndmask_b32_e64 v104, v101, v103, s[40:41]
	s_nop 1
	v_mov_b32_dpp v104, v104 quad_perm:[1,0,3,2] row_mask:0xf bank_mask:0xf bound_ctrl:1
	v_cndmask_b32_e64 v101, v104, v101, s[40:41]
	v_cndmask_b32_e64 v103, v103, v104, s[40:41]
	v_add_u32_e32 v104, 0x22600, v102
	v_cvt_pk_bf16_f32 v101, v101, v103
	v_lshl_add_u64 v[104:105], v[104:105], 1, s[54:55]
	global_store_dword v[104:105], v101, off sc1
	v_mul_f32_e32 v101, 0xbfb8aa3b, v62
	v_mul_f32_e32 v103, 0xbfb8aa3b, v63
	v_exp_f32_e32 v101, v101
	v_exp_f32_e32 v103, v103
	v_mov_b32_e32 v105, v1
	v_add_f32_e32 v101, 1.0, v101
	v_add_f32_e32 v103, 1.0, v103
	v_rcp_f32_e32 v101, v101
	v_rcp_f32_e32 v103, v103
	v_mul_f32_e32 v101, v62, v101
	v_mul_f32_e32 v103, v63, v103
	v_mul_f32_e32 v101, v46, v101
	v_mul_f32_e32 v103, v47, v103
	v_cndmask_b32_e64 v104, v101, v103, s[40:41]
	s_nop 1
	v_mov_b32_dpp v104, v104 quad_perm:[1,0,3,2] row_mask:0xf bank_mask:0xf bound_ctrl:1
	v_cndmask_b32_e64 v101, v104, v101, s[40:41]
	v_cndmask_b32_e64 v103, v103, v104, s[40:41]
	v_add_u32_e32 v104, 0x26800, v102
	v_cvt_pk_bf16_f32 v101, v101, v103
	v_lshl_add_u64 v[104:105], v[104:105], 1, s[54:55]
	global_store_dword v[104:105], v101, off sc1
	v_mul_f32_e32 v101, 0xbfb8aa3b, v64
	v_mul_f32_e32 v103, 0xbfb8aa3b, v65
	v_exp_f32_e32 v101, v101
	v_exp_f32_e32 v103, v103
	v_mov_b32_e32 v105, v1
	v_add_f32_e32 v101, 1.0, v101
	v_add_f32_e32 v103, 1.0, v103
	v_rcp_f32_e32 v101, v101
	v_rcp_f32_e32 v103, v103
	v_mul_f32_e32 v101, v64, v101
	v_mul_f32_e32 v103, v65, v103
	v_mul_f32_e32 v101, v48, v101
	v_mul_f32_e32 v103, v49, v103
	v_cndmask_b32_e64 v104, v101, v103, s[40:41]
	s_nop 1
	v_mov_b32_dpp v104, v104 quad_perm:[1,0,3,2] row_mask:0xf bank_mask:0xf bound_ctrl:1
	v_cndmask_b32_e64 v101, v104, v101, s[40:41]
	v_cndmask_b32_e64 v103, v103, v104, s[40:41]
	v_add_u32_e32 v104, 0x27e00, v102
	v_cvt_pk_bf16_f32 v101, v101, v103
	v_lshl_add_u64 v[104:105], v[104:105], 1, s[54:55]
	global_store_dword v[104:105], v101, off sc1
	v_mul_f32_e32 v101, 0xbfb8aa3b, v18
	v_mul_f32_e32 v103, 0xbfb8aa3b, v19
	v_exp_f32_e32 v101, v101
	v_exp_f32_e32 v103, v103
	v_mov_b32_e32 v105, v1
	v_add_f32_e32 v101, 1.0, v101
	v_add_f32_e32 v103, 1.0, v103
	v_rcp_f32_e32 v101, v101
	v_rcp_f32_e32 v103, v103
	v_mul_f32_e32 v101, v18, v101
	v_mul_f32_e32 v103, v19, v103
	v_mul_f32_e32 v101, v2, v101
	v_mul_f32_e32 v103, v3, v103
	v_cndmask_b32_e64 v104, v101, v103, s[40:41]
	s_nop 1
	v_mov_b32_dpp v104, v104 quad_perm:[1,0,3,2] row_mask:0xf bank_mask:0xf bound_ctrl:1
	v_cndmask_b32_e64 v101, v104, v101, s[40:41]
	v_cndmask_b32_e64 v103, v103, v104, s[40:41]
	v_add_u32_e32 v104, 0x2c000, v102
	v_cvt_pk_bf16_f32 v101, v101, v103
	v_lshl_add_u64 v[104:105], v[104:105], 1, s[54:55]
	global_store_dword v[104:105], v101, off sc1
	v_mul_f32_e32 v101, 0xbfb8aa3b, v20
	v_mul_f32_e32 v103, 0xbfb8aa3b, v21
	v_exp_f32_e32 v101, v101
	v_exp_f32_e32 v103, v103
	v_mov_b32_e32 v105, v1
	v_add_f32_e32 v101, 1.0, v101
	v_add_f32_e32 v103, 1.0, v103
	v_rcp_f32_e32 v101, v101
	v_rcp_f32_e32 v103, v103
	v_mul_f32_e32 v101, v20, v101
	v_mul_f32_e32 v103, v21, v103
	v_mul_f32_e32 v101, v4, v101
	v_mul_f32_e32 v103, v5, v103
	v_cndmask_b32_e64 v104, v101, v103, s[40:41]
	s_nop 1
	v_mov_b32_dpp v104, v104 quad_perm:[1,0,3,2] row_mask:0xf bank_mask:0xf bound_ctrl:1
	v_cndmask_b32_e64 v101, v104, v101, s[40:41]
	v_cndmask_b32_e64 v103, v103, v104, s[40:41]
	v_add_u32_e32 v104, 0x2d600, v102
	v_cvt_pk_bf16_f32 v101, v101, v103
	v_lshl_add_u64 v[104:105], v[104:105], 1, s[54:55]
	global_store_dword v[104:105], v101, off sc1
	v_mul_f32_e32 v101, 0xbfb8aa3b, v22
	v_mul_f32_e32 v103, 0xbfb8aa3b, v23
	v_exp_f32_e32 v101, v101
	v_exp_f32_e32 v103, v103
	v_mov_b32_e32 v105, v1
	v_add_f32_e32 v101, 1.0, v101
	v_add_f32_e32 v103, 1.0, v103
	v_rcp_f32_e32 v101, v101
	v_rcp_f32_e32 v103, v103
	v_mul_f32_e32 v101, v22, v101
	v_mul_f32_e32 v103, v23, v103
	v_mul_f32_e32 v101, v6, v101
	v_mul_f32_e32 v103, v7, v103
	v_cndmask_b32_e64 v104, v101, v103, s[40:41]
	s_nop 1
	v_mov_b32_dpp v104, v104 quad_perm:[1,0,3,2] row_mask:0xf bank_mask:0xf bound_ctrl:1
	v_cndmask_b32_e64 v101, v104, v101, s[40:41]
	v_cndmask_b32_e64 v103, v103, v104, s[40:41]
	v_add_u32_e32 v104, 0x31800, v102
	v_cvt_pk_bf16_f32 v101, v101, v103
	v_lshl_add_u64 v[104:105], v[104:105], 1, s[54:55]
	global_store_dword v[104:105], v101, off sc1
	v_mul_f32_e32 v101, 0xbfb8aa3b, v24
	v_mul_f32_e32 v103, 0xbfb8aa3b, v25
	v_exp_f32_e32 v101, v101
	v_exp_f32_e32 v103, v103
	v_mov_b32_e32 v105, v1
	v_add_f32_e32 v101, 1.0, v101
	v_add_f32_e32 v103, 1.0, v103
	v_rcp_f32_e32 v101, v101
	v_rcp_f32_e32 v103, v103
	v_mul_f32_e32 v101, v24, v101
	v_mul_f32_e32 v103, v25, v103
	v_mul_f32_e32 v101, v8, v101
	v_mul_f32_e32 v103, v9, v103
	v_cndmask_b32_e64 v104, v101, v103, s[40:41]
	s_nop 1
	v_mov_b32_dpp v104, v104 quad_perm:[1,0,3,2] row_mask:0xf bank_mask:0xf bound_ctrl:1
	v_cndmask_b32_e64 v101, v104, v101, s[40:41]
	v_cndmask_b32_e64 v103, v103, v104, s[40:41]
	v_add_u32_e32 v104, 0x32e00, v102
	v_cvt_pk_bf16_f32 v101, v101, v103
	v_lshl_add_u64 v[104:105], v[104:105], 1, s[54:55]
	global_store_dword v[104:105], v101, off sc1
	v_mul_f32_e32 v101, 0xbfb8aa3b, v26
	v_mul_f32_e32 v103, 0xbfb8aa3b, v27
	v_exp_f32_e32 v101, v101
	v_exp_f32_e32 v103, v103
	v_mov_b32_e32 v105, v1
	v_add_f32_e32 v101, 1.0, v101
	v_add_f32_e32 v103, 1.0, v103
	v_rcp_f32_e32 v101, v101
	v_rcp_f32_e32 v103, v103
	v_mul_f32_e32 v101, v26, v101
	v_mul_f32_e32 v103, v27, v103
	v_mul_f32_e32 v101, v10, v101
	v_mul_f32_e32 v103, v11, v103
	v_cndmask_b32_e64 v104, v101, v103, s[40:41]
	s_nop 1
	v_mov_b32_dpp v104, v104 quad_perm:[1,0,3,2] row_mask:0xf bank_mask:0xf bound_ctrl:1
	v_cndmask_b32_e64 v101, v104, v101, s[40:41]
	v_cndmask_b32_e64 v103, v103, v104, s[40:41]
	v_add_u32_e32 v104, 0x37000, v102
	v_cvt_pk_bf16_f32 v101, v101, v103
	v_lshl_add_u64 v[104:105], v[104:105], 1, s[54:55]
	global_store_dword v[104:105], v101, off sc1
	v_mul_f32_e32 v101, 0xbfb8aa3b, v28
	v_mul_f32_e32 v103, 0xbfb8aa3b, v29
	v_exp_f32_e32 v101, v101
	v_exp_f32_e32 v103, v103
	v_mov_b32_e32 v105, v1
	v_add_f32_e32 v101, 1.0, v101
	v_add_f32_e32 v103, 1.0, v103
	v_rcp_f32_e32 v101, v101
	v_rcp_f32_e32 v103, v103
	v_mul_f32_e32 v101, v28, v101
	v_mul_f32_e32 v103, v29, v103
	v_mul_f32_e32 v101, v12, v101
	v_mul_f32_e32 v103, v13, v103
	v_cndmask_b32_e64 v104, v101, v103, s[40:41]
	s_nop 1
	v_mov_b32_dpp v104, v104 quad_perm:[1,0,3,2] row_mask:0xf bank_mask:0xf bound_ctrl:1
	v_cndmask_b32_e64 v101, v104, v101, s[40:41]
	v_cndmask_b32_e64 v103, v103, v104, s[40:41]
	v_add_u32_e32 v104, 0x38600, v102
	v_cvt_pk_bf16_f32 v101, v101, v103
	v_lshl_add_u64 v[104:105], v[104:105], 1, s[54:55]
	global_store_dword v[104:105], v101, off sc1
	v_mul_f32_e32 v101, 0xbfb8aa3b, v30
	v_mul_f32_e32 v103, 0xbfb8aa3b, v31
	v_exp_f32_e32 v101, v101
	v_exp_f32_e32 v103, v103
	v_mov_b32_e32 v105, v1
	v_add_f32_e32 v101, 1.0, v101
	v_add_f32_e32 v103, 1.0, v103
	v_rcp_f32_e32 v101, v101
	v_rcp_f32_e32 v103, v103
	v_mul_f32_e32 v101, v30, v101
	v_mul_f32_e32 v103, v31, v103
	v_mul_f32_e32 v101, v14, v101
	v_mul_f32_e32 v103, v15, v103
	v_cndmask_b32_e64 v104, v101, v103, s[40:41]
	s_nop 1
	v_mov_b32_dpp v104, v104 quad_perm:[1,0,3,2] row_mask:0xf bank_mask:0xf bound_ctrl:1
	v_cndmask_b32_e64 v101, v104, v101, s[40:41]
	v_cndmask_b32_e64 v103, v103, v104, s[40:41]
	v_add_u32_e32 v104, 0x3c800, v102
	v_cvt_pk_bf16_f32 v101, v101, v103
	v_lshl_add_u64 v[104:105], v[104:105], 1, s[54:55]
	global_store_dword v[104:105], v101, off sc1
	v_mul_f32_e32 v101, 0xbfb8aa3b, v32
	v_mul_f32_e32 v103, 0xbfb8aa3b, v33
	v_exp_f32_e32 v101, v101
	v_exp_f32_e32 v103, v103
	v_add_u32_e32 v102, 0x3de00, v102
	v_add_f32_e32 v101, 1.0, v101
	v_add_f32_e32 v103, 1.0, v103
	v_rcp_f32_e32 v101, v101
	v_rcp_f32_e32 v103, v103
	v_mul_f32_e32 v101, v32, v101
	v_mul_f32_e32 v103, v33, v103
	v_mul_f32_e32 v101, v16, v101
	v_mul_f32_e32 v103, v17, v103
	v_cndmask_b32_e64 v104, v101, v103, s[40:41]
	s_nop 1
	v_mov_b32_dpp v104, v104 quad_perm:[1,0,3,2] row_mask:0xf bank_mask:0xf bound_ctrl:1
	v_cndmask_b32_e64 v101, v104, v101, s[40:41]
	v_cndmask_b32_e64 v103, v103, v104, s[40:41]
	v_cvt_pk_bf16_f32 v101, v101, v103
	v_mov_b32_e32 v103, v1
	v_lshl_add_u64 v[102:103], v[102:103], 1, s[54:55]
	global_store_dword v[102:103], v101, off sc1
.LBB0_508:
	s_andn2_b64 vcc, exec, s[0:1]
	s_cbranch_vccnz .LBB0_450
	v_mul_lo_u32 v101, s44, v108
	v_add_u32_e32 v102, v100, v101
	v_mov_b32_e32 v103, v1
	v_lshl_add_u64 v[102:103], v[102:103], 2, s[48:49]
	v_add_u32_e32 v104, s44, v101
	global_store_dword v[102:103], v82, off sc1
	v_add_u32_e32 v102, v100, v104
	v_mov_b32_e32 v103, v1
	v_lshl_add_u64 v[102:103], v[102:103], 2, s[48:49]
	global_store_dword v[102:103], v83, off sc1
	v_add_u32_e32 v102, s44, v104
	v_add_u32_e32 v82, v100, v102
	v_mov_b32_e32 v83, v1
	v_lshl_add_u64 v[82:83], v[82:83], 2, s[48:49]
	global_store_dword v[82:83], v84, off sc1
	v_add_u32_e32 v84, s44, v102
	v_add_u32_e32 v82, v100, v84
	v_mov_b32_e32 v83, v1
	v_lshl_add_u64 v[82:83], v[82:83], 2, s[48:49]
	s_mul_i32 s0, s44, 5
	global_store_dword v[82:83], v85, off sc1
	v_add_u32_e32 v85, s0, v84
	v_add_u32_e32 v82, v100, v85
	v_mov_b32_e32 v83, v1
	v_lshl_add_u64 v[82:83], v[82:83], 2, s[48:49]
	global_store_dword v[82:83], v86, off sc1
	v_add_u32_e32 v86, s44, v85
	v_add_u32_e32 v82, v100, v86
	v_mov_b32_e32 v83, v1
	v_lshl_add_u64 v[82:83], v[82:83], 2, s[48:49]
	global_store_dword v[82:83], v87, off sc1
	v_add_u32_e32 v87, s44, v86
	v_add_u32_e32 v82, v100, v87
	v_mov_b32_e32 v83, v1
	v_lshl_add_u64 v[82:83], v[82:83], 2, s[48:49]
	global_store_dword v[82:83], v88, off sc1
	v_add_u32_e32 v88, s44, v87
	v_add_u32_e32 v82, v100, v88
	v_mov_b32_e32 v83, v1
	v_lshl_add_u64 v[82:83], v[82:83], 2, s[48:49]
	global_store_dword v[82:83], v89, off sc1
	v_add_u32_e32 v89, s0, v88
	v_add_u32_e32 v82, v100, v89
	v_mov_b32_e32 v83, v1
	v_lshl_add_u64 v[82:83], v[82:83], 2, s[48:49]
	global_store_dword v[82:83], v90, off sc1
	v_add_u32_e32 v90, s44, v89
	v_add_u32_e32 v82, v100, v90
	v_mov_b32_e32 v83, v1
	v_lshl_add_u64 v[82:83], v[82:83], 2, s[48:49]
	global_store_dword v[82:83], v91, off sc1
	v_add_u32_e32 v91, s44, v90
	v_add_u32_e32 v82, v100, v91
	v_mov_b32_e32 v83, v1
	v_lshl_add_u64 v[82:83], v[82:83], 2, s[48:49]
	global_store_dword v[82:83], v92, off sc1
	v_add_u32_e32 v92, s44, v91
	v_add_u32_e32 v82, v100, v92
	v_mov_b32_e32 v83, v1
	v_lshl_add_u64 v[82:83], v[82:83], 2, s[48:49]
	global_store_dword v[82:83], v93, off sc1
	v_add_u32_e32 v93, s0, v92
	v_add_u32_e32 v82, v100, v93
	v_mov_b32_e32 v83, v1
	v_lshl_add_u64 v[82:83], v[82:83], 2, s[48:49]
	global_store_dword v[82:83], v94, off sc1
	v_add_u32_e32 v94, s44, v93
	v_add_u32_e32 v82, v100, v94
	v_mov_b32_e32 v83, v1
	v_lshl_add_u64 v[82:83], v[82:83], 2, s[48:49]
	global_store_dword v[82:83], v95, off sc1
	v_add_u32_e32 v95, s44, v94
	v_add_u32_e32 v82, v100, v95
	v_mov_b32_e32 v83, v1
	v_lshl_add_u64 v[82:83], v[82:83], 2, s[48:49]
	global_store_dword v[82:83], v96, off sc1
	v_add_u32_e32 v96, s44, v95
	v_add_u32_e32 v82, v100, v96
	v_mov_b32_e32 v83, v1
	v_lshl_add_u64 v[82:83], v[82:83], 2, s[48:49]
	global_store_dword v[82:83], v97, off sc1
	v_or_b32_e32 v97, 32, v100
	v_add_u32_e32 v82, v97, v101
	v_mov_b32_e32 v83, v1
	v_lshl_add_u64 v[82:83], v[82:83], 2, s[48:49]
	global_store_dword v[82:83], v66, off sc1
	v_add_u32_e32 v82, v97, v104
	v_mov_b32_e32 v83, v1
	v_lshl_add_u64 v[82:83], v[82:83], 2, s[48:49]
	global_store_dword v[82:83], v67, off sc1
	v_add_u32_e32 v66, v97, v102
	v_mov_b32_e32 v67, v1
	v_lshl_add_u64 v[66:67], v[66:67], 2, s[48:49]
	global_store_dword v[66:67], v68, off sc1
	v_add_u32_e32 v66, v97, v84
	v_mov_b32_e32 v67, v1
	v_lshl_add_u64 v[66:67], v[66:67], 2, s[48:49]
	global_store_dword v[66:67], v69, off sc1
	v_add_u32_e32 v66, v97, v85
	v_mov_b32_e32 v67, v1
	v_lshl_add_u64 v[66:67], v[66:67], 2, s[48:49]
	global_store_dword v[66:67], v70, off sc1
	v_add_u32_e32 v66, v97, v86
	v_mov_b32_e32 v67, v1
	v_lshl_add_u64 v[66:67], v[66:67], 2, s[48:49]
	global_store_dword v[66:67], v71, off sc1
	v_add_u32_e32 v66, v97, v87
	v_mov_b32_e32 v67, v1
	v_lshl_add_u64 v[66:67], v[66:67], 2, s[48:49]
	global_store_dword v[66:67], v72, off sc1
	v_add_u32_e32 v66, v97, v88
	v_mov_b32_e32 v67, v1
	v_lshl_add_u64 v[66:67], v[66:67], 2, s[48:49]
	global_store_dword v[66:67], v73, off sc1
	v_add_u32_e32 v66, v97, v89
	v_mov_b32_e32 v67, v1
	v_lshl_add_u64 v[66:67], v[66:67], 2, s[48:49]
	global_store_dword v[66:67], v74, off sc1
	v_add_u32_e32 v66, v97, v90
	v_mov_b32_e32 v67, v1
	v_lshl_add_u64 v[66:67], v[66:67], 2, s[48:49]
	global_store_dword v[66:67], v75, off sc1
	v_add_u32_e32 v66, v97, v91
	v_mov_b32_e32 v67, v1
	v_lshl_add_u64 v[66:67], v[66:67], 2, s[48:49]
	global_store_dword v[66:67], v76, off sc1
	v_add_u32_e32 v66, v97, v92
	v_mov_b32_e32 v67, v1
	v_lshl_add_u64 v[66:67], v[66:67], 2, s[48:49]
	global_store_dword v[66:67], v77, off sc1
	v_add_u32_e32 v66, v97, v93
	v_mov_b32_e32 v67, v1
	v_lshl_add_u64 v[66:67], v[66:67], 2, s[48:49]
	global_store_dword v[66:67], v78, off sc1
	v_add_u32_e32 v66, v97, v94
	v_mov_b32_e32 v67, v1
	v_lshl_add_u64 v[66:67], v[66:67], 2, s[48:49]
	global_store_dword v[66:67], v79, off sc1
	v_add_u32_e32 v66, v97, v95
	v_mov_b32_e32 v67, v1
	v_lshl_add_u64 v[66:67], v[66:67], 2, s[48:49]
	global_store_dword v[66:67], v80, off sc1
	v_add_u32_e32 v66, v97, v96
	v_mov_b32_e32 v67, v1
	v_lshl_add_u64 v[66:67], v[66:67], 2, s[48:49]
	global_store_dword v[66:67], v81, off sc1
	v_add_u32_e32 v66, 32, v108
	v_mul_lo_u32 v68, s44, v66
	v_add_u32_e32 v66, v100, v68
	v_mov_b32_e32 v67, v1
	v_lshl_add_u64 v[66:67], v[66:67], 2, s[48:49]
	v_add_u32_e32 v69, s44, v68
	global_store_dword v[66:67], v50, off sc1
	v_add_u32_e32 v66, v100, v69
	v_mov_b32_e32 v67, v1
	v_lshl_add_u64 v[66:67], v[66:67], 2, s[48:49]
	global_store_dword v[66:67], v51, off sc1
	v_add_u32_e32 v66, s44, v69
	v_add_u32_e32 v50, v100, v66
	v_mov_b32_e32 v51, v1
	v_lshl_add_u64 v[50:51], v[50:51], 2, s[48:49]
	global_store_dword v[50:51], v52, off sc1
	v_add_u32_e32 v52, s44, v66
	v_add_u32_e32 v50, v100, v52
	v_mov_b32_e32 v51, v1
	v_lshl_add_u64 v[50:51], v[50:51], 2, s[48:49]
	global_store_dword v[50:51], v53, off sc1
	v_add_u32_e32 v53, s0, v52
	v_add_u32_e32 v50, v100, v53
	v_mov_b32_e32 v51, v1
	v_lshl_add_u64 v[50:51], v[50:51], 2, s[48:49]
	global_store_dword v[50:51], v54, off sc1
	v_add_u32_e32 v54, s44, v53
	v_add_u32_e32 v50, v100, v54
	v_mov_b32_e32 v51, v1
	v_lshl_add_u64 v[50:51], v[50:51], 2, s[48:49]
	global_store_dword v[50:51], v55, off sc1
	v_add_u32_e32 v55, s44, v54
	v_add_u32_e32 v50, v100, v55
	v_mov_b32_e32 v51, v1
	v_lshl_add_u64 v[50:51], v[50:51], 2, s[48:49]
	global_store_dword v[50:51], v56, off sc1
	v_add_u32_e32 v56, s44, v55
	v_add_u32_e32 v50, v100, v56
	v_mov_b32_e32 v51, v1
	v_lshl_add_u64 v[50:51], v[50:51], 2, s[48:49]
	global_store_dword v[50:51], v57, off sc1
	v_add_u32_e32 v57, s0, v56
	v_add_u32_e32 v50, v100, v57
	v_mov_b32_e32 v51, v1
	v_lshl_add_u64 v[50:51], v[50:51], 2, s[48:49]
	global_store_dword v[50:51], v58, off sc1
	v_add_u32_e32 v58, s44, v57
	v_add_u32_e32 v50, v100, v58
	v_mov_b32_e32 v51, v1
	v_lshl_add_u64 v[50:51], v[50:51], 2, s[48:49]
	global_store_dword v[50:51], v59, off sc1
	v_add_u32_e32 v59, s44, v58
	v_add_u32_e32 v50, v100, v59
	v_mov_b32_e32 v51, v1
	v_lshl_add_u64 v[50:51], v[50:51], 2, s[48:49]
	global_store_dword v[50:51], v60, off sc1
	v_add_u32_e32 v60, s44, v59
	v_add_u32_e32 v50, v100, v60
	v_mov_b32_e32 v51, v1
	v_lshl_add_u64 v[50:51], v[50:51], 2, s[48:49]
	global_store_dword v[50:51], v61, off sc1
	v_add_u32_e32 v61, s0, v60
	v_add_u32_e32 v50, v100, v61
	v_mov_b32_e32 v51, v1
	v_lshl_add_u64 v[50:51], v[50:51], 2, s[48:49]
	global_store_dword v[50:51], v62, off sc1
	v_add_u32_e32 v62, s44, v61
	v_add_u32_e32 v50, v100, v62
	v_mov_b32_e32 v51, v1
	v_lshl_add_u64 v[50:51], v[50:51], 2, s[48:49]
	global_store_dword v[50:51], v63, off sc1
	v_add_u32_e32 v63, s44, v62
	v_add_u32_e32 v50, v100, v63
	v_mov_b32_e32 v51, v1
	v_lshl_add_u64 v[50:51], v[50:51], 2, s[48:49]
	global_store_dword v[50:51], v64, off sc1
	v_add_u32_e32 v64, s44, v63
	v_add_u32_e32 v50, v100, v64
	v_mov_b32_e32 v51, v1
	v_lshl_add_u64 v[50:51], v[50:51], 2, s[48:49]
	global_store_dword v[50:51], v65, off sc1
	v_add_u32_e32 v50, v97, v68
	v_mov_b32_e32 v51, v1
	v_lshl_add_u64 v[50:51], v[50:51], 2, s[48:49]
	global_store_dword v[50:51], v34, off sc1
	v_add_u32_e32 v50, v97, v69
	v_mov_b32_e32 v51, v1
	v_lshl_add_u64 v[50:51], v[50:51], 2, s[48:49]
	global_store_dword v[50:51], v35, off sc1
	v_add_u32_e32 v34, v97, v66
	v_mov_b32_e32 v35, v1
	v_lshl_add_u64 v[34:35], v[34:35], 2, s[48:49]
	global_store_dword v[34:35], v36, off sc1
	v_add_u32_e32 v34, v97, v52
	v_mov_b32_e32 v35, v1
	v_lshl_add_u64 v[34:35], v[34:35], 2, s[48:49]
	global_store_dword v[34:35], v37, off sc1
	v_add_u32_e32 v34, v97, v53
	v_mov_b32_e32 v35, v1
	v_lshl_add_u64 v[34:35], v[34:35], 2, s[48:49]
	global_store_dword v[34:35], v38, off sc1
	v_add_u32_e32 v34, v97, v54
	v_mov_b32_e32 v35, v1
	v_lshl_add_u64 v[34:35], v[34:35], 2, s[48:49]
	global_store_dword v[34:35], v39, off sc1
	v_add_u32_e32 v34, v97, v55
	v_mov_b32_e32 v35, v1
	v_lshl_add_u64 v[34:35], v[34:35], 2, s[48:49]
	global_store_dword v[34:35], v40, off sc1
	v_add_u32_e32 v34, v97, v56
	v_mov_b32_e32 v35, v1
	v_lshl_add_u64 v[34:35], v[34:35], 2, s[48:49]
	global_store_dword v[34:35], v41, off sc1
	v_add_u32_e32 v34, v97, v57
	v_mov_b32_e32 v35, v1
	v_lshl_add_u64 v[34:35], v[34:35], 2, s[48:49]
	global_store_dword v[34:35], v42, off sc1
	v_add_u32_e32 v34, v97, v58
	v_mov_b32_e32 v35, v1
	v_lshl_add_u64 v[34:35], v[34:35], 2, s[48:49]
	global_store_dword v[34:35], v43, off sc1
	v_add_u32_e32 v34, v97, v59
	v_mov_b32_e32 v35, v1
	v_lshl_add_u64 v[34:35], v[34:35], 2, s[48:49]
	global_store_dword v[34:35], v44, off sc1
	v_add_u32_e32 v34, v97, v60
	v_mov_b32_e32 v35, v1
	v_lshl_add_u64 v[34:35], v[34:35], 2, s[48:49]
	global_store_dword v[34:35], v45, off sc1
	v_add_u32_e32 v34, v97, v61
	v_mov_b32_e32 v35, v1
	v_lshl_add_u64 v[34:35], v[34:35], 2, s[48:49]
	global_store_dword v[34:35], v46, off sc1
	v_add_u32_e32 v34, v97, v62
	v_mov_b32_e32 v35, v1
	v_lshl_add_u64 v[34:35], v[34:35], 2, s[48:49]
	global_store_dword v[34:35], v47, off sc1
	v_add_u32_e32 v34, v97, v63
	v_mov_b32_e32 v35, v1
	v_lshl_add_u64 v[34:35], v[34:35], 2, s[48:49]
	global_store_dword v[34:35], v48, off sc1
	v_add_u32_e32 v34, v97, v64
	v_mov_b32_e32 v35, v1
	v_lshl_add_u64 v[34:35], v[34:35], 2, s[48:49]
	global_store_dword v[34:35], v49, off sc1
	v_add_u32_e32 v34, 64, v108
	v_mul_lo_u32 v36, s44, v34
	v_add_u32_e32 v34, v100, v36
	v_mov_b32_e32 v35, v1
	v_lshl_add_u64 v[34:35], v[34:35], 2, s[48:49]
	v_add_u32_e32 v37, s44, v36
	global_store_dword v[34:35], v18, off sc1
	v_add_u32_e32 v34, v100, v37
	v_mov_b32_e32 v35, v1
	v_lshl_add_u64 v[34:35], v[34:35], 2, s[48:49]
	global_store_dword v[34:35], v19, off sc1
	v_add_u32_e32 v34, s44, v37
	v_add_u32_e32 v18, v100, v34
	v_mov_b32_e32 v19, v1
	v_lshl_add_u64 v[18:19], v[18:19], 2, s[48:49]
	global_store_dword v[18:19], v20, off sc1
	v_add_u32_e32 v20, s44, v34
	v_add_u32_e32 v18, v100, v20
	v_mov_b32_e32 v19, v1
	v_lshl_add_u64 v[18:19], v[18:19], 2, s[48:49]
	global_store_dword v[18:19], v21, off sc1
	v_add_u32_e32 v21, s0, v20
	v_add_u32_e32 v18, v100, v21
	v_mov_b32_e32 v19, v1
	v_lshl_add_u64 v[18:19], v[18:19], 2, s[48:49]
	global_store_dword v[18:19], v22, off sc1
	v_add_u32_e32 v22, s44, v21
	v_add_u32_e32 v18, v100, v22
	v_mov_b32_e32 v19, v1
	v_lshl_add_u64 v[18:19], v[18:19], 2, s[48:49]
	global_store_dword v[18:19], v23, off sc1
	v_add_u32_e32 v23, s44, v22
	v_add_u32_e32 v18, v100, v23
	v_mov_b32_e32 v19, v1
	v_lshl_add_u64 v[18:19], v[18:19], 2, s[48:49]
	global_store_dword v[18:19], v24, off sc1
	v_add_u32_e32 v24, s44, v23
	v_add_u32_e32 v18, v100, v24
	v_mov_b32_e32 v19, v1
	v_lshl_add_u64 v[18:19], v[18:19], 2, s[48:49]
	global_store_dword v[18:19], v25, off sc1
	v_add_u32_e32 v25, s0, v24
	v_add_u32_e32 v18, v100, v25
	v_mov_b32_e32 v19, v1
	v_lshl_add_u64 v[18:19], v[18:19], 2, s[48:49]
	global_store_dword v[18:19], v26, off sc1
	v_add_u32_e32 v26, s44, v25
	v_add_u32_e32 v18, v100, v26
	v_mov_b32_e32 v19, v1
	v_lshl_add_u64 v[18:19], v[18:19], 2, s[48:49]
	global_store_dword v[18:19], v27, off sc1
	v_add_u32_e32 v27, s44, v26
	v_add_u32_e32 v18, v100, v27
	v_mov_b32_e32 v19, v1
	v_lshl_add_u64 v[18:19], v[18:19], 2, s[48:49]
	global_store_dword v[18:19], v28, off sc1
	v_add_u32_e32 v28, s44, v27
	v_add_u32_e32 v18, v100, v28
	v_mov_b32_e32 v19, v1
	v_lshl_add_u64 v[18:19], v[18:19], 2, s[48:49]
	global_store_dword v[18:19], v29, off sc1
	v_add_u32_e32 v29, s0, v28
	v_add_u32_e32 v18, v100, v29
	v_mov_b32_e32 v19, v1
	v_lshl_add_u64 v[18:19], v[18:19], 2, s[48:49]
	global_store_dword v[18:19], v30, off sc1
	v_add_u32_e32 v30, s44, v29
	v_add_u32_e32 v18, v100, v30
	v_mov_b32_e32 v19, v1
	v_lshl_add_u64 v[18:19], v[18:19], 2, s[48:49]
	global_store_dword v[18:19], v31, off sc1
	v_add_u32_e32 v31, s44, v30
	v_add_u32_e32 v18, v100, v31
	v_mov_b32_e32 v19, v1
	v_lshl_add_u64 v[18:19], v[18:19], 2, s[48:49]
	global_store_dword v[18:19], v32, off sc1
	v_add_u32_e32 v32, s44, v31
	v_add_u32_e32 v18, v100, v32
	v_mov_b32_e32 v19, v1
	v_lshl_add_u64 v[18:19], v[18:19], 2, s[48:49]
	global_store_dword v[18:19], v33, off sc1
	v_add_u32_e32 v18, v97, v36
	v_mov_b32_e32 v19, v1
	v_lshl_add_u64 v[18:19], v[18:19], 2, s[48:49]
	global_store_dword v[18:19], v2, off sc1
	v_add_u32_e32 v18, v97, v37
	v_mov_b32_e32 v19, v1
	v_lshl_add_u64 v[18:19], v[18:19], 2, s[48:49]
	global_store_dword v[18:19], v3, off sc1
	v_add_u32_e32 v2, v97, v34
	v_mov_b32_e32 v3, v1
	v_lshl_add_u64 v[2:3], v[2:3], 2, s[48:49]
	global_store_dword v[2:3], v4, off sc1
	v_add_u32_e32 v2, v97, v20
	v_mov_b32_e32 v3, v1
	v_lshl_add_u64 v[2:3], v[2:3], 2, s[48:49]
	global_store_dword v[2:3], v5, off sc1
	v_add_u32_e32 v2, v97, v21
	v_mov_b32_e32 v3, v1
	v_lshl_add_u64 v[2:3], v[2:3], 2, s[48:49]
	global_store_dword v[2:3], v6, off sc1
	v_add_u32_e32 v2, v97, v22
	v_mov_b32_e32 v3, v1
	v_lshl_add_u64 v[2:3], v[2:3], 2, s[48:49]
	global_store_dword v[2:3], v7, off sc1
	v_add_u32_e32 v2, v97, v23
	v_mov_b32_e32 v3, v1
	v_lshl_add_u64 v[2:3], v[2:3], 2, s[48:49]
	global_store_dword v[2:3], v8, off sc1
	v_add_u32_e32 v2, v97, v24
	v_mov_b32_e32 v3, v1
	v_lshl_add_u64 v[2:3], v[2:3], 2, s[48:49]
	global_store_dword v[2:3], v9, off sc1
	v_add_u32_e32 v2, v97, v25
	v_mov_b32_e32 v3, v1
	v_lshl_add_u64 v[2:3], v[2:3], 2, s[48:49]
	global_store_dword v[2:3], v10, off sc1
	v_add_u32_e32 v2, v97, v26
	v_mov_b32_e32 v3, v1
	v_lshl_add_u64 v[2:3], v[2:3], 2, s[48:49]
	global_store_dword v[2:3], v11, off sc1
	v_add_u32_e32 v2, v97, v27
	v_mov_b32_e32 v3, v1
	v_lshl_add_u64 v[2:3], v[2:3], 2, s[48:49]
	global_store_dword v[2:3], v12, off sc1
	v_add_u32_e32 v2, v97, v28
	v_mov_b32_e32 v3, v1
	v_lshl_add_u64 v[2:3], v[2:3], 2, s[48:49]
	global_store_dword v[2:3], v13, off sc1
	v_add_u32_e32 v2, v97, v29
	v_mov_b32_e32 v3, v1
	v_lshl_add_u64 v[2:3], v[2:3], 2, s[48:49]
	global_store_dword v[2:3], v14, off sc1
	v_add_u32_e32 v2, v97, v30
	v_mov_b32_e32 v3, v1
	v_lshl_add_u64 v[2:3], v[2:3], 2, s[48:49]
	global_store_dword v[2:3], v15, off sc1
	v_add_u32_e32 v2, v97, v31
	v_mov_b32_e32 v3, v1
	v_lshl_add_u64 v[2:3], v[2:3], 2, s[48:49]
	global_store_dword v[2:3], v16, off sc1
	v_add_u32_e32 v2, v97, v32
	v_mov_b32_e32 v3, v1
	v_lshl_add_u64 v[2:3], v[2:3], 2, s[48:49]
	global_store_dword v[2:3], v17, off sc1
	s_branch .LBB0_450

.LBB0_577:
	s_or_b64 exec, exec, s[20:21]
	s_waitcnt lgkmcnt(4)
	v_cvt_pk_bf16_f32 v13, v12, v13
	v_cvt_pk_bf16_f32 v12, v10, v11
	v_cvt_pk_bf16_f32 v10, v6, v7
	v_mad_u64_u32 v[6:7], s[20:21], v2, v0, 0
	v_mov_b32_e32 v2, v7
	v_mad_u64_u32 v[2:3], s[20:21], v3, v0, v[2:3]
	v_mov_b32_e32 v7, v2
	v_lshl_add_u64 v[2:3], v[6:7], 1, v[4:5]
	v_lshlrev_b32_e32 v0, 1, v41
	v_lshl_add_u64 v[2:3], v[2:3], 0, v[0:1]
	v_mov_b32_e32 v39, v1
	v_cvt_pk_bf16_f32 v11, v8, v9
	v_lshl_add_u64 v[2:3], v[2:3], 0, v[38:39]
	s_waitcnt lgkmcnt(0)
	v_cvt_pk_bf16_f32 v45, v44, v45
	v_cvt_pk_bf16_f32 v44, v42, v43
	v_cvt_pk_bf16_f32 v43, v16, v17
	v_cvt_pk_bf16_f32 v42, v14, v15
	global_store_dwordx4 v[2:3], v[10:13], off sc1
	global_store_dwordx4 v[2:3], v[42:45], off offset:16 sc1
	s_barrier

.LBB0_581:
	v_cvt_f64_u32_e32 v[6:7], v0
	v_mul_f64 v[6:7], v[18:19], v[6:7]
	v_mul_f64 v[8:9], v[6:7], s[4:5]
	v_rndne_f64_e32 v[8:9], v[8:9]
	v_fmac_f64_e32 v[6:7], s[6:7], v[8:9]
	s_mov_b32 s34, s10
	s_mov_b32 s10, 0x55555555
	v_fmac_f64_e32 v[6:7], s[8:9], v[8:9]
	s_mov_b32 s11, 0x3fc55555
	v_mul_f64 v[8:9], v[6:7], -v[6:7]
	s_mov_b32 s24, s14
	s_mov_b32 s14, 0x11111111
	v_mul_f64 v[12:13], v[8:9], s[10:11]
	s_mov_b32 s15, 0x3fa11111
	v_mul_f64 v[10:11], v[8:9], 0.5
	v_fma_f64 v[14:15], v[8:9], 0.5, 1.0
	v_mul_f64 v[16:17], v[8:9], s[34:35]
	v_mul_f64 v[42:43], v[8:9], s[12:13]
	v_mul_f64 v[136:137], v[6:7], v[12:13]
	v_fmac_f64_e32 v[6:7], v[6:7], v[12:13]
	v_mul_f64 v[44:45], v[8:9], s[14:15]
	v_mul_f64 v[46:47], v[8:9], s[16:17]
	v_mul_f64 v[12:13], v[10:11], v[16:17]
	v_fmac_f64_e32 v[14:15], v[10:11], v[16:17]
	v_mul_f64 v[10:11], v[42:43], v[136:137]
	v_fmac_f64_e32 v[6:7], v[42:43], v[136:137]
	s_mov_b32 s26, s60
	s_mov_b32 s60, 0xf07c1f08
	v_mul_f64 v[48:49], v[8:9], s[18:19]
	v_mul_f64 v[50:51], v[8:9], s[54:55]
	v_mul_f64 v[16:17], v[44:45], v[12:13]
	v_fmac_f64_e32 v[14:15], v[44:45], v[12:13]
	v_mul_f64 v[12:13], v[46:47], v[10:11]
	v_fmac_f64_e32 v[6:7], v[46:47], v[10:11]
	s_mov_b32 s92, s66
	s_mov_b32 s66, 0x13813814
	s_mov_b32 s61, 0x3f7f07c1
	v_mul_f64 v[52:53], v[8:9], s[56:57]
	v_mul_f64 v[70:71], v[8:9], s[58:59]
	v_mul_f64 v[10:11], v[48:49], v[16:17]
	v_fmac_f64_e32 v[14:15], v[48:49], v[16:17]
	v_mul_f64 v[16:17], v[50:51], v[12:13]
	v_fmac_f64_e32 v[6:7], v[50:51], v[12:13]
	s_mov_b32 s67, 0x3f738138
	v_mul_f64 v[72:73], v[8:9], s[60:61]
	v_mul_f64 v[74:75], v[8:9], s[62:63]
	v_mul_f64 v[12:13], v[52:53], v[10:11]
	v_fmac_f64_e32 v[14:15], v[52:53], v[10:11]
	v_mul_f64 v[10:11], v[70:71], v[16:17]
	v_fmac_f64_e32 v[6:7], v[70:71], v[16:17]
	v_mul_f64 v[76:77], v[8:9], s[64:65]
	v_mul_f64 v[78:79], v[8:9], s[66:67]
	v_mul_f64 v[16:17], v[72:73], v[12:13]
	v_fmac_f64_e32 v[14:15], v[72:73], v[12:13]
	v_mul_f64 v[12:13], v[74:75], v[10:11]
	v_fmac_f64_e32 v[6:7], v[74:75], v[10:11]
	v_mul_f64 v[80:81], v[8:9], s[24:25]
	v_mul_f64 v[82:83], v[8:9], s[68:69]
	v_mul_f64 v[10:11], v[76:77], v[16:17]
	v_fmac_f64_e32 v[14:15], v[76:77], v[16:17]
	v_mul_f64 v[16:17], v[78:79], v[12:13]
	v_fmac_f64_e32 v[6:7], v[78:79], v[12:13]
	v_mul_f64 v[84:85], v[8:9], s[70:71]
	v_mul_f64 v[86:87], v[8:9], s[72:73]
	v_mul_f64 v[12:13], v[80:81], v[10:11]
	v_fmac_f64_e32 v[14:15], v[80:81], v[10:11]
	v_mul_f64 v[10:11], v[82:83], v[16:17]
	v_fmac_f64_e32 v[6:7], v[82:83], v[16:17]
	v_mul_f64 v[88:89], v[8:9], s[74:75]
	v_mul_f64 v[90:91], v[8:9], s[92:93]
	v_mul_f64 v[16:17], v[86:87], v[12:13]
	v_fmac_f64_e32 v[14:15], v[86:87], v[12:13]
	v_mul_f64 v[12:13], v[84:85], v[10:11]
	v_fmac_f64_e32 v[6:7], v[84:85], v[10:11]
	v_mul_f64 v[92:93], v[8:9], s[76:77]
	v_mul_f64 v[94:95], v[8:9], s[78:79]
	v_mul_f64 v[10:11], v[88:89], v[16:17]
	v_fmac_f64_e32 v[14:15], v[88:89], v[16:17]
	v_mul_f64 v[16:17], v[90:91], v[12:13]
	v_fmac_f64_e32 v[6:7], v[90:91], v[12:13]
	v_mul_f64 v[96:97], v[8:9], s[94:95]
	v_mul_f64 v[98:99], v[8:9], s[84:85]
	v_mul_f64 v[12:13], v[94:95], v[10:11]
	v_fmac_f64_e32 v[14:15], v[94:95], v[10:11]
	v_mul_f64 v[10:11], v[92:93], v[16:17]
	v_fmac_f64_e32 v[6:7], v[92:93], v[16:17]
	v_mul_f64 v[100:101], v[8:9], s[40:41]
	v_mul_f64 v[102:103], v[8:9], s[86:87]
	v_mul_f64 v[16:17], v[96:97], v[12:13]
	v_fmac_f64_e32 v[14:15], v[96:97], v[12:13]
	v_mul_f64 v[12:13], v[98:99], v[10:11]
	v_fmac_f64_e32 v[6:7], v[98:99], v[10:11]
	v_mul_f64 v[104:105], v[8:9], s[0:1]
	v_mul_f64 v[106:107], v[8:9], s[88:89]
	v_mul_f64 v[10:11], v[102:103], v[16:17]
	v_fmac_f64_e32 v[14:15], v[102:103], v[16:17]
	v_mul_f64 v[16:17], v[100:101], v[12:13]
	v_fmac_f64_e32 v[6:7], v[100:101], v[12:13]
	v_mul_f64 v[108:109], v[8:9], s[38:39]
	v_mul_f64 v[110:111], v[8:9], s[90:91]
	v_mul_f64 v[12:13], v[104:105], v[10:11]
	v_fmac_f64_e32 v[14:15], v[104:105], v[10:11]
	v_mul_f64 v[10:11], v[106:107], v[16:17]
	v_fmac_f64_e32 v[6:7], v[106:107], v[16:17]
	v_mul_f64 v[112:113], v[8:9], s[82:83]
	v_mul_f64 v[8:9], v[8:9], s[26:27]
	v_mul_f64 v[16:17], v[110:111], v[12:13]
	v_fmac_f64_e32 v[14:15], v[110:111], v[12:13]
	v_mul_f64 v[12:13], v[108:109], v[10:11]
	v_fmac_f64_e32 v[6:7], v[108:109], v[10:11]
	v_add_u32_e32 v4, 0x100, v4
	s_movk_i32 s20, 0x2ff
	v_fmac_f64_e32 v[14:15], v[112:113], v[16:17]
	v_fmac_f64_e32 v[6:7], v[8:9], v[12:13]
	v_cmp_lt_u32_e32 vcc, s20, v4
	v_cvt_f32_f64_e32 v8, v[14:15]
	v_cvt_f32_f64_e32 v9, v[6:7]
	s_mov_b64 s[20:21], 0x800
	v_add_u32_e32 v0, 16, v0
	s_or_b64 s[46:47], vcc, s[46:47]
	global_store_dwordx2 v[2:3], v[8:9], off sc1
	v_lshl_add_u64 v[2:3], v[2:3], 0, s[20:21]
	s_andn2_b64 exec, exec, s[46:47]
	s_cbranch_execnz .LBB0_581
	s_or_b64 exec, exec, s[46:47]
	s_mov_b32 s86, 0x6b015ac0
	s_mov_b32 s88, 0x19e0119e
	s_mov_b32 s90, 0x8421084
	s_mov_b64 s[94:95], s[36:37]
	v_readlane_b32 s36, v255, 8
	s_mov_b32 s85, s28
	s_mov_b32 s87, 0x3f55ac05
	s_mov_b32 s89, 0x3f519e01
	s_mov_b64 s[38:39], s[96:97]
	s_mov_b32 s91, 0x3f508421
	s_mov_b32 s82, s42
	s_mov_b32 s83, s43
	s_mov_b32 s78, s81
	v_readlane_b32 s37, v255, 9

.LBB0_585:
	v_mov_b32_e32 v0, v2
	s_add_i32 s24, s24, -2
	v_add_u32_e32 v2, 0x200, v2
	v_lshl_add_u64 v[4:5], v[0:1], 4, s[4:5]
	v_mov_b32_e32 v0, v3
	v_add_u32_e32 v3, 0x200, v3
	s_cmp_lg_u32 s24, 0
	v_lshl_add_u64 v[6:7], v[0:1], 4, s[4:5]
	global_store_dwordx4 v[4:5], v[190:193], off sc1
	global_store_dwordx4 v[6:7], v[190:193], off sc1
	s_cbranch_scc1 .LBB0_585
	s_mov_b32 s24, 64
	v_mov_b64_e32 v[2:3], v[134:135]
.LBB0_587:
	v_mov_b32_e32 v0, v2
	s_add_i32 s24, s24, -2
	v_add_u32_e32 v2, 0x200, v2
	v_lshl_add_u64 v[4:5], v[0:1], 4, s[6:7]
	v_mov_b32_e32 v0, v3
	v_add_u32_e32 v3, 0x200, v3
	s_cmp_eq_u32 s24, 0
	v_lshl_add_u64 v[6:7], v[0:1], 4, s[6:7]
	global_store_dwordx4 v[4:5], v[190:193], off sc1
	global_store_dwordx4 v[6:7], v[190:193], off sc1
	s_cbranch_scc0 .LBB0_587
.LBB0_588:
	s_or_b64 exec, exec, s[20:21]
	s_movk_i32 s20, 0xd0
	v_readlane_b32 s0, v255, 6
	v_cmp_eq_u32_e32 vcc, s20, v69
	v_readlane_b32 s1, v255, 7
	s_and_b64 s[44:45], vcc, s[0:1]
	s_and_saveexec_b64 s[20:21], s[44:45]
	s_cbranch_execz .LBB0_590
	global_store_dword v[28:29], v1, off sc1

.LBB0_592:
	v_mov_b32_e32 v0, 0xffff7000
	v_lshl_add_u32 v2, v69, 8, v0
	v_or_b32_e32 v0, v2, v134
	v_lshrrev_b32_e32 v2, 6, v2
	v_lshrrev_b32_e32 v3, 6, v0
	v_and_b32_e32 v2, 0x3ffffc0, v2
	v_and_or_b32 v2, v3, 63, v2
	v_readlane_b32 s60, v253, 17
	v_lshlrev_b32_e32 v3, 2, v2
	v_readlane_b32 s64, v253, 21
	v_readlane_b32 s65, v253, 22
	s_mov_b32 s4, 0xfca7ab0c
	s_mov_b32 s5, 0x3e928af3
	v_mov_b64_e32 v[6:7], s[4:5]
	s_mov_b32 s4, 0x652b82fe
	s_mov_b32 s5, 0x3ff71547
	global_load_dword v3, v3, s[64:65]
	s_mov_b32 s6, 0xfefa39ef
	s_mov_b32 s7, 0xbfe62e42
	s_mov_b32 s8, 0x3b39803f
	s_mov_b32 s9, 0xbc7abc9e
	s_mov_b32 s10, 0x6a5dcb37
	s_mov_b32 s11, 0x3e5ade15
	s_mov_b32 s12, 0x623fde64
	s_mov_b32 s13, 0x3ec71dee
	s_mov_b32 s14, 0x7c89e6b0
	s_mov_b32 s15, 0x3efa0199
	s_mov_b32 s16, 0x14761f6e
	s_mov_b32 s17, 0x3f2a01a0
	s_mov_b32 s18, 0x1852b7b0
	s_mov_b32 s19, 0x3f56c16c
	s_mov_b32 s46, 0x11122322
	s_mov_b32 s56, 0x55555555
	v_readlane_b32 s0, v253, 15
	s_mov_b32 s47, 0x3f811111
	s_mov_b32 s52, 0x555502a1
	s_mov_b32 s57, 0x3fc55555
	v_readlane_b32 s1, v253, 16
	s_mov_b32 s53, 0x3fa55555
	s_mov_b32 s1, s57
	s_mov_b32 s54, 11
	s_mov_b32 s55, 0x3fe00000
	s_mov_b32 s20, 0x44800000
	v_readlane_b32 s61, v253, 18
	v_readlane_b32 s62, v253, 19
	v_readlane_b32 s63, v253, 20
	v_readlane_b32 s66, v253, 23
	v_readlane_b32 s67, v253, 24
	v_readlane_b32 s68, v253, 25
	v_readlane_b32 s69, v253, 26
	v_readlane_b32 s70, v253, 27
	v_readlane_b32 s71, v253, 28
	v_readlane_b32 s72, v253, 29
	v_readlane_b32 s73, v253, 30
	v_readlane_b32 s74, v253, 31
	v_readlane_b32 s75, v253, 32
	s_mov_b32 s34, s56
	s_waitcnt vmcnt(0)
	v_cvt_f64_f32_e32 v[4:5], v3
	v_mul_f64 v[8:9], v[4:5], s[4:5]
	v_rndne_f64_e32 v[8:9], v[8:9]
	v_fmac_f64_e32 v[4:5], s[6:7], v[8:9]
	v_fmac_f64_e32 v[4:5], s[8:9], v[8:9]
	v_cvt_i32_f64_e32 v10, v[8:9]
	v_fma_f64 v[8:9], s[10:11], v[4:5], v[6:7]
	v_fma_f64 v[8:9], v[4:5], v[8:9], s[12:13]
	v_fma_f64 v[8:9], v[4:5], v[8:9], s[14:15]
	v_fma_f64 v[8:9], v[4:5], v[8:9], s[16:17]
	v_fma_f64 v[8:9], v[4:5], v[8:9], s[18:19]
	v_fma_f64 v[8:9], v[4:5], v[8:9], s[46:47]
	v_fma_f64 v[8:9], v[4:5], v[8:9], s[52:53]
	v_fma_f64 v[8:9], v[4:5], v[8:9], s[0:1]
	v_fma_f64 v[8:9], v[4:5], v[8:9], s[54:55]
	v_fma_f64 v[8:9], v[4:5], v[8:9], 1.0
	v_fma_f64 v[4:5], v[4:5], v[8:9], 1.0
	v_cmp_nlt_f32_e32 vcc, s20, v3
	s_mov_b32 s20, 0xc4866000
	v_ldexp_f64 v[4:5], v[4:5], v10
	v_cmp_ngt_f32_e64 s[44:45], s20, v3
	v_cndmask_b32_e32 v5, v200, v5, vcc
	s_and_b64 vcc, s[44:45], vcc
	v_lshlrev_b64 v[8:9], 2, v[0:1]
	v_cndmask_b32_e64 v11, 0, v5, s[44:45]
	v_cndmask_b32_e32 v10, 0, v4, vcc
	v_lshl_add_u64 v[4:5], s[60:61], 0, v[8:9]
	global_load_dword v3, v[4:5], off
	v_lshl_add_u64 v[8:9], s[62:63], 0, v[8:9]
	s_waitcnt vmcnt(0)
	v_cvt_f64_f32_e32 v[4:5], v3
	v_mul_f64 v[12:13], v[10:11], v[4:5]
	v_mul_f64 v[14:15], v[12:13], s[4:5]
	v_rndne_f64_e32 v[14:15], v[14:15]
	v_fma_f64 v[16:17], s[6:7], v[14:15], v[12:13]
	v_fmac_f64_e32 v[16:17], s[8:9], v[14:15]
	v_fmac_f64_e32 v[6:7], s[10:11], v[16:17]
	v_fma_f64 v[6:7], v[16:17], v[6:7], s[12:13]
	v_fma_f64 v[6:7], v[16:17], v[6:7], s[14:15]
	v_fma_f64 v[6:7], v[16:17], v[6:7], s[16:17]
	v_fma_f64 v[6:7], v[16:17], v[6:7], s[18:19]
	v_fma_f64 v[6:7], v[16:17], v[6:7], s[46:47]
	v_fma_f64 v[6:7], v[16:17], v[6:7], s[52:53]
	v_fma_f64 v[6:7], v[16:17], v[6:7], s[0:1]
	s_mov_b32 s4, s0
	v_fma_f64 v[6:7], v[16:17], v[6:7], s[54:55]
	s_mov_b32 s0, 0
	v_fma_f64 v[6:7], v[16:17], v[6:7], 1.0
	s_mov_b32 s1, 0x40900000
	v_cvt_i32_f64_e32 v3, v[14:15]
	v_fma_f64 v[6:7], v[16:17], v[6:7], 1.0
	v_cmp_nlt_f64_e32 vcc, s[0:1], v[12:13]
	s_mov_b32 s0, 0
	v_ldexp_f64 v[6:7], v[6:7], v3
	s_mov_b32 s1, 0xc090cc00
	v_cndmask_b32_e32 v3, v200, v7, vcc
	v_cmp_ngt_f64_e64 s[44:45], s[0:1], v[12:13]
	v_writelane_b32 v253, s4, 15
	s_mov_b32 s6, 0x11111111
	v_cndmask_b32_e64 v7, 0, v3, s[44:45]
	global_load_dword v3, v[8:9], off
	v_writelane_b32 v253, s5, 16
	s_mov_b32 s4, 0x6dc9c883
	s_mov_b32 s5, 0x3fc45f30
	s_mov_b32 s7, 0x3fa11111
	s_mov_b32 s24, s6
	s_mov_b32 s8, 0x1e1e1e1e
	s_mov_b32 s9, 0x3f6e1e1e
	s_mov_b32 s0, 0x25d51f87
	s_mov_b32 s1, 0x3f542d66
	s_and_b64 vcc, s[44:45], vcc
	v_cndmask_b32_e32 v6, 0, v6, vcc
	s_waitcnt vmcnt(0)
	v_cvt_f64_f32_e32 v[12:13], v3
	v_mul_f64 v[10:11], v[10:11], v[12:13]
	v_mul_f64 v[14:15], v[10:11], s[4:5]
	s_mov_b32 s4, 0x54442d18
	v_rndne_f64_e32 v[14:15], v[14:15]
	s_mov_b32 s5, 0xc01921fb
	v_fmac_f64_e32 v[10:11], s[4:5], v[14:15]
	s_mov_b32 s4, 0x33145c07
	s_mov_b32 s5, 0xbcb1a626
	v_fmac_f64_e32 v[10:11], s[4:5], v[14:15]
	s_mov_b32 s4, 0x9999999a
	v_mul_f64 v[14:15], v[10:11], -v[10:11]
	s_mov_b32 s5, 0x3fa99999
	v_mul_f64 v[48:49], v[14:15], s[4:5]
	s_mov_b32 s4, 0x18618618
	s_mov_b32 s5, 0x3f986186
	v_mul_f64 v[52:53], v[14:15], s[4:5]
	s_mov_b32 s4, 0x92492492
	s_mov_b32 s5, 0x3f924924
	v_mul_f64 v[70:71], v[14:15], s[4:5]
	s_mov_b32 s4, 0x1c71c71c
	s_mov_b32 s5, 0x3f8c71c7
	v_mul_f64 v[72:73], v[14:15], s[4:5]
	s_mov_b32 s4, 0x16c16c17
	s_mov_b32 s5, 0x3f86c16c
	v_mul_f64 v[16:17], v[14:15], 0.5
	v_mul_f64 v[42:43], v[14:15], s[56:57]
	v_fma_f64 v[44:45], v[14:15], 0.5, 1.0
	v_mul_f64 v[46:47], v[14:15], s[34:35]
	v_mul_f64 v[50:51], v[14:15], s[6:7]
	v_mul_f64 v[74:75], v[14:15], s[4:5]
	s_mov_b32 s4, 0x29e4129e
	s_mov_b32 s6, 0x1a41a41a
	s_mov_b32 s5, 0x3f829e41
	s_mov_b32 s7, 0x3f7a41a4
	v_mul_f64 v[94:95], v[10:11], v[42:43]
	v_fmac_f64_e32 v[10:11], v[10:11], v[42:43]
	v_mul_f64 v[42:43], v[16:17], v[46:47]
	v_fmac_f64_e32 v[44:45], v[16:17], v[46:47]
	v_mul_f64 v[76:77], v[14:15], s[4:5]
	s_mov_b32 s4, 0xf07c1f08
	v_mul_f64 v[80:81], v[14:15], s[6:7]
	s_mov_b32 s6, 0x16816817
	v_mul_f64 v[88:89], v[14:15], s[8:9]
	s_mov_b32 s8, 0x1ac5701b
	v_mul_f64 v[16:17], v[48:49], v[94:95]
	v_fmac_f64_e32 v[10:11], v[48:49], v[94:95]
	v_mul_f64 v[46:47], v[50:51], v[42:43]
	v_fmac_f64_e32 v[44:45], v[50:51], v[42:43]
	s_mov_b32 s5, 0x3f7f07c1
	s_mov_b32 s7, 0x3f768168
	s_mov_b32 s9, 0x3f6ac570
	v_mul_f64 v[42:43], v[52:53], v[16:17]
	v_fmac_f64_e32 v[10:11], v[52:53], v[16:17]
	v_mul_f64 v[16:17], v[70:71], v[46:47]
	v_fmac_f64_e32 v[44:45], v[70:71], v[46:47]
	v_mul_f64 v[78:79], v[14:15], s[4:5]
	v_mul_f64 v[82:83], v[14:15], s[6:7]
	s_mov_b32 s6, 0x13813814
	v_mul_f64 v[90:91], v[14:15], s[8:9]
	s_mov_b32 s8, 0xfd017f40
	v_mul_f64 v[46:47], v[72:73], v[42:43]
	v_fmac_f64_e32 v[10:11], v[72:73], v[42:43]
	v_mul_f64 v[42:43], v[74:75], v[16:17]
	v_fmac_f64_e32 v[44:45], v[74:75], v[16:17]
	s_mov_b32 s7, 0x3f738138
	s_mov_b32 s9, 0x3f67f405
	v_mul_f64 v[16:17], v[76:77], v[46:47]
	v_fmac_f64_e32 v[10:11], v[76:77], v[46:47]
	v_mul_f64 v[46:47], v[78:79], v[42:43]
	v_fmac_f64_e32 v[44:45], v[78:79], v[42:43]
	v_mul_f64 v[84:85], v[14:15], s[6:7]
	v_mul_f64 v[86:87], v[14:15], s[24:25]
	v_mul_f64 v[92:93], v[14:15], s[8:9]
	v_mul_f64 v[42:43], v[80:81], v[16:17]
	v_fmac_f64_e32 v[10:11], v[80:81], v[16:17]
	v_mul_f64 v[16:17], v[82:83], v[46:47]
	v_fmac_f64_e32 v[44:45], v[82:83], v[46:47]
	s_mov_b32 s8, 0x308158ed
	v_mul_f64 v[46:47], v[84:85], v[42:43]
	v_fmac_f64_e32 v[10:11], v[84:85], v[42:43]
	v_mul_f64 v[42:43], v[86:87], v[16:17]
	v_fmac_f64_e32 v[44:45], v[86:87], v[16:17]
	s_mov_b32 s9, 0x3f658ed2
	s_mov_b32 s92, s6
	s_mov_b32 s6, 0xb51f5e1a
	v_mul_f64 v[16:17], v[90:91], v[42:43]
	v_fmac_f64_e32 v[44:45], v[90:91], v[42:43]
	v_mul_f64 v[42:43], v[14:15], s[8:9]
	s_mov_b32 s7, 0x3f603091
	v_mul_f64 v[52:53], v[42:43], v[16:17]
	v_fmac_f64_e32 v[44:45], v[42:43], v[16:17]
	v_mul_f64 v[16:17], v[14:15], s[6:7]
	s_mov_b32 s6, 0x4046ed29
	v_mul_f64 v[48:49], v[88:89], v[46:47]
	v_fmac_f64_e32 v[10:11], v[88:89], v[46:47]
	s_mov_b32 s7, 0x3f61bb4a
	v_mul_f64 v[46:47], v[92:93], v[48:49]
	v_fmac_f64_e32 v[10:11], v[92:93], v[48:49]
	v_mul_f64 v[48:49], v[14:15], s[92:93]
	v_mul_f64 v[42:43], v[14:15], s[6:7]
	s_mov_b32 s6, 0x76b981db
	v_mul_f64 v[50:51], v[48:49], v[46:47]
	v_fmac_f64_e32 v[10:11], v[48:49], v[46:47]
	s_mov_b32 s7, 0x3f5dae60
	v_mul_f64 v[48:49], v[16:17], v[50:51]
	v_fmac_f64_e32 v[10:11], v[16:17], v[50:51]
	v_mul_f64 v[16:17], v[14:15], s[6:7]
	s_mov_b32 s6, 0xb4e81b4f
	s_mov_b32 s7, 0x3f5b4e81
	v_mul_f64 v[46:47], v[42:43], v[52:53]
	v_fmac_f64_e32 v[44:45], v[42:43], v[52:53]
	v_mul_f64 v[42:43], v[14:15], s[6:7]
	s_mov_b32 s6, 0xc201756d
	s_mov_b32 s7, 0x3f5756ca
	v_mul_f64 v[52:53], v[16:17], v[46:47]
	v_fmac_f64_e32 v[44:45], v[16:17], v[46:47]
	v_mul_f64 v[16:17], v[14:15], s[6:7]
	s_mov_b32 s6, 0x7f9b2ce6
	s_mov_b32 s7, 0x3f5934c6
	v_mul_f64 v[50:51], v[42:43], v[48:49]
	v_fmac_f64_e32 v[10:11], v[42:43], v[48:49]
	v_mul_f64 v[42:43], v[14:15], s[6:7]
	v_mul_f64 v[46:47], v[42:43], v[52:53]
	v_mul_f64 v[48:49], v[16:17], v[50:51]
	v_fmac_f64_e32 v[44:45], v[42:43], v[52:53]
	v_fmac_f64_e32 v[10:11], v[16:17], v[50:51]
	v_mul_f64 v[16:17], v[14:15], s[86:87]
	v_mul_f64 v[42:43], v[14:15], s[0:1]
	s_mov_b32 s0, 0x12d50a0
	v_mul_f64 v[50:51], v[42:43], v[48:49]
	v_mul_f64 v[52:53], v[16:17], v[46:47]
	v_fmac_f64_e32 v[10:11], v[42:43], v[48:49]
	v_fmac_f64_e32 v[44:45], v[16:17], v[46:47]
	v_mul_f64 v[16:17], v[14:15], s[88:89]
	s_mov_b32 s1, 0x3f52d50a
	s_mov_b32 s26, s4
	v_mul_f64 v[42:43], v[14:15], s[0:1]
	v_mul_f64 v[48:49], v[16:17], v[50:51]
	v_fmac_f64_e32 v[10:11], v[16:17], v[50:51]
	v_mul_f64 v[16:17], v[14:15], s[90:91]
	v_mul_f64 v[14:15], v[14:15], s[26:27]
	v_mul_f64 v[46:47], v[42:43], v[52:53]
	v_fmac_f64_e32 v[44:45], v[42:43], v[52:53]
	v_fmac_f64_e32 v[10:11], v[14:15], v[48:49]
	v_fmac_f64_e32 v[44:45], v[16:17], v[46:47]
	v_mul_f64 v[10:11], v[6:7], v[10:11]
	v_mul_f64 v[8:9], v[12:13], v[12:13]
	v_fma_f64 v[14:15], v[6:7], v[44:45], -1.0
	v_mul_f64 v[16:17], v[10:11], v[12:13]
	v_fmac_f64_e32 v[8:9], v[4:5], v[4:5]
	v_fmac_f64_e32 v[16:17], v[14:15], v[4:5]
	v_div_scale_f64 v[42:43], s[20:21], v[8:9], v[8:9], v[16:17]
	v_rcp_f64_e32 v[46:47], v[42:43]
	v_mul_f64 v[12:13], v[14:15], v[12:13]
	v_fma_f64 v[4:5], v[10:11], v[4:5], -v[12:13]
	v_div_scale_f64 v[12:13], s[20:21], v[8:9], v[8:9], v[4:5]
	v_fma_f64 v[48:49], -v[42:43], v[46:47], 1.0
	v_fmac_f64_e32 v[46:47], v[46:47], v[48:49]
	v_fma_f64 v[48:49], -v[42:43], v[46:47], 1.0
	v_rcp_f64_e32 v[14:15], v[12:13]
	v_fmac_f64_e32 v[46:47], v[46:47], v[48:49]
	v_div_scale_f64 v[48:49], vcc, v[16:17], v[8:9], v[16:17]
	v_mul_f64 v[50:51], v[48:49], v[46:47]
	v_fma_f64 v[42:43], -v[42:43], v[50:51], v[48:49]
	v_readlane_b32 s4, v253, 33
	s_nop 0
	v_div_fmas_f64 v[42:43], v[42:43], v[46:47], v[50:51]
	v_fma_f64 v[46:47], -v[12:13], v[14:15], 1.0
	v_fmac_f64_e32 v[14:15], v[14:15], v[46:47]
	v_fma_f64 v[46:47], -v[12:13], v[14:15], 1.0
	v_fmac_f64_e32 v[14:15], v[14:15], v[46:47]
	v_div_scale_f64 v[46:47], vcc, v[4:5], v[8:9], v[4:5]
	v_mul_f64 v[48:49], v[46:47], v[14:15]
	v_fma_f64 v[12:13], -v[12:13], v[48:49], v[46:47]
	v_readlane_b32 s14, v253, 43
	s_nop 0
	v_div_fmas_f64 v[12:13], v[12:13], v[14:15], v[48:49]
	v_lshlrev_b32_e32 v14, 1, v0
	v_mov_b32_e32 v15, v1
	v_readlane_b32 s15, v253, 44
	v_mul_f64 v[6:7], v[6:7], v[44:45]
	v_cvt_f32_f64_e32 v6, v[6:7]
	v_lshl_add_u64 v[14:15], v[14:15], 2, s[14:15]
	v_cvt_f32_f64_e32 v7, v[10:11]
	global_store_dwordx2 v[14:15], v[6:7], off sc1
	v_lshlrev_b64 v[6:7], 6, v[0:1]
	v_lshl_add_u64 v[14:15], s[68:69], 0, v[6:7]
	v_lshl_add_u64 v[10:11], s[66:67], 0, v[6:7]
	global_load_dwordx4 v[74:77], v[14:15], off
	global_load_dwordx4 v[70:73], v[10:11], off
	v_mov_b32_e32 v3, v1
	v_lshlrev_b64 v[52:53], 12, v[2:3]
	v_lshl_or_b32 v2, v20, 2, v52
	v_mov_b32_e32 v3, v53
	v_lshl_add_u64 v[50:51], s[72:73], 0, v[2:3]
	v_lshl_add_u64 v[48:49], s[70:71], 0, v[2:3]
	global_load_dword v0, v[50:51], off
	global_load_dword v37, v[48:49], off
	global_load_dword v39, v[48:49], off offset:256
	global_load_dword v41, v[50:51], off offset:256
	global_load_dword v90, v[50:51], off offset:512
	global_load_dword v91, v[48:49], off offset:512
	global_load_dword v92, v[48:49], off offset:768
	global_load_dword v93, v[50:51], off offset:768
	global_load_dwordx4 v[78:81], v[10:11], off offset:16
	global_load_dwordx4 v[82:85], v[14:15], off offset:16
	v_div_fixup_f64 v[44:45], v[12:13], v[8:9], v[4:5]
	v_div_fixup_f64 v[42:43], v[42:43], v[8:9], v[16:17]
	global_load_dwordx4 v[2:5], v[10:11], off offset:48
	s_nop 0
	global_load_dwordx4 v[10:13], v[10:11], off offset:32
	s_nop 0
	global_load_dword v94, v[48:49], off offset:1024
	global_load_dword v95, v[50:51], off offset:1024
	global_load_dwordx4 v[6:9], v[14:15], off offset:48
	s_nop 0
	global_load_dwordx4 v[14:17], v[14:15], off offset:32
	v_readlane_b32 s5, v253, 34
	v_readlane_b32 s6, v253, 35
	v_readlane_b32 s7, v253, 36
	v_readlane_b32 s8, v253, 37
	v_readlane_b32 s9, v253, 38
	v_readlane_b32 s10, v253, 39
	v_readlane_b32 s11, v253, 40
	v_readlane_b32 s12, v253, 41
	v_readlane_b32 s13, v253, 42
	v_readlane_b32 s16, v253, 45
	v_readlane_b32 s17, v253, 46
	v_readlane_b32 s18, v253, 47
	v_readlane_b32 s19, v253, 48
	s_waitcnt vmcnt(17)
	v_cvt_f64_f32_e32 v[88:89], v74
	s_waitcnt vmcnt(16)
	v_cvt_f64_f32_e32 v[86:87], v70
	v_mul_f64 v[46:47], v[44:45], v[88:89]
	v_fma_f64 v[46:47], v[42:43], v[86:87], -v[46:47]
	v_cvt_f32_f64_e32 v46, v[46:47]
	v_mul_f64 v[88:89], v[42:43], v[88:89]
	v_cvt_pk_bf16_f32 v70, v46, s0
	v_lshl_add_u64 v[46:47], v[22:23], 0, v[52:53]
	v_fmac_f64_e32 v[88:89], v[44:45], v[86:87]
	global_store_short v[46:47], v70, off sc1
	v_cvt_f32_f64_e32 v70, v[88:89]
	v_cvt_pk_bf16_f32 v70, v70, s0
	global_store_short v[46:47], v70, off offset:2048 sc1
	global_load_dword v88, v[48:49], off offset:1280
	global_load_dword v89, v[50:51], off offset:1280
	global_load_dword v96, v[48:49], off offset:1536
	global_load_dword v97, v[48:49], off offset:1792
	global_load_dword v98, v[50:51], off offset:1536
	global_load_dword v99, v[50:51], off offset:1792
	v_cvt_f64_f32_e32 v[74:75], v75
	v_cvt_f64_f32_e32 v[70:71], v71
	v_mul_f64 v[86:87], v[44:45], v[74:75]
	v_lshl_add_u64 v[52:53], v[26:27], 0, v[52:53]
	s_waitcnt vmcnt(22)
	v_cvt_pk_bf16_f32 v0, v37, -v0
	v_fma_f64 v[86:87], v[42:43], v[70:71], -v[86:87]
	global_store_dword v[52:53], v0, off sc1
	v_cvt_f32_f64_e32 v0, v[86:87]
	v_mul_f64 v[74:75], v[42:43], v[74:75]
	v_cvt_pk_bf16_f32 v0, v0, s0
	v_fmac_f64_e32 v[74:75], v[44:45], v[70:71]
	global_store_short v[46:47], v0, off offset:2 sc1
	v_cvt_f32_f64_e32 v0, v[74:75]
	v_cvt_f64_f32_e32 v[74:75], v76
	v_cvt_pk_bf16_f32 v0, v0, s0
	v_cvt_f64_f32_e32 v[70:71], v72
	v_mul_f64 v[86:87], v[44:45], v[74:75]
	global_store_short v[46:47], v0, off offset:2050 sc1
	s_waitcnt vmcnt(23)
	v_cvt_pk_bf16_f32 v0, v39, -v41
	v_fma_f64 v[86:87], v[42:43], v[70:71], -v[86:87]
	global_store_dword v[52:53], v0, off offset:256 sc1
	v_cvt_f32_f64_e32 v0, v[86:87]
	v_mul_f64 v[74:75], v[42:43], v[74:75]
	v_cvt_pk_bf16_f32 v0, v0, s0
	v_fmac_f64_e32 v[74:75], v[44:45], v[70:71]
	global_store_short v[46:47], v0, off offset:4 sc1
	v_cvt_f32_f64_e32 v0, v[74:75]
	v_cvt_f64_f32_e32 v[70:71], v73
	v_cvt_f64_f32_e32 v[72:73], v77
	v_cvt_pk_bf16_f32 v0, v0, s0
	v_mul_f64 v[74:75], v[44:45], v[72:73]
	global_store_short v[46:47], v0, off offset:2052 sc1
	s_waitcnt vmcnt(24)
	v_cvt_pk_bf16_f32 v0, v91, -v90
	v_fma_f64 v[74:75], v[42:43], v[70:71], -v[74:75]
	global_store_dword v[52:53], v0, off offset:512 sc1
	v_cvt_f32_f64_e32 v0, v[74:75]
	v_mul_f64 v[72:73], v[42:43], v[72:73]
	v_cvt_pk_bf16_f32 v0, v0, s0
	v_fmac_f64_e32 v[72:73], v[44:45], v[70:71]
	global_store_short v[46:47], v0, off offset:6 sc1
	v_cvt_f32_f64_e32 v0, v[72:73]
	s_waitcnt vmcnt(22)
	v_cvt_f64_f32_e32 v[72:73], v82
	v_cvt_pk_bf16_f32 v0, v0, s0
	v_cvt_f64_f32_e32 v[70:71], v78
	v_mul_f64 v[74:75], v[44:45], v[72:73]
	global_store_short v[46:47], v0, off offset:2054 sc1
	v_cvt_pk_bf16_f32 v0, v92, -v93
	v_fma_f64 v[74:75], v[42:43], v[70:71], -v[74:75]
	global_store_dword v[52:53], v0, off offset:768 sc1
	v_cvt_f32_f64_e32 v39, v[74:75]
	v_mul_f64 v[72:73], v[42:43], v[72:73]
	global_load_dword v0, v[48:49], off offset:2048
	global_load_dword v37, v[50:51], off offset:2048
	v_cvt_pk_bf16_f32 v39, v39, s0
	v_fmac_f64_e32 v[72:73], v[44:45], v[70:71]
	global_store_short v[46:47], v39, off offset:8 sc1
	v_cvt_f32_f64_e32 v39, v[72:73]
	v_cvt_pk_bf16_f32 v39, v39, s0
	v_cvt_f64_f32_e32 v[72:73], v83
	global_store_short v[46:47], v39, off offset:2056 sc1
	s_waitcnt vmcnt(24)
	v_cvt_pk_bf16_f32 v39, v94, -v95
	v_cvt_f64_f32_e32 v[70:71], v79
	v_mul_f64 v[74:75], v[44:45], v[72:73]
	v_mul_f64 v[72:73], v[42:43], v[72:73]
	global_store_dword v[52:53], v39, off offset:1024 sc1
	v_fma_f64 v[74:75], v[42:43], v[70:71], -v[74:75]
	v_fmac_f64_e32 v[72:73], v[44:45], v[70:71]
	global_load_dword v39, v[48:49], off offset:2304
	global_load_dword v41, v[50:51], off offset:2304
	v_cvt_f32_f64_e32 v74, v[74:75]
	v_cvt_f32_f64_e32 v70, v[72:73]
	v_cvt_pk_bf16_f32 v74, v74, s0
	v_cvt_pk_bf16_f32 v70, v70, s0
	global_store_short v[46:47], v74, off offset:10 sc1
	global_store_short v[46:47], v70, off offset:2058 sc1
	v_cvt_f64_f32_e32 v[72:73], v84
	global_load_dword v76, v[48:49], off offset:2560
	global_load_dword v77, v[50:51], off offset:2560
	v_mul_f64 v[74:75], v[44:45], v[72:73]
	v_mul_f64 v[72:73], v[42:43], v[72:73]
	s_waitcnt vmcnt(25)
	v_cvt_pk_bf16_f32 v70, v88, -v89
	global_store_dword v[52:53], v70, off offset:1280 sc1
	v_cvt_f64_f32_e32 v[70:71], v80
	v_fma_f64 v[74:75], v[42:43], v[70:71], -v[74:75]
	v_cvt_f32_f64_e32 v74, v[74:75]
	v_fmac_f64_e32 v[72:73], v[44:45], v[70:71]
	v_cvt_pk_bf16_f32 v74, v74, s0
	v_cvt_f32_f64_e32 v70, v[72:73]
	global_store_short v[46:47], v74, off offset:12 sc1
	v_cvt_pk_bf16_f32 v70, v70, s0
	global_load_dword v78, v[48:49], off offset:2816
	global_load_dword v79, v[50:51], off offset:2816
	v_cvt_f64_f32_e32 v[72:73], v85
	global_store_short v[46:47], v70, off offset:2060 sc1
	s_waitcnt vmcnt(27)
	v_cvt_pk_bf16_f32 v70, v96, -v98
	global_store_dword v[52:53], v70, off offset:1536 sc1
	v_cvt_f64_f32_e32 v[70:71], v81
	v_mul_f64 v[74:75], v[44:45], v[72:73]
	v_fma_f64 v[74:75], v[42:43], v[70:71], -v[74:75]
	v_mul_f64 v[72:73], v[42:43], v[72:73]
	v_cvt_f32_f64_e32 v74, v[74:75]
	v_fmac_f64_e32 v[72:73], v[44:45], v[70:71]
	v_cvt_pk_bf16_f32 v74, v74, s0
	v_cvt_f32_f64_e32 v70, v[72:73]
	global_store_short v[46:47], v74, off offset:14 sc1
	v_cvt_pk_bf16_f32 v70, v70, s0
	global_load_dword v80, v[48:49], off offset:3072
	global_load_dword v81, v[50:51], off offset:3072
	v_cvt_f64_f32_e32 v[72:73], v14
	global_store_short v[46:47], v70, off offset:2062 sc1
	s_waitcnt vmcnt(31)
	v_cvt_pk_bf16_f32 v70, v97, -v99
	global_store_dword v[52:53], v70, off offset:1792 sc1
	v_cvt_f64_f32_e32 v[70:71], v10
	v_mul_f64 v[74:75], v[44:45], v[72:73]
	v_fma_f64 v[74:75], v[42:43], v[70:71], -v[74:75]
	v_cvt_f32_f64_e32 v10, v[74:75]
	v_cvt_pk_bf16_f32 v10, v10, s0
	global_store_short v[46:47], v10, off offset:16 sc1
	global_load_dword v74, v[48:49], off offset:3328
	global_load_dword v75, v[50:51], off offset:3328
	v_mul_f64 v[72:73], v[42:43], v[72:73]
	v_fmac_f64_e32 v[72:73], v[44:45], v[70:71]
	v_cvt_f32_f64_e32 v10, v[72:73]
	v_cvt_pk_bf16_f32 v10, v10, s0
	global_store_short v[46:47], v10, off offset:2064 sc1
	global_load_dword v70, v[48:49], off offset:3584
	global_load_dword v71, v[48:49], off offset:3840
	global_load_dword v72, v[50:51], off offset:3584
	s_nop 0
	global_load_dword v50, v[50:51], off offset:3840
	v_cvt_f64_f32_e32 v[14:15], v15
	v_cvt_f64_f32_e32 v[10:11], v11
	v_mul_f64 v[48:49], v[44:45], v[14:15]
	v_fma_f64 v[48:49], v[42:43], v[10:11], -v[48:49]
	v_mul_f64 v[14:15], v[42:43], v[14:15]
	v_fmac_f64_e32 v[14:15], v[44:45], v[10:11]
	v_cvt_f64_f32_e32 v[10:11], v12
	s_waitcnt vmcnt(28)
	v_cvt_pk_bf16_f32 v0, v0, -v37
	global_store_dword v[52:53], v0, off offset:2048 sc1
	v_cvt_f32_f64_e32 v0, v[48:49]
	v_cvt_pk_bf16_f32 v0, v0, s0
	global_store_short v[46:47], v0, off offset:18 sc1
	v_cvt_f32_f64_e32 v0, v[14:15]
	v_cvt_f64_f32_e32 v[14:15], v16
	v_cvt_pk_bf16_f32 v0, v0, s0
	v_mul_f64 v[48:49], v[44:45], v[14:15]
	global_store_short v[46:47], v0, off offset:2066 sc1
	v_fma_f64 v[48:49], v[42:43], v[10:11], -v[48:49]
	v_mul_f64 v[14:15], v[42:43], v[14:15]
	v_fmac_f64_e32 v[14:15], v[44:45], v[10:11]
	v_cvt_f64_f32_e32 v[10:11], v13
	v_cvt_f64_f32_e32 v[12:13], v17
	s_waitcnt vmcnt(26)
	v_cvt_pk_bf16_f32 v0, v39, -v41
	global_store_dword v[52:53], v0, off offset:2304 sc1
	v_cvt_f32_f64_e32 v0, v[48:49]
	v_cvt_pk_bf16_f32 v0, v0, s0
	global_store_short v[46:47], v0, off offset:20 sc1
	v_cvt_f32_f64_e32 v0, v[14:15]
	v_cvt_pk_bf16_f32 v0, v0, s0
	v_mul_f64 v[14:15], v[44:45], v[12:13]
	global_store_short v[46:47], v0, off offset:2068 sc1
	s_waitcnt vmcnt(25)
	v_cvt_pk_bf16_f32 v0, v76, -v77
	v_fma_f64 v[14:15], v[42:43], v[10:11], -v[14:15]
	global_store_dword v[52:53], v0, off offset:2560 sc1
	v_cvt_f32_f64_e32 v0, v[14:15]
	v_mul_f64 v[12:13], v[42:43], v[12:13]
	v_cvt_pk_bf16_f32 v0, v0, s0
	v_fmac_f64_e32 v[12:13], v[44:45], v[10:11]
	global_store_short v[46:47], v0, off offset:22 sc1
	v_cvt_f32_f64_e32 v0, v[12:13]
	v_cvt_f64_f32_e32 v[12:13], v6
	v_cvt_pk_bf16_f32 v0, v0, s0
	v_cvt_f64_f32_e32 v[10:11], v2
	v_mul_f64 v[14:15], v[44:45], v[12:13]
	global_store_short v[46:47], v0, off offset:2070 sc1
	s_waitcnt vmcnt(24)
	v_cvt_pk_bf16_f32 v0, v78, -v79
	v_fma_f64 v[14:15], v[42:43], v[10:11], -v[14:15]
	global_store_dword v[52:53], v0, off offset:2816 sc1
	v_cvt_f32_f64_e32 v0, v[14:15]
	v_mul_f64 v[12:13], v[42:43], v[12:13]
	v_cvt_pk_bf16_f32 v0, v0, s0
	v_fmac_f64_e32 v[12:13], v[44:45], v[10:11]
	global_store_short v[46:47], v0, off offset:24 sc1
	v_cvt_f32_f64_e32 v0, v[12:13]
	v_cvt_f64_f32_e32 v[6:7], v7
	v_cvt_pk_bf16_f32 v0, v0, s0
	v_cvt_f64_f32_e32 v[2:3], v3
	v_mul_f64 v[10:11], v[44:45], v[6:7]
	global_store_short v[46:47], v0, off offset:2072 sc1
	s_waitcnt vmcnt(22)
	v_cvt_pk_bf16_f32 v0, v80, -v81
	v_fma_f64 v[10:11], v[42:43], v[2:3], -v[10:11]
	global_store_dword v[52:53], v0, off offset:3072 sc1
	v_cvt_f32_f64_e32 v0, v[10:11]
	v_mul_f64 v[6:7], v[42:43], v[6:7]
	v_cvt_pk_bf16_f32 v0, v0, s0
	v_fmac_f64_e32 v[6:7], v[44:45], v[2:3]
	global_store_short v[46:47], v0, off offset:26 sc1
	v_cvt_f32_f64_e32 v0, v[6:7]
	v_cvt_f64_f32_e32 v[6:7], v8
	v_cvt_pk_bf16_f32 v0, v0, s0
	v_cvt_f64_f32_e32 v[2:3], v4
	v_mul_f64 v[10:11], v[44:45], v[6:7]
	global_store_short v[46:47], v0, off offset:2074 sc1
	s_waitcnt vmcnt(20)
	v_cvt_pk_bf16_f32 v0, v74, -v75
	v_fma_f64 v[10:11], v[42:43], v[2:3], -v[10:11]
	global_store_dword v[52:53], v0, off offset:3328 sc1
	v_cvt_f32_f64_e32 v0, v[10:11]
	v_mul_f64 v[6:7], v[42:43], v[6:7]
	v_cvt_pk_bf16_f32 v0, v0, s0
	v_fmac_f64_e32 v[6:7], v[44:45], v[2:3]
	global_store_short v[46:47], v0, off offset:28 sc1
	v_cvt_f32_f64_e32 v0, v[6:7]
	v_cvt_f64_f32_e32 v[2:3], v5
	v_cvt_f64_f32_e32 v[4:5], v9
	v_cvt_pk_bf16_f32 v0, v0, s0
	v_mul_f64 v[6:7], v[44:45], v[4:5]
	global_store_short v[46:47], v0, off offset:2076 sc1
	s_waitcnt vmcnt(19)
	v_cvt_pk_bf16_f32 v0, v70, -v72
	v_fma_f64 v[6:7], v[42:43], v[2:3], -v[6:7]
	global_store_dword v[52:53], v0, off offset:3584 sc1
	v_cvt_f32_f64_e32 v0, v[6:7]
	v_mul_f64 v[4:5], v[42:43], v[4:5]
	v_cvt_pk_bf16_f32 v0, v0, s0
	v_fmac_f64_e32 v[4:5], v[44:45], v[2:3]
	global_store_short v[46:47], v0, off offset:30 sc1
	v_cvt_f32_f64_e32 v0, v[4:5]
	v_cvt_pk_bf16_f32 v0, v0, s0
	global_store_short v[46:47], v0, off offset:2078 sc1
	s_waitcnt vmcnt(21)
	v_cvt_pk_bf16_f32 v0, v71, -v50
	global_store_dword v[52:53], v0, off offset:3840 sc1

.LBB0_598:
	v_lshl_add_u64 v[44:45], v[42:43], 0, s[44:45]
	ds_read_b128 v[46:49], v0
	ds_read_b128 v[2:5], v0 offset:16
	global_load_dwordx4 v[50:53], v[44:45], off
	s_mov_b32 s20, 0x12000
	s_add_u32 s44, s44, 0x48000
	s_addc_u32 s45, s45, 0
	s_cmp_eq_u32 s44, 0x240000
	s_waitcnt vmcnt(0) lgkmcnt(1)
	v_pk_fma_f32 v[70:71], v[50:51], v[46:47], v[6:7] op_sel_hi:[1,0,1]
	v_pk_fma_f32 v[72:73], v[52:53], v[46:47], v[8:9] op_sel_hi:[1,0,1]
	ds_read_b128 v[6:9], v0 offset:4096
	s_waitcnt lgkmcnt(0)
	v_pk_fma_f32 v[74:75], v[50:51], v[6:7], v[14:15] op_sel_hi:[1,0,1]
	v_pk_fma_f32 v[76:77], v[52:53], v[6:7], v[16:17] op_sel_hi:[1,0,1]
	ds_read_b128 v[14:17], v0 offset:8192
	s_waitcnt lgkmcnt(0)
	v_pk_fma_f32 v[50:51], v[50:51], v[14:15], v[10:11] op_sel_hi:[1,0,1]
	v_add_co_u32_e32 v10, vcc, s30, v44
	v_pk_fma_f32 v[52:53], v[52:53], v[14:15], v[12:13] op_sel_hi:[1,0,1]
	s_nop 0
	v_addc_co_u32_e32 v11, vcc, 0, v45, vcc
	global_load_dwordx4 v[10:13], v[10:11], off
	s_waitcnt vmcnt(0)
	v_pk_fma_f32 v[70:71], v[10:11], v[46:47], v[70:71] op_sel:[0,1,0]
	v_pk_fma_f32 v[46:47], v[12:13], v[46:47], v[72:73] op_sel:[0,1,0]
	v_pk_fma_f32 v[72:73], v[10:11], v[6:7], v[74:75] op_sel:[0,1,0]
	v_pk_fma_f32 v[50:51], v[10:11], v[14:15], v[50:51] op_sel:[0,1,0]
	v_add_co_u32_e32 v10, vcc, s20, v44
	v_pk_fma_f32 v[6:7], v[12:13], v[6:7], v[76:77] op_sel:[0,1,0]
	s_nop 0
	v_addc_co_u32_e32 v11, vcc, 0, v45, vcc
	v_pk_fma_f32 v[14:15], v[12:13], v[14:15], v[52:53] op_sel:[0,1,0]
	global_load_dwordx4 v[10:13], v[10:11], off
	s_mov_b32 s20, 0x1b000
	s_waitcnt vmcnt(0)
	v_pk_fma_f32 v[52:53], v[10:11], v[48:49], v[70:71] op_sel_hi:[1,0,1]
	v_pk_fma_f32 v[70:71], v[10:11], v[8:9], v[72:73] op_sel_hi:[1,0,1]
	v_pk_fma_f32 v[50:51], v[10:11], v[16:17], v[50:51] op_sel_hi:[1,0,1]
	v_add_co_u32_e32 v10, vcc, s20, v44
	v_pk_fma_f32 v[46:47], v[12:13], v[48:49], v[46:47] op_sel_hi:[1,0,1]
	s_nop 0
	v_addc_co_u32_e32 v11, vcc, 0, v45, vcc
	v_pk_fma_f32 v[6:7], v[12:13], v[8:9], v[6:7] op_sel_hi:[1,0,1]
	v_pk_fma_f32 v[14:15], v[12:13], v[16:17], v[14:15] op_sel_hi:[1,0,1]
	global_load_dwordx4 v[10:13], v[10:11], off
	v_mov_b32_e32 v8, v49
	s_mov_b32 s20, 0x24000
	s_waitcnt vmcnt(0)
	v_pk_fma_f32 v[48:49], v[10:11], v[8:9], v[52:53] op_sel_hi:[1,0,1]
	v_pk_fma_f32 v[46:47], v[12:13], v[8:9], v[46:47] op_sel_hi:[1,0,1]
	v_mov_b32_e32 v8, v9
	v_pk_fma_f32 v[52:53], v[10:11], v[8:9], v[70:71] op_sel_hi:[1,0,1]
	v_pk_fma_f32 v[70:71], v[12:13], v[8:9], v[6:7] op_sel_hi:[1,0,1]
	v_mov_b32_e32 v6, v17
	v_pk_fma_f32 v[16:17], v[10:11], v[6:7], v[50:51] op_sel_hi:[1,0,1]
	v_pk_fma_f32 v[14:15], v[12:13], v[6:7], v[14:15] op_sel_hi:[1,0,1]
	v_add_co_u32_e32 v6, vcc, s20, v44
	ds_read_b128 v[10:13], v0 offset:4112
	s_nop 0
	v_addc_co_u32_e32 v7, vcc, 0, v45, vcc
	global_load_dwordx4 v[6:9], v[6:7], off
	s_mov_b32 s20, 0x2d000
	s_waitcnt vmcnt(0)
	v_pk_fma_f32 v[50:51], v[6:7], v[2:3], v[48:49] op_sel_hi:[1,0,1]
	v_pk_fma_f32 v[72:73], v[8:9], v[2:3], v[46:47] op_sel_hi:[1,0,1]
	ds_read_b128 v[46:49], v0 offset:8208
	s_waitcnt lgkmcnt(1)
	v_pk_fma_f32 v[52:53], v[6:7], v[10:11], v[52:53] op_sel_hi:[1,0,1]
	v_pk_fma_f32 v[70:71], v[8:9], v[10:11], v[70:71] op_sel_hi:[1,0,1]
	v_add_u32_e32 v0, 32, v0
	s_waitcnt lgkmcnt(0)
	v_pk_fma_f32 v[16:17], v[6:7], v[46:47], v[16:17] op_sel_hi:[1,0,1]
	v_add_co_u32_e32 v6, vcc, s20, v44
	v_pk_fma_f32 v[14:15], v[8:9], v[46:47], v[14:15] op_sel_hi:[1,0,1]
	s_nop 0
	v_addc_co_u32_e32 v7, vcc, 0, v45, vcc
	global_load_dwordx4 v[6:9], v[6:7], off
	s_mov_b32 s20, 0x36000
	s_waitcnt vmcnt(0)
	v_pk_fma_f32 v[50:51], v[6:7], v[2:3], v[50:51] op_sel:[0,1,0]
	v_pk_fma_f32 v[52:53], v[6:7], v[10:11], v[52:53] op_sel:[0,1,0]
	v_pk_fma_f32 v[16:17], v[6:7], v[46:47], v[16:17] op_sel:[0,1,0]
	v_add_co_u32_e32 v6, vcc, s20, v44
	v_pk_fma_f32 v[2:3], v[8:9], v[2:3], v[72:73] op_sel:[0,1,0]
	s_nop 0
	v_addc_co_u32_e32 v7, vcc, 0, v45, vcc
	v_pk_fma_f32 v[10:11], v[8:9], v[10:11], v[70:71] op_sel:[0,1,0]
	v_pk_fma_f32 v[14:15], v[8:9], v[46:47], v[14:15] op_sel:[0,1,0]
	global_load_dwordx4 v[6:9], v[6:7], off
	s_mov_b32 s20, 0x3f000
	s_waitcnt vmcnt(0)
	v_pk_fma_f32 v[50:51], v[6:7], v[4:5], v[50:51] op_sel_hi:[1,0,1]
	v_pk_fma_f32 v[52:53], v[6:7], v[12:13], v[52:53] op_sel_hi:[1,0,1]
	v_pk_fma_f32 v[70:71], v[6:7], v[48:49], v[16:17] op_sel_hi:[1,0,1]
	v_add_co_u32_e32 v6, vcc, s20, v44
	v_pk_fma_f32 v[2:3], v[8:9], v[4:5], v[2:3] op_sel_hi:[1,0,1]
	s_nop 0
	v_addc_co_u32_e32 v7, vcc, 0, v45, vcc
	global_load_dwordx4 v[44:47], v[6:7], off
	v_mov_b32_e32 v4, v5
	v_pk_fma_f32 v[10:11], v[8:9], v[12:13], v[10:11] op_sel_hi:[1,0,1]
	v_pk_fma_f32 v[72:73], v[8:9], v[48:49], v[14:15] op_sel_hi:[1,0,1]
	s_waitcnt vmcnt(0)
	v_pk_fma_f32 v[8:9], v[46:47], v[4:5], v[2:3] op_sel_hi:[1,0,1]
	v_mov_b32_e32 v2, v13
	v_pk_fma_f32 v[14:15], v[44:45], v[2:3], v[52:53] op_sel_hi:[1,0,1]
	v_pk_fma_f32 v[16:17], v[46:47], v[2:3], v[10:11] op_sel_hi:[1,0,1]
	v_mov_b32_e32 v2, v49
	v_pk_fma_f32 v[6:7], v[44:45], v[4:5], v[50:51] op_sel_hi:[1,0,1]
	v_pk_fma_f32 v[10:11], v[44:45], v[2:3], v[70:71] op_sel_hi:[1,0,1]
	v_pk_fma_f32 v[12:13], v[46:47], v[2:3], v[72:73] op_sel_hi:[1,0,1]
	s_cbranch_scc0 .LBB0_598
	ds_write_b128 v56, v[6:9] offset:12288
	ds_write_b128 v56, v[14:17] offset:12544
	ds_write_b128 v56, v[10:13] offset:12800
	s_waitcnt lgkmcnt(0)
	s_barrier
	s_and_saveexec_b64 s[20:21], s[36:37]
	s_cbranch_execz .LBB0_516
	v_lshlrev_b32_e32 v2, 6, v69
	v_or_b32_e32 v4, v2, v20
	v_readlane_b32 s4, v254, 25
	v_ashrrev_i32_e32 v5, 31, v4
	v_readlane_b32 s6, v254, 27
	v_readlane_b32 s7, v254, 28
	v_ashrrev_i32_e32 v3, 31, v2
	v_lshl_add_u64 v[2:3], v[2:3], 2, v[24:25]
	v_lshl_add_u64 v[4:5], v[4:5], 2, s[6:7]
	global_load_dword v0, v[4:5], off
	ds_read2st64_b32 v[4:5], v59 offset0:48 offset1:60
	ds_read2st64_b32 v[6:7], v57 offset0:51 offset1:54
	ds_read2st64_b32 v[8:9], v57 offset0:57 offset1:63
	ds_read2st64_b32 v[10:11], v57 offset0:66 offset1:69
	ds_read2st64_b32 v[12:13], v59 offset0:72 offset1:84
	ds_read2st64_b32 v[14:15], v57 offset0:75 offset1:78
	ds_read2st64_b32 v[16:17], v57 offset0:81 offset1:87
	ds_read2st64_b32 v[42:43], v57 offset0:90 offset1:93
	v_readlane_b32 s5, v254, 26
	v_readlane_b32 s8, v254, 29
	v_readlane_b32 s9, v254, 30
	v_readlane_b32 s10, v254, 31
	v_readlane_b32 s11, v254, 32
	v_readlane_b32 s12, v254, 33
	v_readlane_b32 s13, v254, 34
	v_readlane_b32 s14, v254, 35
	v_readlane_b32 s15, v254, 36
	v_readlane_b32 s16, v254, 37
	v_readlane_b32 s17, v254, 38
	v_readlane_b32 s18, v254, 39
	v_readlane_b32 s19, v254, 40
	s_waitcnt vmcnt(0) lgkmcnt(7)
	v_add_f32_e32 v0, v0, v4
	s_waitcnt lgkmcnt(6)
	v_add_f32_e32 v0, v0, v6
	v_add_f32_e32 v0, v0, v7
	s_waitcnt lgkmcnt(5)
	v_add_f32_e32 v0, v0, v8
	v_add_f32_e32 v0, v0, v5
	v_add_f32_e32 v0, v0, v9
	s_waitcnt lgkmcnt(4)
	v_add_f32_e32 v0, v0, v10
	v_add_f32_e32 v0, v0, v11
	s_waitcnt lgkmcnt(3)
	v_add_f32_e32 v0, v0, v12
	s_waitcnt lgkmcnt(2)
	v_add_f32_e32 v0, v0, v14
	v_add_f32_e32 v0, v0, v15
	s_waitcnt lgkmcnt(1)
	v_add_f32_e32 v0, v0, v16
	v_add_f32_e32 v0, v0, v13
	v_add_f32_e32 v0, v0, v17
	s_waitcnt lgkmcnt(0)
	v_add_f32_e32 v0, v0, v42
	v_add_f32_e32 v0, v0, v43
	global_store_dword v[2:3], v0, off sc1
	s_branch .LBB0_516

.LBB0_644:
	v_lshlrev_b64 v[166:167], 12, v[164:165]
	v_lshl_add_u64 v[166:167], v[142:143], 0, v[166:167]
	s_waitcnt vmcnt(7)
	global_store_dwordx4 v[166:167], v[106:109], off sc1
	s_waitcnt vmcnt(7)
	global_store_dwordx4 v[166:167], v[110:113], off offset:1024 sc1
	s_waitcnt vmcnt(7)
	global_store_dwordx4 v[166:167], v[102:105], off offset:2048 sc1
	s_waitcnt vmcnt(7)
	global_store_dwordx4 v[166:167], v[98:101], off offset:3072 sc1
	s_and_b64 vcc, exec, s[42:43]
	s_waitcnt vmcnt(4)
	v_pk_add_f32 v[172:173], v[66:67], 1.0 op_sel_hi:[1,0]
	v_pk_add_f32 v[170:171], v[62:63], 1.0 op_sel_hi:[1,0]
	v_pk_add_f32 v[168:169], v[58:59], 1.0 op_sel_hi:[1,0]
	v_pk_add_f32 v[166:167], v[50:51], 1.0 op_sel_hi:[1,0]
	s_cbranch_vccnz .LBB0_646
	v_mov_b32_e32 v178, v111
	v_mov_b32_e32 v179, v107
	v_mov_b32_e32 v176, v110
	v_mov_b32_e32 v177, v106
	v_pk_mul_f32 v[178:179], v[178:179], v[178:179]
	v_mov_b32_e32 v182, v99
	v_pk_fma_f32 v[176:177], v[176:177], v[176:177], v[178:179]
	v_mov_b32_e32 v178, v112
	v_mov_b32_e32 v179, v108
	v_pk_fma_f32 v[176:177], v[178:179], v[178:179], v[176:177]
	v_mov_b32_e32 v178, v113
	v_mov_b32_e32 v179, v109
	v_mov_b32_e32 v183, v103
	v_pk_fma_f32 v[176:177], v[178:179], v[178:179], v[176:177]
	v_mov_b32_e32 v178, v98
	v_mov_b32_e32 v179, v102
	v_pk_mul_f32 v[182:183], v[182:183], v[182:183]
	v_add_f32_e32 v0, v176, v177
	v_pk_fma_f32 v[178:179], v[178:179], v[178:179], v[182:183]
	v_mov_b32_e32 v182, v100
	v_mov_b32_e32 v183, v104
	v_pk_fma_f32 v[178:179], v[182:183], v[182:183], v[178:179]
	v_mov_b32_e32 v182, v101
	v_mov_b32_e32 v183, v105
	v_pk_fma_f32 v[178:179], v[182:183], v[182:183], v[178:179]
	v_and_b32_e32 v176, 64, v188
	v_add_f32_e32 v0, v179, v0
	v_add_f32_e32 v0, v178, v0
	v_xor_b32_e32 v175, 16, v188
	v_add_u32_e32 v176, 64, v176
	v_add_f32_dpp v0, v0, v0 quad_perm:[1,0,3,2] row_mask:0xf bank_mask:0xf bound_ctrl:1
	v_cmp_lt_i32_e32 vcc, v175, v176
	v_lshlrev_b64 v[164:165], 10, v[164:165]
	v_add_f32_dpp v0, v0, v0 quad_perm:[2,3,0,1] row_mask:0xf bank_mask:0xf bound_ctrl:1
	v_cndmask_b32_e32 v175, v188, v175, vcc
	v_lshlrev_b32_e32 v175, 2, v175
	v_add_f32_dpp v0, v0, v0 row_half_mirror row_mask:0xf bank_mask:0xf bound_ctrl:1
	v_lshl_add_u64 v[164:165], v[164:165], 1, v[144:145]
	s_nop 0
	v_add_f32_dpp v0, v0, v0 row_mirror row_mask:0xf bank_mask:0xf bound_ctrl:1
	ds_bpermute_b32 v175, v175, v0
	s_waitcnt lgkmcnt(0)
	v_add_f32_e32 v0, v0, v175
	v_xor_b32_e32 v175, 32, v188
	v_cmp_lt_i32_e32 vcc, v175, v176
	v_pk_add_f32 v[176:177], v[68:69], 1.0 op_sel_hi:[1,0]
	s_nop 0
	v_cndmask_b32_e32 v175, v188, v175, vcc
	v_lshlrev_b32_e32 v175, 2, v175
	ds_bpermute_b32 v175, v175, v0
	s_waitcnt lgkmcnt(0)
	v_add_f32_e32 v0, v0, v175
	v_fmamk_f32 v0, v0, 0x3a800000, v186
	v_mul_f32_e32 v175, 0x4b800000, v0
	v_cmp_gt_f32_e32 vcc, s31, v0
	s_nop 1
	v_cndmask_b32_e32 v0, v0, v175, vcc
	v_rsq_f32_e32 v0, v0
	s_nop 0
	v_mul_f32_e32 v175, 0x45800000, v0
	v_cndmask_b32_e32 v0, v0, v175, vcc
	v_pk_mul_f32 v[108:109], v[108:109], v[0:1] op_sel_hi:[1,0]
	v_pk_mul_f32 v[106:107], v[106:107], v[0:1] op_sel_hi:[1,0]
	v_pk_mul_f32 v[108:109], v[32:33], v[108:109]
	v_pk_mul_f32 v[106:107], v[30:31], v[106:107]
	v_pk_fma_f32 v[108:109], v[176:177], v[108:109], v[48:49]
	v_pk_fma_f32 v[106:107], v[172:173], v[106:107], v[46:47]
	v_pk_mul_f32 v[104:105], v[104:105], v[0:1] op_sel_hi:[1,0]
	v_cvt_pk_bf16_f32 v106, v106, v107
	v_cvt_pk_bf16_f32 v107, v108, v109
	global_store_dwordx2 v[164:165], v[106:107], off sc1
	v_pk_mul_f32 v[106:107], v[112:113], v[0:1] op_sel_hi:[1,0]
	v_pk_mul_f32 v[108:109], v[110:111], v[0:1] op_sel_hi:[1,0]
	v_pk_mul_f32 v[106:107], v[28:29], v[106:107]
	v_pk_mul_f32 v[108:109], v[26:27], v[108:109]
	v_pk_add_f32 v[110:111], v[64:65], 1.0 op_sel_hi:[1,0]
	v_pk_fma_f32 v[108:109], v[170:171], v[108:109], v[42:43]
	v_pk_fma_f32 v[106:107], v[110:111], v[106:107], v[44:45]
	v_pk_mul_f32 v[102:103], v[102:103], v[0:1] op_sel_hi:[1,0]
	v_cvt_pk_bf16_f32 v108, v108, v109
	v_cvt_pk_bf16_f32 v109, v106, v107
	v_pk_mul_f32 v[102:103], v[22:23], v[102:103]
	v_pk_mul_f32 v[104:105], v[24:25], v[104:105]
	v_pk_add_f32 v[106:107], v[60:61], 1.0 op_sel_hi:[1,0]
	v_pk_fma_f32 v[102:103], v[168:169], v[102:103], v[38:39]
	v_pk_fma_f32 v[104:105], v[106:107], v[104:105], v[40:41]
	v_cvt_pk_bf16_f32 v102, v102, v103
	v_cvt_pk_bf16_f32 v103, v104, v105
	v_pk_mul_f32 v[100:101], v[100:101], v[0:1] op_sel_hi:[1,0]
	v_pk_mul_f32 v[98:99], v[98:99], v[0:1] op_sel_hi:[1,0]
	global_store_dwordx2 v[164:165], v[102:103], off offset:1024 sc1
	v_pk_mul_f32 v[98:99], v[18:19], v[98:99]
	v_pk_mul_f32 v[100:101], v[20:21], v[100:101]
	v_pk_add_f32 v[102:103], v[52:53], 1.0 op_sel_hi:[1,0]
	v_pk_fma_f32 v[98:99], v[166:167], v[98:99], v[34:35]
	v_pk_fma_f32 v[100:101], v[102:103], v[100:101], v[36:37]
	v_cvt_pk_bf16_f32 v98, v98, v99
	v_cvt_pk_bf16_f32 v99, v100, v101
	global_store_dwordx2 v[164:165], v[108:109], off offset:512 sc1
	global_store_dwordx2 v[164:165], v[98:99], off offset:1536 sc1

.LBB0_648:
	v_lshlrev_b64 v[98:99], 12, v[162:163]
	v_lshl_add_u64 v[98:99], v[142:143], 0, v[98:99]
	s_and_b64 vcc, exec, s[42:43]
	global_store_dwordx4 v[98:99], v[94:97], off sc1
	global_store_dwordx4 v[98:99], v[90:93], off offset:1024 sc1
	global_store_dwordx4 v[98:99], v[86:89], off offset:2048 sc1
	global_store_dwordx4 v[98:99], v[82:85], off offset:3072 sc1
	s_cbranch_vccnz .LBB0_606
	v_mov_b32_e32 v100, v91
	v_mov_b32_e32 v101, v95
	v_mov_b32_e32 v98, v90
	v_mov_b32_e32 v99, v94
	v_pk_mul_f32 v[100:101], v[100:101], v[100:101]
	v_mov_b32_e32 v102, v83
	v_pk_fma_f32 v[98:99], v[98:99], v[98:99], v[100:101]
	v_mov_b32_e32 v100, v92
	v_mov_b32_e32 v101, v96
	v_pk_fma_f32 v[98:99], v[100:101], v[100:101], v[98:99]
	v_mov_b32_e32 v100, v93
	v_mov_b32_e32 v101, v97
	v_mov_b32_e32 v103, v87
	v_pk_fma_f32 v[98:99], v[100:101], v[100:101], v[98:99]
	v_mov_b32_e32 v100, v82
	v_mov_b32_e32 v101, v86
	v_pk_mul_f32 v[102:103], v[102:103], v[102:103]
	v_add_f32_e32 v0, v98, v99
	v_pk_fma_f32 v[100:101], v[100:101], v[100:101], v[102:103]
	v_mov_b32_e32 v102, v84
	v_mov_b32_e32 v103, v88
	v_pk_fma_f32 v[100:101], v[102:103], v[102:103], v[100:101]
	v_mov_b32_e32 v102, v85
	v_mov_b32_e32 v103, v89
	v_pk_fma_f32 v[100:101], v[102:103], v[102:103], v[100:101]
	v_and_b32_e32 v99, 64, v188
	v_add_f32_e32 v0, v101, v0
	v_add_f32_e32 v0, v100, v0
	v_xor_b32_e32 v98, 16, v188
	v_add_u32_e32 v99, 64, v99
	v_add_f32_dpp v0, v0, v0 quad_perm:[1,0,3,2] row_mask:0xf bank_mask:0xf bound_ctrl:1
	v_cmp_lt_i32_e32 vcc, v98, v99
	s_nop 0
	v_add_f32_dpp v0, v0, v0 quad_perm:[2,3,0,1] row_mask:0xf bank_mask:0xf bound_ctrl:1
	v_cndmask_b32_e32 v98, v188, v98, vcc
	v_lshlrev_b32_e32 v98, 2, v98
	v_add_f32_dpp v0, v0, v0 row_half_mirror row_mask:0xf bank_mask:0xf bound_ctrl:1
	s_nop 1
	v_add_f32_dpp v0, v0, v0 row_mirror row_mask:0xf bank_mask:0xf bound_ctrl:1
	ds_bpermute_b32 v98, v98, v0
	s_waitcnt lgkmcnt(0)
	v_add_f32_e32 v0, v0, v98
	v_xor_b32_e32 v98, 32, v188
	v_cmp_lt_i32_e32 vcc, v98, v99
	s_nop 1
	v_cndmask_b32_e32 v98, v188, v98, vcc
	v_lshlrev_b32_e32 v98, 2, v98
	ds_bpermute_b32 v98, v98, v0
	s_waitcnt lgkmcnt(0)
	v_add_f32_e32 v0, v0, v98
	v_fmamk_f32 v0, v0, 0x3a800000, v186
	v_mul_f32_e32 v98, 0x4b800000, v0
	v_cmp_gt_f32_e32 vcc, s31, v0
	s_nop 1
	v_cndmask_b32_e32 v0, v0, v98, vcc
	v_rsq_f32_e32 v0, v0
	v_lshlrev_b64 v[98:99], 10, v[162:163]
	v_lshl_add_u64 v[98:99], v[98:99], 1, v[144:145]
	v_mul_f32_e32 v100, 0x45800000, v0
	v_cndmask_b32_e32 v0, v0, v100, vcc
	v_pk_mul_f32 v[96:97], v[96:97], v[0:1] op_sel_hi:[1,0]
	v_pk_mul_f32 v[94:95], v[94:95], v[0:1] op_sel_hi:[1,0]
	v_pk_mul_f32 v[96:97], v[32:33], v[96:97]
	v_pk_mul_f32 v[94:95], v[30:31], v[94:95]
	v_pk_add_f32 v[100:101], v[68:69], 1.0 op_sel_hi:[1,0]
	v_pk_fma_f32 v[94:95], v[172:173], v[94:95], v[46:47]
	v_pk_fma_f32 v[96:97], v[100:101], v[96:97], v[48:49]
	v_cvt_pk_bf16_f32 v94, v94, v95
	v_cvt_pk_bf16_f32 v95, v96, v97
	v_pk_mul_f32 v[92:93], v[92:93], v[0:1] op_sel_hi:[1,0]
	v_pk_mul_f32 v[90:91], v[90:91], v[0:1] op_sel_hi:[1,0]
	global_store_dwordx2 v[98:99], v[94:95], off sc1
	v_pk_mul_f32 v[90:91], v[26:27], v[90:91]
	v_pk_mul_f32 v[92:93], v[28:29], v[92:93]
	v_pk_add_f32 v[94:95], v[64:65], 1.0 op_sel_hi:[1,0]
	v_pk_fma_f32 v[90:91], v[170:171], v[90:91], v[42:43]
	v_pk_fma_f32 v[92:93], v[94:95], v[92:93], v[44:45]
	v_cvt_pk_bf16_f32 v90, v90, v91
	v_cvt_pk_bf16_f32 v91, v92, v93
	v_pk_mul_f32 v[88:89], v[88:89], v[0:1] op_sel_hi:[1,0]
	v_pk_mul_f32 v[86:87], v[86:87], v[0:1] op_sel_hi:[1,0]
	global_store_dwordx2 v[98:99], v[90:91], off offset:512 sc1
	v_pk_mul_f32 v[86:87], v[22:23], v[86:87]
	v_pk_mul_f32 v[88:89], v[24:25], v[88:89]
	v_pk_add_f32 v[90:91], v[60:61], 1.0 op_sel_hi:[1,0]
	v_pk_fma_f32 v[86:87], v[168:169], v[86:87], v[38:39]
	v_pk_fma_f32 v[88:89], v[90:91], v[88:89], v[40:41]
	v_cvt_pk_bf16_f32 v86, v86, v87
	v_cvt_pk_bf16_f32 v87, v88, v89
	v_pk_mul_f32 v[84:85], v[84:85], v[0:1] op_sel_hi:[1,0]
	v_pk_mul_f32 v[82:83], v[82:83], v[0:1] op_sel_hi:[1,0]
	global_store_dwordx2 v[98:99], v[86:87], off offset:1024 sc1
	v_pk_mul_f32 v[82:83], v[18:19], v[82:83]
	v_pk_mul_f32 v[84:85], v[20:21], v[84:85]
	v_pk_add_f32 v[86:87], v[52:53], 1.0 op_sel_hi:[1,0]
	v_pk_fma_f32 v[82:83], v[166:167], v[82:83], v[34:35]
	v_pk_fma_f32 v[84:85], v[86:87], v[84:85], v[36:37]
	v_cvt_pk_bf16_f32 v82, v82, v83
	v_cvt_pk_bf16_f32 v83, v84, v85
	global_store_dwordx2 v[98:99], v[82:83], off offset:1536 sc1
	s_branch .LBB0_606

.LBB0_710:
	s_andn2_saveexec_b64 s[20:21], s[20:21]
	s_cbranch_execz .Ltr_8
	s_mov_b64 s[20:21], exec
	s_waitcnt lgkmcnt(0)
	s_waitcnt vmcnt(0)
	v_mbcnt_lo_u32_b32 v0, s20, 0
	v_mbcnt_hi_u32_b32 v0, s21, v0
	v_cmp_eq_u32_e32 vcc, 0, v0
	s_and_saveexec_b64 s[40:41], vcc
	s_cbranch_execz .LBB0_713
	s_bcnt1_i32_b64 s20, s[20:21]
	v_readlane_b32 s4, v252, 34
	v_mov_b32_e32 v3, s20
	v_readlane_b32 s5, v252, 35
	s_nop 4
	global_atomic_add v3, v1, v3, s[4:5] sc0
